# P6 and P4c epilogues: batched serialized loads; gated-DeltaNet chunk forward substitution rewritten as fully unrolled register-resident fp32 solve with prefetched L (same FMA order)
# speedup vs baseline: 1.1143x; 1.0437x over previous
; __device__ __forceinline__ void gdn_chunk_item(const Params& p, int item, char* smem) {
;     ...
;     for (int t = 0; t < 64; t++) Xs[t * 256 + tid] = sm_bt[t] * sm_eg[t] * val[t];
;   } else {
; #pragma unroll
;     for (int t = 0; t < 64; t++) Xs[t * 256 + tid] = vv[t];
;   }
;   {
;     float* xc = Xs + tid;
; #pragma unroll 1
;     for (int b4 = 0; b4 < 16; b4++) {
;       const int t0 = b4 * 4;
;       float a0 = xc[t0 * 256], a1 = xc[(t0 + 1) * 256], a2 = xc[(t0 + 2) * 256], a3 = xc[(t0 + 3) * 256];
;       const float* l0p = Ls + t0 * 68;
; #pragma unroll 2
;       for (int sg = 0; sg < b4; sg++) {
;         const float4 l0 = *(const float4*)&l0p[sg * 4], l1 = *(const float4*)&l0p[68 + sg * 4];
;         const float4 l2 = *(const float4*)&l0p[136 + sg * 4], l3 = *(const float4*)&l0p[204 + sg * 4];
;         const float* xp = xc + sg * 1024;
;         const float x0 = xp[0], x1 = xp[256], x2 = xp[512], x3 = xp[768];
;         a0 -= l0.x * x0; a0 -= l0.y * x1; a0 -= l0.z * x2; a0 -= l0.w * x3;
;         a1 -= l1.x * x0; a1 -= l1.y * x1; a1 -= l1.z * x2; a1 -= l1.w * x3;
;         a2 -= l2.x * x0; a2 -= l2.y * x1; a2 -= l2.z * x2; a2 -= l2.w * x3;
;         a3 -= l3.x * x0; a3 -= l3.y * x1; a3 -= l3.z * x2; a3 -= l3.w * x3;
;       }
;       const float4 d1 = *(const float4*)&l0p[68 + t0], d2 = *(const float4*)&l0p[136 + t0], d3 = *(const float4*)&l0p[204 + t0];
;       a1 -= d1.x * a0;
;       a2 -= d2.x * a0; a2 -= d2.y * a1;
;       a3 -= d3.x * a0; a3 -= d3.y * a1; a3 -= d3.z * a2;
;       xc[t0 * 256] = a0; xc[(t0 + 1) * 256] = a1; xc[(t0 + 2) * 256] = a2; xc[(t0 + 3) * 256] = a3;
;     }
; #pragma unroll
;     for (int t = 0; t < 64; t++) val[t] = xc[t * 256];
;   }
.LBB0_874:
	s_or_b64 exec, exec, s[36:37]
	v_mov_b32_e32 v53, v35
	v_mov_b32_e32 v47, v35
	v_mov_b32_e32 v49, v35
	v_mov_b32_e32 v51, v35
	v_lshl_add_u64 v[10:11], vcc, 0, v[52:53]
	v_lshl_add_u64 v[8:9], vcc, 0, v[46:47]
	v_lshl_add_u64 v[6:7], vcc, 0, v[48:49]
	v_lshl_add_u64 v[4:5], vcc, 0, v[50:51]
	s_mov_b32 s3, 0
	s_mov_b32 s36, 0x9000
	ds_write2st64_b32 v210, v182, v183 offset0:240 offset1:244
	ds_write2st64_b32 v210, v190, v191 offset0:248 offset1:252
	v_mov_b32_e32 v54, 0
	ds_read2st64_b32 v[58:59], v210 offset0:0 offset1:4
	ds_read2st64_b32 v[60:61], v210 offset0:8 offset1:12
	ds_read2st64_b32 v[62:63], v210 offset0:16 offset1:20
	ds_read2st64_b32 v[64:65], v210 offset0:24 offset1:28
	ds_read2st64_b32 v[66:67], v210 offset0:32 offset1:36
	ds_read2st64_b32 v[68:69], v210 offset0:40 offset1:44
	ds_read2st64_b32 v[70:71], v210 offset0:48 offset1:52
	ds_read2st64_b32 v[72:73], v210 offset0:56 offset1:60
	ds_read2st64_b32 v[74:75], v210 offset0:64 offset1:68
	ds_read2st64_b32 v[76:77], v210 offset0:72 offset1:76
	ds_read2st64_b32 v[78:79], v210 offset0:80 offset1:84
	ds_read2st64_b32 v[80:81], v210 offset0:88 offset1:92
	ds_read2st64_b32 v[82:83], v210 offset0:96 offset1:100
	ds_read2st64_b32 v[84:85], v210 offset0:104 offset1:108
	ds_read2st64_b32 v[86:87], v210 offset0:112 offset1:116
	ds_read2st64_b32 v[88:89], v210 offset0:120 offset1:124
	ds_read2st64_b32 v[90:91], v210 offset0:128 offset1:132
	ds_read2st64_b32 v[92:93], v210 offset0:136 offset1:140
	ds_read2st64_b32 v[94:95], v210 offset0:144 offset1:148
	ds_read2st64_b32 v[96:97], v210 offset0:152 offset1:156
	ds_read2st64_b32 v[98:99], v210 offset0:160 offset1:164
	ds_read2st64_b32 v[100:101], v210 offset0:168 offset1:172
	ds_read2st64_b32 v[102:103], v210 offset0:176 offset1:180
	ds_read2st64_b32 v[104:105], v210 offset0:184 offset1:188
	ds_read2st64_b32 v[106:107], v210 offset0:192 offset1:196
	ds_read2st64_b32 v[108:109], v210 offset0:200 offset1:204
	ds_read2st64_b32 v[110:111], v210 offset0:208 offset1:212
	ds_read2st64_b32 v[112:113], v210 offset0:216 offset1:220
	ds_read2st64_b32 v[114:115], v210 offset0:224 offset1:228
	ds_read2st64_b32 v[116:117], v210 offset0:232 offset1:236
	ds_read2st64_b32 v[118:119], v210 offset0:240 offset1:244
	ds_read2st64_b32 v[120:121], v210 offset0:248 offset1:252
	ds_read_b128 v[122:125], v54 offset:37136
	ds_read_b128 v[126:129], v54 offset:37408
	ds_read_b128 v[130:133], v54 offset:37680
	ds_read_b128 v[142:145], v54 offset:37952
	ds_read_b128 v[146:149], v54 offset:38224
	ds_read_b128 v[150:153], v54 offset:38496
	ds_read_b128 v[154:157], v54 offset:38768
	ds_read_b128 v[158:161], v54 offset:39040
	ds_read_b128 v[162:165], v54 offset:39312
	ds_read_b128 v[166:169], v54 offset:39584
	ds_read_b128 v[170:173], v54 offset:39856
	s_waitcnt lgkmcnt(11)
	ds_read_b128 v[184:187], v54 offset:40128
	s_waitcnt lgkmcnt(11)
	v_fma_f32 v59, -v122, v58, v59
	ds_read_b128 v[122:125], v54 offset:40400
	s_waitcnt lgkmcnt(11)
	v_fma_f32 v60, -v126, v58, v60
	v_fma_f32 v60, -v127, v59, v60
	ds_read_b128 v[126:129], v54 offset:40672
	s_waitcnt lgkmcnt(11)
	v_fma_f32 v61, -v130, v58, v61
	v_fma_f32 v61, -v131, v59, v61
	v_fma_f32 v61, -v132, v60, v61
	ds_read_b128 v[130:133], v54 offset:40944
	s_waitcnt lgkmcnt(11)
	v_fma_f32 v62, -v142, v58, v62
	v_fma_f32 v62, -v143, v59, v62
	v_fma_f32 v62, -v144, v60, v62
	v_fma_f32 v62, -v145, v61, v62
	ds_read_b128 v[142:145], v54 offset:41216
	s_waitcnt lgkmcnt(11)
	v_fma_f32 v63, -v146, v58, v63
	v_fma_f32 v63, -v147, v59, v63
	v_fma_f32 v63, -v148, v60, v63
	v_fma_f32 v63, -v149, v61, v63
	ds_read_b128 v[146:149], v54 offset:41488
	s_waitcnt lgkmcnt(11)
	v_fma_f32 v64, -v150, v58, v64
	v_fma_f32 v64, -v151, v59, v64
	v_fma_f32 v64, -v152, v60, v64
	v_fma_f32 v64, -v153, v61, v64
	ds_read_b128 v[150:153], v54 offset:41760
	s_waitcnt lgkmcnt(11)
	v_fma_f32 v65, -v154, v58, v65
	v_fma_f32 v65, -v155, v59, v65
	v_fma_f32 v65, -v156, v60, v65
	v_fma_f32 v65, -v157, v61, v65
	ds_read_b128 v[154:157], v54 offset:42032
	s_waitcnt lgkmcnt(11)
	v_fma_f32 v66, -v158, v58, v66
	v_fma_f32 v66, -v159, v59, v66
	v_fma_f32 v66, -v160, v60, v66
	v_fma_f32 v66, -v161, v61, v66
	ds_read_b128 v[158:161], v54 offset:42304
	s_waitcnt lgkmcnt(11)
	v_fma_f32 v67, -v162, v58, v67
	v_fma_f32 v67, -v163, v59, v67
	v_fma_f32 v67, -v164, v60, v67
	v_fma_f32 v67, -v165, v61, v67
	ds_read_b128 v[162:165], v54 offset:42576
	s_waitcnt lgkmcnt(11)
	v_fma_f32 v68, -v166, v58, v68
	v_fma_f32 v68, -v167, v59, v68
	v_fma_f32 v68, -v168, v60, v68
	v_fma_f32 v68, -v169, v61, v68
	ds_read_b128 v[166:169], v54 offset:42848
	s_waitcnt lgkmcnt(11)
	v_fma_f32 v69, -v170, v58, v69
	v_fma_f32 v69, -v171, v59, v69
	v_fma_f32 v69, -v172, v60, v69
	v_fma_f32 v69, -v173, v61, v69
	ds_read_b128 v[170:173], v54 offset:43120
	s_waitcnt lgkmcnt(11)
	v_fma_f32 v70, -v184, v58, v70
	v_fma_f32 v70, -v185, v59, v70
	v_fma_f32 v70, -v186, v60, v70
	v_fma_f32 v70, -v187, v61, v70
	ds_read_b128 v[184:187], v54 offset:43392
	s_waitcnt lgkmcnt(11)
	v_fma_f32 v71, -v122, v58, v71
	v_fma_f32 v71, -v123, v59, v71
	v_fma_f32 v71, -v124, v60, v71
	v_fma_f32 v71, -v125, v61, v71
	ds_read_b128 v[122:125], v54 offset:43664
	s_waitcnt lgkmcnt(11)
	v_fma_f32 v72, -v126, v58, v72
	v_fma_f32 v72, -v127, v59, v72
	v_fma_f32 v72, -v128, v60, v72
	v_fma_f32 v72, -v129, v61, v72
	ds_read_b128 v[126:129], v54 offset:43936
	s_waitcnt lgkmcnt(11)
	v_fma_f32 v73, -v130, v58, v73
	v_fma_f32 v73, -v131, v59, v73
	v_fma_f32 v73, -v132, v60, v73
	v_fma_f32 v73, -v133, v61, v73
	ds_read_b128 v[130:133], v54 offset:44208
	s_waitcnt lgkmcnt(11)
; __device__ __forceinline__ void gdn_chunk_item(const Params& p, int item, char* smem) {
;     ...
;     for (int b4 = 0; b4 < 16; b4++) {
;       const int t0 = b4 * 4;
;       float a0 = xc[t0 * 256], a1 = xc[(t0 + 1) * 256], a2 = xc[(t0 + 2) * 256], a3 = xc[(t0 + 3) * 256];
;       const float* l0p = Ls + t0 * 68;
; #pragma unroll 2
;       for (int sg = 0; sg < b4; sg++) {
;         const float4 l0 = *(const float4*)&l0p[sg * 4], l1 = *(const float4*)&l0p[68 + sg * 4];
;         const float4 l2 = *(const float4*)&l0p[136 + sg * 4], l3 = *(const float4*)&l0p[204 + sg * 4];
;         const float* xp = xc + sg * 1024;
;         const float x0 = xp[0], x1 = xp[256], x2 = xp[512], x3 = xp[768];
;         a0 -= l0.x * x0; a0 -= l0.y * x1; a0 -= l0.z * x2; a0 -= l0.w * x3;
;         a1 -= l1.x * x0; a1 -= l1.y * x1; a1 -= l1.z * x2; a1 -= l1.w * x3;
;         a2 -= l2.x * x0; a2 -= l2.y * x1; a2 -= l2.z * x2; a2 -= l2.w * x3;
;         a3 -= l3.x * x0; a3 -= l3.y * x1; a3 -= l3.z * x2; a3 -= l3.w * x3;
;       }
;       const float4 d1 = *(const float4*)&l0p[68 + t0], d2 = *(const float4*)&l0p[136 + t0], d3 = *(const float4*)&l0p[204 + t0];
;       a1 -= d1.x * a0;
;       a2 -= d2.x * a0; a2 -= d2.y * a1;
;       a3 -= d3.x * a0; a3 -= d3.y * a1; a3 -= d3.z * a2;
;       xc[t0 * 256] = a0; xc[(t0 + 1) * 256] = a1; xc[(t0 + 2) * 256] = a2; xc[(t0 + 3) * 256] = a3;
	v_fma_f32 v74, -v142, v58, v74
	v_fma_f32 v74, -v143, v59, v74
	v_fma_f32 v74, -v144, v60, v74
	v_fma_f32 v74, -v145, v61, v74
	ds_read_b128 v[142:145], v54 offset:44480
	s_waitcnt lgkmcnt(11)
	v_fma_f32 v75, -v146, v58, v75
	v_fma_f32 v75, -v147, v59, v75
	v_fma_f32 v75, -v148, v60, v75
	v_fma_f32 v75, -v149, v61, v75
	ds_read_b128 v[146:149], v54 offset:44752
	s_waitcnt lgkmcnt(11)
	v_fma_f32 v76, -v150, v58, v76
	v_fma_f32 v76, -v151, v59, v76
	v_fma_f32 v76, -v152, v60, v76
	v_fma_f32 v76, -v153, v61, v76
	ds_read_b128 v[150:153], v54 offset:45024
	s_waitcnt lgkmcnt(11)
	v_fma_f32 v77, -v154, v58, v77
	v_fma_f32 v77, -v155, v59, v77
	v_fma_f32 v77, -v156, v60, v77
	v_fma_f32 v77, -v157, v61, v77
	ds_read_b128 v[154:157], v54 offset:45296
	s_waitcnt lgkmcnt(11)
	v_fma_f32 v78, -v158, v58, v78
	v_fma_f32 v78, -v159, v59, v78
	v_fma_f32 v78, -v160, v60, v78
	v_fma_f32 v78, -v161, v61, v78
	ds_read_b128 v[158:161], v54 offset:45568
	s_waitcnt lgkmcnt(11)
	v_fma_f32 v79, -v162, v58, v79
	v_fma_f32 v79, -v163, v59, v79
	v_fma_f32 v79, -v164, v60, v79
	v_fma_f32 v79, -v165, v61, v79
	ds_read_b128 v[162:165], v54 offset:45840
	s_waitcnt lgkmcnt(11)
	v_fma_f32 v80, -v166, v58, v80
	v_fma_f32 v80, -v167, v59, v80
	v_fma_f32 v80, -v168, v60, v80
	v_fma_f32 v80, -v169, v61, v80
	ds_read_b128 v[166:169], v54 offset:46112
	s_waitcnt lgkmcnt(11)
	v_fma_f32 v81, -v170, v58, v81
	v_fma_f32 v81, -v171, v59, v81
	v_fma_f32 v81, -v172, v60, v81
	v_fma_f32 v81, -v173, v61, v81
	ds_read_b128 v[170:173], v54 offset:46384
	s_waitcnt lgkmcnt(11)
	v_fma_f32 v82, -v184, v58, v82
	v_fma_f32 v82, -v185, v59, v82
	v_fma_f32 v82, -v186, v60, v82
	v_fma_f32 v82, -v187, v61, v82
	ds_read_b128 v[184:187], v54 offset:46656
	s_waitcnt lgkmcnt(11)
	v_fma_f32 v83, -v122, v58, v83
	v_fma_f32 v83, -v123, v59, v83
	v_fma_f32 v83, -v124, v60, v83
	v_fma_f32 v83, -v125, v61, v83
	ds_read_b128 v[122:125], v54 offset:46928
	s_waitcnt lgkmcnt(11)
	v_fma_f32 v84, -v126, v58, v84
	v_fma_f32 v84, -v127, v59, v84
	v_fma_f32 v84, -v128, v60, v84
	v_fma_f32 v84, -v129, v61, v84
	ds_read_b128 v[126:129], v54 offset:47200
	s_waitcnt lgkmcnt(11)
	v_fma_f32 v85, -v130, v58, v85
	v_fma_f32 v85, -v131, v59, v85
	v_fma_f32 v85, -v132, v60, v85
	v_fma_f32 v85, -v133, v61, v85
	ds_read_b128 v[130:133], v54 offset:47472
	s_waitcnt lgkmcnt(11)
	v_fma_f32 v86, -v142, v58, v86
	v_fma_f32 v86, -v143, v59, v86
	v_fma_f32 v86, -v144, v60, v86
	v_fma_f32 v86, -v145, v61, v86
	ds_read_b128 v[142:145], v54 offset:47744
	s_waitcnt lgkmcnt(11)
	v_fma_f32 v87, -v146, v58, v87
	v_fma_f32 v87, -v147, v59, v87
	v_fma_f32 v87, -v148, v60, v87
	v_fma_f32 v87, -v149, v61, v87
	ds_read_b128 v[146:149], v54 offset:48016
	s_waitcnt lgkmcnt(11)
	v_fma_f32 v88, -v150, v58, v88
	v_fma_f32 v88, -v151, v59, v88
	v_fma_f32 v88, -v152, v60, v88
	v_fma_f32 v88, -v153, v61, v88
	ds_read_b128 v[150:153], v54 offset:48288
	s_waitcnt lgkmcnt(11)
	v_fma_f32 v89, -v154, v58, v89
	v_fma_f32 v89, -v155, v59, v89
	v_fma_f32 v89, -v156, v60, v89
	v_fma_f32 v89, -v157, v61, v89
	ds_read_b128 v[154:157], v54 offset:48560
	s_waitcnt lgkmcnt(11)
	v_fma_f32 v90, -v158, v58, v90
	v_fma_f32 v90, -v159, v59, v90
	v_fma_f32 v90, -v160, v60, v90
	v_fma_f32 v90, -v161, v61, v90
	ds_read_b128 v[158:161], v54 offset:48832
	s_waitcnt lgkmcnt(11)
	v_fma_f32 v91, -v162, v58, v91
	v_fma_f32 v91, -v163, v59, v91
	v_fma_f32 v91, -v164, v60, v91
	v_fma_f32 v91, -v165, v61, v91
	ds_read_b128 v[162:165], v54 offset:49104
	s_waitcnt lgkmcnt(11)
	v_fma_f32 v92, -v166, v58, v92
	v_fma_f32 v92, -v167, v59, v92
	v_fma_f32 v92, -v168, v60, v92
	v_fma_f32 v92, -v169, v61, v92
	ds_read_b128 v[166:169], v54 offset:49376
	s_waitcnt lgkmcnt(11)
	v_fma_f32 v93, -v170, v58, v93
	v_fma_f32 v93, -v171, v59, v93
	v_fma_f32 v93, -v172, v60, v93
	v_fma_f32 v93, -v173, v61, v93
	ds_read_b128 v[170:173], v54 offset:49648
	s_waitcnt lgkmcnt(11)
	v_fma_f32 v94, -v184, v58, v94
	v_fma_f32 v94, -v185, v59, v94
	v_fma_f32 v94, -v186, v60, v94
	v_fma_f32 v94, -v187, v61, v94
	ds_read_b128 v[184:187], v54 offset:49920
	s_waitcnt lgkmcnt(11)
	v_fma_f32 v95, -v122, v58, v95
	v_fma_f32 v95, -v123, v59, v95
	v_fma_f32 v95, -v124, v60, v95
	v_fma_f32 v95, -v125, v61, v95
	ds_read_b128 v[122:125], v54 offset:50192
	s_waitcnt lgkmcnt(11)
	v_fma_f32 v96, -v126, v58, v96
	v_fma_f32 v96, -v127, v59, v96
	v_fma_f32 v96, -v128, v60, v96
	v_fma_f32 v96, -v129, v61, v96
	ds_read_b128 v[126:129], v54 offset:50464
	s_waitcnt lgkmcnt(11)
	v_fma_f32 v97, -v130, v58, v97
	v_fma_f32 v97, -v131, v59, v97
	v_fma_f32 v97, -v132, v60, v97
	v_fma_f32 v97, -v133, v61, v97
	ds_read_b128 v[130:133], v54 offset:50736
	s_waitcnt lgkmcnt(11)
	v_fma_f32 v98, -v142, v58, v98
	v_fma_f32 v98, -v143, v59, v98
	v_fma_f32 v98, -v144, v60, v98
	v_fma_f32 v98, -v145, v61, v98
	ds_read_b128 v[142:145], v54 offset:51008
	s_waitcnt lgkmcnt(11)
	v_fma_f32 v99, -v146, v58, v99
	v_fma_f32 v99, -v147, v59, v99
	v_fma_f32 v99, -v148, v60, v99
	v_fma_f32 v99, -v149, v61, v99
	ds_read_b128 v[146:149], v54 offset:51280
	s_waitcnt lgkmcnt(11)
	v_fma_f32 v100, -v150, v58, v100
	v_fma_f32 v100, -v151, v59, v100
	v_fma_f32 v100, -v152, v60, v100
	v_fma_f32 v100, -v153, v61, v100
	ds_read_b128 v[150:153], v54 offset:51552
	s_waitcnt lgkmcnt(11)
	v_fma_f32 v101, -v154, v58, v101
	v_fma_f32 v101, -v155, v59, v101
	v_fma_f32 v101, -v156, v60, v101
	v_fma_f32 v101, -v157, v61, v101
	ds_read_b128 v[154:157], v54 offset:51824
	s_waitcnt lgkmcnt(11)
	v_fma_f32 v102, -v158, v58, v102
	v_fma_f32 v102, -v159, v59, v102
	v_fma_f32 v102, -v160, v60, v102
	v_fma_f32 v102, -v161, v61, v102
	ds_read_b128 v[158:161], v54 offset:52096
	s_waitcnt lgkmcnt(11)
; __device__ __forceinline__ void gdn_chunk_item(const Params& p, int item, char* smem) {
;     ...
;     for (int b4 = 0; b4 < 16; b4++) {
;       const int t0 = b4 * 4;
;       float a0 = xc[t0 * 256], a1 = xc[(t0 + 1) * 256], a2 = xc[(t0 + 2) * 256], a3 = xc[(t0 + 3) * 256];
;       const float* l0p = Ls + t0 * 68;
; #pragma unroll 2
;       for (int sg = 0; sg < b4; sg++) {
;         const float4 l0 = *(const float4*)&l0p[sg * 4], l1 = *(const float4*)&l0p[68 + sg * 4];
;         const float4 l2 = *(const float4*)&l0p[136 + sg * 4], l3 = *(const float4*)&l0p[204 + sg * 4];
;         const float* xp = xc + sg * 1024;
;         const float x0 = xp[0], x1 = xp[256], x2 = xp[512], x3 = xp[768];
;         a0 -= l0.x * x0; a0 -= l0.y * x1; a0 -= l0.z * x2; a0 -= l0.w * x3;
;         a1 -= l1.x * x0; a1 -= l1.y * x1; a1 -= l1.z * x2; a1 -= l1.w * x3;
;         a2 -= l2.x * x0; a2 -= l2.y * x1; a2 -= l2.z * x2; a2 -= l2.w * x3;
;         a3 -= l3.x * x0; a3 -= l3.y * x1; a3 -= l3.z * x2; a3 -= l3.w * x3;
;       }
;       const float4 d1 = *(const float4*)&l0p[68 + t0], d2 = *(const float4*)&l0p[136 + t0], d3 = *(const float4*)&l0p[204 + t0];
;       a1 -= d1.x * a0;
;       a2 -= d2.x * a0; a2 -= d2.y * a1;
;       a3 -= d3.x * a0; a3 -= d3.y * a1; a3 -= d3.z * a2;
;       xc[t0 * 256] = a0; xc[(t0 + 1) * 256] = a1; xc[(t0 + 2) * 256] = a2; xc[(t0 + 3) * 256] = a3;
	v_fma_f32 v103, -v162, v58, v103
	v_fma_f32 v103, -v163, v59, v103
	v_fma_f32 v103, -v164, v60, v103
	v_fma_f32 v103, -v165, v61, v103
	ds_read_b128 v[162:165], v54 offset:52368
	s_waitcnt lgkmcnt(11)
	v_fma_f32 v104, -v166, v58, v104
	v_fma_f32 v104, -v167, v59, v104
	v_fma_f32 v104, -v168, v60, v104
	v_fma_f32 v104, -v169, v61, v104
	ds_read_b128 v[166:169], v54 offset:52640
	s_waitcnt lgkmcnt(11)
	v_fma_f32 v105, -v170, v58, v105
	v_fma_f32 v105, -v171, v59, v105
	v_fma_f32 v105, -v172, v60, v105
	v_fma_f32 v105, -v173, v61, v105
	ds_read_b128 v[170:173], v54 offset:52912
	s_waitcnt lgkmcnt(11)
	v_fma_f32 v106, -v184, v58, v106
	v_fma_f32 v106, -v185, v59, v106
	v_fma_f32 v106, -v186, v60, v106
	v_fma_f32 v106, -v187, v61, v106
	ds_read_b128 v[184:187], v54 offset:53184
	s_waitcnt lgkmcnt(11)
	v_fma_f32 v107, -v122, v58, v107
	v_fma_f32 v107, -v123, v59, v107
	v_fma_f32 v107, -v124, v60, v107
	v_fma_f32 v107, -v125, v61, v107
	ds_read_b128 v[122:125], v54 offset:53456
	s_waitcnt lgkmcnt(11)
	v_fma_f32 v108, -v126, v58, v108
	v_fma_f32 v108, -v127, v59, v108
	v_fma_f32 v108, -v128, v60, v108
	v_fma_f32 v108, -v129, v61, v108
	ds_read_b128 v[126:129], v54 offset:53728
	s_waitcnt lgkmcnt(11)
	v_fma_f32 v109, -v130, v58, v109
	v_fma_f32 v109, -v131, v59, v109
	v_fma_f32 v109, -v132, v60, v109
	v_fma_f32 v109, -v133, v61, v109
	ds_read_b128 v[130:133], v54 offset:54000
	s_waitcnt lgkmcnt(11)
	v_fma_f32 v110, -v142, v58, v110
	v_fma_f32 v110, -v143, v59, v110
	v_fma_f32 v110, -v144, v60, v110
	v_fma_f32 v110, -v145, v61, v110
	ds_read_b128 v[142:145], v54 offset:38240
	s_waitcnt lgkmcnt(11)
	v_fma_f32 v111, -v146, v58, v111
	v_fma_f32 v111, -v147, v59, v111
	v_fma_f32 v111, -v148, v60, v111
	v_fma_f32 v111, -v149, v61, v111
	ds_read_b128 v[146:149], v54 offset:38512
	s_waitcnt lgkmcnt(11)
	v_fma_f32 v112, -v150, v58, v112
	v_fma_f32 v112, -v151, v59, v112
	v_fma_f32 v112, -v152, v60, v112
	v_fma_f32 v112, -v153, v61, v112
	ds_read_b128 v[150:153], v54 offset:38784
	s_waitcnt lgkmcnt(11)
	v_fma_f32 v113, -v154, v58, v113
	v_fma_f32 v113, -v155, v59, v113
	v_fma_f32 v113, -v156, v60, v113
	v_fma_f32 v113, -v157, v61, v113
	ds_read_b128 v[154:157], v54 offset:39056
	s_waitcnt lgkmcnt(11)
	v_fma_f32 v114, -v158, v58, v114
	v_fma_f32 v114, -v159, v59, v114
	v_fma_f32 v114, -v160, v60, v114
	v_fma_f32 v114, -v161, v61, v114
	ds_read_b128 v[158:161], v54 offset:39328
	s_waitcnt lgkmcnt(11)
	v_fma_f32 v115, -v162, v58, v115
	v_fma_f32 v115, -v163, v59, v115
	v_fma_f32 v115, -v164, v60, v115
	v_fma_f32 v115, -v165, v61, v115
	ds_read_b128 v[162:165], v54 offset:39600
	s_waitcnt lgkmcnt(11)
	v_fma_f32 v116, -v166, v58, v116
	v_fma_f32 v116, -v167, v59, v116
	v_fma_f32 v116, -v168, v60, v116
	v_fma_f32 v116, -v169, v61, v116
	ds_read_b128 v[166:169], v54 offset:39872
	s_waitcnt lgkmcnt(11)
	v_fma_f32 v117, -v170, v58, v117
	v_fma_f32 v117, -v171, v59, v117
	v_fma_f32 v117, -v172, v60, v117
	v_fma_f32 v117, -v173, v61, v117
	ds_read_b128 v[170:173], v54 offset:40144
	s_waitcnt lgkmcnt(11)
	v_fma_f32 v118, -v184, v58, v118
	v_fma_f32 v118, -v185, v59, v118
	v_fma_f32 v118, -v186, v60, v118
	v_fma_f32 v118, -v187, v61, v118
	ds_read_b128 v[184:187], v54 offset:40416
	s_waitcnt lgkmcnt(11)
	v_fma_f32 v119, -v122, v58, v119
	v_fma_f32 v119, -v123, v59, v119
	v_fma_f32 v119, -v124, v60, v119
	v_fma_f32 v119, -v125, v61, v119
	ds_read_b128 v[122:125], v54 offset:40688
	s_waitcnt lgkmcnt(11)
	v_fma_f32 v120, -v126, v58, v120
	v_fma_f32 v120, -v127, v59, v120
	v_fma_f32 v120, -v128, v60, v120
	v_fma_f32 v120, -v129, v61, v120
	ds_read_b128 v[126:129], v54 offset:40960
	s_waitcnt lgkmcnt(11)
	v_fma_f32 v121, -v130, v58, v121
	v_fma_f32 v121, -v131, v59, v121
	v_fma_f32 v121, -v132, v60, v121
	v_fma_f32 v121, -v133, v61, v121
	ds_read_b128 v[130:133], v54 offset:41232
	s_waitcnt lgkmcnt(11)
	v_fma_f32 v63, -v142, v62, v63
	ds_read_b128 v[142:145], v54 offset:41504
	s_waitcnt lgkmcnt(11)
	v_fma_f32 v64, -v146, v62, v64
	v_fma_f32 v64, -v147, v63, v64
	ds_read_b128 v[146:149], v54 offset:41776
	s_waitcnt lgkmcnt(11)
	v_fma_f32 v65, -v150, v62, v65
	v_fma_f32 v65, -v151, v63, v65
	v_fma_f32 v65, -v152, v64, v65
	ds_read_b128 v[150:153], v54 offset:42048
	s_waitcnt lgkmcnt(11)
	v_fma_f32 v66, -v154, v62, v66
	v_fma_f32 v66, -v155, v63, v66
	v_fma_f32 v66, -v156, v64, v66
	v_fma_f32 v66, -v157, v65, v66
	ds_read_b128 v[154:157], v54 offset:42320
	s_waitcnt lgkmcnt(11)
	v_fma_f32 v67, -v158, v62, v67
	v_fma_f32 v67, -v159, v63, v67
	v_fma_f32 v67, -v160, v64, v67
	v_fma_f32 v67, -v161, v65, v67
	ds_read_b128 v[158:161], v54 offset:42592
	s_waitcnt lgkmcnt(11)
	v_fma_f32 v68, -v162, v62, v68
	v_fma_f32 v68, -v163, v63, v68
	v_fma_f32 v68, -v164, v64, v68
	v_fma_f32 v68, -v165, v65, v68
	ds_read_b128 v[162:165], v54 offset:42864
	s_waitcnt lgkmcnt(11)
	v_fma_f32 v69, -v166, v62, v69
	v_fma_f32 v69, -v167, v63, v69
	v_fma_f32 v69, -v168, v64, v69
	v_fma_f32 v69, -v169, v65, v69
	ds_read_b128 v[166:169], v54 offset:43136
	s_waitcnt lgkmcnt(11)
	v_fma_f32 v70, -v170, v62, v70
	v_fma_f32 v70, -v171, v63, v70
	v_fma_f32 v70, -v172, v64, v70
	v_fma_f32 v70, -v173, v65, v70
	ds_read_b128 v[170:173], v54 offset:43408
	s_waitcnt lgkmcnt(11)
	v_fma_f32 v71, -v184, v62, v71
	v_fma_f32 v71, -v185, v63, v71
	v_fma_f32 v71, -v186, v64, v71
	v_fma_f32 v71, -v187, v65, v71
	ds_read_b128 v[184:187], v54 offset:43680
	s_waitcnt lgkmcnt(11)
	v_fma_f32 v72, -v122, v62, v72
	v_fma_f32 v72, -v123, v63, v72
	v_fma_f32 v72, -v124, v64, v72
	v_fma_f32 v72, -v125, v65, v72
	ds_read_b128 v[122:125], v54 offset:43952
	s_waitcnt lgkmcnt(11)
; __device__ __forceinline__ void gdn_chunk_item(const Params& p, int item, char* smem) {
;     ...
;     for (int b4 = 0; b4 < 16; b4++) {
;       const int t0 = b4 * 4;
;       float a0 = xc[t0 * 256], a1 = xc[(t0 + 1) * 256], a2 = xc[(t0 + 2) * 256], a3 = xc[(t0 + 3) * 256];
;       const float* l0p = Ls + t0 * 68;
; #pragma unroll 2
;       for (int sg = 0; sg < b4; sg++) {
;         const float4 l0 = *(const float4*)&l0p[sg * 4], l1 = *(const float4*)&l0p[68 + sg * 4];
;         const float4 l2 = *(const float4*)&l0p[136 + sg * 4], l3 = *(const float4*)&l0p[204 + sg * 4];
;         const float* xp = xc + sg * 1024;
;         const float x0 = xp[0], x1 = xp[256], x2 = xp[512], x3 = xp[768];
;         a0 -= l0.x * x0; a0 -= l0.y * x1; a0 -= l0.z * x2; a0 -= l0.w * x3;
;         a1 -= l1.x * x0; a1 -= l1.y * x1; a1 -= l1.z * x2; a1 -= l1.w * x3;
;         a2 -= l2.x * x0; a2 -= l2.y * x1; a2 -= l2.z * x2; a2 -= l2.w * x3;
;         a3 -= l3.x * x0; a3 -= l3.y * x1; a3 -= l3.z * x2; a3 -= l3.w * x3;
;       }
;       const float4 d1 = *(const float4*)&l0p[68 + t0], d2 = *(const float4*)&l0p[136 + t0], d3 = *(const float4*)&l0p[204 + t0];
;       a1 -= d1.x * a0;
;       a2 -= d2.x * a0; a2 -= d2.y * a1;
;       a3 -= d3.x * a0; a3 -= d3.y * a1; a3 -= d3.z * a2;
;       xc[t0 * 256] = a0; xc[(t0 + 1) * 256] = a1; xc[(t0 + 2) * 256] = a2; xc[(t0 + 3) * 256] = a3;
	v_fma_f32 v73, -v126, v62, v73
	v_fma_f32 v73, -v127, v63, v73
	v_fma_f32 v73, -v128, v64, v73
	v_fma_f32 v73, -v129, v65, v73
	ds_read_b128 v[126:129], v54 offset:44224
	s_waitcnt lgkmcnt(11)
	v_fma_f32 v74, -v130, v62, v74
	v_fma_f32 v74, -v131, v63, v74
	v_fma_f32 v74, -v132, v64, v74
	v_fma_f32 v74, -v133, v65, v74
	ds_read_b128 v[130:133], v54 offset:44496
	s_waitcnt lgkmcnt(11)
	v_fma_f32 v75, -v142, v62, v75
	v_fma_f32 v75, -v143, v63, v75
	v_fma_f32 v75, -v144, v64, v75
	v_fma_f32 v75, -v145, v65, v75
	ds_read_b128 v[142:145], v54 offset:44768
	s_waitcnt lgkmcnt(11)
	v_fma_f32 v76, -v146, v62, v76
	v_fma_f32 v76, -v147, v63, v76
	v_fma_f32 v76, -v148, v64, v76
	v_fma_f32 v76, -v149, v65, v76
	ds_read_b128 v[146:149], v54 offset:45040
	s_waitcnt lgkmcnt(11)
	v_fma_f32 v77, -v150, v62, v77
	v_fma_f32 v77, -v151, v63, v77
	v_fma_f32 v77, -v152, v64, v77
	v_fma_f32 v77, -v153, v65, v77
	ds_read_b128 v[150:153], v54 offset:45312
	s_waitcnt lgkmcnt(11)
	v_fma_f32 v78, -v154, v62, v78
	v_fma_f32 v78, -v155, v63, v78
	v_fma_f32 v78, -v156, v64, v78
	v_fma_f32 v78, -v157, v65, v78
	ds_read_b128 v[154:157], v54 offset:45584
	s_waitcnt lgkmcnt(11)
	v_fma_f32 v79, -v158, v62, v79
	v_fma_f32 v79, -v159, v63, v79
	v_fma_f32 v79, -v160, v64, v79
	v_fma_f32 v79, -v161, v65, v79
	ds_read_b128 v[158:161], v54 offset:45856
	s_waitcnt lgkmcnt(11)
	v_fma_f32 v80, -v162, v62, v80
	v_fma_f32 v80, -v163, v63, v80
	v_fma_f32 v80, -v164, v64, v80
	v_fma_f32 v80, -v165, v65, v80
	ds_read_b128 v[162:165], v54 offset:46128
	s_waitcnt lgkmcnt(11)
	v_fma_f32 v81, -v166, v62, v81
	v_fma_f32 v81, -v167, v63, v81
	v_fma_f32 v81, -v168, v64, v81
	v_fma_f32 v81, -v169, v65, v81
	ds_read_b128 v[166:169], v54 offset:46400
	s_waitcnt lgkmcnt(11)
	v_fma_f32 v82, -v170, v62, v82
	v_fma_f32 v82, -v171, v63, v82
	v_fma_f32 v82, -v172, v64, v82
	v_fma_f32 v82, -v173, v65, v82
	ds_read_b128 v[170:173], v54 offset:46672
	s_waitcnt lgkmcnt(11)
	v_fma_f32 v83, -v184, v62, v83
	v_fma_f32 v83, -v185, v63, v83
	v_fma_f32 v83, -v186, v64, v83
	v_fma_f32 v83, -v187, v65, v83
	ds_read_b128 v[184:187], v54 offset:46944
	s_waitcnt lgkmcnt(11)
	v_fma_f32 v84, -v122, v62, v84
	v_fma_f32 v84, -v123, v63, v84
	v_fma_f32 v84, -v124, v64, v84
	v_fma_f32 v84, -v125, v65, v84
	ds_read_b128 v[122:125], v54 offset:47216
	s_waitcnt lgkmcnt(11)
	v_fma_f32 v85, -v126, v62, v85
	v_fma_f32 v85, -v127, v63, v85
	v_fma_f32 v85, -v128, v64, v85
	v_fma_f32 v85, -v129, v65, v85
	ds_read_b128 v[126:129], v54 offset:47488
	s_waitcnt lgkmcnt(11)
	v_fma_f32 v86, -v130, v62, v86
	v_fma_f32 v86, -v131, v63, v86
	v_fma_f32 v86, -v132, v64, v86
	v_fma_f32 v86, -v133, v65, v86
	ds_read_b128 v[130:133], v54 offset:47760
	s_waitcnt lgkmcnt(11)
	v_fma_f32 v87, -v142, v62, v87
	v_fma_f32 v87, -v143, v63, v87
	v_fma_f32 v87, -v144, v64, v87
	v_fma_f32 v87, -v145, v65, v87
	ds_read_b128 v[142:145], v54 offset:48032
	s_waitcnt lgkmcnt(11)
	v_fma_f32 v88, -v146, v62, v88
	v_fma_f32 v88, -v147, v63, v88
	v_fma_f32 v88, -v148, v64, v88
	v_fma_f32 v88, -v149, v65, v88
	ds_read_b128 v[146:149], v54 offset:48304
	s_waitcnt lgkmcnt(11)
	v_fma_f32 v89, -v150, v62, v89
	v_fma_f32 v89, -v151, v63, v89
	v_fma_f32 v89, -v152, v64, v89
	v_fma_f32 v89, -v153, v65, v89
	ds_read_b128 v[150:153], v54 offset:48576
	s_waitcnt lgkmcnt(11)
	v_fma_f32 v90, -v154, v62, v90
	v_fma_f32 v90, -v155, v63, v90
	v_fma_f32 v90, -v156, v64, v90
	v_fma_f32 v90, -v157, v65, v90
	ds_read_b128 v[154:157], v54 offset:48848
	s_waitcnt lgkmcnt(11)
	v_fma_f32 v91, -v158, v62, v91
	v_fma_f32 v91, -v159, v63, v91
	v_fma_f32 v91, -v160, v64, v91
	v_fma_f32 v91, -v161, v65, v91
	ds_read_b128 v[158:161], v54 offset:49120
	s_waitcnt lgkmcnt(11)
	v_fma_f32 v92, -v162, v62, v92
	v_fma_f32 v92, -v163, v63, v92
	v_fma_f32 v92, -v164, v64, v92
	v_fma_f32 v92, -v165, v65, v92
	ds_read_b128 v[162:165], v54 offset:49392
	s_waitcnt lgkmcnt(11)
	v_fma_f32 v93, -v166, v62, v93
	v_fma_f32 v93, -v167, v63, v93
	v_fma_f32 v93, -v168, v64, v93
	v_fma_f32 v93, -v169, v65, v93
	ds_read_b128 v[166:169], v54 offset:49664
	s_waitcnt lgkmcnt(11)
	v_fma_f32 v94, -v170, v62, v94
	v_fma_f32 v94, -v171, v63, v94
	v_fma_f32 v94, -v172, v64, v94
	v_fma_f32 v94, -v173, v65, v94
	ds_read_b128 v[170:173], v54 offset:49936
	s_waitcnt lgkmcnt(11)
	v_fma_f32 v95, -v184, v62, v95
	v_fma_f32 v95, -v185, v63, v95
	v_fma_f32 v95, -v186, v64, v95
	v_fma_f32 v95, -v187, v65, v95
	ds_read_b128 v[184:187], v54 offset:50208
	s_waitcnt lgkmcnt(11)
	v_fma_f32 v96, -v122, v62, v96
	v_fma_f32 v96, -v123, v63, v96
	v_fma_f32 v96, -v124, v64, v96
	v_fma_f32 v96, -v125, v65, v96
	ds_read_b128 v[122:125], v54 offset:50480
	s_waitcnt lgkmcnt(11)
	v_fma_f32 v97, -v126, v62, v97
	v_fma_f32 v97, -v127, v63, v97
	v_fma_f32 v97, -v128, v64, v97
	v_fma_f32 v97, -v129, v65, v97
	ds_read_b128 v[126:129], v54 offset:50752
	s_waitcnt lgkmcnt(11)
	v_fma_f32 v98, -v130, v62, v98
	v_fma_f32 v98, -v131, v63, v98
	v_fma_f32 v98, -v132, v64, v98
	v_fma_f32 v98, -v133, v65, v98
	ds_read_b128 v[130:133], v54 offset:51024
	s_waitcnt lgkmcnt(11)
	v_fma_f32 v99, -v142, v62, v99
	v_fma_f32 v99, -v143, v63, v99
	v_fma_f32 v99, -v144, v64, v99
	v_fma_f32 v99, -v145, v65, v99
	ds_read_b128 v[142:145], v54 offset:51296
	s_waitcnt lgkmcnt(11)
	v_fma_f32 v100, -v146, v62, v100
	v_fma_f32 v100, -v147, v63, v100
	v_fma_f32 v100, -v148, v64, v100
	v_fma_f32 v100, -v149, v65, v100
	ds_read_b128 v[146:149], v54 offset:51568
	s_waitcnt lgkmcnt(11)
	v_fma_f32 v101, -v150, v62, v101
	v_fma_f32 v101, -v151, v63, v101
	v_fma_f32 v101, -v152, v64, v101
	v_fma_f32 v101, -v153, v65, v101
	ds_read_b128 v[150:153], v54 offset:51840
	s_waitcnt lgkmcnt(11)
; __device__ __forceinline__ void gdn_chunk_item(const Params& p, int item, char* smem) {
;     ...
;     for (int b4 = 0; b4 < 16; b4++) {
;       const int t0 = b4 * 4;
;       float a0 = xc[t0 * 256], a1 = xc[(t0 + 1) * 256], a2 = xc[(t0 + 2) * 256], a3 = xc[(t0 + 3) * 256];
;       const float* l0p = Ls + t0 * 68;
; #pragma unroll 2
;       for (int sg = 0; sg < b4; sg++) {
;         const float4 l0 = *(const float4*)&l0p[sg * 4], l1 = *(const float4*)&l0p[68 + sg * 4];
;         const float4 l2 = *(const float4*)&l0p[136 + sg * 4], l3 = *(const float4*)&l0p[204 + sg * 4];
;         const float* xp = xc + sg * 1024;
;         const float x0 = xp[0], x1 = xp[256], x2 = xp[512], x3 = xp[768];
;         a0 -= l0.x * x0; a0 -= l0.y * x1; a0 -= l0.z * x2; a0 -= l0.w * x3;
;         a1 -= l1.x * x0; a1 -= l1.y * x1; a1 -= l1.z * x2; a1 -= l1.w * x3;
;         a2 -= l2.x * x0; a2 -= l2.y * x1; a2 -= l2.z * x2; a2 -= l2.w * x3;
;         a3 -= l3.x * x0; a3 -= l3.y * x1; a3 -= l3.z * x2; a3 -= l3.w * x3;
;       }
;       const float4 d1 = *(const float4*)&l0p[68 + t0], d2 = *(const float4*)&l0p[136 + t0], d3 = *(const float4*)&l0p[204 + t0];
;       a1 -= d1.x * a0;
;       a2 -= d2.x * a0; a2 -= d2.y * a1;
;       a3 -= d3.x * a0; a3 -= d3.y * a1; a3 -= d3.z * a2;
;       xc[t0 * 256] = a0; xc[(t0 + 1) * 256] = a1; xc[(t0 + 2) * 256] = a2; xc[(t0 + 3) * 256] = a3;
	v_fma_f32 v102, -v154, v62, v102
	v_fma_f32 v102, -v155, v63, v102
	v_fma_f32 v102, -v156, v64, v102
	v_fma_f32 v102, -v157, v65, v102
	ds_read_b128 v[154:157], v54 offset:52112
	s_waitcnt lgkmcnt(11)
	v_fma_f32 v103, -v158, v62, v103
	v_fma_f32 v103, -v159, v63, v103
	v_fma_f32 v103, -v160, v64, v103
	v_fma_f32 v103, -v161, v65, v103
	ds_read_b128 v[158:161], v54 offset:52384
	s_waitcnt lgkmcnt(11)
	v_fma_f32 v104, -v162, v62, v104
	v_fma_f32 v104, -v163, v63, v104
	v_fma_f32 v104, -v164, v64, v104
	v_fma_f32 v104, -v165, v65, v104
	ds_read_b128 v[162:165], v54 offset:52656
	s_waitcnt lgkmcnt(11)
	v_fma_f32 v105, -v166, v62, v105
	v_fma_f32 v105, -v167, v63, v105
	v_fma_f32 v105, -v168, v64, v105
	v_fma_f32 v105, -v169, v65, v105
	ds_read_b128 v[166:169], v54 offset:52928
	s_waitcnt lgkmcnt(11)
	v_fma_f32 v106, -v170, v62, v106
	v_fma_f32 v106, -v171, v63, v106
	v_fma_f32 v106, -v172, v64, v106
	v_fma_f32 v106, -v173, v65, v106
	ds_read_b128 v[170:173], v54 offset:53200
	s_waitcnt lgkmcnt(11)
	v_fma_f32 v107, -v184, v62, v107
	v_fma_f32 v107, -v185, v63, v107
	v_fma_f32 v107, -v186, v64, v107
	v_fma_f32 v107, -v187, v65, v107
	ds_read_b128 v[184:187], v54 offset:53472
	s_waitcnt lgkmcnt(11)
	v_fma_f32 v108, -v122, v62, v108
	v_fma_f32 v108, -v123, v63, v108
	v_fma_f32 v108, -v124, v64, v108
	v_fma_f32 v108, -v125, v65, v108
	ds_read_b128 v[122:125], v54 offset:53744
	s_waitcnt lgkmcnt(11)
	v_fma_f32 v109, -v126, v62, v109
	v_fma_f32 v109, -v127, v63, v109
	v_fma_f32 v109, -v128, v64, v109
	v_fma_f32 v109, -v129, v65, v109
	ds_read_b128 v[126:129], v54 offset:54016
	s_waitcnt lgkmcnt(11)
	v_fma_f32 v110, -v130, v62, v110
	v_fma_f32 v110, -v131, v63, v110
	v_fma_f32 v110, -v132, v64, v110
	v_fma_f32 v110, -v133, v65, v110
	ds_read_b128 v[130:133], v54 offset:39344
	s_waitcnt lgkmcnt(11)
	v_fma_f32 v111, -v142, v62, v111
	v_fma_f32 v111, -v143, v63, v111
	v_fma_f32 v111, -v144, v64, v111
	v_fma_f32 v111, -v145, v65, v111
	ds_read_b128 v[142:145], v54 offset:39616
	s_waitcnt lgkmcnt(11)
	v_fma_f32 v112, -v146, v62, v112
	v_fma_f32 v112, -v147, v63, v112
	v_fma_f32 v112, -v148, v64, v112
	v_fma_f32 v112, -v149, v65, v112
	ds_read_b128 v[146:149], v54 offset:39888
	s_waitcnt lgkmcnt(11)
	v_fma_f32 v113, -v150, v62, v113
	v_fma_f32 v113, -v151, v63, v113
	v_fma_f32 v113, -v152, v64, v113
	v_fma_f32 v113, -v153, v65, v113
	ds_read_b128 v[150:153], v54 offset:40160
	s_waitcnt lgkmcnt(11)
	v_fma_f32 v114, -v154, v62, v114
	v_fma_f32 v114, -v155, v63, v114
	v_fma_f32 v114, -v156, v64, v114
	v_fma_f32 v114, -v157, v65, v114
	ds_read_b128 v[154:157], v54 offset:40432
	s_waitcnt lgkmcnt(11)
	v_fma_f32 v115, -v158, v62, v115
	v_fma_f32 v115, -v159, v63, v115
	v_fma_f32 v115, -v160, v64, v115
	v_fma_f32 v115, -v161, v65, v115
	ds_read_b128 v[158:161], v54 offset:40704
	s_waitcnt lgkmcnt(11)
	v_fma_f32 v116, -v162, v62, v116
	v_fma_f32 v116, -v163, v63, v116
	v_fma_f32 v116, -v164, v64, v116
	v_fma_f32 v116, -v165, v65, v116
	ds_read_b128 v[162:165], v54 offset:40976
	s_waitcnt lgkmcnt(11)
	v_fma_f32 v117, -v166, v62, v117
	v_fma_f32 v117, -v167, v63, v117
	v_fma_f32 v117, -v168, v64, v117
	v_fma_f32 v117, -v169, v65, v117
	ds_read_b128 v[166:169], v54 offset:41248
	s_waitcnt lgkmcnt(11)
	v_fma_f32 v118, -v170, v62, v118
	v_fma_f32 v118, -v171, v63, v118
	v_fma_f32 v118, -v172, v64, v118
	v_fma_f32 v118, -v173, v65, v118
	ds_read_b128 v[170:173], v54 offset:41520
	s_waitcnt lgkmcnt(11)
	v_fma_f32 v119, -v184, v62, v119
	v_fma_f32 v119, -v185, v63, v119
	v_fma_f32 v119, -v186, v64, v119
	v_fma_f32 v119, -v187, v65, v119
	ds_read_b128 v[184:187], v54 offset:41792
	s_waitcnt lgkmcnt(11)
	v_fma_f32 v120, -v122, v62, v120
	v_fma_f32 v120, -v123, v63, v120
	v_fma_f32 v120, -v124, v64, v120
	v_fma_f32 v120, -v125, v65, v120
	ds_read_b128 v[122:125], v54 offset:42064
	s_waitcnt lgkmcnt(11)
	v_fma_f32 v121, -v126, v62, v121
	v_fma_f32 v121, -v127, v63, v121
	v_fma_f32 v121, -v128, v64, v121
	v_fma_f32 v121, -v129, v65, v121
	ds_read_b128 v[126:129], v54 offset:42336
	s_waitcnt lgkmcnt(11)
	v_fma_f32 v67, -v130, v66, v67
	ds_read_b128 v[130:133], v54 offset:42608
	s_waitcnt lgkmcnt(11)
	v_fma_f32 v68, -v142, v66, v68
	v_fma_f32 v68, -v143, v67, v68
	ds_read_b128 v[142:145], v54 offset:42880
	s_waitcnt lgkmcnt(11)
	v_fma_f32 v69, -v146, v66, v69
	v_fma_f32 v69, -v147, v67, v69
	v_fma_f32 v69, -v148, v68, v69
	ds_read_b128 v[146:149], v54 offset:43152
	s_waitcnt lgkmcnt(11)
	v_fma_f32 v70, -v150, v66, v70
	v_fma_f32 v70, -v151, v67, v70
	v_fma_f32 v70, -v152, v68, v70
	v_fma_f32 v70, -v153, v69, v70
	ds_read_b128 v[150:153], v54 offset:43424
	s_waitcnt lgkmcnt(11)
	v_fma_f32 v71, -v154, v66, v71
	v_fma_f32 v71, -v155, v67, v71
	v_fma_f32 v71, -v156, v68, v71
	v_fma_f32 v71, -v157, v69, v71
	ds_read_b128 v[154:157], v54 offset:43696
	s_waitcnt lgkmcnt(11)
	v_fma_f32 v72, -v158, v66, v72
	v_fma_f32 v72, -v159, v67, v72
	v_fma_f32 v72, -v160, v68, v72
	v_fma_f32 v72, -v161, v69, v72
	ds_read_b128 v[158:161], v54 offset:43968
	s_waitcnt lgkmcnt(11)
	v_fma_f32 v73, -v162, v66, v73
	v_fma_f32 v73, -v163, v67, v73
	v_fma_f32 v73, -v164, v68, v73
	v_fma_f32 v73, -v165, v69, v73
	ds_read_b128 v[162:165], v54 offset:44240
	s_waitcnt lgkmcnt(11)
	v_fma_f32 v74, -v166, v66, v74
	v_fma_f32 v74, -v167, v67, v74
	v_fma_f32 v74, -v168, v68, v74
	v_fma_f32 v74, -v169, v69, v74
	ds_read_b128 v[166:169], v54 offset:44512
	s_waitcnt lgkmcnt(11)
	v_fma_f32 v75, -v170, v66, v75
	v_fma_f32 v75, -v171, v67, v75
	v_fma_f32 v75, -v172, v68, v75
	v_fma_f32 v75, -v173, v69, v75
	ds_read_b128 v[170:173], v54 offset:44784
	s_waitcnt lgkmcnt(11)
; __device__ __forceinline__ void gdn_chunk_item(const Params& p, int item, char* smem) {
;     ...
; #pragma unroll 2
;       for (int sg = 0; sg < b4; sg++) {
;         const float4 l0 = *(const float4*)&l0p[sg * 4], l1 = *(const float4*)&l0p[68 + sg * 4];
;         const float4 l2 = *(const float4*)&l0p[136 + sg * 4], l3 = *(const float4*)&l0p[204 + sg * 4];
;         const float* xp = xc + sg * 1024;
;         const float x0 = xp[0], x1 = xp[256], x2 = xp[512], x3 = xp[768];
;         a0 -= l0.x * x0; a0 -= l0.y * x1; a0 -= l0.z * x2; a0 -= l0.w * x3;
;         a1 -= l1.x * x0; a1 -= l1.y * x1; a1 -= l1.z * x2; a1 -= l1.w * x3;
;         a2 -= l2.x * x0; a2 -= l2.y * x1; a2 -= l2.z * x2; a2 -= l2.w * x3;
;         a3 -= l3.x * x0; a3 -= l3.y * x1; a3 -= l3.z * x2; a3 -= l3.w * x3;
;       }
;       const float4 d1 = *(const float4*)&l0p[68 + t0], d2 = *(const float4*)&l0p[136 + t0], d3 = *(const float4*)&l0p[204 + t0];
;       a1 -= d1.x * a0;
;       a2 -= d2.x * a0; a2 -= d2.y * a1;
;       a3 -= d3.x * a0; a3 -= d3.y * a1; a3 -= d3.z * a2;
	v_fma_f32 v76, -v184, v66, v76
	v_fma_f32 v76, -v185, v67, v76
	v_fma_f32 v76, -v186, v68, v76
	v_fma_f32 v76, -v187, v69, v76
	ds_read_b128 v[184:187], v54 offset:45056
	s_waitcnt lgkmcnt(11)
	v_fma_f32 v77, -v122, v66, v77
	v_fma_f32 v77, -v123, v67, v77
	v_fma_f32 v77, -v124, v68, v77
	v_fma_f32 v77, -v125, v69, v77
	ds_read_b128 v[122:125], v54 offset:45328
	s_waitcnt lgkmcnt(11)
	v_fma_f32 v78, -v126, v66, v78
	v_fma_f32 v78, -v127, v67, v78
	v_fma_f32 v78, -v128, v68, v78
	v_fma_f32 v78, -v129, v69, v78
	ds_read_b128 v[126:129], v54 offset:45600
	s_waitcnt lgkmcnt(11)
	v_fma_f32 v79, -v130, v66, v79
	v_fma_f32 v79, -v131, v67, v79
	v_fma_f32 v79, -v132, v68, v79
	v_fma_f32 v79, -v133, v69, v79
	ds_read_b128 v[130:133], v54 offset:45872
	s_waitcnt lgkmcnt(11)
	v_fma_f32 v80, -v142, v66, v80
	v_fma_f32 v80, -v143, v67, v80
	v_fma_f32 v80, -v144, v68, v80
	v_fma_f32 v80, -v145, v69, v80
	ds_read_b128 v[142:145], v54 offset:46144
	s_waitcnt lgkmcnt(11)
	v_fma_f32 v81, -v146, v66, v81
	v_fma_f32 v81, -v147, v67, v81
	v_fma_f32 v81, -v148, v68, v81
	v_fma_f32 v81, -v149, v69, v81
	ds_read_b128 v[146:149], v54 offset:46416
	s_waitcnt lgkmcnt(11)
	v_fma_f32 v82, -v150, v66, v82
	v_fma_f32 v82, -v151, v67, v82
	v_fma_f32 v82, -v152, v68, v82
	v_fma_f32 v82, -v153, v69, v82
	ds_read_b128 v[150:153], v54 offset:46688
	s_waitcnt lgkmcnt(11)
	v_fma_f32 v83, -v154, v66, v83
	v_fma_f32 v83, -v155, v67, v83
	v_fma_f32 v83, -v156, v68, v83
	v_fma_f32 v83, -v157, v69, v83
	ds_read_b128 v[154:157], v54 offset:46960
	s_waitcnt lgkmcnt(11)
	v_fma_f32 v84, -v158, v66, v84
	v_fma_f32 v84, -v159, v67, v84
	v_fma_f32 v84, -v160, v68, v84
	v_fma_f32 v84, -v161, v69, v84
	ds_read_b128 v[158:161], v54 offset:47232
	s_waitcnt lgkmcnt(11)
	v_fma_f32 v85, -v162, v66, v85
	v_fma_f32 v85, -v163, v67, v85
	v_fma_f32 v85, -v164, v68, v85
	v_fma_f32 v85, -v165, v69, v85
	ds_read_b128 v[162:165], v54 offset:47504
	s_waitcnt lgkmcnt(11)
	v_fma_f32 v86, -v166, v66, v86
	v_fma_f32 v86, -v167, v67, v86
	v_fma_f32 v86, -v168, v68, v86
	v_fma_f32 v86, -v169, v69, v86
	ds_read_b128 v[166:169], v54 offset:47776
	s_waitcnt lgkmcnt(11)
	v_fma_f32 v87, -v170, v66, v87
	v_fma_f32 v87, -v171, v67, v87
	v_fma_f32 v87, -v172, v68, v87
	v_fma_f32 v87, -v173, v69, v87
	ds_read_b128 v[170:173], v54 offset:48048
	s_waitcnt lgkmcnt(11)
	v_fma_f32 v88, -v184, v66, v88
	v_fma_f32 v88, -v185, v67, v88
	v_fma_f32 v88, -v186, v68, v88
	v_fma_f32 v88, -v187, v69, v88
	ds_read_b128 v[184:187], v54 offset:48320
	s_waitcnt lgkmcnt(11)
	v_fma_f32 v89, -v122, v66, v89
	v_fma_f32 v89, -v123, v67, v89
	v_fma_f32 v89, -v124, v68, v89
	v_fma_f32 v89, -v125, v69, v89
	ds_read_b128 v[122:125], v54 offset:48592
	s_waitcnt lgkmcnt(11)
	v_fma_f32 v90, -v126, v66, v90
	v_fma_f32 v90, -v127, v67, v90
	v_fma_f32 v90, -v128, v68, v90
	v_fma_f32 v90, -v129, v69, v90
	ds_read_b128 v[126:129], v54 offset:48864
	s_waitcnt lgkmcnt(11)
	v_fma_f32 v91, -v130, v66, v91
	v_fma_f32 v91, -v131, v67, v91
	v_fma_f32 v91, -v132, v68, v91
	v_fma_f32 v91, -v133, v69, v91
	ds_read_b128 v[130:133], v54 offset:49136
	s_waitcnt lgkmcnt(11)
	v_fma_f32 v92, -v142, v66, v92
	v_fma_f32 v92, -v143, v67, v92
	v_fma_f32 v92, -v144, v68, v92
	v_fma_f32 v92, -v145, v69, v92
	ds_read_b128 v[142:145], v54 offset:49408
	s_waitcnt lgkmcnt(11)
	v_fma_f32 v93, -v146, v66, v93
	v_fma_f32 v93, -v147, v67, v93
	v_fma_f32 v93, -v148, v68, v93
	v_fma_f32 v93, -v149, v69, v93
	ds_read_b128 v[146:149], v54 offset:49680
	s_waitcnt lgkmcnt(11)
	v_fma_f32 v94, -v150, v66, v94
	v_fma_f32 v94, -v151, v67, v94
	v_fma_f32 v94, -v152, v68, v94
	v_fma_f32 v94, -v153, v69, v94
	ds_read_b128 v[150:153], v54 offset:49952
	s_waitcnt lgkmcnt(11)
	v_fma_f32 v95, -v154, v66, v95
	v_fma_f32 v95, -v155, v67, v95
	v_fma_f32 v95, -v156, v68, v95
	v_fma_f32 v95, -v157, v69, v95
	ds_read_b128 v[154:157], v54 offset:50224
	s_waitcnt lgkmcnt(11)
	v_fma_f32 v96, -v158, v66, v96
	v_fma_f32 v96, -v159, v67, v96
	v_fma_f32 v96, -v160, v68, v96
	v_fma_f32 v96, -v161, v69, v96
	ds_read_b128 v[158:161], v54 offset:50496
	s_waitcnt lgkmcnt(11)
	v_fma_f32 v97, -v162, v66, v97
	v_fma_f32 v97, -v163, v67, v97
	v_fma_f32 v97, -v164, v68, v97
	v_fma_f32 v97, -v165, v69, v97
	ds_read_b128 v[162:165], v54 offset:50768
	s_waitcnt lgkmcnt(11)
	v_fma_f32 v98, -v166, v66, v98
	v_fma_f32 v98, -v167, v67, v98
	v_fma_f32 v98, -v168, v68, v98
	v_fma_f32 v98, -v169, v69, v98
	ds_read_b128 v[166:169], v54 offset:51040
	s_waitcnt lgkmcnt(11)
	v_fma_f32 v99, -v170, v66, v99
	v_fma_f32 v99, -v171, v67, v99
	v_fma_f32 v99, -v172, v68, v99
	v_fma_f32 v99, -v173, v69, v99
	ds_read_b128 v[170:173], v54 offset:51312
	s_waitcnt lgkmcnt(11)
	v_fma_f32 v100, -v184, v66, v100
	v_fma_f32 v100, -v185, v67, v100
	v_fma_f32 v100, -v186, v68, v100
	v_fma_f32 v100, -v187, v69, v100
	ds_read_b128 v[184:187], v54 offset:51584
	s_waitcnt lgkmcnt(11)
	v_fma_f32 v101, -v122, v66, v101
	v_fma_f32 v101, -v123, v67, v101
	v_fma_f32 v101, -v124, v68, v101
	v_fma_f32 v101, -v125, v69, v101
	ds_read_b128 v[122:125], v54 offset:51856
	s_waitcnt lgkmcnt(11)
	v_fma_f32 v102, -v126, v66, v102
	v_fma_f32 v102, -v127, v67, v102
	v_fma_f32 v102, -v128, v68, v102
	v_fma_f32 v102, -v129, v69, v102
	ds_read_b128 v[126:129], v54 offset:52128
	s_waitcnt lgkmcnt(11)
	v_fma_f32 v103, -v130, v66, v103
	v_fma_f32 v103, -v131, v67, v103
	v_fma_f32 v103, -v132, v68, v103
	v_fma_f32 v103, -v133, v69, v103
	ds_read_b128 v[130:133], v54 offset:52400
	s_waitcnt lgkmcnt(11)
	v_fma_f32 v104, -v142, v66, v104
	v_fma_f32 v104, -v143, v67, v104
	v_fma_f32 v104, -v144, v68, v104
	v_fma_f32 v104, -v145, v69, v104
	ds_read_b128 v[142:145], v54 offset:52672
	s_waitcnt lgkmcnt(11)
; __device__ __forceinline__ void gdn_chunk_item(const Params& p, int item, char* smem) {
;     ...
; #pragma unroll 2
;       for (int sg = 0; sg < b4; sg++) {
;         const float4 l0 = *(const float4*)&l0p[sg * 4], l1 = *(const float4*)&l0p[68 + sg * 4];
;         const float4 l2 = *(const float4*)&l0p[136 + sg * 4], l3 = *(const float4*)&l0p[204 + sg * 4];
;         const float* xp = xc + sg * 1024;
;         const float x0 = xp[0], x1 = xp[256], x2 = xp[512], x3 = xp[768];
;         a0 -= l0.x * x0; a0 -= l0.y * x1; a0 -= l0.z * x2; a0 -= l0.w * x3;
;         a1 -= l1.x * x0; a1 -= l1.y * x1; a1 -= l1.z * x2; a1 -= l1.w * x3;
;         a2 -= l2.x * x0; a2 -= l2.y * x1; a2 -= l2.z * x2; a2 -= l2.w * x3;
;         a3 -= l3.x * x0; a3 -= l3.y * x1; a3 -= l3.z * x2; a3 -= l3.w * x3;
;       }
;       const float4 d1 = *(const float4*)&l0p[68 + t0], d2 = *(const float4*)&l0p[136 + t0], d3 = *(const float4*)&l0p[204 + t0];
;       a1 -= d1.x * a0;
;       a2 -= d2.x * a0; a2 -= d2.y * a1;
;       a3 -= d3.x * a0; a3 -= d3.y * a1; a3 -= d3.z * a2;
	v_fma_f32 v105, -v146, v66, v105
	v_fma_f32 v105, -v147, v67, v105
	v_fma_f32 v105, -v148, v68, v105
	v_fma_f32 v105, -v149, v69, v105
	ds_read_b128 v[146:149], v54 offset:52944
	s_waitcnt lgkmcnt(11)
	v_fma_f32 v106, -v150, v66, v106
	v_fma_f32 v106, -v151, v67, v106
	v_fma_f32 v106, -v152, v68, v106
	v_fma_f32 v106, -v153, v69, v106
	ds_read_b128 v[150:153], v54 offset:53216
	s_waitcnt lgkmcnt(11)
	v_fma_f32 v107, -v154, v66, v107
	v_fma_f32 v107, -v155, v67, v107
	v_fma_f32 v107, -v156, v68, v107
	v_fma_f32 v107, -v157, v69, v107
	ds_read_b128 v[154:157], v54 offset:53488
	s_waitcnt lgkmcnt(11)
	v_fma_f32 v108, -v158, v66, v108
	v_fma_f32 v108, -v159, v67, v108
	v_fma_f32 v108, -v160, v68, v108
	v_fma_f32 v108, -v161, v69, v108
	ds_read_b128 v[158:161], v54 offset:53760
	s_waitcnt lgkmcnt(11)
	v_fma_f32 v109, -v162, v66, v109
	v_fma_f32 v109, -v163, v67, v109
	v_fma_f32 v109, -v164, v68, v109
	v_fma_f32 v109, -v165, v69, v109
	ds_read_b128 v[162:165], v54 offset:54032
	s_waitcnt lgkmcnt(11)
	v_fma_f32 v110, -v166, v66, v110
	v_fma_f32 v110, -v167, v67, v110
	v_fma_f32 v110, -v168, v68, v110
	v_fma_f32 v110, -v169, v69, v110
	ds_read_b128 v[166:169], v54 offset:40448
	s_waitcnt lgkmcnt(11)
	v_fma_f32 v111, -v170, v66, v111
	v_fma_f32 v111, -v171, v67, v111
	v_fma_f32 v111, -v172, v68, v111
	v_fma_f32 v111, -v173, v69, v111
	ds_read_b128 v[170:173], v54 offset:40720
	s_waitcnt lgkmcnt(11)
	v_fma_f32 v112, -v184, v66, v112
	v_fma_f32 v112, -v185, v67, v112
	v_fma_f32 v112, -v186, v68, v112
	v_fma_f32 v112, -v187, v69, v112
	ds_read_b128 v[184:187], v54 offset:40992
	s_waitcnt lgkmcnt(11)
	v_fma_f32 v113, -v122, v66, v113
	v_fma_f32 v113, -v123, v67, v113
	v_fma_f32 v113, -v124, v68, v113
	v_fma_f32 v113, -v125, v69, v113
	ds_read_b128 v[122:125], v54 offset:41264
	s_waitcnt lgkmcnt(11)
	v_fma_f32 v114, -v126, v66, v114
	v_fma_f32 v114, -v127, v67, v114
	v_fma_f32 v114, -v128, v68, v114
	v_fma_f32 v114, -v129, v69, v114
	ds_read_b128 v[126:129], v54 offset:41536
	s_waitcnt lgkmcnt(11)
	v_fma_f32 v115, -v130, v66, v115
	v_fma_f32 v115, -v131, v67, v115
	v_fma_f32 v115, -v132, v68, v115
	v_fma_f32 v115, -v133, v69, v115
	ds_read_b128 v[130:133], v54 offset:41808
	s_waitcnt lgkmcnt(11)
	v_fma_f32 v116, -v142, v66, v116
	v_fma_f32 v116, -v143, v67, v116
	v_fma_f32 v116, -v144, v68, v116
	v_fma_f32 v116, -v145, v69, v116
	ds_read_b128 v[142:145], v54 offset:42080
	s_waitcnt lgkmcnt(11)
	v_fma_f32 v117, -v146, v66, v117
	v_fma_f32 v117, -v147, v67, v117
	v_fma_f32 v117, -v148, v68, v117
	v_fma_f32 v117, -v149, v69, v117
	ds_read_b128 v[146:149], v54 offset:42352
	s_waitcnt lgkmcnt(11)
	v_fma_f32 v118, -v150, v66, v118
	v_fma_f32 v118, -v151, v67, v118
	v_fma_f32 v118, -v152, v68, v118
	v_fma_f32 v118, -v153, v69, v118
	ds_read_b128 v[150:153], v54 offset:42624
	s_waitcnt lgkmcnt(11)
	v_fma_f32 v119, -v154, v66, v119
	v_fma_f32 v119, -v155, v67, v119
	v_fma_f32 v119, -v156, v68, v119
	v_fma_f32 v119, -v157, v69, v119
	ds_read_b128 v[154:157], v54 offset:42896
	s_waitcnt lgkmcnt(11)
	v_fma_f32 v120, -v158, v66, v120
	v_fma_f32 v120, -v159, v67, v120
	v_fma_f32 v120, -v160, v68, v120
	v_fma_f32 v120, -v161, v69, v120
	ds_read_b128 v[158:161], v54 offset:43168
	s_waitcnt lgkmcnt(11)
	v_fma_f32 v121, -v162, v66, v121
	v_fma_f32 v121, -v163, v67, v121
	v_fma_f32 v121, -v164, v68, v121
	v_fma_f32 v121, -v165, v69, v121
	ds_read_b128 v[162:165], v54 offset:43440
	s_waitcnt lgkmcnt(11)
	v_fma_f32 v71, -v166, v70, v71
	ds_read_b128 v[166:169], v54 offset:43712
	s_waitcnt lgkmcnt(11)
	v_fma_f32 v72, -v170, v70, v72
	v_fma_f32 v72, -v171, v71, v72
	ds_read_b128 v[170:173], v54 offset:43984
	s_waitcnt lgkmcnt(11)
	v_fma_f32 v73, -v184, v70, v73
	v_fma_f32 v73, -v185, v71, v73
	v_fma_f32 v73, -v186, v72, v73
	ds_read_b128 v[184:187], v54 offset:44256
	s_waitcnt lgkmcnt(11)
	v_fma_f32 v74, -v122, v70, v74
	v_fma_f32 v74, -v123, v71, v74
	v_fma_f32 v74, -v124, v72, v74
	v_fma_f32 v74, -v125, v73, v74
	ds_read_b128 v[122:125], v54 offset:44528
	s_waitcnt lgkmcnt(11)
	v_fma_f32 v75, -v126, v70, v75
	v_fma_f32 v75, -v127, v71, v75
	v_fma_f32 v75, -v128, v72, v75
	v_fma_f32 v75, -v129, v73, v75
	ds_read_b128 v[126:129], v54 offset:44800
	s_waitcnt lgkmcnt(11)
	v_fma_f32 v76, -v130, v70, v76
	v_fma_f32 v76, -v131, v71, v76
	v_fma_f32 v76, -v132, v72, v76
	v_fma_f32 v76, -v133, v73, v76
	ds_read_b128 v[130:133], v54 offset:45072
	s_waitcnt lgkmcnt(11)
	v_fma_f32 v77, -v142, v70, v77
	v_fma_f32 v77, -v143, v71, v77
	v_fma_f32 v77, -v144, v72, v77
	v_fma_f32 v77, -v145, v73, v77
	ds_read_b128 v[142:145], v54 offset:45344
	s_waitcnt lgkmcnt(11)
	v_fma_f32 v78, -v146, v70, v78
	v_fma_f32 v78, -v147, v71, v78
	v_fma_f32 v78, -v148, v72, v78
	v_fma_f32 v78, -v149, v73, v78
	ds_read_b128 v[146:149], v54 offset:45616
	s_waitcnt lgkmcnt(11)
	v_fma_f32 v79, -v150, v70, v79
	v_fma_f32 v79, -v151, v71, v79
	v_fma_f32 v79, -v152, v72, v79
	v_fma_f32 v79, -v153, v73, v79
	ds_read_b128 v[150:153], v54 offset:45888
	s_waitcnt lgkmcnt(11)
	v_fma_f32 v80, -v154, v70, v80
	v_fma_f32 v80, -v155, v71, v80
	v_fma_f32 v80, -v156, v72, v80
	v_fma_f32 v80, -v157, v73, v80
	ds_read_b128 v[154:157], v54 offset:46160
	s_waitcnt lgkmcnt(11)
	v_fma_f32 v81, -v158, v70, v81
	v_fma_f32 v81, -v159, v71, v81
	v_fma_f32 v81, -v160, v72, v81
	v_fma_f32 v81, -v161, v73, v81
	ds_read_b128 v[158:161], v54 offset:46432
	s_waitcnt lgkmcnt(11)
	v_fma_f32 v82, -v162, v70, v82
	v_fma_f32 v82, -v163, v71, v82
	v_fma_f32 v82, -v164, v72, v82
	v_fma_f32 v82, -v165, v73, v82
	ds_read_b128 v[162:165], v54 offset:46704
	s_waitcnt lgkmcnt(11)
; __device__ __forceinline__ void gdn_chunk_item(const Params& p, int item, char* smem) {
;     ...
; #pragma unroll 2
;       for (int sg = 0; sg < b4; sg++) {
;         const float4 l0 = *(const float4*)&l0p[sg * 4], l1 = *(const float4*)&l0p[68 + sg * 4];
;         const float4 l2 = *(const float4*)&l0p[136 + sg * 4], l3 = *(const float4*)&l0p[204 + sg * 4];
;         const float* xp = xc + sg * 1024;
;         const float x0 = xp[0], x1 = xp[256], x2 = xp[512], x3 = xp[768];
;         a0 -= l0.x * x0; a0 -= l0.y * x1; a0 -= l0.z * x2; a0 -= l0.w * x3;
;         a1 -= l1.x * x0; a1 -= l1.y * x1; a1 -= l1.z * x2; a1 -= l1.w * x3;
;         a2 -= l2.x * x0; a2 -= l2.y * x1; a2 -= l2.z * x2; a2 -= l2.w * x3;
;         a3 -= l3.x * x0; a3 -= l3.y * x1; a3 -= l3.z * x2; a3 -= l3.w * x3;
;       }
;       const float4 d1 = *(const float4*)&l0p[68 + t0], d2 = *(const float4*)&l0p[136 + t0], d3 = *(const float4*)&l0p[204 + t0];
;       a1 -= d1.x * a0;
;       a2 -= d2.x * a0; a2 -= d2.y * a1;
;       a3 -= d3.x * a0; a3 -= d3.y * a1; a3 -= d3.z * a2;
	v_fma_f32 v83, -v166, v70, v83
	v_fma_f32 v83, -v167, v71, v83
	v_fma_f32 v83, -v168, v72, v83
	v_fma_f32 v83, -v169, v73, v83
	ds_read_b128 v[166:169], v54 offset:46976
	s_waitcnt lgkmcnt(11)
	v_fma_f32 v84, -v170, v70, v84
	v_fma_f32 v84, -v171, v71, v84
	v_fma_f32 v84, -v172, v72, v84
	v_fma_f32 v84, -v173, v73, v84
	ds_read_b128 v[170:173], v54 offset:47248
	s_waitcnt lgkmcnt(11)
	v_fma_f32 v85, -v184, v70, v85
	v_fma_f32 v85, -v185, v71, v85
	v_fma_f32 v85, -v186, v72, v85
	v_fma_f32 v85, -v187, v73, v85
	ds_read_b128 v[184:187], v54 offset:47520
	s_waitcnt lgkmcnt(11)
	v_fma_f32 v86, -v122, v70, v86
	v_fma_f32 v86, -v123, v71, v86
	v_fma_f32 v86, -v124, v72, v86
	v_fma_f32 v86, -v125, v73, v86
	ds_read_b128 v[122:125], v54 offset:47792
	s_waitcnt lgkmcnt(11)
	v_fma_f32 v87, -v126, v70, v87
	v_fma_f32 v87, -v127, v71, v87
	v_fma_f32 v87, -v128, v72, v87
	v_fma_f32 v87, -v129, v73, v87
	ds_read_b128 v[126:129], v54 offset:48064
	s_waitcnt lgkmcnt(11)
	v_fma_f32 v88, -v130, v70, v88
	v_fma_f32 v88, -v131, v71, v88
	v_fma_f32 v88, -v132, v72, v88
	v_fma_f32 v88, -v133, v73, v88
	ds_read_b128 v[130:133], v54 offset:48336
	s_waitcnt lgkmcnt(11)
	v_fma_f32 v89, -v142, v70, v89
	v_fma_f32 v89, -v143, v71, v89
	v_fma_f32 v89, -v144, v72, v89
	v_fma_f32 v89, -v145, v73, v89
	ds_read_b128 v[142:145], v54 offset:48608
	s_waitcnt lgkmcnt(11)
	v_fma_f32 v90, -v146, v70, v90
	v_fma_f32 v90, -v147, v71, v90
	v_fma_f32 v90, -v148, v72, v90
	v_fma_f32 v90, -v149, v73, v90
	ds_read_b128 v[146:149], v54 offset:48880
	s_waitcnt lgkmcnt(11)
	v_fma_f32 v91, -v150, v70, v91
	v_fma_f32 v91, -v151, v71, v91
	v_fma_f32 v91, -v152, v72, v91
	v_fma_f32 v91, -v153, v73, v91
	ds_read_b128 v[150:153], v54 offset:49152
	s_waitcnt lgkmcnt(11)
	v_fma_f32 v92, -v154, v70, v92
	v_fma_f32 v92, -v155, v71, v92
	v_fma_f32 v92, -v156, v72, v92
	v_fma_f32 v92, -v157, v73, v92
	ds_read_b128 v[154:157], v54 offset:49424
	s_waitcnt lgkmcnt(11)
	v_fma_f32 v93, -v158, v70, v93
	v_fma_f32 v93, -v159, v71, v93
	v_fma_f32 v93, -v160, v72, v93
	v_fma_f32 v93, -v161, v73, v93
	ds_read_b128 v[158:161], v54 offset:49696
	s_waitcnt lgkmcnt(11)
	v_fma_f32 v94, -v162, v70, v94
	v_fma_f32 v94, -v163, v71, v94
	v_fma_f32 v94, -v164, v72, v94
	v_fma_f32 v94, -v165, v73, v94
	ds_read_b128 v[162:165], v54 offset:49968
	s_waitcnt lgkmcnt(11)
	v_fma_f32 v95, -v166, v70, v95
	v_fma_f32 v95, -v167, v71, v95
	v_fma_f32 v95, -v168, v72, v95
	v_fma_f32 v95, -v169, v73, v95
	ds_read_b128 v[166:169], v54 offset:50240
	s_waitcnt lgkmcnt(11)
	v_fma_f32 v96, -v170, v70, v96
	v_fma_f32 v96, -v171, v71, v96
	v_fma_f32 v96, -v172, v72, v96
	v_fma_f32 v96, -v173, v73, v96
	ds_read_b128 v[170:173], v54 offset:50512
	s_waitcnt lgkmcnt(11)
	v_fma_f32 v97, -v184, v70, v97
	v_fma_f32 v97, -v185, v71, v97
	v_fma_f32 v97, -v186, v72, v97
	v_fma_f32 v97, -v187, v73, v97
	ds_read_b128 v[184:187], v54 offset:50784
	s_waitcnt lgkmcnt(11)
	v_fma_f32 v98, -v122, v70, v98
	v_fma_f32 v98, -v123, v71, v98
	v_fma_f32 v98, -v124, v72, v98
	v_fma_f32 v98, -v125, v73, v98
	ds_read_b128 v[122:125], v54 offset:51056
	s_waitcnt lgkmcnt(11)
	v_fma_f32 v99, -v126, v70, v99
	v_fma_f32 v99, -v127, v71, v99
	v_fma_f32 v99, -v128, v72, v99
	v_fma_f32 v99, -v129, v73, v99
	ds_read_b128 v[126:129], v54 offset:51328
	s_waitcnt lgkmcnt(11)
	v_fma_f32 v100, -v130, v70, v100
	v_fma_f32 v100, -v131, v71, v100
	v_fma_f32 v100, -v132, v72, v100
	v_fma_f32 v100, -v133, v73, v100
	ds_read_b128 v[130:133], v54 offset:51600
	s_waitcnt lgkmcnt(11)
	v_fma_f32 v101, -v142, v70, v101
	v_fma_f32 v101, -v143, v71, v101
	v_fma_f32 v101, -v144, v72, v101
	v_fma_f32 v101, -v145, v73, v101
	ds_read_b128 v[142:145], v54 offset:51872
	s_waitcnt lgkmcnt(11)
	v_fma_f32 v102, -v146, v70, v102
	v_fma_f32 v102, -v147, v71, v102
	v_fma_f32 v102, -v148, v72, v102
	v_fma_f32 v102, -v149, v73, v102
	ds_read_b128 v[146:149], v54 offset:52144
	s_waitcnt lgkmcnt(11)
	v_fma_f32 v103, -v150, v70, v103
	v_fma_f32 v103, -v151, v71, v103
	v_fma_f32 v103, -v152, v72, v103
	v_fma_f32 v103, -v153, v73, v103
	ds_read_b128 v[150:153], v54 offset:52416
	s_waitcnt lgkmcnt(11)
	v_fma_f32 v104, -v154, v70, v104
	v_fma_f32 v104, -v155, v71, v104
	v_fma_f32 v104, -v156, v72, v104
	v_fma_f32 v104, -v157, v73, v104
	ds_read_b128 v[154:157], v54 offset:52688
	s_waitcnt lgkmcnt(11)
	v_fma_f32 v105, -v158, v70, v105
	v_fma_f32 v105, -v159, v71, v105
	v_fma_f32 v105, -v160, v72, v105
	v_fma_f32 v105, -v161, v73, v105
	ds_read_b128 v[158:161], v54 offset:52960
	s_waitcnt lgkmcnt(11)
	v_fma_f32 v106, -v162, v70, v106
	v_fma_f32 v106, -v163, v71, v106
	v_fma_f32 v106, -v164, v72, v106
	v_fma_f32 v106, -v165, v73, v106
	ds_read_b128 v[162:165], v54 offset:53232
	s_waitcnt lgkmcnt(11)
	v_fma_f32 v107, -v166, v70, v107
	v_fma_f32 v107, -v167, v71, v107
	v_fma_f32 v107, -v168, v72, v107
	v_fma_f32 v107, -v169, v73, v107
	ds_read_b128 v[166:169], v54 offset:53504
	s_waitcnt lgkmcnt(11)
	v_fma_f32 v108, -v170, v70, v108
	v_fma_f32 v108, -v171, v71, v108
	v_fma_f32 v108, -v172, v72, v108
	v_fma_f32 v108, -v173, v73, v108
	ds_read_b128 v[170:173], v54 offset:53776
	s_waitcnt lgkmcnt(11)
	v_fma_f32 v109, -v184, v70, v109
	v_fma_f32 v109, -v185, v71, v109
	v_fma_f32 v109, -v186, v72, v109
	v_fma_f32 v109, -v187, v73, v109
	ds_read_b128 v[184:187], v54 offset:54048
	s_waitcnt lgkmcnt(11)
	v_fma_f32 v110, -v122, v70, v110
	v_fma_f32 v110, -v123, v71, v110
	v_fma_f32 v110, -v124, v72, v110
	v_fma_f32 v110, -v125, v73, v110
	ds_read_b128 v[122:125], v54 offset:41552
	s_waitcnt lgkmcnt(11)
	v_fma_f32 v111, -v126, v70, v111
	v_fma_f32 v111, -v127, v71, v111
	v_fma_f32 v111, -v128, v72, v111
	v_fma_f32 v111, -v129, v73, v111
	ds_read_b128 v[126:129], v54 offset:41824
	s_waitcnt lgkmcnt(11)
; __device__ __forceinline__ void gdn_chunk_item(const Params& p, int item, char* smem) {
;     ...
; #pragma unroll 2
;       for (int sg = 0; sg < b4; sg++) {
;         const float4 l0 = *(const float4*)&l0p[sg * 4], l1 = *(const float4*)&l0p[68 + sg * 4];
;         const float4 l2 = *(const float4*)&l0p[136 + sg * 4], l3 = *(const float4*)&l0p[204 + sg * 4];
;         const float* xp = xc + sg * 1024;
;         const float x0 = xp[0], x1 = xp[256], x2 = xp[512], x3 = xp[768];
;         a0 -= l0.x * x0; a0 -= l0.y * x1; a0 -= l0.z * x2; a0 -= l0.w * x3;
;         a1 -= l1.x * x0; a1 -= l1.y * x1; a1 -= l1.z * x2; a1 -= l1.w * x3;
;         a2 -= l2.x * x0; a2 -= l2.y * x1; a2 -= l2.z * x2; a2 -= l2.w * x3;
;         a3 -= l3.x * x0; a3 -= l3.y * x1; a3 -= l3.z * x2; a3 -= l3.w * x3;
;       }
;       const float4 d1 = *(const float4*)&l0p[68 + t0], d2 = *(const float4*)&l0p[136 + t0], d3 = *(const float4*)&l0p[204 + t0];
;       a1 -= d1.x * a0;
;       a2 -= d2.x * a0; a2 -= d2.y * a1;
;       a3 -= d3.x * a0; a3 -= d3.y * a1; a3 -= d3.z * a2;
	v_fma_f32 v112, -v130, v70, v112
	v_fma_f32 v112, -v131, v71, v112
	v_fma_f32 v112, -v132, v72, v112
	v_fma_f32 v112, -v133, v73, v112
	ds_read_b128 v[130:133], v54 offset:42096
	s_waitcnt lgkmcnt(11)
	v_fma_f32 v113, -v142, v70, v113
	v_fma_f32 v113, -v143, v71, v113
	v_fma_f32 v113, -v144, v72, v113
	v_fma_f32 v113, -v145, v73, v113
	ds_read_b128 v[142:145], v54 offset:42368
	s_waitcnt lgkmcnt(11)
	v_fma_f32 v114, -v146, v70, v114
	v_fma_f32 v114, -v147, v71, v114
	v_fma_f32 v114, -v148, v72, v114
	v_fma_f32 v114, -v149, v73, v114
	ds_read_b128 v[146:149], v54 offset:42640
	s_waitcnt lgkmcnt(11)
	v_fma_f32 v115, -v150, v70, v115
	v_fma_f32 v115, -v151, v71, v115
	v_fma_f32 v115, -v152, v72, v115
	v_fma_f32 v115, -v153, v73, v115
	ds_read_b128 v[150:153], v54 offset:42912
	s_waitcnt lgkmcnt(11)
	v_fma_f32 v116, -v154, v70, v116
	v_fma_f32 v116, -v155, v71, v116
	v_fma_f32 v116, -v156, v72, v116
	v_fma_f32 v116, -v157, v73, v116
	ds_read_b128 v[154:157], v54 offset:43184
	s_waitcnt lgkmcnt(11)
	v_fma_f32 v117, -v158, v70, v117
	v_fma_f32 v117, -v159, v71, v117
	v_fma_f32 v117, -v160, v72, v117
	v_fma_f32 v117, -v161, v73, v117
	ds_read_b128 v[158:161], v54 offset:43456
	s_waitcnt lgkmcnt(11)
	v_fma_f32 v118, -v162, v70, v118
	v_fma_f32 v118, -v163, v71, v118
	v_fma_f32 v118, -v164, v72, v118
	v_fma_f32 v118, -v165, v73, v118
	ds_read_b128 v[162:165], v54 offset:43728
	s_waitcnt lgkmcnt(11)
	v_fma_f32 v119, -v166, v70, v119
	v_fma_f32 v119, -v167, v71, v119
	v_fma_f32 v119, -v168, v72, v119
	v_fma_f32 v119, -v169, v73, v119
	ds_read_b128 v[166:169], v54 offset:44000
	s_waitcnt lgkmcnt(11)
	v_fma_f32 v120, -v170, v70, v120
	v_fma_f32 v120, -v171, v71, v120
	v_fma_f32 v120, -v172, v72, v120
	v_fma_f32 v120, -v173, v73, v120
	ds_read_b128 v[170:173], v54 offset:44272
	s_waitcnt lgkmcnt(11)
	v_fma_f32 v121, -v184, v70, v121
	v_fma_f32 v121, -v185, v71, v121
	v_fma_f32 v121, -v186, v72, v121
	v_fma_f32 v121, -v187, v73, v121
	ds_read_b128 v[184:187], v54 offset:44544
	s_waitcnt lgkmcnt(11)
	v_fma_f32 v75, -v122, v74, v75
	ds_read_b128 v[122:125], v54 offset:44816
	s_waitcnt lgkmcnt(11)
	v_fma_f32 v76, -v126, v74, v76
	v_fma_f32 v76, -v127, v75, v76
	ds_read_b128 v[126:129], v54 offset:45088
	s_waitcnt lgkmcnt(11)
	v_fma_f32 v77, -v130, v74, v77
	v_fma_f32 v77, -v131, v75, v77
	v_fma_f32 v77, -v132, v76, v77
	ds_read_b128 v[130:133], v54 offset:45360
	s_waitcnt lgkmcnt(11)
	v_fma_f32 v78, -v142, v74, v78
	v_fma_f32 v78, -v143, v75, v78
	v_fma_f32 v78, -v144, v76, v78
	v_fma_f32 v78, -v145, v77, v78
	ds_read_b128 v[142:145], v54 offset:45632
	s_waitcnt lgkmcnt(11)
	v_fma_f32 v79, -v146, v74, v79
	v_fma_f32 v79, -v147, v75, v79
	v_fma_f32 v79, -v148, v76, v79
	v_fma_f32 v79, -v149, v77, v79
	ds_read_b128 v[146:149], v54 offset:45904
	s_waitcnt lgkmcnt(11)
	v_fma_f32 v80, -v150, v74, v80
	v_fma_f32 v80, -v151, v75, v80
	v_fma_f32 v80, -v152, v76, v80
	v_fma_f32 v80, -v153, v77, v80
	ds_read_b128 v[150:153], v54 offset:46176
	s_waitcnt lgkmcnt(11)
	v_fma_f32 v81, -v154, v74, v81
	v_fma_f32 v81, -v155, v75, v81
	v_fma_f32 v81, -v156, v76, v81
	v_fma_f32 v81, -v157, v77, v81
	ds_read_b128 v[154:157], v54 offset:46448
	s_waitcnt lgkmcnt(11)
	v_fma_f32 v82, -v158, v74, v82
	v_fma_f32 v82, -v159, v75, v82
	v_fma_f32 v82, -v160, v76, v82
	v_fma_f32 v82, -v161, v77, v82
	ds_read_b128 v[158:161], v54 offset:46720
	s_waitcnt lgkmcnt(11)
	v_fma_f32 v83, -v162, v74, v83
	v_fma_f32 v83, -v163, v75, v83
	v_fma_f32 v83, -v164, v76, v83
	v_fma_f32 v83, -v165, v77, v83
	ds_read_b128 v[162:165], v54 offset:46992
	s_waitcnt lgkmcnt(11)
	v_fma_f32 v84, -v166, v74, v84
	v_fma_f32 v84, -v167, v75, v84
	v_fma_f32 v84, -v168, v76, v84
	v_fma_f32 v84, -v169, v77, v84
	ds_read_b128 v[166:169], v54 offset:47264
	s_waitcnt lgkmcnt(11)
	v_fma_f32 v85, -v170, v74, v85
	v_fma_f32 v85, -v171, v75, v85
	v_fma_f32 v85, -v172, v76, v85
	v_fma_f32 v85, -v173, v77, v85
	ds_read_b128 v[170:173], v54 offset:47536
	s_waitcnt lgkmcnt(11)
	v_fma_f32 v86, -v184, v74, v86
	v_fma_f32 v86, -v185, v75, v86
	v_fma_f32 v86, -v186, v76, v86
	v_fma_f32 v86, -v187, v77, v86
	ds_read_b128 v[184:187], v54 offset:47808
	s_waitcnt lgkmcnt(11)
	v_fma_f32 v87, -v122, v74, v87
	v_fma_f32 v87, -v123, v75, v87
	v_fma_f32 v87, -v124, v76, v87
	v_fma_f32 v87, -v125, v77, v87
	ds_read_b128 v[122:125], v54 offset:48080
	s_waitcnt lgkmcnt(11)
	v_fma_f32 v88, -v126, v74, v88
	v_fma_f32 v88, -v127, v75, v88
	v_fma_f32 v88, -v128, v76, v88
	v_fma_f32 v88, -v129, v77, v88
	ds_read_b128 v[126:129], v54 offset:48352
	s_waitcnt lgkmcnt(11)
	v_fma_f32 v89, -v130, v74, v89
	v_fma_f32 v89, -v131, v75, v89
	v_fma_f32 v89, -v132, v76, v89
	v_fma_f32 v89, -v133, v77, v89
	ds_read_b128 v[130:133], v54 offset:48624
	s_waitcnt lgkmcnt(11)
	v_fma_f32 v90, -v142, v74, v90
	v_fma_f32 v90, -v143, v75, v90
	v_fma_f32 v90, -v144, v76, v90
	v_fma_f32 v90, -v145, v77, v90
	ds_read_b128 v[142:145], v54 offset:48896
	s_waitcnt lgkmcnt(11)
	v_fma_f32 v91, -v146, v74, v91
	v_fma_f32 v91, -v147, v75, v91
	v_fma_f32 v91, -v148, v76, v91
	v_fma_f32 v91, -v149, v77, v91
	ds_read_b128 v[146:149], v54 offset:49168
	s_waitcnt lgkmcnt(11)
	v_fma_f32 v92, -v150, v74, v92
	v_fma_f32 v92, -v151, v75, v92
	v_fma_f32 v92, -v152, v76, v92
	v_fma_f32 v92, -v153, v77, v92
	ds_read_b128 v[150:153], v54 offset:49440
	s_waitcnt lgkmcnt(11)
	v_fma_f32 v93, -v154, v74, v93
	v_fma_f32 v93, -v155, v75, v93
	v_fma_f32 v93, -v156, v76, v93
	v_fma_f32 v93, -v157, v77, v93
	ds_read_b128 v[154:157], v54 offset:49712
	s_waitcnt lgkmcnt(11)
	v_fma_f32 v94, -v158, v74, v94
	v_fma_f32 v94, -v159, v75, v94
	v_fma_f32 v94, -v160, v76, v94
	v_fma_f32 v94, -v161, v77, v94
	ds_read_b128 v[158:161], v54 offset:49984
	s_waitcnt lgkmcnt(11)
; __device__ __forceinline__ void gdn_chunk_item(const Params& p, int item, char* smem) {
;     ...
; #pragma unroll 2
;       for (int sg = 0; sg < b4; sg++) {
;         const float4 l0 = *(const float4*)&l0p[sg * 4], l1 = *(const float4*)&l0p[68 + sg * 4];
;         const float4 l2 = *(const float4*)&l0p[136 + sg * 4], l3 = *(const float4*)&l0p[204 + sg * 4];
;         const float* xp = xc + sg * 1024;
;         const float x0 = xp[0], x1 = xp[256], x2 = xp[512], x3 = xp[768];
;         a0 -= l0.x * x0; a0 -= l0.y * x1; a0 -= l0.z * x2; a0 -= l0.w * x3;
;         a1 -= l1.x * x0; a1 -= l1.y * x1; a1 -= l1.z * x2; a1 -= l1.w * x3;
;         a2 -= l2.x * x0; a2 -= l2.y * x1; a2 -= l2.z * x2; a2 -= l2.w * x3;
;         a3 -= l3.x * x0; a3 -= l3.y * x1; a3 -= l3.z * x2; a3 -= l3.w * x3;
;       }
;       const float4 d1 = *(const float4*)&l0p[68 + t0], d2 = *(const float4*)&l0p[136 + t0], d3 = *(const float4*)&l0p[204 + t0];
;       a1 -= d1.x * a0;
;       a2 -= d2.x * a0; a2 -= d2.y * a1;
;       a3 -= d3.x * a0; a3 -= d3.y * a1; a3 -= d3.z * a2;
	v_fma_f32 v95, -v162, v74, v95
	v_fma_f32 v95, -v163, v75, v95
	v_fma_f32 v95, -v164, v76, v95
	v_fma_f32 v95, -v165, v77, v95
	ds_read_b128 v[162:165], v54 offset:50256
	s_waitcnt lgkmcnt(11)
	v_fma_f32 v96, -v166, v74, v96
	v_fma_f32 v96, -v167, v75, v96
	v_fma_f32 v96, -v168, v76, v96
	v_fma_f32 v96, -v169, v77, v96
	ds_read_b128 v[166:169], v54 offset:50528
	s_waitcnt lgkmcnt(11)
	v_fma_f32 v97, -v170, v74, v97
	v_fma_f32 v97, -v171, v75, v97
	v_fma_f32 v97, -v172, v76, v97
	v_fma_f32 v97, -v173, v77, v97
	ds_read_b128 v[170:173], v54 offset:50800
	s_waitcnt lgkmcnt(11)
	v_fma_f32 v98, -v184, v74, v98
	v_fma_f32 v98, -v185, v75, v98
	v_fma_f32 v98, -v186, v76, v98
	v_fma_f32 v98, -v187, v77, v98
	ds_read_b128 v[184:187], v54 offset:51072
	s_waitcnt lgkmcnt(11)
	v_fma_f32 v99, -v122, v74, v99
	v_fma_f32 v99, -v123, v75, v99
	v_fma_f32 v99, -v124, v76, v99
	v_fma_f32 v99, -v125, v77, v99
	ds_read_b128 v[122:125], v54 offset:51344
	s_waitcnt lgkmcnt(11)
	v_fma_f32 v100, -v126, v74, v100
	v_fma_f32 v100, -v127, v75, v100
	v_fma_f32 v100, -v128, v76, v100
	v_fma_f32 v100, -v129, v77, v100
	ds_read_b128 v[126:129], v54 offset:51616
	s_waitcnt lgkmcnt(11)
	v_fma_f32 v101, -v130, v74, v101
	v_fma_f32 v101, -v131, v75, v101
	v_fma_f32 v101, -v132, v76, v101
	v_fma_f32 v101, -v133, v77, v101
	ds_read_b128 v[130:133], v54 offset:51888
	s_waitcnt lgkmcnt(11)
	v_fma_f32 v102, -v142, v74, v102
	v_fma_f32 v102, -v143, v75, v102
	v_fma_f32 v102, -v144, v76, v102
	v_fma_f32 v102, -v145, v77, v102
	ds_read_b128 v[142:145], v54 offset:52160
	s_waitcnt lgkmcnt(11)
	v_fma_f32 v103, -v146, v74, v103
	v_fma_f32 v103, -v147, v75, v103
	v_fma_f32 v103, -v148, v76, v103
	v_fma_f32 v103, -v149, v77, v103
	ds_read_b128 v[146:149], v54 offset:52432
	s_waitcnt lgkmcnt(11)
	v_fma_f32 v104, -v150, v74, v104
	v_fma_f32 v104, -v151, v75, v104
	v_fma_f32 v104, -v152, v76, v104
	v_fma_f32 v104, -v153, v77, v104
	ds_read_b128 v[150:153], v54 offset:52704
	s_waitcnt lgkmcnt(11)
	v_fma_f32 v105, -v154, v74, v105
	v_fma_f32 v105, -v155, v75, v105
	v_fma_f32 v105, -v156, v76, v105
	v_fma_f32 v105, -v157, v77, v105
	ds_read_b128 v[154:157], v54 offset:52976
	s_waitcnt lgkmcnt(11)
	v_fma_f32 v106, -v158, v74, v106
	v_fma_f32 v106, -v159, v75, v106
	v_fma_f32 v106, -v160, v76, v106
	v_fma_f32 v106, -v161, v77, v106
	ds_read_b128 v[158:161], v54 offset:53248
	s_waitcnt lgkmcnt(11)
	v_fma_f32 v107, -v162, v74, v107
	v_fma_f32 v107, -v163, v75, v107
	v_fma_f32 v107, -v164, v76, v107
	v_fma_f32 v107, -v165, v77, v107
	ds_read_b128 v[162:165], v54 offset:53520
	s_waitcnt lgkmcnt(11)
	v_fma_f32 v108, -v166, v74, v108
	v_fma_f32 v108, -v167, v75, v108
	v_fma_f32 v108, -v168, v76, v108
	v_fma_f32 v108, -v169, v77, v108
	ds_read_b128 v[166:169], v54 offset:53792
	s_waitcnt lgkmcnt(11)
	v_fma_f32 v109, -v170, v74, v109
	v_fma_f32 v109, -v171, v75, v109
	v_fma_f32 v109, -v172, v76, v109
	v_fma_f32 v109, -v173, v77, v109
	ds_read_b128 v[170:173], v54 offset:54064
	s_waitcnt lgkmcnt(11)
	v_fma_f32 v110, -v184, v74, v110
	v_fma_f32 v110, -v185, v75, v110
	v_fma_f32 v110, -v186, v76, v110
	v_fma_f32 v110, -v187, v77, v110
	ds_read_b128 v[184:187], v54 offset:42656
	s_waitcnt lgkmcnt(11)
	v_fma_f32 v111, -v122, v74, v111
	v_fma_f32 v111, -v123, v75, v111
	v_fma_f32 v111, -v124, v76, v111
	v_fma_f32 v111, -v125, v77, v111
	ds_read_b128 v[122:125], v54 offset:42928
	s_waitcnt lgkmcnt(11)
	v_fma_f32 v112, -v126, v74, v112
	v_fma_f32 v112, -v127, v75, v112
	v_fma_f32 v112, -v128, v76, v112
	v_fma_f32 v112, -v129, v77, v112
	ds_read_b128 v[126:129], v54 offset:43200
	s_waitcnt lgkmcnt(11)
	v_fma_f32 v113, -v130, v74, v113
	v_fma_f32 v113, -v131, v75, v113
	v_fma_f32 v113, -v132, v76, v113
	v_fma_f32 v113, -v133, v77, v113
	ds_read_b128 v[130:133], v54 offset:43472
	s_waitcnt lgkmcnt(11)
	v_fma_f32 v114, -v142, v74, v114
	v_fma_f32 v114, -v143, v75, v114
	v_fma_f32 v114, -v144, v76, v114
	v_fma_f32 v114, -v145, v77, v114
	ds_read_b128 v[142:145], v54 offset:43744
	s_waitcnt lgkmcnt(11)
	v_fma_f32 v115, -v146, v74, v115
	v_fma_f32 v115, -v147, v75, v115
	v_fma_f32 v115, -v148, v76, v115
	v_fma_f32 v115, -v149, v77, v115
	ds_read_b128 v[146:149], v54 offset:44016
	s_waitcnt lgkmcnt(11)
	v_fma_f32 v116, -v150, v74, v116
	v_fma_f32 v116, -v151, v75, v116
	v_fma_f32 v116, -v152, v76, v116
	v_fma_f32 v116, -v153, v77, v116
	ds_read_b128 v[150:153], v54 offset:44288
	s_waitcnt lgkmcnt(11)
	v_fma_f32 v117, -v154, v74, v117
	v_fma_f32 v117, -v155, v75, v117
	v_fma_f32 v117, -v156, v76, v117
	v_fma_f32 v117, -v157, v77, v117
	ds_read_b128 v[154:157], v54 offset:44560
	s_waitcnt lgkmcnt(11)
	v_fma_f32 v118, -v158, v74, v118
	v_fma_f32 v118, -v159, v75, v118
	v_fma_f32 v118, -v160, v76, v118
	v_fma_f32 v118, -v161, v77, v118
	ds_read_b128 v[158:161], v54 offset:44832
	s_waitcnt lgkmcnt(11)
	v_fma_f32 v119, -v162, v74, v119
	v_fma_f32 v119, -v163, v75, v119
	v_fma_f32 v119, -v164, v76, v119
	v_fma_f32 v119, -v165, v77, v119
	ds_read_b128 v[162:165], v54 offset:45104
	s_waitcnt lgkmcnt(11)
	v_fma_f32 v120, -v166, v74, v120
	v_fma_f32 v120, -v167, v75, v120
	v_fma_f32 v120, -v168, v76, v120
	v_fma_f32 v120, -v169, v77, v120
	ds_read_b128 v[166:169], v54 offset:45376
	s_waitcnt lgkmcnt(11)
	v_fma_f32 v121, -v170, v74, v121
	v_fma_f32 v121, -v171, v75, v121
	v_fma_f32 v121, -v172, v76, v121
	v_fma_f32 v121, -v173, v77, v121
	ds_read_b128 v[170:173], v54 offset:45648
	s_waitcnt lgkmcnt(11)
	v_fma_f32 v79, -v184, v78, v79
	ds_read_b128 v[184:187], v54 offset:45920
	s_waitcnt lgkmcnt(11)
	v_fma_f32 v80, -v122, v78, v80
	v_fma_f32 v80, -v123, v79, v80
	ds_read_b128 v[122:125], v54 offset:46192
	s_waitcnt lgkmcnt(11)
; __device__ __forceinline__ void gdn_chunk_item(const Params& p, int item, char* smem) {
;     ...
; #pragma unroll 2
;       for (int sg = 0; sg < b4; sg++) {
;         const float4 l0 = *(const float4*)&l0p[sg * 4], l1 = *(const float4*)&l0p[68 + sg * 4];
;         const float4 l2 = *(const float4*)&l0p[136 + sg * 4], l3 = *(const float4*)&l0p[204 + sg * 4];
;         const float* xp = xc + sg * 1024;
;         const float x0 = xp[0], x1 = xp[256], x2 = xp[512], x3 = xp[768];
;         a0 -= l0.x * x0; a0 -= l0.y * x1; a0 -= l0.z * x2; a0 -= l0.w * x3;
;         a1 -= l1.x * x0; a1 -= l1.y * x1; a1 -= l1.z * x2; a1 -= l1.w * x3;
;         a2 -= l2.x * x0; a2 -= l2.y * x1; a2 -= l2.z * x2; a2 -= l2.w * x3;
;         a3 -= l3.x * x0; a3 -= l3.y * x1; a3 -= l3.z * x2; a3 -= l3.w * x3;
;       }
;       const float4 d1 = *(const float4*)&l0p[68 + t0], d2 = *(const float4*)&l0p[136 + t0], d3 = *(const float4*)&l0p[204 + t0];
;       a1 -= d1.x * a0;
;       a2 -= d2.x * a0; a2 -= d2.y * a1;
;       a3 -= d3.x * a0; a3 -= d3.y * a1; a3 -= d3.z * a2;
	v_fma_f32 v81, -v126, v78, v81
	v_fma_f32 v81, -v127, v79, v81
	v_fma_f32 v81, -v128, v80, v81
	ds_read_b128 v[126:129], v54 offset:46464
	s_waitcnt lgkmcnt(11)
	v_fma_f32 v82, -v130, v78, v82
	v_fma_f32 v82, -v131, v79, v82
	v_fma_f32 v82, -v132, v80, v82
	v_fma_f32 v82, -v133, v81, v82
	ds_read_b128 v[130:133], v54 offset:46736
	s_waitcnt lgkmcnt(11)
	v_fma_f32 v83, -v142, v78, v83
	v_fma_f32 v83, -v143, v79, v83
	v_fma_f32 v83, -v144, v80, v83
	v_fma_f32 v83, -v145, v81, v83
	ds_read_b128 v[142:145], v54 offset:47008
	s_waitcnt lgkmcnt(11)
	v_fma_f32 v84, -v146, v78, v84
	v_fma_f32 v84, -v147, v79, v84
	v_fma_f32 v84, -v148, v80, v84
	v_fma_f32 v84, -v149, v81, v84
	ds_read_b128 v[146:149], v54 offset:47280
	s_waitcnt lgkmcnt(11)
	v_fma_f32 v85, -v150, v78, v85
	v_fma_f32 v85, -v151, v79, v85
	v_fma_f32 v85, -v152, v80, v85
	v_fma_f32 v85, -v153, v81, v85
	ds_read_b128 v[150:153], v54 offset:47552
	s_waitcnt lgkmcnt(11)
	v_fma_f32 v86, -v154, v78, v86
	v_fma_f32 v86, -v155, v79, v86
	v_fma_f32 v86, -v156, v80, v86
	v_fma_f32 v86, -v157, v81, v86
	ds_read_b128 v[154:157], v54 offset:47824
	s_waitcnt lgkmcnt(11)
	v_fma_f32 v87, -v158, v78, v87
	v_fma_f32 v87, -v159, v79, v87
	v_fma_f32 v87, -v160, v80, v87
	v_fma_f32 v87, -v161, v81, v87
	ds_read_b128 v[158:161], v54 offset:48096
	s_waitcnt lgkmcnt(11)
	v_fma_f32 v88, -v162, v78, v88
	v_fma_f32 v88, -v163, v79, v88
	v_fma_f32 v88, -v164, v80, v88
	v_fma_f32 v88, -v165, v81, v88
	ds_read_b128 v[162:165], v54 offset:48368
	s_waitcnt lgkmcnt(11)
	v_fma_f32 v89, -v166, v78, v89
	v_fma_f32 v89, -v167, v79, v89
	v_fma_f32 v89, -v168, v80, v89
	v_fma_f32 v89, -v169, v81, v89
	ds_read_b128 v[166:169], v54 offset:48640
	s_waitcnt lgkmcnt(11)
	v_fma_f32 v90, -v170, v78, v90
	v_fma_f32 v90, -v171, v79, v90
	v_fma_f32 v90, -v172, v80, v90
	v_fma_f32 v90, -v173, v81, v90
	ds_read_b128 v[170:173], v54 offset:48912
	s_waitcnt lgkmcnt(11)
	v_fma_f32 v91, -v184, v78, v91
	v_fma_f32 v91, -v185, v79, v91
	v_fma_f32 v91, -v186, v80, v91
	v_fma_f32 v91, -v187, v81, v91
	ds_read_b128 v[184:187], v54 offset:49184
	s_waitcnt lgkmcnt(11)
	v_fma_f32 v92, -v122, v78, v92
	v_fma_f32 v92, -v123, v79, v92
	v_fma_f32 v92, -v124, v80, v92
	v_fma_f32 v92, -v125, v81, v92
	ds_read_b128 v[122:125], v54 offset:49456
	s_waitcnt lgkmcnt(11)
	v_fma_f32 v93, -v126, v78, v93
	v_fma_f32 v93, -v127, v79, v93
	v_fma_f32 v93, -v128, v80, v93
	v_fma_f32 v93, -v129, v81, v93
	ds_read_b128 v[126:129], v54 offset:49728
	s_waitcnt lgkmcnt(11)
	v_fma_f32 v94, -v130, v78, v94
	v_fma_f32 v94, -v131, v79, v94
	v_fma_f32 v94, -v132, v80, v94
	v_fma_f32 v94, -v133, v81, v94
	ds_read_b128 v[130:133], v54 offset:50000
	s_waitcnt lgkmcnt(11)
	v_fma_f32 v95, -v142, v78, v95
	v_fma_f32 v95, -v143, v79, v95
	v_fma_f32 v95, -v144, v80, v95
	v_fma_f32 v95, -v145, v81, v95
	ds_read_b128 v[142:145], v54 offset:50272
	s_waitcnt lgkmcnt(11)
	v_fma_f32 v96, -v146, v78, v96
	v_fma_f32 v96, -v147, v79, v96
	v_fma_f32 v96, -v148, v80, v96
	v_fma_f32 v96, -v149, v81, v96
	ds_read_b128 v[146:149], v54 offset:50544
	s_waitcnt lgkmcnt(11)
	v_fma_f32 v97, -v150, v78, v97
	v_fma_f32 v97, -v151, v79, v97
	v_fma_f32 v97, -v152, v80, v97
	v_fma_f32 v97, -v153, v81, v97
	ds_read_b128 v[150:153], v54 offset:50816
	s_waitcnt lgkmcnt(11)
	v_fma_f32 v98, -v154, v78, v98
	v_fma_f32 v98, -v155, v79, v98
	v_fma_f32 v98, -v156, v80, v98
	v_fma_f32 v98, -v157, v81, v98
	ds_read_b128 v[154:157], v54 offset:51088
	s_waitcnt lgkmcnt(11)
	v_fma_f32 v99, -v158, v78, v99
	v_fma_f32 v99, -v159, v79, v99
	v_fma_f32 v99, -v160, v80, v99
	v_fma_f32 v99, -v161, v81, v99
	ds_read_b128 v[158:161], v54 offset:51360
	s_waitcnt lgkmcnt(11)
	v_fma_f32 v100, -v162, v78, v100
	v_fma_f32 v100, -v163, v79, v100
	v_fma_f32 v100, -v164, v80, v100
	v_fma_f32 v100, -v165, v81, v100
	ds_read_b128 v[162:165], v54 offset:51632
	s_waitcnt lgkmcnt(11)
	v_fma_f32 v101, -v166, v78, v101
	v_fma_f32 v101, -v167, v79, v101
	v_fma_f32 v101, -v168, v80, v101
	v_fma_f32 v101, -v169, v81, v101
	ds_read_b128 v[166:169], v54 offset:51904
	s_waitcnt lgkmcnt(11)
	v_fma_f32 v102, -v170, v78, v102
	v_fma_f32 v102, -v171, v79, v102
	v_fma_f32 v102, -v172, v80, v102
	v_fma_f32 v102, -v173, v81, v102
	ds_read_b128 v[170:173], v54 offset:52176
	s_waitcnt lgkmcnt(11)
	v_fma_f32 v103, -v184, v78, v103
	v_fma_f32 v103, -v185, v79, v103
	v_fma_f32 v103, -v186, v80, v103
	v_fma_f32 v103, -v187, v81, v103
	ds_read_b128 v[184:187], v54 offset:52448
	s_waitcnt lgkmcnt(11)
	v_fma_f32 v104, -v122, v78, v104
	v_fma_f32 v104, -v123, v79, v104
	v_fma_f32 v104, -v124, v80, v104
	v_fma_f32 v104, -v125, v81, v104
	ds_read_b128 v[122:125], v54 offset:52720
	s_waitcnt lgkmcnt(11)
	v_fma_f32 v105, -v126, v78, v105
	v_fma_f32 v105, -v127, v79, v105
	v_fma_f32 v105, -v128, v80, v105
	v_fma_f32 v105, -v129, v81, v105
	ds_read_b128 v[126:129], v54 offset:52992
	s_waitcnt lgkmcnt(11)
	v_fma_f32 v106, -v130, v78, v106
	v_fma_f32 v106, -v131, v79, v106
	v_fma_f32 v106, -v132, v80, v106
	v_fma_f32 v106, -v133, v81, v106
	ds_read_b128 v[130:133], v54 offset:53264
	s_waitcnt lgkmcnt(11)
	v_fma_f32 v107, -v142, v78, v107
	v_fma_f32 v107, -v143, v79, v107
	v_fma_f32 v107, -v144, v80, v107
	v_fma_f32 v107, -v145, v81, v107
	ds_read_b128 v[142:145], v54 offset:53536
	s_waitcnt lgkmcnt(11)
	v_fma_f32 v108, -v146, v78, v108
	v_fma_f32 v108, -v147, v79, v108
	v_fma_f32 v108, -v148, v80, v108
	v_fma_f32 v108, -v149, v81, v108
	ds_read_b128 v[146:149], v54 offset:53808
	s_waitcnt lgkmcnt(11)
	v_fma_f32 v109, -v150, v78, v109
	v_fma_f32 v109, -v151, v79, v109
	v_fma_f32 v109, -v152, v80, v109
	v_fma_f32 v109, -v153, v81, v109
	ds_read_b128 v[150:153], v54 offset:54080
	s_waitcnt lgkmcnt(11)
; __device__ __forceinline__ void gdn_chunk_item(const Params& p, int item, char* smem) {
;     ...
; #pragma unroll 2
;       for (int sg = 0; sg < b4; sg++) {
;         const float4 l0 = *(const float4*)&l0p[sg * 4], l1 = *(const float4*)&l0p[68 + sg * 4];
;         const float4 l2 = *(const float4*)&l0p[136 + sg * 4], l3 = *(const float4*)&l0p[204 + sg * 4];
;         const float* xp = xc + sg * 1024;
;         const float x0 = xp[0], x1 = xp[256], x2 = xp[512], x3 = xp[768];
;         a0 -= l0.x * x0; a0 -= l0.y * x1; a0 -= l0.z * x2; a0 -= l0.w * x3;
;         a1 -= l1.x * x0; a1 -= l1.y * x1; a1 -= l1.z * x2; a1 -= l1.w * x3;
;         a2 -= l2.x * x0; a2 -= l2.y * x1; a2 -= l2.z * x2; a2 -= l2.w * x3;
;         a3 -= l3.x * x0; a3 -= l3.y * x1; a3 -= l3.z * x2; a3 -= l3.w * x3;
;       }
;       const float4 d1 = *(const float4*)&l0p[68 + t0], d2 = *(const float4*)&l0p[136 + t0], d3 = *(const float4*)&l0p[204 + t0];
;       a1 -= d1.x * a0;
;       a2 -= d2.x * a0; a2 -= d2.y * a1;
;       a3 -= d3.x * a0; a3 -= d3.y * a1; a3 -= d3.z * a2;
	v_fma_f32 v110, -v154, v78, v110
	v_fma_f32 v110, -v155, v79, v110
	v_fma_f32 v110, -v156, v80, v110
	v_fma_f32 v110, -v157, v81, v110
	ds_read_b128 v[154:157], v54 offset:43760
	s_waitcnt lgkmcnt(11)
	v_fma_f32 v111, -v158, v78, v111
	v_fma_f32 v111, -v159, v79, v111
	v_fma_f32 v111, -v160, v80, v111
	v_fma_f32 v111, -v161, v81, v111
	ds_read_b128 v[158:161], v54 offset:44032
	s_waitcnt lgkmcnt(11)
	v_fma_f32 v112, -v162, v78, v112
	v_fma_f32 v112, -v163, v79, v112
	v_fma_f32 v112, -v164, v80, v112
	v_fma_f32 v112, -v165, v81, v112
	ds_read_b128 v[162:165], v54 offset:44304
	s_waitcnt lgkmcnt(11)
	v_fma_f32 v113, -v166, v78, v113
	v_fma_f32 v113, -v167, v79, v113
	v_fma_f32 v113, -v168, v80, v113
	v_fma_f32 v113, -v169, v81, v113
	ds_read_b128 v[166:169], v54 offset:44576
	s_waitcnt lgkmcnt(11)
	v_fma_f32 v114, -v170, v78, v114
	v_fma_f32 v114, -v171, v79, v114
	v_fma_f32 v114, -v172, v80, v114
	v_fma_f32 v114, -v173, v81, v114
	ds_read_b128 v[170:173], v54 offset:44848
	s_waitcnt lgkmcnt(11)
	v_fma_f32 v115, -v184, v78, v115
	v_fma_f32 v115, -v185, v79, v115
	v_fma_f32 v115, -v186, v80, v115
	v_fma_f32 v115, -v187, v81, v115
	ds_read_b128 v[184:187], v54 offset:45120
	s_waitcnt lgkmcnt(11)
	v_fma_f32 v116, -v122, v78, v116
	v_fma_f32 v116, -v123, v79, v116
	v_fma_f32 v116, -v124, v80, v116
	v_fma_f32 v116, -v125, v81, v116
	ds_read_b128 v[122:125], v54 offset:45392
	s_waitcnt lgkmcnt(11)
	v_fma_f32 v117, -v126, v78, v117
	v_fma_f32 v117, -v127, v79, v117
	v_fma_f32 v117, -v128, v80, v117
	v_fma_f32 v117, -v129, v81, v117
	ds_read_b128 v[126:129], v54 offset:45664
	s_waitcnt lgkmcnt(11)
	v_fma_f32 v118, -v130, v78, v118
	v_fma_f32 v118, -v131, v79, v118
	v_fma_f32 v118, -v132, v80, v118
	v_fma_f32 v118, -v133, v81, v118
	ds_read_b128 v[130:133], v54 offset:45936
	s_waitcnt lgkmcnt(11)
	v_fma_f32 v119, -v142, v78, v119
	v_fma_f32 v119, -v143, v79, v119
	v_fma_f32 v119, -v144, v80, v119
	v_fma_f32 v119, -v145, v81, v119
	ds_read_b128 v[142:145], v54 offset:46208
	s_waitcnt lgkmcnt(11)
	v_fma_f32 v120, -v146, v78, v120
	v_fma_f32 v120, -v147, v79, v120
	v_fma_f32 v120, -v148, v80, v120
	v_fma_f32 v120, -v149, v81, v120
	ds_read_b128 v[146:149], v54 offset:46480
	s_waitcnt lgkmcnt(11)
	v_fma_f32 v121, -v150, v78, v121
	v_fma_f32 v121, -v151, v79, v121
	v_fma_f32 v121, -v152, v80, v121
	v_fma_f32 v121, -v153, v81, v121
	ds_read_b128 v[150:153], v54 offset:46752
	s_waitcnt lgkmcnt(11)
	v_fma_f32 v83, -v154, v82, v83
	ds_read_b128 v[154:157], v54 offset:47024
	s_waitcnt lgkmcnt(11)
	v_fma_f32 v84, -v158, v82, v84
	v_fma_f32 v84, -v159, v83, v84
	ds_read_b128 v[158:161], v54 offset:47296
	s_waitcnt lgkmcnt(11)
	v_fma_f32 v85, -v162, v82, v85
	v_fma_f32 v85, -v163, v83, v85
	v_fma_f32 v85, -v164, v84, v85
	ds_read_b128 v[162:165], v54 offset:47568
	s_waitcnt lgkmcnt(11)
	v_fma_f32 v86, -v166, v82, v86
	v_fma_f32 v86, -v167, v83, v86
	v_fma_f32 v86, -v168, v84, v86
	v_fma_f32 v86, -v169, v85, v86
	ds_read_b128 v[166:169], v54 offset:47840
	s_waitcnt lgkmcnt(11)
	v_fma_f32 v87, -v170, v82, v87
	v_fma_f32 v87, -v171, v83, v87
	v_fma_f32 v87, -v172, v84, v87
	v_fma_f32 v87, -v173, v85, v87
	ds_read_b128 v[170:173], v54 offset:48112
	s_waitcnt lgkmcnt(11)
	v_fma_f32 v88, -v184, v82, v88
	v_fma_f32 v88, -v185, v83, v88
	v_fma_f32 v88, -v186, v84, v88
	v_fma_f32 v88, -v187, v85, v88
	ds_read_b128 v[184:187], v54 offset:48384
	s_waitcnt lgkmcnt(11)
	v_fma_f32 v89, -v122, v82, v89
	v_fma_f32 v89, -v123, v83, v89
	v_fma_f32 v89, -v124, v84, v89
	v_fma_f32 v89, -v125, v85, v89
	ds_read_b128 v[122:125], v54 offset:48656
	s_waitcnt lgkmcnt(11)
	v_fma_f32 v90, -v126, v82, v90
	v_fma_f32 v90, -v127, v83, v90
	v_fma_f32 v90, -v128, v84, v90
	v_fma_f32 v90, -v129, v85, v90
	ds_read_b128 v[126:129], v54 offset:48928
	s_waitcnt lgkmcnt(11)
	v_fma_f32 v91, -v130, v82, v91
	v_fma_f32 v91, -v131, v83, v91
	v_fma_f32 v91, -v132, v84, v91
	v_fma_f32 v91, -v133, v85, v91
	ds_read_b128 v[130:133], v54 offset:49200
	s_waitcnt lgkmcnt(11)
	v_fma_f32 v92, -v142, v82, v92
	v_fma_f32 v92, -v143, v83, v92
	v_fma_f32 v92, -v144, v84, v92
	v_fma_f32 v92, -v145, v85, v92
	ds_read_b128 v[142:145], v54 offset:49472
	s_waitcnt lgkmcnt(11)
	v_fma_f32 v93, -v146, v82, v93
	v_fma_f32 v93, -v147, v83, v93
	v_fma_f32 v93, -v148, v84, v93
	v_fma_f32 v93, -v149, v85, v93
	ds_read_b128 v[146:149], v54 offset:49744
	s_waitcnt lgkmcnt(11)
	v_fma_f32 v94, -v150, v82, v94
	v_fma_f32 v94, -v151, v83, v94
	v_fma_f32 v94, -v152, v84, v94
	v_fma_f32 v94, -v153, v85, v94
	ds_read_b128 v[150:153], v54 offset:50016
	s_waitcnt lgkmcnt(11)
	v_fma_f32 v95, -v154, v82, v95
	v_fma_f32 v95, -v155, v83, v95
	v_fma_f32 v95, -v156, v84, v95
	v_fma_f32 v95, -v157, v85, v95
	ds_read_b128 v[154:157], v54 offset:50288
	s_waitcnt lgkmcnt(11)
	v_fma_f32 v96, -v158, v82, v96
	v_fma_f32 v96, -v159, v83, v96
	v_fma_f32 v96, -v160, v84, v96
	v_fma_f32 v96, -v161, v85, v96
	ds_read_b128 v[158:161], v54 offset:50560
	s_waitcnt lgkmcnt(11)
	v_fma_f32 v97, -v162, v82, v97
	v_fma_f32 v97, -v163, v83, v97
	v_fma_f32 v97, -v164, v84, v97
	v_fma_f32 v97, -v165, v85, v97
	ds_read_b128 v[162:165], v54 offset:50832
	s_waitcnt lgkmcnt(11)
	v_fma_f32 v98, -v166, v82, v98
	v_fma_f32 v98, -v167, v83, v98
	v_fma_f32 v98, -v168, v84, v98
	v_fma_f32 v98, -v169, v85, v98
	ds_read_b128 v[166:169], v54 offset:51104
	s_waitcnt lgkmcnt(11)
	v_fma_f32 v99, -v170, v82, v99
	v_fma_f32 v99, -v171, v83, v99
	v_fma_f32 v99, -v172, v84, v99
	v_fma_f32 v99, -v173, v85, v99
	ds_read_b128 v[170:173], v54 offset:51376
	s_waitcnt lgkmcnt(11)
	v_fma_f32 v100, -v184, v82, v100
	v_fma_f32 v100, -v185, v83, v100
	v_fma_f32 v100, -v186, v84, v100
	v_fma_f32 v100, -v187, v85, v100
	ds_read_b128 v[184:187], v54 offset:51648
	s_waitcnt lgkmcnt(11)
; __device__ __forceinline__ void gdn_chunk_item(const Params& p, int item, char* smem) {
;     ...
; #pragma unroll 2
;       for (int sg = 0; sg < b4; sg++) {
;         const float4 l0 = *(const float4*)&l0p[sg * 4], l1 = *(const float4*)&l0p[68 + sg * 4];
;         const float4 l2 = *(const float4*)&l0p[136 + sg * 4], l3 = *(const float4*)&l0p[204 + sg * 4];
;         const float* xp = xc + sg * 1024;
;         const float x0 = xp[0], x1 = xp[256], x2 = xp[512], x3 = xp[768];
;         a0 -= l0.x * x0; a0 -= l0.y * x1; a0 -= l0.z * x2; a0 -= l0.w * x3;
;         a1 -= l1.x * x0; a1 -= l1.y * x1; a1 -= l1.z * x2; a1 -= l1.w * x3;
;         a2 -= l2.x * x0; a2 -= l2.y * x1; a2 -= l2.z * x2; a2 -= l2.w * x3;
;         a3 -= l3.x * x0; a3 -= l3.y * x1; a3 -= l3.z * x2; a3 -= l3.w * x3;
;       }
;       const float4 d1 = *(const float4*)&l0p[68 + t0], d2 = *(const float4*)&l0p[136 + t0], d3 = *(const float4*)&l0p[204 + t0];
;       a1 -= d1.x * a0;
;       a2 -= d2.x * a0; a2 -= d2.y * a1;
;       a3 -= d3.x * a0; a3 -= d3.y * a1; a3 -= d3.z * a2;
	v_fma_f32 v101, -v122, v82, v101
	v_fma_f32 v101, -v123, v83, v101
	v_fma_f32 v101, -v124, v84, v101
	v_fma_f32 v101, -v125, v85, v101
	ds_read_b128 v[122:125], v54 offset:51920
	s_waitcnt lgkmcnt(11)
	v_fma_f32 v102, -v126, v82, v102
	v_fma_f32 v102, -v127, v83, v102
	v_fma_f32 v102, -v128, v84, v102
	v_fma_f32 v102, -v129, v85, v102
	ds_read_b128 v[126:129], v54 offset:52192
	s_waitcnt lgkmcnt(11)
	v_fma_f32 v103, -v130, v82, v103
	v_fma_f32 v103, -v131, v83, v103
	v_fma_f32 v103, -v132, v84, v103
	v_fma_f32 v103, -v133, v85, v103
	ds_read_b128 v[130:133], v54 offset:52464
	s_waitcnt lgkmcnt(11)
	v_fma_f32 v104, -v142, v82, v104
	v_fma_f32 v104, -v143, v83, v104
	v_fma_f32 v104, -v144, v84, v104
	v_fma_f32 v104, -v145, v85, v104
	ds_read_b128 v[142:145], v54 offset:52736
	s_waitcnt lgkmcnt(11)
	v_fma_f32 v105, -v146, v82, v105
	v_fma_f32 v105, -v147, v83, v105
	v_fma_f32 v105, -v148, v84, v105
	v_fma_f32 v105, -v149, v85, v105
	ds_read_b128 v[146:149], v54 offset:53008
	s_waitcnt lgkmcnt(11)
	v_fma_f32 v106, -v150, v82, v106
	v_fma_f32 v106, -v151, v83, v106
	v_fma_f32 v106, -v152, v84, v106
	v_fma_f32 v106, -v153, v85, v106
	ds_read_b128 v[150:153], v54 offset:53280
	s_waitcnt lgkmcnt(11)
	v_fma_f32 v107, -v154, v82, v107
	v_fma_f32 v107, -v155, v83, v107
	v_fma_f32 v107, -v156, v84, v107
	v_fma_f32 v107, -v157, v85, v107
	ds_read_b128 v[154:157], v54 offset:53552
	s_waitcnt lgkmcnt(11)
	v_fma_f32 v108, -v158, v82, v108
	v_fma_f32 v108, -v159, v83, v108
	v_fma_f32 v108, -v160, v84, v108
	v_fma_f32 v108, -v161, v85, v108
	ds_read_b128 v[158:161], v54 offset:53824
	s_waitcnt lgkmcnt(11)
	v_fma_f32 v109, -v162, v82, v109
	v_fma_f32 v109, -v163, v83, v109
	v_fma_f32 v109, -v164, v84, v109
	v_fma_f32 v109, -v165, v85, v109
	ds_read_b128 v[162:165], v54 offset:54096
	s_waitcnt lgkmcnt(11)
	v_fma_f32 v110, -v166, v82, v110
	v_fma_f32 v110, -v167, v83, v110
	v_fma_f32 v110, -v168, v84, v110
	v_fma_f32 v110, -v169, v85, v110
	ds_read_b128 v[166:169], v54 offset:44864
	s_waitcnt lgkmcnt(11)
	v_fma_f32 v111, -v170, v82, v111
	v_fma_f32 v111, -v171, v83, v111
	v_fma_f32 v111, -v172, v84, v111
	v_fma_f32 v111, -v173, v85, v111
	ds_read_b128 v[170:173], v54 offset:45136
	s_waitcnt lgkmcnt(11)
	v_fma_f32 v112, -v184, v82, v112
	v_fma_f32 v112, -v185, v83, v112
	v_fma_f32 v112, -v186, v84, v112
	v_fma_f32 v112, -v187, v85, v112
	ds_read_b128 v[184:187], v54 offset:45408
	s_waitcnt lgkmcnt(11)
	v_fma_f32 v113, -v122, v82, v113
	v_fma_f32 v113, -v123, v83, v113
	v_fma_f32 v113, -v124, v84, v113
	v_fma_f32 v113, -v125, v85, v113
	ds_read_b128 v[122:125], v54 offset:45680
	s_waitcnt lgkmcnt(11)
	v_fma_f32 v114, -v126, v82, v114
	v_fma_f32 v114, -v127, v83, v114
	v_fma_f32 v114, -v128, v84, v114
	v_fma_f32 v114, -v129, v85, v114
	ds_read_b128 v[126:129], v54 offset:45952
	s_waitcnt lgkmcnt(11)
	v_fma_f32 v115, -v130, v82, v115
	v_fma_f32 v115, -v131, v83, v115
	v_fma_f32 v115, -v132, v84, v115
	v_fma_f32 v115, -v133, v85, v115
	ds_read_b128 v[130:133], v54 offset:46224
	s_waitcnt lgkmcnt(11)
	v_fma_f32 v116, -v142, v82, v116
	v_fma_f32 v116, -v143, v83, v116
	v_fma_f32 v116, -v144, v84, v116
	v_fma_f32 v116, -v145, v85, v116
	ds_read_b128 v[142:145], v54 offset:46496
	s_waitcnt lgkmcnt(11)
	v_fma_f32 v117, -v146, v82, v117
	v_fma_f32 v117, -v147, v83, v117
	v_fma_f32 v117, -v148, v84, v117
	v_fma_f32 v117, -v149, v85, v117
	ds_read_b128 v[146:149], v54 offset:46768
	s_waitcnt lgkmcnt(11)
	v_fma_f32 v118, -v150, v82, v118
	v_fma_f32 v118, -v151, v83, v118
	v_fma_f32 v118, -v152, v84, v118
	v_fma_f32 v118, -v153, v85, v118
	ds_read_b128 v[150:153], v54 offset:47040
	s_waitcnt lgkmcnt(11)
	v_fma_f32 v119, -v154, v82, v119
	v_fma_f32 v119, -v155, v83, v119
	v_fma_f32 v119, -v156, v84, v119
	v_fma_f32 v119, -v157, v85, v119
	ds_read_b128 v[154:157], v54 offset:47312
	s_waitcnt lgkmcnt(11)
	v_fma_f32 v120, -v158, v82, v120
	v_fma_f32 v120, -v159, v83, v120
	v_fma_f32 v120, -v160, v84, v120
	v_fma_f32 v120, -v161, v85, v120
	ds_read_b128 v[158:161], v54 offset:47584
	s_waitcnt lgkmcnt(11)
	v_fma_f32 v121, -v162, v82, v121
	v_fma_f32 v121, -v163, v83, v121
	v_fma_f32 v121, -v164, v84, v121
	v_fma_f32 v121, -v165, v85, v121
	ds_read_b128 v[162:165], v54 offset:47856
	s_waitcnt lgkmcnt(11)
	v_fma_f32 v87, -v166, v86, v87
	ds_read_b128 v[166:169], v54 offset:48128
	s_waitcnt lgkmcnt(11)
	v_fma_f32 v88, -v170, v86, v88
	v_fma_f32 v88, -v171, v87, v88
	ds_read_b128 v[170:173], v54 offset:48400
	s_waitcnt lgkmcnt(11)
	v_fma_f32 v89, -v184, v86, v89
	v_fma_f32 v89, -v185, v87, v89
	v_fma_f32 v89, -v186, v88, v89
	ds_read_b128 v[184:187], v54 offset:48672
	s_waitcnt lgkmcnt(11)
	v_fma_f32 v90, -v122, v86, v90
	v_fma_f32 v90, -v123, v87, v90
	v_fma_f32 v90, -v124, v88, v90
	v_fma_f32 v90, -v125, v89, v90
	ds_read_b128 v[122:125], v54 offset:48944
	s_waitcnt lgkmcnt(11)
	v_fma_f32 v91, -v126, v86, v91
	v_fma_f32 v91, -v127, v87, v91
	v_fma_f32 v91, -v128, v88, v91
	v_fma_f32 v91, -v129, v89, v91
	ds_read_b128 v[126:129], v54 offset:49216
	s_waitcnt lgkmcnt(11)
	v_fma_f32 v92, -v130, v86, v92
	v_fma_f32 v92, -v131, v87, v92
	v_fma_f32 v92, -v132, v88, v92
	v_fma_f32 v92, -v133, v89, v92
	ds_read_b128 v[130:133], v54 offset:49488
	s_waitcnt lgkmcnt(11)
	v_fma_f32 v93, -v142, v86, v93
	v_fma_f32 v93, -v143, v87, v93
	v_fma_f32 v93, -v144, v88, v93
	v_fma_f32 v93, -v145, v89, v93
	ds_read_b128 v[142:145], v54 offset:49760
	s_waitcnt lgkmcnt(11)
	v_fma_f32 v94, -v146, v86, v94
	v_fma_f32 v94, -v147, v87, v94
	v_fma_f32 v94, -v148, v88, v94
	v_fma_f32 v94, -v149, v89, v94
	ds_read_b128 v[146:149], v54 offset:50032
	s_waitcnt lgkmcnt(11)
; __device__ __forceinline__ void gdn_chunk_item(const Params& p, int item, char* smem) {
;     ...
; #pragma unroll 2
;       for (int sg = 0; sg < b4; sg++) {
;         const float4 l0 = *(const float4*)&l0p[sg * 4], l1 = *(const float4*)&l0p[68 + sg * 4];
;         const float4 l2 = *(const float4*)&l0p[136 + sg * 4], l3 = *(const float4*)&l0p[204 + sg * 4];
;         const float* xp = xc + sg * 1024;
;         const float x0 = xp[0], x1 = xp[256], x2 = xp[512], x3 = xp[768];
;         a0 -= l0.x * x0; a0 -= l0.y * x1; a0 -= l0.z * x2; a0 -= l0.w * x3;
;         a1 -= l1.x * x0; a1 -= l1.y * x1; a1 -= l1.z * x2; a1 -= l1.w * x3;
;         a2 -= l2.x * x0; a2 -= l2.y * x1; a2 -= l2.z * x2; a2 -= l2.w * x3;
;         a3 -= l3.x * x0; a3 -= l3.y * x1; a3 -= l3.z * x2; a3 -= l3.w * x3;
;       }
;       const float4 d1 = *(const float4*)&l0p[68 + t0], d2 = *(const float4*)&l0p[136 + t0], d3 = *(const float4*)&l0p[204 + t0];
;       a1 -= d1.x * a0;
;       a2 -= d2.x * a0; a2 -= d2.y * a1;
;       a3 -= d3.x * a0; a3 -= d3.y * a1; a3 -= d3.z * a2;
	v_fma_f32 v95, -v150, v86, v95
	v_fma_f32 v95, -v151, v87, v95
	v_fma_f32 v95, -v152, v88, v95
	v_fma_f32 v95, -v153, v89, v95
	ds_read_b128 v[150:153], v54 offset:50304
	s_waitcnt lgkmcnt(11)
	v_fma_f32 v96, -v154, v86, v96
	v_fma_f32 v96, -v155, v87, v96
	v_fma_f32 v96, -v156, v88, v96
	v_fma_f32 v96, -v157, v89, v96
	ds_read_b128 v[154:157], v54 offset:50576
	s_waitcnt lgkmcnt(11)
	v_fma_f32 v97, -v158, v86, v97
	v_fma_f32 v97, -v159, v87, v97
	v_fma_f32 v97, -v160, v88, v97
	v_fma_f32 v97, -v161, v89, v97
	ds_read_b128 v[158:161], v54 offset:50848
	s_waitcnt lgkmcnt(11)
	v_fma_f32 v98, -v162, v86, v98
	v_fma_f32 v98, -v163, v87, v98
	v_fma_f32 v98, -v164, v88, v98
	v_fma_f32 v98, -v165, v89, v98
	ds_read_b128 v[162:165], v54 offset:51120
	s_waitcnt lgkmcnt(11)
	v_fma_f32 v99, -v166, v86, v99
	v_fma_f32 v99, -v167, v87, v99
	v_fma_f32 v99, -v168, v88, v99
	v_fma_f32 v99, -v169, v89, v99
	ds_read_b128 v[166:169], v54 offset:51392
	s_waitcnt lgkmcnt(11)
	v_fma_f32 v100, -v170, v86, v100
	v_fma_f32 v100, -v171, v87, v100
	v_fma_f32 v100, -v172, v88, v100
	v_fma_f32 v100, -v173, v89, v100
	ds_read_b128 v[170:173], v54 offset:51664
	s_waitcnt lgkmcnt(11)
	v_fma_f32 v101, -v184, v86, v101
	v_fma_f32 v101, -v185, v87, v101
	v_fma_f32 v101, -v186, v88, v101
	v_fma_f32 v101, -v187, v89, v101
	ds_read_b128 v[184:187], v54 offset:51936
	s_waitcnt lgkmcnt(11)
	v_fma_f32 v102, -v122, v86, v102
	v_fma_f32 v102, -v123, v87, v102
	v_fma_f32 v102, -v124, v88, v102
	v_fma_f32 v102, -v125, v89, v102
	ds_read_b128 v[122:125], v54 offset:52208
	s_waitcnt lgkmcnt(11)
	v_fma_f32 v103, -v126, v86, v103
	v_fma_f32 v103, -v127, v87, v103
	v_fma_f32 v103, -v128, v88, v103
	v_fma_f32 v103, -v129, v89, v103
	ds_read_b128 v[126:129], v54 offset:52480
	s_waitcnt lgkmcnt(11)
	v_fma_f32 v104, -v130, v86, v104
	v_fma_f32 v104, -v131, v87, v104
	v_fma_f32 v104, -v132, v88, v104
	v_fma_f32 v104, -v133, v89, v104
	ds_read_b128 v[130:133], v54 offset:52752
	s_waitcnt lgkmcnt(11)
	v_fma_f32 v105, -v142, v86, v105
	v_fma_f32 v105, -v143, v87, v105
	v_fma_f32 v105, -v144, v88, v105
	v_fma_f32 v105, -v145, v89, v105
	ds_read_b128 v[142:145], v54 offset:53024
	s_waitcnt lgkmcnt(11)
	v_fma_f32 v106, -v146, v86, v106
	v_fma_f32 v106, -v147, v87, v106
	v_fma_f32 v106, -v148, v88, v106
	v_fma_f32 v106, -v149, v89, v106
	ds_read_b128 v[146:149], v54 offset:53296
	s_waitcnt lgkmcnt(11)
	v_fma_f32 v107, -v150, v86, v107
	v_fma_f32 v107, -v151, v87, v107
	v_fma_f32 v107, -v152, v88, v107
	v_fma_f32 v107, -v153, v89, v107
	ds_read_b128 v[150:153], v54 offset:53568
	s_waitcnt lgkmcnt(11)
	v_fma_f32 v108, -v154, v86, v108
	v_fma_f32 v108, -v155, v87, v108
	v_fma_f32 v108, -v156, v88, v108
	v_fma_f32 v108, -v157, v89, v108
	ds_read_b128 v[154:157], v54 offset:53840
	s_waitcnt lgkmcnt(11)
	v_fma_f32 v109, -v158, v86, v109
	v_fma_f32 v109, -v159, v87, v109
	v_fma_f32 v109, -v160, v88, v109
	v_fma_f32 v109, -v161, v89, v109
	ds_read_b128 v[158:161], v54 offset:54112
	s_waitcnt lgkmcnt(11)
	v_fma_f32 v110, -v162, v86, v110
	v_fma_f32 v110, -v163, v87, v110
	v_fma_f32 v110, -v164, v88, v110
	v_fma_f32 v110, -v165, v89, v110
	ds_read_b128 v[162:165], v54 offset:45968
	s_waitcnt lgkmcnt(11)
	v_fma_f32 v111, -v166, v86, v111
	v_fma_f32 v111, -v167, v87, v111
	v_fma_f32 v111, -v168, v88, v111
	v_fma_f32 v111, -v169, v89, v111
	ds_read_b128 v[166:169], v54 offset:46240
	s_waitcnt lgkmcnt(11)
	v_fma_f32 v112, -v170, v86, v112
	v_fma_f32 v112, -v171, v87, v112
	v_fma_f32 v112, -v172, v88, v112
	v_fma_f32 v112, -v173, v89, v112
	ds_read_b128 v[170:173], v54 offset:46512
	s_waitcnt lgkmcnt(11)
	v_fma_f32 v113, -v184, v86, v113
	v_fma_f32 v113, -v185, v87, v113
	v_fma_f32 v113, -v186, v88, v113
	v_fma_f32 v113, -v187, v89, v113
	ds_read_b128 v[184:187], v54 offset:46784
	s_waitcnt lgkmcnt(11)
	v_fma_f32 v114, -v122, v86, v114
	v_fma_f32 v114, -v123, v87, v114
	v_fma_f32 v114, -v124, v88, v114
	v_fma_f32 v114, -v125, v89, v114
	ds_read_b128 v[122:125], v54 offset:47056
	s_waitcnt lgkmcnt(11)
	v_fma_f32 v115, -v126, v86, v115
	v_fma_f32 v115, -v127, v87, v115
	v_fma_f32 v115, -v128, v88, v115
	v_fma_f32 v115, -v129, v89, v115
	ds_read_b128 v[126:129], v54 offset:47328
	s_waitcnt lgkmcnt(11)
	v_fma_f32 v116, -v130, v86, v116
	v_fma_f32 v116, -v131, v87, v116
	v_fma_f32 v116, -v132, v88, v116
	v_fma_f32 v116, -v133, v89, v116
	ds_read_b128 v[130:133], v54 offset:47600
	s_waitcnt lgkmcnt(11)
	v_fma_f32 v117, -v142, v86, v117
	v_fma_f32 v117, -v143, v87, v117
	v_fma_f32 v117, -v144, v88, v117
	v_fma_f32 v117, -v145, v89, v117
	ds_read_b128 v[142:145], v54 offset:47872
	s_waitcnt lgkmcnt(11)
	v_fma_f32 v118, -v146, v86, v118
	v_fma_f32 v118, -v147, v87, v118
	v_fma_f32 v118, -v148, v88, v118
	v_fma_f32 v118, -v149, v89, v118
	ds_read_b128 v[146:149], v54 offset:48144
	s_waitcnt lgkmcnt(11)
	v_fma_f32 v119, -v150, v86, v119
	v_fma_f32 v119, -v151, v87, v119
	v_fma_f32 v119, -v152, v88, v119
	v_fma_f32 v119, -v153, v89, v119
	ds_read_b128 v[150:153], v54 offset:48416
	s_waitcnt lgkmcnt(11)
	v_fma_f32 v120, -v154, v86, v120
	v_fma_f32 v120, -v155, v87, v120
	v_fma_f32 v120, -v156, v88, v120
	v_fma_f32 v120, -v157, v89, v120
	ds_read_b128 v[154:157], v54 offset:48688
	s_waitcnt lgkmcnt(11)
	v_fma_f32 v121, -v158, v86, v121
	v_fma_f32 v121, -v159, v87, v121
	v_fma_f32 v121, -v160, v88, v121
	v_fma_f32 v121, -v161, v89, v121
	ds_read_b128 v[158:161], v54 offset:48960
	s_waitcnt lgkmcnt(11)
	v_fma_f32 v91, -v162, v90, v91
	ds_read_b128 v[162:165], v54 offset:49232
	s_waitcnt lgkmcnt(11)
	v_fma_f32 v92, -v166, v90, v92
	v_fma_f32 v92, -v167, v91, v92
	ds_read_b128 v[166:169], v54 offset:49504
	s_waitcnt lgkmcnt(11)
; __device__ __forceinline__ void gdn_chunk_item(const Params& p, int item, char* smem) {
;     ...
; #pragma unroll 2
;       for (int sg = 0; sg < b4; sg++) {
;         const float4 l0 = *(const float4*)&l0p[sg * 4], l1 = *(const float4*)&l0p[68 + sg * 4];
;         const float4 l2 = *(const float4*)&l0p[136 + sg * 4], l3 = *(const float4*)&l0p[204 + sg * 4];
;         const float* xp = xc + sg * 1024;
;         const float x0 = xp[0], x1 = xp[256], x2 = xp[512], x3 = xp[768];
;         a0 -= l0.x * x0; a0 -= l0.y * x1; a0 -= l0.z * x2; a0 -= l0.w * x3;
;         a1 -= l1.x * x0; a1 -= l1.y * x1; a1 -= l1.z * x2; a1 -= l1.w * x3;
;         a2 -= l2.x * x0; a2 -= l2.y * x1; a2 -= l2.z * x2; a2 -= l2.w * x3;
;         a3 -= l3.x * x0; a3 -= l3.y * x1; a3 -= l3.z * x2; a3 -= l3.w * x3;
;       }
;       const float4 d1 = *(const float4*)&l0p[68 + t0], d2 = *(const float4*)&l0p[136 + t0], d3 = *(const float4*)&l0p[204 + t0];
;       a1 -= d1.x * a0;
;       a2 -= d2.x * a0; a2 -= d2.y * a1;
;       a3 -= d3.x * a0; a3 -= d3.y * a1; a3 -= d3.z * a2;
	v_fma_f32 v93, -v170, v90, v93
	v_fma_f32 v93, -v171, v91, v93
	v_fma_f32 v93, -v172, v92, v93
	ds_read_b128 v[170:173], v54 offset:49776
	s_waitcnt lgkmcnt(11)
	v_fma_f32 v94, -v184, v90, v94
	v_fma_f32 v94, -v185, v91, v94
	v_fma_f32 v94, -v186, v92, v94
	v_fma_f32 v94, -v187, v93, v94
	ds_read_b128 v[184:187], v54 offset:50048
	s_waitcnt lgkmcnt(11)
	v_fma_f32 v95, -v122, v90, v95
	v_fma_f32 v95, -v123, v91, v95
	v_fma_f32 v95, -v124, v92, v95
	v_fma_f32 v95, -v125, v93, v95
	ds_read_b128 v[122:125], v54 offset:50320
	s_waitcnt lgkmcnt(11)
	v_fma_f32 v96, -v126, v90, v96
	v_fma_f32 v96, -v127, v91, v96
	v_fma_f32 v96, -v128, v92, v96
	v_fma_f32 v96, -v129, v93, v96
	ds_read_b128 v[126:129], v54 offset:50592
	s_waitcnt lgkmcnt(11)
	v_fma_f32 v97, -v130, v90, v97
	v_fma_f32 v97, -v131, v91, v97
	v_fma_f32 v97, -v132, v92, v97
	v_fma_f32 v97, -v133, v93, v97
	ds_read_b128 v[130:133], v54 offset:50864
	s_waitcnt lgkmcnt(11)
	v_fma_f32 v98, -v142, v90, v98
	v_fma_f32 v98, -v143, v91, v98
	v_fma_f32 v98, -v144, v92, v98
	v_fma_f32 v98, -v145, v93, v98
	ds_read_b128 v[142:145], v54 offset:51136
	s_waitcnt lgkmcnt(11)
	v_fma_f32 v99, -v146, v90, v99
	v_fma_f32 v99, -v147, v91, v99
	v_fma_f32 v99, -v148, v92, v99
	v_fma_f32 v99, -v149, v93, v99
	ds_read_b128 v[146:149], v54 offset:51408
	s_waitcnt lgkmcnt(11)
	v_fma_f32 v100, -v150, v90, v100
	v_fma_f32 v100, -v151, v91, v100
	v_fma_f32 v100, -v152, v92, v100
	v_fma_f32 v100, -v153, v93, v100
	ds_read_b128 v[150:153], v54 offset:51680
	s_waitcnt lgkmcnt(11)
	v_fma_f32 v101, -v154, v90, v101
	v_fma_f32 v101, -v155, v91, v101
	v_fma_f32 v101, -v156, v92, v101
	v_fma_f32 v101, -v157, v93, v101
	ds_read_b128 v[154:157], v54 offset:51952
	s_waitcnt lgkmcnt(11)
	v_fma_f32 v102, -v158, v90, v102
	v_fma_f32 v102, -v159, v91, v102
	v_fma_f32 v102, -v160, v92, v102
	v_fma_f32 v102, -v161, v93, v102
	ds_read_b128 v[158:161], v54 offset:52224
	s_waitcnt lgkmcnt(11)
	v_fma_f32 v103, -v162, v90, v103
	v_fma_f32 v103, -v163, v91, v103
	v_fma_f32 v103, -v164, v92, v103
	v_fma_f32 v103, -v165, v93, v103
	ds_read_b128 v[162:165], v54 offset:52496
	s_waitcnt lgkmcnt(11)
	v_fma_f32 v104, -v166, v90, v104
	v_fma_f32 v104, -v167, v91, v104
	v_fma_f32 v104, -v168, v92, v104
	v_fma_f32 v104, -v169, v93, v104
	ds_read_b128 v[166:169], v54 offset:52768
	s_waitcnt lgkmcnt(11)
	v_fma_f32 v105, -v170, v90, v105
	v_fma_f32 v105, -v171, v91, v105
	v_fma_f32 v105, -v172, v92, v105
	v_fma_f32 v105, -v173, v93, v105
	ds_read_b128 v[170:173], v54 offset:53040
	s_waitcnt lgkmcnt(11)
	v_fma_f32 v106, -v184, v90, v106
	v_fma_f32 v106, -v185, v91, v106
	v_fma_f32 v106, -v186, v92, v106
	v_fma_f32 v106, -v187, v93, v106
	ds_read_b128 v[184:187], v54 offset:53312
	s_waitcnt lgkmcnt(11)
	v_fma_f32 v107, -v122, v90, v107
	v_fma_f32 v107, -v123, v91, v107
	v_fma_f32 v107, -v124, v92, v107
	v_fma_f32 v107, -v125, v93, v107
	ds_read_b128 v[122:125], v54 offset:53584
	s_waitcnt lgkmcnt(11)
	v_fma_f32 v108, -v126, v90, v108
	v_fma_f32 v108, -v127, v91, v108
	v_fma_f32 v108, -v128, v92, v108
	v_fma_f32 v108, -v129, v93, v108
	ds_read_b128 v[126:129], v54 offset:53856
	s_waitcnt lgkmcnt(11)
	v_fma_f32 v109, -v130, v90, v109
	v_fma_f32 v109, -v131, v91, v109
	v_fma_f32 v109, -v132, v92, v109
	v_fma_f32 v109, -v133, v93, v109
	ds_read_b128 v[130:133], v54 offset:54128
	s_waitcnt lgkmcnt(11)
	v_fma_f32 v110, -v142, v90, v110
	v_fma_f32 v110, -v143, v91, v110
	v_fma_f32 v110, -v144, v92, v110
	v_fma_f32 v110, -v145, v93, v110
	ds_read_b128 v[142:145], v54 offset:47072
	s_waitcnt lgkmcnt(11)
	v_fma_f32 v111, -v146, v90, v111
	v_fma_f32 v111, -v147, v91, v111
	v_fma_f32 v111, -v148, v92, v111
	v_fma_f32 v111, -v149, v93, v111
	ds_read_b128 v[146:149], v54 offset:47344
	s_waitcnt lgkmcnt(11)
	v_fma_f32 v112, -v150, v90, v112
	v_fma_f32 v112, -v151, v91, v112
	v_fma_f32 v112, -v152, v92, v112
	v_fma_f32 v112, -v153, v93, v112
	ds_read_b128 v[150:153], v54 offset:47616
	s_waitcnt lgkmcnt(11)
	v_fma_f32 v113, -v154, v90, v113
	v_fma_f32 v113, -v155, v91, v113
	v_fma_f32 v113, -v156, v92, v113
	v_fma_f32 v113, -v157, v93, v113
	ds_read_b128 v[154:157], v54 offset:47888
	s_waitcnt lgkmcnt(11)
	v_fma_f32 v114, -v158, v90, v114
	v_fma_f32 v114, -v159, v91, v114
	v_fma_f32 v114, -v160, v92, v114
	v_fma_f32 v114, -v161, v93, v114
	ds_read_b128 v[158:161], v54 offset:48160
	s_waitcnt lgkmcnt(11)
	v_fma_f32 v115, -v162, v90, v115
	v_fma_f32 v115, -v163, v91, v115
	v_fma_f32 v115, -v164, v92, v115
	v_fma_f32 v115, -v165, v93, v115
	ds_read_b128 v[162:165], v54 offset:48432
	s_waitcnt lgkmcnt(11)
	v_fma_f32 v116, -v166, v90, v116
	v_fma_f32 v116, -v167, v91, v116
	v_fma_f32 v116, -v168, v92, v116
	v_fma_f32 v116, -v169, v93, v116
	ds_read_b128 v[166:169], v54 offset:48704
	s_waitcnt lgkmcnt(11)
	v_fma_f32 v117, -v170, v90, v117
	v_fma_f32 v117, -v171, v91, v117
	v_fma_f32 v117, -v172, v92, v117
	v_fma_f32 v117, -v173, v93, v117
	ds_read_b128 v[170:173], v54 offset:48976
	s_waitcnt lgkmcnt(11)
	v_fma_f32 v118, -v184, v90, v118
	v_fma_f32 v118, -v185, v91, v118
	v_fma_f32 v118, -v186, v92, v118
	v_fma_f32 v118, -v187, v93, v118
	ds_read_b128 v[184:187], v54 offset:49248
	s_waitcnt lgkmcnt(11)
	v_fma_f32 v119, -v122, v90, v119
	v_fma_f32 v119, -v123, v91, v119
	v_fma_f32 v119, -v124, v92, v119
	v_fma_f32 v119, -v125, v93, v119
	ds_read_b128 v[122:125], v54 offset:49520
	s_waitcnt lgkmcnt(11)
	v_fma_f32 v120, -v126, v90, v120
	v_fma_f32 v120, -v127, v91, v120
	v_fma_f32 v120, -v128, v92, v120
	v_fma_f32 v120, -v129, v93, v120
	ds_read_b128 v[126:129], v54 offset:49792
	s_waitcnt lgkmcnt(11)
; __device__ __forceinline__ void gdn_chunk_item(const Params& p, int item, char* smem) {
;     ...
; #pragma unroll 2
;       for (int sg = 0; sg < b4; sg++) {
;         const float4 l0 = *(const float4*)&l0p[sg * 4], l1 = *(const float4*)&l0p[68 + sg * 4];
;         const float4 l2 = *(const float4*)&l0p[136 + sg * 4], l3 = *(const float4*)&l0p[204 + sg * 4];
;         const float* xp = xc + sg * 1024;
;         const float x0 = xp[0], x1 = xp[256], x2 = xp[512], x3 = xp[768];
;         a0 -= l0.x * x0; a0 -= l0.y * x1; a0 -= l0.z * x2; a0 -= l0.w * x3;
;         a1 -= l1.x * x0; a1 -= l1.y * x1; a1 -= l1.z * x2; a1 -= l1.w * x3;
;         a2 -= l2.x * x0; a2 -= l2.y * x1; a2 -= l2.z * x2; a2 -= l2.w * x3;
;         a3 -= l3.x * x0; a3 -= l3.y * x1; a3 -= l3.z * x2; a3 -= l3.w * x3;
;       }
;       const float4 d1 = *(const float4*)&l0p[68 + t0], d2 = *(const float4*)&l0p[136 + t0], d3 = *(const float4*)&l0p[204 + t0];
;       a1 -= d1.x * a0;
;       a2 -= d2.x * a0; a2 -= d2.y * a1;
;       a3 -= d3.x * a0; a3 -= d3.y * a1; a3 -= d3.z * a2;
	v_fma_f32 v121, -v130, v90, v121
	v_fma_f32 v121, -v131, v91, v121
	v_fma_f32 v121, -v132, v92, v121
	v_fma_f32 v121, -v133, v93, v121
	ds_read_b128 v[130:133], v54 offset:50064
	s_waitcnt lgkmcnt(11)
	v_fma_f32 v95, -v142, v94, v95
	ds_read_b128 v[142:145], v54 offset:50336
	s_waitcnt lgkmcnt(11)
	v_fma_f32 v96, -v146, v94, v96
	v_fma_f32 v96, -v147, v95, v96
	ds_read_b128 v[146:149], v54 offset:50608
	s_waitcnt lgkmcnt(11)
	v_fma_f32 v97, -v150, v94, v97
	v_fma_f32 v97, -v151, v95, v97
	v_fma_f32 v97, -v152, v96, v97
	ds_read_b128 v[150:153], v54 offset:50880
	s_waitcnt lgkmcnt(11)
	v_fma_f32 v98, -v154, v94, v98
	v_fma_f32 v98, -v155, v95, v98
	v_fma_f32 v98, -v156, v96, v98
	v_fma_f32 v98, -v157, v97, v98
	ds_read_b128 v[154:157], v54 offset:51152
	s_waitcnt lgkmcnt(11)
	v_fma_f32 v99, -v158, v94, v99
	v_fma_f32 v99, -v159, v95, v99
	v_fma_f32 v99, -v160, v96, v99
	v_fma_f32 v99, -v161, v97, v99
	ds_read_b128 v[158:161], v54 offset:51424
	s_waitcnt lgkmcnt(11)
	v_fma_f32 v100, -v162, v94, v100
	v_fma_f32 v100, -v163, v95, v100
	v_fma_f32 v100, -v164, v96, v100
	v_fma_f32 v100, -v165, v97, v100
	ds_read_b128 v[162:165], v54 offset:51696
	s_waitcnt lgkmcnt(11)
	v_fma_f32 v101, -v166, v94, v101
	v_fma_f32 v101, -v167, v95, v101
	v_fma_f32 v101, -v168, v96, v101
	v_fma_f32 v101, -v169, v97, v101
	ds_read_b128 v[166:169], v54 offset:51968
	s_waitcnt lgkmcnt(11)
	v_fma_f32 v102, -v170, v94, v102
	v_fma_f32 v102, -v171, v95, v102
	v_fma_f32 v102, -v172, v96, v102
	v_fma_f32 v102, -v173, v97, v102
	ds_read_b128 v[170:173], v54 offset:52240
	s_waitcnt lgkmcnt(11)
	v_fma_f32 v103, -v184, v94, v103
	v_fma_f32 v103, -v185, v95, v103
	v_fma_f32 v103, -v186, v96, v103
	v_fma_f32 v103, -v187, v97, v103
	ds_read_b128 v[184:187], v54 offset:52512
	s_waitcnt lgkmcnt(11)
	v_fma_f32 v104, -v122, v94, v104
	v_fma_f32 v104, -v123, v95, v104
	v_fma_f32 v104, -v124, v96, v104
	v_fma_f32 v104, -v125, v97, v104
	ds_read_b128 v[122:125], v54 offset:52784
	s_waitcnt lgkmcnt(11)
	v_fma_f32 v105, -v126, v94, v105
	v_fma_f32 v105, -v127, v95, v105
	v_fma_f32 v105, -v128, v96, v105
	v_fma_f32 v105, -v129, v97, v105
	ds_read_b128 v[126:129], v54 offset:53056
	s_waitcnt lgkmcnt(11)
	v_fma_f32 v106, -v130, v94, v106
	v_fma_f32 v106, -v131, v95, v106
	v_fma_f32 v106, -v132, v96, v106
	v_fma_f32 v106, -v133, v97, v106
	ds_read_b128 v[130:133], v54 offset:53328
	s_waitcnt lgkmcnt(11)
	v_fma_f32 v107, -v142, v94, v107
	v_fma_f32 v107, -v143, v95, v107
	v_fma_f32 v107, -v144, v96, v107
	v_fma_f32 v107, -v145, v97, v107
	ds_read_b128 v[142:145], v54 offset:53600
	s_waitcnt lgkmcnt(11)
	v_fma_f32 v108, -v146, v94, v108
	v_fma_f32 v108, -v147, v95, v108
	v_fma_f32 v108, -v148, v96, v108
	v_fma_f32 v108, -v149, v97, v108
	ds_read_b128 v[146:149], v54 offset:53872
	s_waitcnt lgkmcnt(11)
	v_fma_f32 v109, -v150, v94, v109
	v_fma_f32 v109, -v151, v95, v109
	v_fma_f32 v109, -v152, v96, v109
	v_fma_f32 v109, -v153, v97, v109
	ds_read_b128 v[150:153], v54 offset:54144
	s_waitcnt lgkmcnt(11)
	v_fma_f32 v110, -v154, v94, v110
	v_fma_f32 v110, -v155, v95, v110
	v_fma_f32 v110, -v156, v96, v110
	v_fma_f32 v110, -v157, v97, v110
	ds_read_b128 v[154:157], v54 offset:48176
	s_waitcnt lgkmcnt(11)
	v_fma_f32 v111, -v158, v94, v111
	v_fma_f32 v111, -v159, v95, v111
	v_fma_f32 v111, -v160, v96, v111
	v_fma_f32 v111, -v161, v97, v111
	ds_read_b128 v[158:161], v54 offset:48448
	s_waitcnt lgkmcnt(11)
	v_fma_f32 v112, -v162, v94, v112
	v_fma_f32 v112, -v163, v95, v112
	v_fma_f32 v112, -v164, v96, v112
	v_fma_f32 v112, -v165, v97, v112
	ds_read_b128 v[162:165], v54 offset:48720
	s_waitcnt lgkmcnt(11)
	v_fma_f32 v113, -v166, v94, v113
	v_fma_f32 v113, -v167, v95, v113
	v_fma_f32 v113, -v168, v96, v113
	v_fma_f32 v113, -v169, v97, v113
	ds_read_b128 v[166:169], v54 offset:48992
	s_waitcnt lgkmcnt(11)
	v_fma_f32 v114, -v170, v94, v114
	v_fma_f32 v114, -v171, v95, v114
	v_fma_f32 v114, -v172, v96, v114
	v_fma_f32 v114, -v173, v97, v114
	ds_read_b128 v[170:173], v54 offset:49264
	s_waitcnt lgkmcnt(11)
	v_fma_f32 v115, -v184, v94, v115
	v_fma_f32 v115, -v185, v95, v115
	v_fma_f32 v115, -v186, v96, v115
	v_fma_f32 v115, -v187, v97, v115
	ds_read_b128 v[184:187], v54 offset:49536
	s_waitcnt lgkmcnt(11)
	v_fma_f32 v116, -v122, v94, v116
	v_fma_f32 v116, -v123, v95, v116
	v_fma_f32 v116, -v124, v96, v116
	v_fma_f32 v116, -v125, v97, v116
	ds_read_b128 v[122:125], v54 offset:49808
	s_waitcnt lgkmcnt(11)
	v_fma_f32 v117, -v126, v94, v117
	v_fma_f32 v117, -v127, v95, v117
	v_fma_f32 v117, -v128, v96, v117
	v_fma_f32 v117, -v129, v97, v117
	ds_read_b128 v[126:129], v54 offset:50080
	s_waitcnt lgkmcnt(11)
	v_fma_f32 v118, -v130, v94, v118
	v_fma_f32 v118, -v131, v95, v118
	v_fma_f32 v118, -v132, v96, v118
	v_fma_f32 v118, -v133, v97, v118
	ds_read_b128 v[130:133], v54 offset:50352
	s_waitcnt lgkmcnt(11)
	v_fma_f32 v119, -v142, v94, v119
	v_fma_f32 v119, -v143, v95, v119
	v_fma_f32 v119, -v144, v96, v119
	v_fma_f32 v119, -v145, v97, v119
	ds_read_b128 v[142:145], v54 offset:50624
	s_waitcnt lgkmcnt(11)
	v_fma_f32 v120, -v146, v94, v120
	v_fma_f32 v120, -v147, v95, v120
	v_fma_f32 v120, -v148, v96, v120
	v_fma_f32 v120, -v149, v97, v120
	ds_read_b128 v[146:149], v54 offset:50896
	s_waitcnt lgkmcnt(11)
	v_fma_f32 v121, -v150, v94, v121
	v_fma_f32 v121, -v151, v95, v121
	v_fma_f32 v121, -v152, v96, v121
	v_fma_f32 v121, -v153, v97, v121
	ds_read_b128 v[150:153], v54 offset:51168
	s_waitcnt lgkmcnt(11)
	v_fma_f32 v99, -v154, v98, v99
	ds_read_b128 v[154:157], v54 offset:51440
	s_waitcnt lgkmcnt(11)
	v_fma_f32 v100, -v158, v98, v100
	v_fma_f32 v100, -v159, v99, v100
	ds_read_b128 v[158:161], v54 offset:51712
	s_waitcnt lgkmcnt(11)
; __device__ __forceinline__ void gdn_chunk_item(const Params& p, int item, char* smem) {
;     ...
; #pragma unroll 2
;       for (int sg = 0; sg < b4; sg++) {
;         const float4 l0 = *(const float4*)&l0p[sg * 4], l1 = *(const float4*)&l0p[68 + sg * 4];
;         const float4 l2 = *(const float4*)&l0p[136 + sg * 4], l3 = *(const float4*)&l0p[204 + sg * 4];
;         const float* xp = xc + sg * 1024;
;         const float x0 = xp[0], x1 = xp[256], x2 = xp[512], x3 = xp[768];
;         a0 -= l0.x * x0; a0 -= l0.y * x1; a0 -= l0.z * x2; a0 -= l0.w * x3;
;         a1 -= l1.x * x0; a1 -= l1.y * x1; a1 -= l1.z * x2; a1 -= l1.w * x3;
;         a2 -= l2.x * x0; a2 -= l2.y * x1; a2 -= l2.z * x2; a2 -= l2.w * x3;
;         a3 -= l3.x * x0; a3 -= l3.y * x1; a3 -= l3.z * x2; a3 -= l3.w * x3;
;       }
;       const float4 d1 = *(const float4*)&l0p[68 + t0], d2 = *(const float4*)&l0p[136 + t0], d3 = *(const float4*)&l0p[204 + t0];
;       a1 -= d1.x * a0;
;       a2 -= d2.x * a0; a2 -= d2.y * a1;
;       a3 -= d3.x * a0; a3 -= d3.y * a1; a3 -= d3.z * a2;
	v_fma_f32 v101, -v162, v98, v101
	v_fma_f32 v101, -v163, v99, v101
	v_fma_f32 v101, -v164, v100, v101
	ds_read_b128 v[162:165], v54 offset:51984
	s_waitcnt lgkmcnt(11)
	v_fma_f32 v102, -v166, v98, v102
	v_fma_f32 v102, -v167, v99, v102
	v_fma_f32 v102, -v168, v100, v102
	v_fma_f32 v102, -v169, v101, v102
	ds_read_b128 v[166:169], v54 offset:52256
	s_waitcnt lgkmcnt(11)
	v_fma_f32 v103, -v170, v98, v103
	v_fma_f32 v103, -v171, v99, v103
	v_fma_f32 v103, -v172, v100, v103
	v_fma_f32 v103, -v173, v101, v103
	ds_read_b128 v[170:173], v54 offset:52528
	s_waitcnt lgkmcnt(11)
	v_fma_f32 v104, -v184, v98, v104
	v_fma_f32 v104, -v185, v99, v104
	v_fma_f32 v104, -v186, v100, v104
	v_fma_f32 v104, -v187, v101, v104
	ds_read_b128 v[184:187], v54 offset:52800
	s_waitcnt lgkmcnt(11)
	v_fma_f32 v105, -v122, v98, v105
	v_fma_f32 v105, -v123, v99, v105
	v_fma_f32 v105, -v124, v100, v105
	v_fma_f32 v105, -v125, v101, v105
	ds_read_b128 v[122:125], v54 offset:53072
	s_waitcnt lgkmcnt(11)
	v_fma_f32 v106, -v126, v98, v106
	v_fma_f32 v106, -v127, v99, v106
	v_fma_f32 v106, -v128, v100, v106
	v_fma_f32 v106, -v129, v101, v106
	ds_read_b128 v[126:129], v54 offset:53344
	s_waitcnt lgkmcnt(11)
	v_fma_f32 v107, -v130, v98, v107
	v_fma_f32 v107, -v131, v99, v107
	v_fma_f32 v107, -v132, v100, v107
	v_fma_f32 v107, -v133, v101, v107
	ds_read_b128 v[130:133], v54 offset:53616
	s_waitcnt lgkmcnt(11)
	v_fma_f32 v108, -v142, v98, v108
	v_fma_f32 v108, -v143, v99, v108
	v_fma_f32 v108, -v144, v100, v108
	v_fma_f32 v108, -v145, v101, v108
	ds_read_b128 v[142:145], v54 offset:53888
	s_waitcnt lgkmcnt(11)
	v_fma_f32 v109, -v146, v98, v109
	v_fma_f32 v109, -v147, v99, v109
	v_fma_f32 v109, -v148, v100, v109
	v_fma_f32 v109, -v149, v101, v109
	ds_read_b128 v[146:149], v54 offset:54160
	s_waitcnt lgkmcnt(11)
	v_fma_f32 v110, -v150, v98, v110
	v_fma_f32 v110, -v151, v99, v110
	v_fma_f32 v110, -v152, v100, v110
	v_fma_f32 v110, -v153, v101, v110
	ds_read_b128 v[150:153], v54 offset:49280
	s_waitcnt lgkmcnt(11)
	v_fma_f32 v111, -v154, v98, v111
	v_fma_f32 v111, -v155, v99, v111
	v_fma_f32 v111, -v156, v100, v111
	v_fma_f32 v111, -v157, v101, v111
	ds_read_b128 v[154:157], v54 offset:49552
	s_waitcnt lgkmcnt(11)
	v_fma_f32 v112, -v158, v98, v112
	v_fma_f32 v112, -v159, v99, v112
	v_fma_f32 v112, -v160, v100, v112
	v_fma_f32 v112, -v161, v101, v112
	ds_read_b128 v[158:161], v54 offset:49824
	s_waitcnt lgkmcnt(11)
	v_fma_f32 v113, -v162, v98, v113
	v_fma_f32 v113, -v163, v99, v113
	v_fma_f32 v113, -v164, v100, v113
	v_fma_f32 v113, -v165, v101, v113
	ds_read_b128 v[162:165], v54 offset:50096
	s_waitcnt lgkmcnt(11)
	v_fma_f32 v114, -v166, v98, v114
	v_fma_f32 v114, -v167, v99, v114
	v_fma_f32 v114, -v168, v100, v114
	v_fma_f32 v114, -v169, v101, v114
	ds_read_b128 v[166:169], v54 offset:50368
	s_waitcnt lgkmcnt(11)
	v_fma_f32 v115, -v170, v98, v115
	v_fma_f32 v115, -v171, v99, v115
	v_fma_f32 v115, -v172, v100, v115
	v_fma_f32 v115, -v173, v101, v115
	ds_read_b128 v[170:173], v54 offset:50640
	s_waitcnt lgkmcnt(11)
	v_fma_f32 v116, -v184, v98, v116
	v_fma_f32 v116, -v185, v99, v116
	v_fma_f32 v116, -v186, v100, v116
	v_fma_f32 v116, -v187, v101, v116
	ds_read_b128 v[184:187], v54 offset:50912
	s_waitcnt lgkmcnt(11)
	v_fma_f32 v117, -v122, v98, v117
	v_fma_f32 v117, -v123, v99, v117
	v_fma_f32 v117, -v124, v100, v117
	v_fma_f32 v117, -v125, v101, v117
	ds_read_b128 v[122:125], v54 offset:51184
	s_waitcnt lgkmcnt(11)
	v_fma_f32 v118, -v126, v98, v118
	v_fma_f32 v118, -v127, v99, v118
	v_fma_f32 v118, -v128, v100, v118
	v_fma_f32 v118, -v129, v101, v118
	ds_read_b128 v[126:129], v54 offset:51456
	s_waitcnt lgkmcnt(11)
	v_fma_f32 v119, -v130, v98, v119
	v_fma_f32 v119, -v131, v99, v119
	v_fma_f32 v119, -v132, v100, v119
	v_fma_f32 v119, -v133, v101, v119
	ds_read_b128 v[130:133], v54 offset:51728
	s_waitcnt lgkmcnt(11)
	v_fma_f32 v120, -v142, v98, v120
	v_fma_f32 v120, -v143, v99, v120
	v_fma_f32 v120, -v144, v100, v120
	v_fma_f32 v120, -v145, v101, v120
	ds_read_b128 v[142:145], v54 offset:52000
	s_waitcnt lgkmcnt(11)
	v_fma_f32 v121, -v146, v98, v121
	v_fma_f32 v121, -v147, v99, v121
	v_fma_f32 v121, -v148, v100, v121
	v_fma_f32 v121, -v149, v101, v121
	ds_read_b128 v[146:149], v54 offset:52272
	s_waitcnt lgkmcnt(11)
	v_fma_f32 v103, -v150, v102, v103
	ds_read_b128 v[150:153], v54 offset:52544
	s_waitcnt lgkmcnt(11)
	v_fma_f32 v104, -v154, v102, v104
	v_fma_f32 v104, -v155, v103, v104
	ds_read_b128 v[154:157], v54 offset:52816
	s_waitcnt lgkmcnt(11)
	v_fma_f32 v105, -v158, v102, v105
	v_fma_f32 v105, -v159, v103, v105
	v_fma_f32 v105, -v160, v104, v105
	ds_read_b128 v[158:161], v54 offset:53088
	s_waitcnt lgkmcnt(11)
	v_fma_f32 v106, -v162, v102, v106
	v_fma_f32 v106, -v163, v103, v106
	v_fma_f32 v106, -v164, v104, v106
	v_fma_f32 v106, -v165, v105, v106
	ds_read_b128 v[162:165], v54 offset:53360
	s_waitcnt lgkmcnt(11)
	v_fma_f32 v107, -v166, v102, v107
	v_fma_f32 v107, -v167, v103, v107
	v_fma_f32 v107, -v168, v104, v107
	v_fma_f32 v107, -v169, v105, v107
	ds_read_b128 v[166:169], v54 offset:53632
	s_waitcnt lgkmcnt(11)
	v_fma_f32 v108, -v170, v102, v108
	v_fma_f32 v108, -v171, v103, v108
	v_fma_f32 v108, -v172, v104, v108
	v_fma_f32 v108, -v173, v105, v108
	ds_read_b128 v[170:173], v54 offset:53904
	s_waitcnt lgkmcnt(11)
	v_fma_f32 v109, -v184, v102, v109
	v_fma_f32 v109, -v185, v103, v109
	v_fma_f32 v109, -v186, v104, v109
	v_fma_f32 v109, -v187, v105, v109
	ds_read_b128 v[184:187], v54 offset:54176
	s_waitcnt lgkmcnt(11)
	v_fma_f32 v110, -v122, v102, v110
	v_fma_f32 v110, -v123, v103, v110
	v_fma_f32 v110, -v124, v104, v110
	v_fma_f32 v110, -v125, v105, v110
	ds_read_b128 v[122:125], v54 offset:50384
	s_waitcnt lgkmcnt(11)
; __device__ __forceinline__ void gdn_chunk_item(const Params& p, int item, char* smem) {
;     ...
; #pragma unroll 2
;       for (int sg = 0; sg < b4; sg++) {
;         const float4 l0 = *(const float4*)&l0p[sg * 4], l1 = *(const float4*)&l0p[68 + sg * 4];
;         const float4 l2 = *(const float4*)&l0p[136 + sg * 4], l3 = *(const float4*)&l0p[204 + sg * 4];
;         const float* xp = xc + sg * 1024;
;         const float x0 = xp[0], x1 = xp[256], x2 = xp[512], x3 = xp[768];
;         a0 -= l0.x * x0; a0 -= l0.y * x1; a0 -= l0.z * x2; a0 -= l0.w * x3;
;         a1 -= l1.x * x0; a1 -= l1.y * x1; a1 -= l1.z * x2; a1 -= l1.w * x3;
;         a2 -= l2.x * x0; a2 -= l2.y * x1; a2 -= l2.z * x2; a2 -= l2.w * x3;
;         a3 -= l3.x * x0; a3 -= l3.y * x1; a3 -= l3.z * x2; a3 -= l3.w * x3;
;       }
;       const float4 d1 = *(const float4*)&l0p[68 + t0], d2 = *(const float4*)&l0p[136 + t0], d3 = *(const float4*)&l0p[204 + t0];
;       a1 -= d1.x * a0;
;       a2 -= d2.x * a0; a2 -= d2.y * a1;
;       a3 -= d3.x * a0; a3 -= d3.y * a1; a3 -= d3.z * a2;
	v_fma_f32 v111, -v126, v102, v111
	v_fma_f32 v111, -v127, v103, v111
	v_fma_f32 v111, -v128, v104, v111
	v_fma_f32 v111, -v129, v105, v111
	ds_read_b128 v[126:129], v54 offset:50656
	s_waitcnt lgkmcnt(11)
	v_fma_f32 v112, -v130, v102, v112
	v_fma_f32 v112, -v131, v103, v112
	v_fma_f32 v112, -v132, v104, v112
	v_fma_f32 v112, -v133, v105, v112
	ds_read_b128 v[130:133], v54 offset:50928
	s_waitcnt lgkmcnt(11)
	v_fma_f32 v113, -v142, v102, v113
	v_fma_f32 v113, -v143, v103, v113
	v_fma_f32 v113, -v144, v104, v113
	v_fma_f32 v113, -v145, v105, v113
	ds_read_b128 v[142:145], v54 offset:51200
	s_waitcnt lgkmcnt(11)
	v_fma_f32 v114, -v146, v102, v114
	v_fma_f32 v114, -v147, v103, v114
	v_fma_f32 v114, -v148, v104, v114
	v_fma_f32 v114, -v149, v105, v114
	ds_read_b128 v[146:149], v54 offset:51472
	s_waitcnt lgkmcnt(11)
	v_fma_f32 v115, -v150, v102, v115
	v_fma_f32 v115, -v151, v103, v115
	v_fma_f32 v115, -v152, v104, v115
	v_fma_f32 v115, -v153, v105, v115
	ds_read_b128 v[150:153], v54 offset:51744
	s_waitcnt lgkmcnt(11)
	v_fma_f32 v116, -v154, v102, v116
	v_fma_f32 v116, -v155, v103, v116
	v_fma_f32 v116, -v156, v104, v116
	v_fma_f32 v116, -v157, v105, v116
	ds_read_b128 v[154:157], v54 offset:52016
	s_waitcnt lgkmcnt(11)
	v_fma_f32 v117, -v158, v102, v117
	v_fma_f32 v117, -v159, v103, v117
	v_fma_f32 v117, -v160, v104, v117
	v_fma_f32 v117, -v161, v105, v117
	ds_read_b128 v[158:161], v54 offset:52288
	s_waitcnt lgkmcnt(11)
	v_fma_f32 v118, -v162, v102, v118
	v_fma_f32 v118, -v163, v103, v118
	v_fma_f32 v118, -v164, v104, v118
	v_fma_f32 v118, -v165, v105, v118
	ds_read_b128 v[162:165], v54 offset:52560
	s_waitcnt lgkmcnt(11)
	v_fma_f32 v119, -v166, v102, v119
	v_fma_f32 v119, -v167, v103, v119
	v_fma_f32 v119, -v168, v104, v119
	v_fma_f32 v119, -v169, v105, v119
	ds_read_b128 v[166:169], v54 offset:52832
	s_waitcnt lgkmcnt(11)
	v_fma_f32 v120, -v170, v102, v120
	v_fma_f32 v120, -v171, v103, v120
	v_fma_f32 v120, -v172, v104, v120
	v_fma_f32 v120, -v173, v105, v120
	ds_read_b128 v[170:173], v54 offset:53104
	s_waitcnt lgkmcnt(11)
	v_fma_f32 v121, -v184, v102, v121
	v_fma_f32 v121, -v185, v103, v121
	v_fma_f32 v121, -v186, v104, v121
	v_fma_f32 v121, -v187, v105, v121
	ds_read_b128 v[184:187], v54 offset:53376
	s_waitcnt lgkmcnt(11)
	v_fma_f32 v107, -v122, v106, v107
	ds_read_b128 v[122:125], v54 offset:53648
	s_waitcnt lgkmcnt(11)
	v_fma_f32 v108, -v126, v106, v108
	v_fma_f32 v108, -v127, v107, v108
	ds_read_b128 v[126:129], v54 offset:53920
	s_waitcnt lgkmcnt(11)
	v_fma_f32 v109, -v130, v106, v109
	v_fma_f32 v109, -v131, v107, v109
	v_fma_f32 v109, -v132, v108, v109
	ds_read_b128 v[130:133], v54 offset:54192
	s_waitcnt lgkmcnt(11)
	v_fma_f32 v110, -v142, v106, v110
	v_fma_f32 v110, -v143, v107, v110
	v_fma_f32 v110, -v144, v108, v110
	v_fma_f32 v110, -v145, v109, v110
	ds_read_b128 v[142:145], v54 offset:51488
	s_waitcnt lgkmcnt(11)
	v_fma_f32 v111, -v146, v106, v111
	v_fma_f32 v111, -v147, v107, v111
	v_fma_f32 v111, -v148, v108, v111
	v_fma_f32 v111, -v149, v109, v111
	ds_read_b128 v[146:149], v54 offset:51760
	s_waitcnt lgkmcnt(11)
	v_fma_f32 v112, -v150, v106, v112
	v_fma_f32 v112, -v151, v107, v112
	v_fma_f32 v112, -v152, v108, v112
	v_fma_f32 v112, -v153, v109, v112
	ds_read_b128 v[150:153], v54 offset:52032
	s_waitcnt lgkmcnt(11)
	v_fma_f32 v113, -v154, v106, v113
	v_fma_f32 v113, -v155, v107, v113
	v_fma_f32 v113, -v156, v108, v113
	v_fma_f32 v113, -v157, v109, v113
	ds_read_b128 v[154:157], v54 offset:52304
	s_waitcnt lgkmcnt(11)
	v_fma_f32 v114, -v158, v106, v114
	v_fma_f32 v114, -v159, v107, v114
	v_fma_f32 v114, -v160, v108, v114
	v_fma_f32 v114, -v161, v109, v114
	ds_read_b128 v[158:161], v54 offset:52576
	s_waitcnt lgkmcnt(11)
	v_fma_f32 v115, -v162, v106, v115
	v_fma_f32 v115, -v163, v107, v115
	v_fma_f32 v115, -v164, v108, v115
	v_fma_f32 v115, -v165, v109, v115
	ds_read_b128 v[162:165], v54 offset:52848
	s_waitcnt lgkmcnt(11)
	v_fma_f32 v116, -v166, v106, v116
	v_fma_f32 v116, -v167, v107, v116
	v_fma_f32 v116, -v168, v108, v116
	v_fma_f32 v116, -v169, v109, v116
	ds_read_b128 v[166:169], v54 offset:53120
	s_waitcnt lgkmcnt(11)
	v_fma_f32 v117, -v170, v106, v117
	v_fma_f32 v117, -v171, v107, v117
	v_fma_f32 v117, -v172, v108, v117
	v_fma_f32 v117, -v173, v109, v117
	ds_read_b128 v[170:173], v54 offset:53392
	s_waitcnt lgkmcnt(11)
	v_fma_f32 v118, -v184, v106, v118
	v_fma_f32 v118, -v185, v107, v118
	v_fma_f32 v118, -v186, v108, v118
	v_fma_f32 v118, -v187, v109, v118
	ds_read_b128 v[184:187], v54 offset:53664
	s_waitcnt lgkmcnt(11)
	v_fma_f32 v119, -v122, v106, v119
	v_fma_f32 v119, -v123, v107, v119
	v_fma_f32 v119, -v124, v108, v119
	v_fma_f32 v119, -v125, v109, v119
	ds_read_b128 v[122:125], v54 offset:53936
	s_waitcnt lgkmcnt(11)
	v_fma_f32 v120, -v126, v106, v120
	v_fma_f32 v120, -v127, v107, v120
	v_fma_f32 v120, -v128, v108, v120
	v_fma_f32 v120, -v129, v109, v120
	ds_read_b128 v[126:129], v54 offset:54208
	s_waitcnt lgkmcnt(11)
	v_fma_f32 v121, -v130, v106, v121
	v_fma_f32 v121, -v131, v107, v121
	v_fma_f32 v121, -v132, v108, v121
	v_fma_f32 v121, -v133, v109, v121
	ds_read_b128 v[130:133], v54 offset:52592
	s_waitcnt lgkmcnt(11)
; __device__ __forceinline__ void gdn_chunk_item(const Params& p, int item, char* smem) {
;     ...
;         a0 -= l0.x * x0; a0 -= l0.y * x1; a0 -= l0.z * x2; a0 -= l0.w * x3;
;         a1 -= l1.x * x0; a1 -= l1.y * x1; a1 -= l1.z * x2; a1 -= l1.w * x3;
;         a2 -= l2.x * x0; a2 -= l2.y * x1; a2 -= l2.z * x2; a2 -= l2.w * x3;
;         a3 -= l3.x * x0; a3 -= l3.y * x1; a3 -= l3.z * x2; a3 -= l3.w * x3;
;       }
;       const float4 d1 = *(const float4*)&l0p[68 + t0], d2 = *(const float4*)&l0p[136 + t0], d3 = *(const float4*)&l0p[204 + t0];
;       a1 -= d1.x * a0;
;       a2 -= d2.x * a0; a2 -= d2.y * a1;
;       a3 -= d3.x * a0; a3 -= d3.y * a1; a3 -= d3.z * a2;
;       xc[t0 * 256] = a0; xc[(t0 + 1) * 256] = a1; xc[(t0 + 2) * 256] = a2; xc[(t0 + 3) * 256] = a3;
	v_fma_f32 v111, -v142, v110, v111
	ds_read_b128 v[142:145], v54 offset:52864
	s_waitcnt lgkmcnt(11)
	v_fma_f32 v112, -v146, v110, v112
	v_fma_f32 v112, -v147, v111, v112
	ds_read_b128 v[146:149], v54 offset:53136
	s_waitcnt lgkmcnt(11)
	v_fma_f32 v113, -v150, v110, v113
	v_fma_f32 v113, -v151, v111, v113
	v_fma_f32 v113, -v152, v112, v113
	ds_read_b128 v[150:153], v54 offset:53408
	s_waitcnt lgkmcnt(11)
	v_fma_f32 v114, -v154, v110, v114
	v_fma_f32 v114, -v155, v111, v114
	v_fma_f32 v114, -v156, v112, v114
	v_fma_f32 v114, -v157, v113, v114
	ds_read_b128 v[154:157], v54 offset:53680
	s_waitcnt lgkmcnt(11)
	v_fma_f32 v115, -v158, v110, v115
	v_fma_f32 v115, -v159, v111, v115
	v_fma_f32 v115, -v160, v112, v115
	v_fma_f32 v115, -v161, v113, v115
	ds_read_b128 v[158:161], v54 offset:53952
	s_waitcnt lgkmcnt(11)
	v_fma_f32 v116, -v162, v110, v116
	v_fma_f32 v116, -v163, v111, v116
	v_fma_f32 v116, -v164, v112, v116
	v_fma_f32 v116, -v165, v113, v116
	ds_read_b128 v[162:165], v54 offset:54224
	s_waitcnt lgkmcnt(11)
	v_fma_f32 v117, -v166, v110, v117
	v_fma_f32 v117, -v167, v111, v117
	v_fma_f32 v117, -v168, v112, v117
	v_fma_f32 v117, -v169, v113, v117
	ds_read_b128 v[166:169], v54 offset:53696
	s_waitcnt lgkmcnt(11)
	v_fma_f32 v118, -v170, v110, v118
	v_fma_f32 v118, -v171, v111, v118
	v_fma_f32 v118, -v172, v112, v118
	v_fma_f32 v118, -v173, v113, v118
	ds_read_b128 v[170:173], v54 offset:53968
	s_waitcnt lgkmcnt(11)
	v_fma_f32 v119, -v184, v110, v119
	v_fma_f32 v119, -v185, v111, v119
	v_fma_f32 v119, -v186, v112, v119
	v_fma_f32 v119, -v187, v113, v119
	ds_read_b128 v[184:187], v54 offset:54240
	s_waitcnt lgkmcnt(11)
	v_fma_f32 v120, -v122, v110, v120
	v_fma_f32 v120, -v123, v111, v120
	v_fma_f32 v120, -v124, v112, v120
	v_fma_f32 v120, -v125, v113, v120
	s_waitcnt lgkmcnt(10)
	v_fma_f32 v121, -v126, v110, v121
	v_fma_f32 v121, -v127, v111, v121
	v_fma_f32 v121, -v128, v112, v121
	v_fma_f32 v121, -v129, v113, v121
	s_waitcnt lgkmcnt(9)
	v_fma_f32 v115, -v130, v114, v115
	s_waitcnt lgkmcnt(8)
	v_fma_f32 v116, -v142, v114, v116
	v_fma_f32 v116, -v143, v115, v116
	s_waitcnt lgkmcnt(7)
	v_fma_f32 v117, -v146, v114, v117
	v_fma_f32 v117, -v147, v115, v117
	v_fma_f32 v117, -v148, v116, v117
	s_waitcnt lgkmcnt(6)
	v_fma_f32 v118, -v150, v114, v118
	v_fma_f32 v118, -v151, v115, v118
	v_fma_f32 v118, -v152, v116, v118
	v_fma_f32 v118, -v153, v117, v118
	s_waitcnt lgkmcnt(5)
	v_fma_f32 v119, -v154, v114, v119
	v_fma_f32 v119, -v155, v115, v119
	v_fma_f32 v119, -v156, v116, v119
	v_fma_f32 v119, -v157, v117, v119
	s_waitcnt lgkmcnt(4)
	v_fma_f32 v120, -v158, v114, v120
	v_fma_f32 v120, -v159, v115, v120
	v_fma_f32 v120, -v160, v116, v120
	v_fma_f32 v120, -v161, v117, v120
	s_waitcnt lgkmcnt(3)
	v_fma_f32 v121, -v162, v114, v121
	v_fma_f32 v121, -v163, v115, v121
	v_fma_f32 v121, -v164, v116, v121
	v_fma_f32 v121, -v165, v117, v121
	s_waitcnt lgkmcnt(2)
	v_fma_f32 v119, -v166, v118, v119
	s_waitcnt lgkmcnt(1)
	v_fma_f32 v120, -v170, v118, v120
	v_fma_f32 v120, -v171, v119, v120
	s_waitcnt lgkmcnt(0)
	v_fma_f32 v121, -v184, v118, v121
	v_fma_f32 v121, -v185, v119, v121
	v_fma_f32 v121, -v186, v120, v121
	ds_write2st64_b32 v210, v58, v59 offset0:0 offset1:4
	ds_write2st64_b32 v210, v60, v61 offset0:8 offset1:12
	ds_write2st64_b32 v210, v62, v63 offset0:16 offset1:20
	ds_write2st64_b32 v210, v64, v65 offset0:24 offset1:28
	ds_write2st64_b32 v210, v66, v67 offset0:32 offset1:36
	ds_write2st64_b32 v210, v68, v69 offset0:40 offset1:44
	ds_write2st64_b32 v210, v70, v71 offset0:48 offset1:52
	ds_write2st64_b32 v210, v72, v73 offset0:56 offset1:60
	ds_write2st64_b32 v210, v74, v75 offset0:64 offset1:68
	ds_write2st64_b32 v210, v76, v77 offset0:72 offset1:76
	ds_write2st64_b32 v210, v78, v79 offset0:80 offset1:84
	ds_write2st64_b32 v210, v80, v81 offset0:88 offset1:92
	ds_write2st64_b32 v210, v82, v83 offset0:96 offset1:100
	ds_write2st64_b32 v210, v84, v85 offset0:104 offset1:108
	ds_write2st64_b32 v210, v86, v87 offset0:112 offset1:116
	ds_write2st64_b32 v210, v88, v89 offset0:120 offset1:124
	ds_write2st64_b32 v210, v90, v91 offset0:128 offset1:132
	ds_write2st64_b32 v210, v92, v93 offset0:136 offset1:140
	ds_write2st64_b32 v210, v94, v95 offset0:144 offset1:148
	ds_write2st64_b32 v210, v96, v97 offset0:152 offset1:156
	ds_write2st64_b32 v210, v98, v99 offset0:160 offset1:164
	ds_write2st64_b32 v210, v100, v101 offset0:168 offset1:172
	ds_write2st64_b32 v210, v102, v103 offset0:176 offset1:180
	ds_write2st64_b32 v210, v104, v105 offset0:184 offset1:188
	ds_write2st64_b32 v210, v106, v107 offset0:192 offset1:196
	ds_write2st64_b32 v210, v108, v109 offset0:200 offset1:204
	ds_write2st64_b32 v210, v110, v111 offset0:208 offset1:212
	ds_write2st64_b32 v210, v112, v113 offset0:216 offset1:220
	ds_write2st64_b32 v210, v114, v115 offset0:224 offset1:228
	ds_write2st64_b32 v210, v116, v117 offset0:232 offset1:236
	ds_write2st64_b32 v210, v118, v119 offset0:240 offset1:244
	ds_write2st64_b32 v210, v120, v121 offset0:248 offset1:252

; __device__ __forceinline__ u16 f2bf(float f) { return (u16)(pack2(f, f) & 0xffffu); }
; __device__ __forceinline__ int rowmap(int e, int lane) { return (e & 3) + 8 * (e >> 2) + 4 * (lane >> 5); }
; __device__ __forceinline__ void phase4c(const Params& p, char* smem) {
;     ...
; #pragma unroll
;     for (int i = 0; i < 2; i++)
; #pragma unroll
;       for (int j = 0; j < 2; j++)
; #pragma unroll
;         for (int e = 0; e < 16; e++) {
;           const int rl = wm * 64 + i * 32 + rowmap(e, lane);
;           const float rs = rsqrtf(SSQ1[m0 + rl] * (1.f / 1024.f) + EPSF);
;           Aq[rl * 136 + wn * 64 + j * 32 + r] = f2bf(acc[i][j][e] * rs);
;         }
; #pragma unroll
;     for (int q = 0; q < 8; q++) {
;       int idx = tid + 256 * q; int row = idx >> 4, ch = idx & 15;
;       *(uint4*)&Bk[row * 136 + ch * 8] = *(const uint4*)(KEYS + ((size_t)nt * 128 + row) * 128 + ch * 8);
;     }
.LBB0_1420:
	s_lshl_b32 s98, s2, 14
	v_add_u32_e32 v0, s20, v172
	v_ashrrev_i32_e32 v1, 31, v0
	v_lshl_add_u64 v[0:1], v[0:1], 2, s[94:95]
	global_load_dwordx4 a[196:199], v[0:1], off
	v_accvgpr_read_b32 v0, a137
	v_add_u32_e32 v0, s20, v0
	v_ashrrev_i32_e32 v1, 31, v0
	v_lshl_add_u64 v[0:1], v[0:1], 2, s[94:95]
	global_load_dwordx4 a[200:203], v[0:1], off
	v_accvgpr_read_b32 v0, a138
	v_add_u32_e32 v0, s20, v0
	v_ashrrev_i32_e32 v1, 31, v0
	v_lshl_add_u64 v[0:1], v[0:1], 2, s[94:95]
	global_load_dwordx4 a[204:207], v[0:1], off
	v_accvgpr_read_b32 v0, a139
	v_add_u32_e32 v0, s20, v0
	v_ashrrev_i32_e32 v1, 31, v0
	v_lshl_add_u64 v[0:1], v[0:1], 2, s[94:95]
	global_load_dwordx4 a[208:211], v[0:1], off
	v_accvgpr_read_b32 v0, a141
	v_add_u32_e32 v0, s20, v0
	v_ashrrev_i32_e32 v1, 31, v0
	v_lshl_add_u64 v[0:1], v[0:1], 2, s[94:95]
	global_load_dwordx4 a[212:215], v[0:1], off
	v_accvgpr_read_b32 v0, a144
	v_add_u32_e32 v0, s20, v0
	v_ashrrev_i32_e32 v1, 31, v0
	v_lshl_add_u64 v[0:1], v[0:1], 2, s[94:95]
	global_load_dwordx4 a[216:219], v[0:1], off
	v_add_u32_e32 v0, s20, v175
	v_ashrrev_i32_e32 v1, 31, v0
	v_lshl_add_u64 v[0:1], v[0:1], 2, s[94:95]
	global_load_dwordx4 a[220:223], v[0:1], off
	v_add_u32_e32 v0, s20, v39
	v_ashrrev_i32_e32 v1, 31, v0
	v_lshl_add_u64 v[0:1], v[0:1], 2, s[94:95]
	global_load_dwordx4 a[224:227], v[0:1], off
	v_accvgpr_read_b32 v8, a145
	v_or_b32_e32 v0, s98, v8
	v_lshlrev_b32_e32 v0, 1, v0
	v_mov_b32_e32 v1, 0
	v_lshl_add_u64 v[0:1], v[22:23], 0, v[0:1]
	global_load_dwordx4 a[228:231], v[0:1], off
	v_accvgpr_read_b32 v0, a135
	v_or_b32_e32 v0, s98, v0
	v_lshlrev_b32_e32 v0, 1, v0
	v_mov_b32_e32 v1, 0
	v_lshl_add_u64 v[0:1], v[22:23], 0, v[0:1]
	global_load_dwordx4 a[232:235], v[0:1], off
	v_accvgpr_read_b32 v0, a133
	v_or_b32_e32 v0, s98, v0
	v_lshlrev_b32_e32 v0, 1, v0
	v_mov_b32_e32 v1, 0
	v_lshl_add_u64 v[0:1], v[22:23], 0, v[0:1]
	global_load_dwordx4 a[236:239], v[0:1], off
	v_accvgpr_read_b32 v0, a149
	v_or_b32_e32 v0, s98, v0
	v_lshlrev_b32_e32 v0, 1, v0
	v_mov_b32_e32 v1, 0
	v_lshl_add_u64 v[0:1], v[22:23], 0, v[0:1]
	global_load_dwordx4 a[240:243], v[0:1], off
	v_or_b32_e32 v0, 0x2000, v8
	v_or_b32_e32 v0, s98, v0
	v_lshlrev_b32_e32 v0, 1, v0
	v_mov_b32_e32 v1, 0
	v_lshl_add_u64 v[0:1], v[22:23], 0, v[0:1]
	global_load_dwordx4 a[244:247], v[0:1], off
	v_accvgpr_read_b32 v0, a152
	v_add_lshl_u32 v0, s98, v0, 1
	v_mov_b32_e32 v1, 0
	v_lshl_add_u64 v[0:1], v[22:23], 0, v[0:1]
	global_load_dwordx4 a[248:251], v[0:1], off
	v_accvgpr_read_b32 v0, a154
	v_add_lshl_u32 v0, s98, v0, 1
	v_mov_b32_e32 v1, 0
	v_lshl_add_u64 v[0:1], v[22:23], 0, v[0:1]
	global_load_dwordx4 a[252:255], v[0:1], off
	s_waitcnt vmcnt(0)
	v_accvgpr_read_b32 v0, a196
	v_accvgpr_read_b32 v1, a197
	v_accvgpr_read_b32 v2, a198
	v_accvgpr_read_b32 v3, a199
	v_mov_b64_e32 v[56:57], s[18:19]
	v_accvgpr_read_b32 v194, a48
	v_accvgpr_read_b32 v193, a49
	v_accvgpr_read_b32 v192, a50
	v_accvgpr_read_b32 v191, a51
	v_accvgpr_read_b32 v190, a52
	v_accvgpr_read_b32 v189, a53
	v_accvgpr_read_b32 v188, a54
	v_accvgpr_read_b32 v135, a55
	v_accvgpr_read_b32 v187, a56
	v_accvgpr_read_b32 v137, a57
	v_accvgpr_read_b32 v186, a58
	v_accvgpr_read_b32 v185, a59
	v_accvgpr_read_b32 v184, a60
	v_accvgpr_read_b32 v183, a61
	v_accvgpr_read_b32 v182, a62
	v_accvgpr_read_b32 v253, a63
	v_accvgpr_read_b32 v252, a32
	v_accvgpr_read_b32 v251, a33
	v_accvgpr_read_b32 v250, a34
	v_accvgpr_read_b32 v249, a35
	v_accvgpr_read_b32 v248, a36
	v_accvgpr_read_b32 v247, a37
	v_accvgpr_read_b32 v246, a38
	v_accvgpr_read_b32 v245, a39
	v_accvgpr_read_b32 v244, a40
	v_accvgpr_read_b32 v243, a41
	v_accvgpr_read_b32 v242, a42
	v_accvgpr_read_b32 v241, a43
	v_accvgpr_read_b32 v240, a44
	v_accvgpr_read_b32 v237, a45
	v_accvgpr_read_b32 v236, a46
	v_accvgpr_read_b32 v115, a47
	v_accvgpr_read_b32 v114, a16
	v_accvgpr_read_b32 v113, a17
	v_accvgpr_read_b32 v112, a18
	v_accvgpr_read_b32 v111, a19
	v_accvgpr_read_b32 v110, a20
	v_accvgpr_read_b32 v109, a21
	v_accvgpr_read_b32 v108, a22
	v_accvgpr_read_b32 v107, a23
	v_accvgpr_read_b32 v106, a24
	v_accvgpr_read_b32 v105, a25
	v_accvgpr_read_b32 v104, a26
	v_accvgpr_read_b32 v103, a27
	v_accvgpr_read_b32 v102, a28
	v_accvgpr_read_b32 v101, a29
	v_accvgpr_read_b32 v100, a30
	v_accvgpr_read_b32 v99, a31
	v_accvgpr_read_b32 v98, a0
	v_accvgpr_read_b32 v97, a1
	v_accvgpr_read_b32 v96, a2
	v_accvgpr_read_b32 v95, a3
	v_accvgpr_read_b32 v94, a4
	v_accvgpr_read_b32 v93, a5
	v_accvgpr_read_b32 v92, a6
	v_accvgpr_read_b32 v91, a7
	v_accvgpr_read_b32 v90, a8
	v_accvgpr_read_b32 v89, a9
	v_accvgpr_read_b32 v88, a10
	v_accvgpr_read_b32 v87, a11
	v_accvgpr_read_b32 v86, a12
	v_accvgpr_read_b32 v85, a13
	v_accvgpr_read_b32 v84, a14
	v_accvgpr_read_b32 v6, a15
	v_pk_fma_f32 v[0:1], v[0:1], s[16:17], v[56:57] op_sel_hi:[1,0,0]
	s_nop 0
	v_mul_f32_e32 v8, 0x4b800000, v0
	v_cmp_gt_f32_e64 s[0:1], s26, v0
	v_cmp_gt_f32_e32 vcc, s26, v1
	s_nop 0
	v_cndmask_b32_e64 v0, v0, v8, s[0:1]
	v_rsq_f32_e32 v0, v0
	s_nop 0
	v_mul_f32_e32 v8, 0x45800000, v0
	v_cndmask_b32_e64 v58, v0, v8, s[0:1]
	v_mul_f32_e32 v0, v194, v58
	v_cvt_pk_bf16_f32 v0, v0, s0
	ds_write_b16 v204, v0
	v_mul_f32_e32 v0, 0x4b800000, v1
	v_cndmask_b32_e32 v0, v1, v0, vcc
	v_rsq_f32_e32 v0, v0
	s_nop 0
	v_mul_f32_e32 v1, 0x45800000, v0
	v_cndmask_b32_e32 v59, v0, v1, vcc
	v_mul_f32_e32 v0, v193, v59
	v_cvt_pk_bf16_f32 v0, v0, s0
	ds_write_b16 v205, v0
	v_pk_fma_f32 v[0:1], v[2:3], s[16:17], v[56:57] op_sel_hi:[1,0,0]
	s_nop 0
	v_mul_f32_e32 v2, 0x4b800000, v0
	v_cmp_gt_f32_e64 s[0:1], s26, v0
	v_cmp_gt_f32_e32 vcc, s26, v1
	s_nop 0
	v_cndmask_b32_e64 v0, v0, v2, s[0:1]
	v_rsq_f32_e32 v0, v0
	s_nop 0
; __device__ __forceinline__ u16 f2bf(float f) { return (u16)(pack2(f, f) & 0xffffu); }
; __device__ __forceinline__ int rowmap(int e, int lane) { return (e & 3) + 8 * (e >> 2) + 4 * (lane >> 5); }
; __device__ __forceinline__ void phase4c(const Params& p, char* smem) {
;     ...
;         for (int e = 0; e < 16; e++) {
;           const int rl = wm * 64 + i * 32 + rowmap(e, lane);
;           const float rs = rsqrtf(SSQ1[m0 + rl] * (1.f / 1024.f) + EPSF);
;           Aq[rl * 136 + wn * 64 + j * 32 + r] = f2bf(acc[i][j][e] * rs);
	v_mul_f32_e32 v2, 0x45800000, v0
	v_cndmask_b32_e64 v60, v0, v2, s[0:1]
	v_mul_f32_e32 v0, v192, v60
	v_cvt_pk_bf16_f32 v0, v0, s0
	ds_write_b16 v206, v0
	v_mul_f32_e32 v0, 0x4b800000, v1
	v_cndmask_b32_e32 v0, v1, v0, vcc
	v_rsq_f32_e32 v0, v0
	s_nop 0
	v_mul_f32_e32 v1, 0x45800000, v0
	v_cndmask_b32_e32 v61, v0, v1, vcc
	v_mul_f32_e32 v0, v191, v61
	v_cvt_pk_bf16_f32 v0, v0, s0
	ds_write_b16 v207, v0
	v_accvgpr_read_b32 v0, a200
	v_accvgpr_read_b32 v1, a201
	v_accvgpr_read_b32 v2, a202
	v_accvgpr_read_b32 v3, a203
	v_pk_fma_f32 v[0:1], v[0:1], s[16:17], v[56:57] op_sel_hi:[1,0,0]
	s_nop 0
	v_mul_f32_e32 v8, 0x4b800000, v0
	v_cmp_gt_f32_e64 s[0:1], s26, v0
	v_cmp_gt_f32_e32 vcc, s26, v1
	s_nop 0
	v_cndmask_b32_e64 v0, v0, v8, s[0:1]
	v_rsq_f32_e32 v0, v0
	s_nop 0
	v_mul_f32_e32 v8, 0x45800000, v0
	v_cndmask_b32_e64 v62, v0, v8, s[0:1]
	v_mul_f32_e32 v0, v190, v62
	v_cvt_pk_bf16_f32 v0, v0, s0
	ds_write_b16 v208, v0
	v_mul_f32_e32 v0, 0x4b800000, v1
	v_cndmask_b32_e32 v0, v1, v0, vcc
	v_rsq_f32_e32 v0, v0
	s_nop 0
	v_mul_f32_e32 v1, 0x45800000, v0
	v_cndmask_b32_e32 v63, v0, v1, vcc
	v_mul_f32_e32 v0, v189, v63
	v_cvt_pk_bf16_f32 v0, v0, s0
	ds_write_b16 v209, v0
	v_pk_fma_f32 v[0:1], v[2:3], s[16:17], v[56:57] op_sel_hi:[1,0,0]
	s_nop 0
	v_mul_f32_e32 v2, 0x4b800000, v0
	v_cmp_gt_f32_e64 s[0:1], s26, v0
	v_cmp_gt_f32_e32 vcc, s26, v1
	s_nop 0
	v_cndmask_b32_e64 v0, v0, v2, s[0:1]
	v_rsq_f32_e32 v0, v0
	s_nop 0
	v_mul_f32_e32 v2, 0x45800000, v0
	v_cndmask_b32_e64 v64, v0, v2, s[0:1]
	v_mul_f32_e32 v0, v188, v64
	v_cvt_pk_bf16_f32 v0, v0, s0
	ds_write_b16 v210, v0
	v_mul_f32_e32 v0, 0x4b800000, v1
	v_cndmask_b32_e32 v0, v1, v0, vcc
	v_rsq_f32_e32 v0, v0
	s_nop 0
	v_mul_f32_e32 v1, 0x45800000, v0
	v_cndmask_b32_e32 v65, v0, v1, vcc
	v_mul_f32_e32 v0, v135, v65
	v_cvt_pk_bf16_f32 v0, v0, s0
	ds_write_b16 v211, v0
	v_accvgpr_read_b32 v0, a204
	v_accvgpr_read_b32 v1, a205
	v_accvgpr_read_b32 v2, a206
	v_accvgpr_read_b32 v3, a207
	v_pk_fma_f32 v[0:1], v[0:1], s[16:17], v[56:57] op_sel_hi:[1,0,0]
	s_nop 0
	v_mul_f32_e32 v8, 0x4b800000, v0
	v_cmp_gt_f32_e64 s[0:1], s26, v0
	v_cmp_gt_f32_e32 vcc, s26, v1
	s_nop 0
	v_cndmask_b32_e64 v0, v0, v8, s[0:1]
	v_rsq_f32_e32 v0, v0
	s_nop 0
	v_mul_f32_e32 v8, 0x45800000, v0
	v_cndmask_b32_e64 v66, v0, v8, s[0:1]
	v_mul_f32_e32 v0, v187, v66
	v_cvt_pk_bf16_f32 v0, v0, s0
	ds_write_b16 v212, v0
	v_mul_f32_e32 v0, 0x4b800000, v1
	v_cndmask_b32_e32 v0, v1, v0, vcc
	v_rsq_f32_e32 v0, v0
	s_nop 0
	v_mul_f32_e32 v1, 0x45800000, v0
	v_cndmask_b32_e32 v67, v0, v1, vcc
	v_mul_f32_e32 v0, v137, v67
	v_cvt_pk_bf16_f32 v0, v0, s0
	ds_write_b16 v213, v0
	v_pk_fma_f32 v[0:1], v[2:3], s[16:17], v[56:57] op_sel_hi:[1,0,0]
	s_nop 0
	v_mul_f32_e32 v2, 0x4b800000, v0
	v_cmp_gt_f32_e64 s[0:1], s26, v0
	v_cmp_gt_f32_e32 vcc, s26, v1
	s_nop 0
	v_cndmask_b32_e64 v0, v0, v2, s[0:1]
	v_rsq_f32_e32 v0, v0
	s_nop 0
	v_mul_f32_e32 v2, 0x45800000, v0
	v_cndmask_b32_e64 v68, v0, v2, s[0:1]
	v_mul_f32_e32 v0, v186, v68
	v_cvt_pk_bf16_f32 v0, v0, s0
	ds_write_b16 v214, v0
	v_mul_f32_e32 v0, 0x4b800000, v1
	v_cndmask_b32_e32 v0, v1, v0, vcc
	v_rsq_f32_e32 v0, v0
	s_nop 0
	v_mul_f32_e32 v1, 0x45800000, v0
	v_cndmask_b32_e32 v69, v0, v1, vcc
	v_mul_f32_e32 v0, v185, v69
	v_cvt_pk_bf16_f32 v0, v0, s0
	ds_write_b16 v215, v0
	v_accvgpr_read_b32 v0, a208
	v_accvgpr_read_b32 v1, a209
	v_accvgpr_read_b32 v2, a210
	v_accvgpr_read_b32 v3, a211
	v_pk_fma_f32 v[0:1], v[0:1], s[16:17], v[56:57] op_sel_hi:[1,0,0]
	s_nop 0
	v_mul_f32_e32 v8, 0x4b800000, v0
	v_cmp_gt_f32_e64 s[0:1], s26, v0
	v_cmp_gt_f32_e32 vcc, s26, v1
	s_nop 0
	v_cndmask_b32_e64 v0, v0, v8, s[0:1]
	v_rsq_f32_e32 v0, v0
	s_nop 0
	v_mul_f32_e32 v8, 0x45800000, v0
	v_cndmask_b32_e64 v8, v0, v8, s[0:1]
	v_mul_f32_e32 v0, v184, v8
	v_cvt_pk_bf16_f32 v0, v0, s0
	ds_write_b16 v216, v0
	v_mul_f32_e32 v0, 0x4b800000, v1
	v_cndmask_b32_e32 v0, v1, v0, vcc
	v_rsq_f32_e32 v0, v0
	s_nop 0
	v_mul_f32_e32 v1, 0x45800000, v0
	v_cndmask_b32_e32 v9, v0, v1, vcc
	v_mul_f32_e32 v0, v183, v9
	v_cvt_pk_bf16_f32 v0, v0, s0
	ds_write_b16 v217, v0
	v_pk_fma_f32 v[0:1], v[2:3], s[16:17], v[56:57] op_sel_hi:[1,0,0]
	s_nop 0
	v_mul_f32_e32 v2, 0x4b800000, v0
	v_cmp_gt_f32_e64 s[0:1], s26, v0
	v_cmp_gt_f32_e32 vcc, s26, v1
	s_nop 0
	v_cndmask_b32_e64 v0, v0, v2, s[0:1]
	v_rsq_f32_e32 v0, v0
	s_nop 0
	v_mul_f32_e32 v2, 0x45800000, v0
	v_cndmask_b32_e64 v0, v0, v2, s[0:1]
	v_mul_f32_e32 v2, v182, v0
	v_cvt_pk_bf16_f32 v2, v2, s0
	ds_write_b16 v218, v2
	v_mul_f32_e32 v2, 0x4b800000, v1
	v_cndmask_b32_e32 v1, v1, v2, vcc
	v_rsq_f32_e32 v1, v1
	v_mul_f32_e32 v0, v236, v0
	v_cvt_pk_bf16_f32 v0, v0, s0
	v_mul_f32_e32 v2, 0x45800000, v1
	v_cndmask_b32_e32 v1, v1, v2, vcc
	v_mul_f32_e32 v2, v253, v1
	v_cvt_pk_bf16_f32 v2, v2, s0
	ds_write_b16 v219, v2
	v_mul_f32_e32 v2, v252, v58
	v_cvt_pk_bf16_f32 v2, v2, s0
	ds_write_b16 v204, v2 offset:64
	v_mul_f32_e32 v2, v251, v59
	v_cvt_pk_bf16_f32 v2, v2, s0
	ds_write_b16 v205, v2 offset:64
	v_mul_f32_e32 v2, v250, v60
	v_cvt_pk_bf16_f32 v2, v2, s0
	ds_write_b16 v206, v2 offset:64
	v_mul_f32_e32 v2, v249, v61
	v_cvt_pk_bf16_f32 v2, v2, s0
	ds_write_b16 v207, v2 offset:64
	v_mul_f32_e32 v2, v248, v62
	v_cvt_pk_bf16_f32 v2, v2, s0
	ds_write_b16 v208, v2 offset:64
	v_mul_f32_e32 v2, v247, v63
	v_cvt_pk_bf16_f32 v2, v2, s0
	ds_write_b16 v209, v2 offset:64
	v_mul_f32_e32 v2, v246, v64
	v_cvt_pk_bf16_f32 v2, v2, s0
	ds_write_b16 v210, v2 offset:64
	v_mul_f32_e32 v2, v245, v65
	v_cvt_pk_bf16_f32 v2, v2, s0
	ds_write_b16 v211, v2 offset:64
	v_mul_f32_e32 v2, v244, v66
	v_cvt_pk_bf16_f32 v2, v2, s0
	ds_write_b16 v212, v2 offset:64
	v_mul_f32_e32 v2, v243, v67
	v_cvt_pk_bf16_f32 v2, v2, s0
; __device__ __forceinline__ u16 f2bf(float f) { return (u16)(pack2(f, f) & 0xffffu); }
; __device__ __forceinline__ int rowmap(int e, int lane) { return (e & 3) + 8 * (e >> 2) + 4 * (lane >> 5); }
; __device__ __forceinline__ void phase4c(const Params& p, char* smem) {
;     ...
;         for (int e = 0; e < 16; e++) {
;           const int rl = wm * 64 + i * 32 + rowmap(e, lane);
;           const float rs = rsqrtf(SSQ1[m0 + rl] * (1.f / 1024.f) + EPSF);
;           Aq[rl * 136 + wn * 64 + j * 32 + r] = f2bf(acc[i][j][e] * rs);
	ds_write_b16 v213, v2 offset:64
	v_mul_f32_e32 v2, v242, v68
	v_cvt_pk_bf16_f32 v2, v2, s0
	ds_write_b16 v214, v2 offset:64
	v_mul_f32_e32 v2, v241, v69
	v_cvt_pk_bf16_f32 v2, v2, s0
	ds_write_b16 v215, v2 offset:64
	v_mul_f32_e32 v2, v240, v8
	v_cvt_pk_bf16_f32 v2, v2, s0
	ds_write_b16 v216, v2 offset:64
	v_mul_f32_e32 v2, v237, v9
	v_cvt_pk_bf16_f32 v2, v2, s0
	ds_write_b16 v217, v2 offset:64
	ds_write_b16 v218, v0 offset:64
	v_mul_f32_e32 v0, v115, v1
	v_cvt_pk_bf16_f32 v0, v0, s0
	ds_write_b16 v219, v0 offset:64
	v_accvgpr_read_b32 v0, a212
	v_accvgpr_read_b32 v1, a213
	v_accvgpr_read_b32 v2, a214
	v_accvgpr_read_b32 v3, a215
	v_pk_fma_f32 v[0:1], v[0:1], s[16:17], v[56:57] op_sel_hi:[1,0,0]
	s_nop 0
	v_mul_f32_e32 v8, 0x4b800000, v0
	v_cmp_gt_f32_e64 s[0:1], s26, v0
	v_cmp_gt_f32_e32 vcc, s26, v1
	s_nop 0
	v_cndmask_b32_e64 v0, v0, v8, s[0:1]
	v_rsq_f32_e32 v0, v0
	s_nop 0
	v_mul_f32_e32 v8, 0x45800000, v0
	v_cndmask_b32_e64 v58, v0, v8, s[0:1]
	v_mul_f32_e32 v0, v114, v58
	v_cvt_pk_bf16_f32 v0, v0, s0
	ds_write_b16 v220, v0
	v_mul_f32_e32 v0, 0x4b800000, v1
	v_cndmask_b32_e32 v0, v1, v0, vcc
	v_rsq_f32_e32 v0, v0
	s_nop 0
	v_mul_f32_e32 v1, 0x45800000, v0
	v_cndmask_b32_e32 v59, v0, v1, vcc
	v_mul_f32_e32 v0, v113, v59
	v_cvt_pk_bf16_f32 v0, v0, s0
	ds_write_b16 v221, v0
	v_pk_fma_f32 v[0:1], v[2:3], s[16:17], v[56:57] op_sel_hi:[1,0,0]
	s_nop 0
	v_mul_f32_e32 v2, 0x4b800000, v0
	v_cmp_gt_f32_e64 s[0:1], s26, v0
	v_cmp_gt_f32_e32 vcc, s26, v1
	s_nop 0
	v_cndmask_b32_e64 v0, v0, v2, s[0:1]
	v_rsq_f32_e32 v0, v0
	s_nop 0
	v_mul_f32_e32 v2, 0x45800000, v0
	v_cndmask_b32_e64 v60, v0, v2, s[0:1]
	v_mul_f32_e32 v0, v112, v60
	v_cvt_pk_bf16_f32 v0, v0, s0
	ds_write_b16 v222, v0
	v_mul_f32_e32 v0, 0x4b800000, v1
	v_cndmask_b32_e32 v0, v1, v0, vcc
	v_rsq_f32_e32 v0, v0
	s_nop 0
	v_mul_f32_e32 v1, 0x45800000, v0
	v_cndmask_b32_e32 v61, v0, v1, vcc
	v_mul_f32_e32 v0, v111, v61
	v_cvt_pk_bf16_f32 v0, v0, s0
	ds_write_b16 v223, v0
	v_accvgpr_read_b32 v0, a216
	v_accvgpr_read_b32 v1, a217
	v_accvgpr_read_b32 v2, a218
	v_accvgpr_read_b32 v3, a219
	v_pk_fma_f32 v[0:1], v[0:1], s[16:17], v[56:57] op_sel_hi:[1,0,0]
	s_nop 0
	v_mul_f32_e32 v8, 0x4b800000, v0
	v_cmp_gt_f32_e64 s[0:1], s26, v0
	v_cmp_gt_f32_e32 vcc, s26, v1
	s_nop 0
	v_cndmask_b32_e64 v0, v0, v8, s[0:1]
	v_rsq_f32_e32 v0, v0
	s_nop 0
	v_mul_f32_e32 v8, 0x45800000, v0
	v_cndmask_b32_e64 v62, v0, v8, s[0:1]
	v_mul_f32_e32 v0, v110, v62
	v_cvt_pk_bf16_f32 v0, v0, s0
	ds_write_b16 v224, v0
	v_mul_f32_e32 v0, 0x4b800000, v1
	v_cndmask_b32_e32 v0, v1, v0, vcc
	v_rsq_f32_e32 v0, v0
	s_nop 0
	v_mul_f32_e32 v1, 0x45800000, v0
	v_cndmask_b32_e32 v63, v0, v1, vcc
	v_mul_f32_e32 v0, v109, v63
	v_cvt_pk_bf16_f32 v0, v0, s0
	ds_write_b16 v225, v0
	v_pk_fma_f32 v[0:1], v[2:3], s[16:17], v[56:57] op_sel_hi:[1,0,0]
	s_nop 0
	v_mul_f32_e32 v2, 0x4b800000, v0
	v_cmp_gt_f32_e64 s[0:1], s26, v0
	v_cmp_gt_f32_e32 vcc, s26, v1
	s_nop 0
	v_cndmask_b32_e64 v0, v0, v2, s[0:1]
	v_rsq_f32_e32 v0, v0
	s_nop 0
	v_mul_f32_e32 v2, 0x45800000, v0
	v_cndmask_b32_e64 v64, v0, v2, s[0:1]
	v_mul_f32_e32 v0, v108, v64
	v_cvt_pk_bf16_f32 v0, v0, s0
	ds_write_b16 v226, v0
	v_mul_f32_e32 v0, 0x4b800000, v1
	v_cndmask_b32_e32 v0, v1, v0, vcc
	v_rsq_f32_e32 v0, v0
	s_nop 0
	v_mul_f32_e32 v1, 0x45800000, v0
	v_cndmask_b32_e32 v65, v0, v1, vcc
	v_mul_f32_e32 v0, v107, v65
	v_cvt_pk_bf16_f32 v0, v0, s0
	ds_write_b16 v227, v0
	v_accvgpr_read_b32 v0, a220
	v_accvgpr_read_b32 v1, a221
	v_accvgpr_read_b32 v2, a222
	v_accvgpr_read_b32 v3, a223
	v_pk_fma_f32 v[0:1], v[0:1], s[16:17], v[56:57] op_sel_hi:[1,0,0]
	s_nop 0
	v_mul_f32_e32 v8, 0x4b800000, v0
	v_cmp_gt_f32_e64 s[0:1], s26, v0
	v_cmp_gt_f32_e32 vcc, s26, v1
	s_nop 0
	v_cndmask_b32_e64 v0, v0, v8, s[0:1]
	v_rsq_f32_e32 v0, v0
	s_nop 0
	v_mul_f32_e32 v8, 0x45800000, v0
	v_cndmask_b32_e64 v66, v0, v8, s[0:1]
	v_mul_f32_e32 v0, v106, v66
	v_cvt_pk_bf16_f32 v0, v0, s0
	ds_write_b16 v228, v0
	v_mul_f32_e32 v0, 0x4b800000, v1
	v_cndmask_b32_e32 v0, v1, v0, vcc
	v_rsq_f32_e32 v0, v0
	s_nop 0
	v_mul_f32_e32 v1, 0x45800000, v0
	v_cndmask_b32_e32 v67, v0, v1, vcc
	v_mul_f32_e32 v0, v105, v67
	v_cvt_pk_bf16_f32 v0, v0, s0
	ds_write_b16 v229, v0
	v_pk_fma_f32 v[0:1], v[2:3], s[16:17], v[56:57] op_sel_hi:[1,0,0]
	s_nop 0
	v_mul_f32_e32 v2, 0x4b800000, v0
	v_cmp_gt_f32_e64 s[0:1], s26, v0
	v_cmp_gt_f32_e32 vcc, s26, v1
	s_nop 0
	v_cndmask_b32_e64 v0, v0, v2, s[0:1]
	v_rsq_f32_e32 v0, v0
	s_nop 0
	v_mul_f32_e32 v2, 0x45800000, v0
	v_cndmask_b32_e64 v68, v0, v2, s[0:1]
	v_mul_f32_e32 v0, v104, v68
	v_cvt_pk_bf16_f32 v0, v0, s0
	ds_write_b16 v230, v0
	v_mul_f32_e32 v0, 0x4b800000, v1
	v_cndmask_b32_e32 v0, v1, v0, vcc
	v_rsq_f32_e32 v0, v0
	s_nop 0
	v_mul_f32_e32 v1, 0x45800000, v0
	v_cndmask_b32_e32 v69, v0, v1, vcc
	v_mul_f32_e32 v0, v103, v69
	v_cvt_pk_bf16_f32 v0, v0, s0
	ds_write_b16 v231, v0
	v_accvgpr_read_b32 v0, a224
	v_accvgpr_read_b32 v1, a225
	v_accvgpr_read_b32 v2, a226
	v_accvgpr_read_b32 v3, a227
	v_pk_fma_f32 v[0:1], v[0:1], s[16:17], v[56:57] op_sel_hi:[1,0,0]
	s_nop 0
	v_mul_f32_e32 v8, 0x4b800000, v0
	v_cmp_gt_f32_e64 s[0:1], s26, v0
	v_cmp_gt_f32_e32 vcc, s26, v1
	s_nop 0
	v_cndmask_b32_e64 v0, v0, v8, s[0:1]
	v_rsq_f32_e32 v0, v0
	s_nop 0
	v_mul_f32_e32 v8, 0x45800000, v0
	v_cndmask_b32_e64 v8, v0, v8, s[0:1]
	v_mul_f32_e32 v0, v102, v8
	v_cvt_pk_bf16_f32 v0, v0, s0
	ds_write_b16 v232, v0
	v_mul_f32_e32 v0, 0x4b800000, v1
	v_cndmask_b32_e32 v0, v1, v0, vcc
	v_rsq_f32_e32 v0, v0
	s_nop 0
	v_mul_f32_e32 v1, 0x45800000, v0
	v_cndmask_b32_e32 v9, v0, v1, vcc
	v_mul_f32_e32 v0, v101, v9
	v_cvt_pk_bf16_f32 v0, v0, s0
	ds_write_b16 v233, v0
	v_pk_fma_f32 v[0:1], v[2:3], s[16:17], v[56:57] op_sel_hi:[1,0,0]
; __device__ __forceinline__ u16 f2bf(float f) { return (u16)(pack2(f, f) & 0xffffu); }
; __device__ __forceinline__ int rowmap(int e, int lane) { return (e & 3) + 8 * (e >> 2) + 4 * (lane >> 5); }
; __device__ __forceinline__ void phase4c(const Params& p, char* smem) {
;     ...
;         for (int e = 0; e < 16; e++) {
;           const int rl = wm * 64 + i * 32 + rowmap(e, lane);
;           const float rs = rsqrtf(SSQ1[m0 + rl] * (1.f / 1024.f) + EPSF);
;           Aq[rl * 136 + wn * 64 + j * 32 + r] = f2bf(acc[i][j][e] * rs);
;         }
; #pragma unroll
;     for (int q = 0; q < 8; q++) {
;       int idx = tid + 256 * q; int row = idx >> 4, ch = idx & 15;
;       *(uint4*)&Bk[row * 136 + ch * 8] = *(const uint4*)(KEYS + ((size_t)nt * 128 + row) * 128 + ch * 8);
;     }
;     __syncthreads();
;     zero_acc(acc);
; #pragma unroll
;     for (int ks = 0; ks < 8; ks++) {
;       bf16x8 a[2], bq[2];
; #pragma unroll
;       for (int i = 0; i < 2; i++) a[i] = *(const bf16x8*)&Aq[(wm * 64 + i * 32 + r) * 136 + ks * 16 + hh];
; #pragma unroll
;       for (int j = 0; j < 2; j++) bq[j] = *(const bf16x8*)&Bk[(wn * 64 + j * 32 + r) * 136 + ks * 16 + hh];
; #pragma unroll
;       for (int i = 0; i < 2; i++)
; #pragma unroll
;         for (int j = 0; j < 2; j++) acc[i][j] = mfma16(a[i], bq[j], acc[i][j]);
;     }
	s_nop 0
	v_mul_f32_e32 v2, 0x4b800000, v0
	v_cmp_gt_f32_e64 s[0:1], s26, v0
	v_cmp_gt_f32_e32 vcc, s26, v1
	s_nop 0
	v_cndmask_b32_e64 v0, v0, v2, s[0:1]
	v_rsq_f32_e32 v0, v0
	s_nop 0
	v_mul_f32_e32 v2, 0x45800000, v0
	v_cndmask_b32_e64 v0, v0, v2, s[0:1]
	v_mul_f32_e32 v2, v100, v0
	v_cvt_pk_bf16_f32 v2, v2, s0
	ds_write_b16 v234, v2
	v_mul_f32_e32 v2, 0x4b800000, v1
	v_cndmask_b32_e32 v1, v1, v2, vcc
	v_rsq_f32_e32 v1, v1
	v_mul_f32_e32 v0, v84, v0
	v_cvt_pk_bf16_f32 v0, v0, s0
	v_mul_f32_e32 v2, 0x45800000, v1
	v_cndmask_b32_e32 v1, v1, v2, vcc
	v_mul_f32_e32 v2, v99, v1
	v_cvt_pk_bf16_f32 v2, v2, s0
	ds_write_b16 v235, v2
	v_mul_f32_e32 v2, v98, v58
	v_cvt_pk_bf16_f32 v2, v2, s0
	ds_write_b16 v220, v2 offset:64
	v_mul_f32_e32 v2, v97, v59
	v_cvt_pk_bf16_f32 v2, v2, s0
	ds_write_b16 v221, v2 offset:64
	v_mul_f32_e32 v2, v96, v60
	v_cvt_pk_bf16_f32 v2, v2, s0
	ds_write_b16 v222, v2 offset:64
	v_mul_f32_e32 v2, v95, v61
	v_cvt_pk_bf16_f32 v2, v2, s0
	ds_write_b16 v223, v2 offset:64
	v_mul_f32_e32 v2, v94, v62
	v_cvt_pk_bf16_f32 v2, v2, s0
	ds_write_b16 v224, v2 offset:64
	v_mul_f32_e32 v2, v93, v63
	v_cvt_pk_bf16_f32 v2, v2, s0
	ds_write_b16 v225, v2 offset:64
	v_mul_f32_e32 v2, v92, v64
	v_cvt_pk_bf16_f32 v2, v2, s0
	ds_write_b16 v226, v2 offset:64
	v_mul_f32_e32 v2, v91, v65
	v_cvt_pk_bf16_f32 v2, v2, s0
	ds_write_b16 v227, v2 offset:64
	v_mul_f32_e32 v2, v90, v66
	v_cvt_pk_bf16_f32 v2, v2, s0
	ds_write_b16 v228, v2 offset:64
	v_mul_f32_e32 v2, v89, v67
	v_cvt_pk_bf16_f32 v2, v2, s0
	ds_write_b16 v229, v2 offset:64
	v_mul_f32_e32 v2, v88, v68
	v_cvt_pk_bf16_f32 v2, v2, s0
	ds_write_b16 v230, v2 offset:64
	v_mul_f32_e32 v2, v87, v69
	v_cvt_pk_bf16_f32 v2, v2, s0
	ds_write_b16 v231, v2 offset:64
	v_mul_f32_e32 v2, v86, v8
	v_cvt_pk_bf16_f32 v2, v2, s0
	ds_write_b16 v232, v2 offset:64
	v_mul_f32_e32 v2, v85, v9
	v_cvt_pk_bf16_f32 v2, v2, s0
	ds_write_b16 v233, v2 offset:64
	ds_write_b16 v234, v0 offset:64
	v_mul_f32_e32 v0, v6, v1
	v_cvt_pk_bf16_f32 v0, v0, s0
	s_lshl_b32 s0, s2, 14
	v_accvgpr_read_b32 v8, a145
	ds_write_b16 v235, v0 offset:64
	v_accvgpr_read_b32 v6, a146
	ds_write_b128 v6, a[228:231]
	v_accvgpr_read_b32 v6, a147
	ds_write_b128 v6, a[232:235]
	v_accvgpr_read_b32 v6, a148
	ds_write_b128 v6, a[236:239]
	v_accvgpr_read_b32 v6, a150
	ds_write_b128 v6, a[240:243]
	v_accvgpr_read_b32 v6, a151
	ds_write_b128 v6, a[244:247]
	v_accvgpr_read_b32 v6, a153
	ds_write_b128 v6, a[248:251]
	v_accvgpr_read_b32 v6, a155
	ds_write_b128 v6, a[252:255]
	v_accvgpr_read_b32 v0, a156
	v_add_lshl_u32 v6, s0, v0, 1
	v_lshl_add_u64 v[0:1], v[22:23], 0, v[6:7]
	global_load_dwordx4 v[0:3], v[0:1], off
	v_accvgpr_read_b32 v6, a157
	s_waitcnt vmcnt(0)
	ds_write_b128 v6, v[0:3]
	s_waitcnt lgkmcnt(0)
	s_barrier
	ds_read_b128 v[0:3], v238 offset:8704
	ds_read_b128 v[8:11], v239 offset:43520
	ds_read_b128 v[56:59], v238
	ds_read_b128 v[60:63], v238 offset:32
	ds_read_b128 v[64:67], v239 offset:34816
	ds_read_b128 v[68:71], v239 offset:34848
	s_waitcnt lgkmcnt(1)
	v_mfma_f32_32x32x16_bf16 a[48:63], v[56:59], v[64:67], 0
	v_mfma_f32_32x32x16_bf16 a[32:47], v[56:59], v[8:11], 0
	v_mfma_f32_32x32x16_bf16 a[16:31], v[0:3], v[64:67], 0
	v_mfma_f32_32x32x16_bf16 a[0:15], v[0:3], v[8:11], 0
	ds_read_b128 v[0:3], v238 offset:8736
	ds_read_b128 v[8:11], v239 offset:43552
	s_waitcnt lgkmcnt(2)
	v_mfma_f32_32x32x16_bf16 a[48:63], v[60:63], v[68:71], a[48:63]
	s_waitcnt lgkmcnt(0)
	v_mfma_f32_32x32x16_bf16 a[32:47], v[60:63], v[8:11], a[32:47]
	v_mfma_f32_32x32x16_bf16 a[16:31], v[0:3], v[68:71], a[16:31]
	v_mfma_f32_32x32x16_bf16 a[0:15], v[0:3], v[8:11], a[0:15]
	ds_read_b128 v[0:3], v238 offset:64
	ds_read_b128 v[8:11], v238 offset:8768
	ds_read_b128 v[56:59], v239 offset:34880
	ds_read_b128 v[60:63], v239 offset:43584
	s_waitcnt lgkmcnt(1)
	v_mfma_f32_32x32x16_bf16 a[48:63], v[0:3], v[56:59], a[48:63]
	s_waitcnt lgkmcnt(0)
	v_mfma_f32_32x32x16_bf16 a[32:47], v[0:3], v[60:63], a[32:47]
	v_mfma_f32_32x32x16_bf16 a[16:31], v[8:11], v[56:59], a[16:31]
	v_mfma_f32_32x32x16_bf16 a[0:15], v[8:11], v[60:63], a[0:15]
	ds_read_b128 v[0:3], v238 offset:96
	ds_read_b128 v[8:11], v238 offset:8800
	ds_read_b128 v[56:59], v239 offset:34912
	ds_read_b128 v[60:63], v239 offset:43616
	s_waitcnt lgkmcnt(1)
	v_mfma_f32_32x32x16_bf16 a[48:63], v[0:3], v[56:59], a[48:63]
	s_waitcnt lgkmcnt(0)
	v_mfma_f32_32x32x16_bf16 a[32:47], v[0:3], v[60:63], a[32:47]
	v_mfma_f32_32x32x16_bf16 a[16:31], v[8:11], v[56:59], a[16:31]
	v_mfma_f32_32x32x16_bf16 a[0:15], v[8:11], v[60:63], a[0:15]
	ds_read_b128 v[0:3], v238 offset:128
	ds_read_b128 v[8:11], v238 offset:8832
	ds_read_b128 v[56:59], v239 offset:34944
	ds_read_b128 v[60:63], v239 offset:43648
	s_waitcnt lgkmcnt(1)
	v_mfma_f32_32x32x16_bf16 a[48:63], v[0:3], v[56:59], a[48:63]
	s_waitcnt lgkmcnt(0)
	v_mfma_f32_32x32x16_bf16 a[32:47], v[0:3], v[60:63], a[32:47]
	v_mfma_f32_32x32x16_bf16 a[16:31], v[8:11], v[56:59], a[16:31]
	v_mfma_f32_32x32x16_bf16 a[0:15], v[8:11], v[60:63], a[0:15]
	ds_read_b128 v[0:3], v238 offset:160
	ds_read_b128 v[8:11], v238 offset:8864
	ds_read_b128 v[56:59], v239 offset:34976
	ds_read_b128 v[60:63], v239 offset:43680
	s_waitcnt lgkmcnt(1)
	v_mfma_f32_32x32x16_bf16 a[48:63], v[0:3], v[56:59], a[48:63]
	s_waitcnt lgkmcnt(0)
	v_mfma_f32_32x32x16_bf16 a[32:47], v[0:3], v[60:63], a[32:47]
	v_mfma_f32_32x32x16_bf16 a[16:31], v[8:11], v[56:59], a[16:31]
	v_mfma_f32_32x32x16_bf16 a[0:15], v[8:11], v[60:63], a[0:15]
	ds_read_b128 v[0:3], v238 offset:192
	ds_read_b128 v[8:11], v238 offset:8896
	ds_read_b128 v[56:59], v239 offset:35008
	ds_read_b128 v[60:63], v239 offset:43712
	s_waitcnt lgkmcnt(1)
	v_mfma_f32_32x32x16_bf16 a[48:63], v[0:3], v[56:59], a[48:63]
	s_waitcnt lgkmcnt(0)
	v_mfma_f32_32x32x16_bf16 a[32:47], v[0:3], v[60:63], a[32:47]
	v_mfma_f32_32x32x16_bf16 a[16:31], v[8:11], v[56:59], a[16:31]
	v_mfma_f32_32x32x16_bf16 a[0:15], v[8:11], v[60:63], a[0:15]
	ds_read_b128 v[0:3], v238 offset:224
	ds_read_b128 v[8:11], v238 offset:8928
	ds_read_b128 v[56:59], v239 offset:35040
	ds_read_b128 v[60:63], v239 offset:43744
	s_waitcnt lgkmcnt(0)
	s_barrier
; __device__ __forceinline__ int rowmap(int e, int lane) { return (e & 3) + 8 * (e >> 2) + 4 * (lane >> 5); }
; __device__ __forceinline__ void phase4c(const Params& p, char* smem) {
;     ...
;     for (int ks = 0; ks < 8; ks++) {
;       bf16x8 a[2], bq[2];
; #pragma unroll
;       for (int i = 0; i < 2; i++) a[i] = *(const bf16x8*)&Aq[(wm * 64 + i * 32 + r) * 136 + ks * 16 + hh];
; #pragma unroll
;       for (int j = 0; j < 2; j++) bq[j] = *(const bf16x8*)&Bk[(wn * 64 + j * 32 + r) * 136 + ks * 16 + hh];
; #pragma unroll
;       for (int i = 0; i < 2; i++)
; #pragma unroll
;         for (int j = 0; j < 2; j++) acc[i][j] = mfma16(a[i], bq[j], acc[i][j]);
;     }
;     __syncthreads();
;     float* SC = (float*)smem;
; #pragma unroll
;     for (int i = 0; i < 2; i++)
; #pragma unroll
;       for (int j = 0; j < 2; j++)
; #pragma unroll
;         for (int e = 0; e < 16; e++) SC[(wm * 64 + i * 32 + rowmap(e, lane)) * 132 + wn * 64 + j * 32 + r] = acc[i][j][e];
;     __syncthreads();
;     {
;       const int tokl = tid >> 1, part = tid & 1;
;       float sv[64];
; #pragma unroll
;       for (int i = 0; i < 16; i++) {
;         float4 x = *(const float4*)&SC[tokl * 132 + part * 64 + i * 4];
;         const unsigned ib = 127u - (unsigned)(part * 64 + i * 4);
;         sv[4 * i]     = __uint_as_float((__float_as_uint(x.x) & ~127u) | ib);
;         sv[4 * i + 1] = __uint_as_float((__float_as_uint(x.y) & ~127u) | (ib - 1u));
;         sv[4 * i + 2] = __uint_as_float((__float_as_uint(x.z) & ~127u) | (ib - 2u));
;         sv[4 * i + 3] = __uint_as_float((__float_as_uint(x.w) & ~127u) | (ib - 3u));
;       }
	v_mfma_f32_32x32x16_bf16 a[48:63], v[0:3], v[56:59], a[48:63]
	v_mfma_f32_32x32x16_bf16 a[32:47], v[0:3], v[60:63], a[32:47]
	v_mfma_f32_32x32x16_bf16 a[16:31], v[8:11], v[56:59], a[16:31]
	v_mfma_f32_32x32x16_bf16 a[0:15], v[8:11], v[60:63], a[0:15]
	s_nop 8
	ds_write_b32 v195, a48
	ds_write_b32 v195, a49 offset:528
	ds_write_b32 v195, a50 offset:1056
	ds_write_b32 v195, a51 offset:1584
	ds_write_b32 v195, a52 offset:4224
	ds_write_b32 v195, a53 offset:4752
	ds_write_b32 v195, a54 offset:5280
	ds_write_b32 v195, a55 offset:5808
	ds_write_b32 v195, a56 offset:8448
	ds_write_b32 v195, a57 offset:8976
	ds_write_b32 v195, a58 offset:9504
	ds_write_b32 v195, a59 offset:10032
	ds_write_b32 v195, a60 offset:12672
	ds_write_b32 v195, a61 offset:13200
	ds_write_b32 v195, a62 offset:13728
	ds_write_b32 v195, a63 offset:14256
	ds_write_b32 v195, a32 offset:128
	ds_write_b32 v195, a33 offset:656
	ds_write_b32 v195, a34 offset:1184
	ds_write_b32 v195, a35 offset:1712
	ds_write_b32 v195, a36 offset:4352
	ds_write_b32 v195, a37 offset:4880
	ds_write_b32 v195, a38 offset:5408
	ds_write_b32 v195, a39 offset:5936
	ds_write_b32 v195, a40 offset:8576
	ds_write_b32 v195, a41 offset:9104
	ds_write_b32 v195, a42 offset:9632
	ds_write_b32 v195, a43 offset:10160
	ds_write_b32 v195, a44 offset:12800
	ds_write_b32 v195, a45 offset:13328
	ds_write_b32 v195, a46 offset:13856
	ds_write_b32 v195, a47 offset:14384
	ds_write_b32 v195, a16 offset:16896
	ds_write_b32 v195, a17 offset:17424
	ds_write_b32 v195, a18 offset:17952
	ds_write_b32 v195, a19 offset:18480
	ds_write_b32 v195, a20 offset:21120
	ds_write_b32 v195, a21 offset:21648
	ds_write_b32 v195, a22 offset:22176
	ds_write_b32 v195, a23 offset:22704
	ds_write_b32 v195, a24 offset:25344
	ds_write_b32 v195, a25 offset:25872
	ds_write_b32 v195, a26 offset:26400
	ds_write_b32 v195, a27 offset:26928
	ds_write_b32 v195, a28 offset:29568
	ds_write_b32 v195, a29 offset:30096
	ds_write_b32 v195, a30 offset:30624
	ds_write_b32 v195, a31 offset:31152
	ds_write_b32 v195, a0 offset:17024
	ds_write_b32 v195, a1 offset:17552
	ds_write_b32 v195, a2 offset:18080
	ds_write_b32 v195, a3 offset:18608
	ds_write_b32 v195, a4 offset:21248
	ds_write_b32 v195, a5 offset:21776
	ds_write_b32 v195, a6 offset:22304
	ds_write_b32 v195, a7 offset:22832
	ds_write_b32 v195, a8 offset:25472
	ds_write_b32 v195, a9 offset:26000
	ds_write_b32 v195, a10 offset:26528
	ds_write_b32 v195, a11 offset:27056
	ds_write_b32 v195, a12 offset:29696
	ds_write_b32 v195, a13 offset:30224
	ds_write_b32 v195, a14 offset:30752
	ds_write_b32 v195, a15 offset:31280
	s_waitcnt lgkmcnt(0)
	s_barrier
	ds_read_b128 v[0:3], v174
	ds_read_b128 v[8:11], v174 offset:16
	ds_read_b128 v[56:59], v174 offset:32
	ds_read_b128 v[60:63], v174 offset:48
	s_waitcnt lgkmcnt(3)
	v_and_b32_e32 v0, 0xffffff80, v0
	v_bitop3_b32 v72, v173, s27, v0 bitop3:0x36
	v_and_b32_e32 v0, 0xffffff80, v1
	v_sub_u32_e32 v0, v0, v173
	v_add_u32_e32 v75, 0x7e, v0
	v_and_b32_e32 v0, 0xffffff80, v2
	v_sub_u32_e32 v0, v0, v173
	v_add_u32_e32 v76, 0x7d, v0
	v_and_b32_e32 v0, 0xffffff80, v3
	v_sub_u32_e32 v0, v0, v173
	v_add_u32_e32 v79, 0x7c, v0
	s_waitcnt lgkmcnt(2)
	v_and_b32_e32 v0, 0xffffff80, v8
	v_sub_u32_e32 v0, v0, v173
	v_add_u32_e32 v78, 0x7b, v0
	v_and_b32_e32 v0, 0xffffff80, v9
	v_sub_u32_e32 v0, v0, v173
	v_add_u32_e32 v81, 0x7a, v0
	v_and_b32_e32 v0, 0xffffff80, v10
	v_sub_u32_e32 v0, v0, v173
	v_add_u32_e32 v80, 0x79, v0
	v_and_b32_e32 v0, 0xffffff80, v11
	v_sub_u32_e32 v0, v0, v173
	v_add_u32_e32 v83, 0x78, v0
	s_waitcnt lgkmcnt(1)
	v_and_b32_e32 v0, 0xffffff80, v56
	v_sub_u32_e32 v0, v0, v173
	v_add_u32_e32 v82, 0x77, v0
	v_and_b32_e32 v0, 0xffffff80, v57
	v_sub_u32_e32 v0, v0, v173
	v_add_u32_e32 v85, 0x76, v0
	v_and_b32_e32 v0, 0xffffff80, v58
	v_sub_u32_e32 v0, v0, v173
	v_add_u32_e32 v84, 0x75, v0
	v_and_b32_e32 v0, 0xffffff80, v59
	v_sub_u32_e32 v0, v0, v173
	v_add_u32_e32 v87, 0x74, v0
	s_waitcnt lgkmcnt(0)
	v_and_b32_e32 v0, 0xffffff80, v60
	v_sub_u32_e32 v0, v0, v173
	ds_read_b128 v[8:11], v174 offset:64
	v_add_u32_e32 v86, 0x73, v0
	v_and_b32_e32 v0, 0xffffff80, v61
	v_sub_u32_e32 v0, v0, v173
	v_add_u32_e32 v90, 0x72, v0
	v_and_b32_e32 v0, 0xffffff80, v62
	v_sub_u32_e32 v0, v0, v173
	v_add_u32_e32 v89, 0x71, v0
	v_and_b32_e32 v0, 0xffffff80, v63
	s_waitcnt lgkmcnt(0)
	v_and_b32_e32 v1, 0xffffff80, v9
	v_sub_u32_e32 v0, v0, v173
	v_sub_u32_e32 v1, v1, v173
	v_add_u32_e32 v92, 0x70, v0
	v_and_b32_e32 v0, 0xffffff80, v8
	v_add_u32_e32 v2, 0x6e, v1
	v_and_b32_e32 v1, 0xffffff80, v10
	v_and_b32_e32 v3, 0xffffff80, v11
	ds_read_b128 v[8:11], v174 offset:80
	v_sub_u32_e32 v0, v0, v173
	v_add_u32_e32 v0, 0x6f, v0
	v_sub_u32_e32 v1, v1, v173
	v_sub_u32_e32 v3, v3, v173
	s_waitcnt lgkmcnt(0)
	v_and_b32_e32 v6, 0xffffff80, v8
	v_sub_u32_e32 v6, v6, v173
	v_add_u32_e32 v59, 0x6b, v6
	v_and_b32_e32 v6, 0xffffff80, v9
	v_sub_u32_e32 v6, v6, v173
	v_add_u32_e32 v62, 0x6a, v6
	v_and_b32_e32 v6, 0xffffff80, v10
	v_sub_u32_e32 v6, v6, v173
	v_add_u32_e32 v61, 0x69, v6
	v_and_b32_e32 v6, 0xffffff80, v11
	ds_read_b128 v[8:11], v174 offset:96
	v_sub_u32_e32 v6, v6, v173
	v_add_u32_e32 v64, 0x68, v6
	v_add_u32_e32 v1, 0x6d, v1
	v_add_u32_e32 v3, 0x6c, v3
	s_waitcnt lgkmcnt(0)
	v_and_b32_e32 v6, 0xffffff80, v8
	v_sub_u32_e32 v6, v6, v173
	v_add_u32_e32 v67, 0x67, v6
	v_and_b32_e32 v6, 0xffffff80, v9
	v_sub_u32_e32 v6, v6, v173
	v_add_u32_e32 v69, 0x66, v6
	v_and_b32_e32 v6, 0xffffff80, v10
	v_sub_u32_e32 v6, v6, v173
	v_add_u32_e32 v68, 0x65, v6
	v_and_b32_e32 v6, 0xffffff80, v11
	ds_read_b128 v[8:11], v174 offset:112
	v_sub_u32_e32 v6, v6, v173
	v_add_u32_e32 v70, 0x64, v6
	v_max_f32_e32 v2, v2, v2
	v_max_f32_e32 v0, v0, v0
	s_waitcnt lgkmcnt(0)
; #define CE_DESC(a, b) { const float hi_ = fmaxf(a, b), lo_ = fminf(a, b); a = hi_; b = lo_; }
; __device__ __forceinline__ void phase4c(const Params& p, char* smem) {
;     ...
;       for (int i = 0; i < 16; i++) {
;         float4 x = *(const float4*)&SC[tokl * 132 + part * 64 + i * 4];
;         const unsigned ib = 127u - (unsigned)(part * 64 + i * 4);
;         sv[4 * i]     = __uint_as_float((__float_as_uint(x.x) & ~127u) | ib);
;         sv[4 * i + 1] = __uint_as_float((__float_as_uint(x.y) & ~127u) | (ib - 1u));
;         sv[4 * i + 2] = __uint_as_float((__float_as_uint(x.z) & ~127u) | (ib - 2u));
;         sv[4 * i + 3] = __uint_as_float((__float_as_uint(x.w) & ~127u) | (ib - 3u));
;       }
;     ...
; #pragma unroll
;       for (int g = 0; g < 4; g++) {
; #pragma unroll
;         for (int lk = 1; lk <= 4; lk++) {
; #pragma unroll
;           for (int lj = lk - 1; lj >= 0; lj--) {
; #pragma unroll
;             for (int i = 0; i < 16; i++) {
;               const int l = i ^ (1 << lj);
;               if (l > i) {
;                 if ((i & (1 << lk)) == 0) { CE_DESC(sv[g * 16 + i], sv[g * 16 + l]) } else { CE_DESC(sv[g * 16 + l], sv[g * 16 + i]) }
;               }
;             }
;           }
;         }
;       }
	v_and_b32_e32 v6, 0xffffff80, v8
	v_sub_u32_e32 v6, v6, v173
	v_add_u32_e32 v99, 0x63, v6
	v_and_b32_e32 v6, 0xffffff80, v9
	v_sub_u32_e32 v6, v6, v173
	v_add_u32_e32 v102, 0x62, v6
	v_and_b32_e32 v6, 0xffffff80, v10
	v_sub_u32_e32 v6, v6, v173
	v_add_u32_e32 v101, 0x61, v6
	v_and_b32_e32 v6, 0xffffff80, v11
	ds_read_b128 v[8:11], v174 offset:128
	v_sub_u32_e32 v6, v6, v173
	v_add_u32_e32 v104, 0x60, v6
	v_max_f32_e32 v1, v1, v1
	s_waitcnt lgkmcnt(0)
	v_and_b32_e32 v6, 0xffffff80, v8
	v_and_b32_e32 v8, 0xffffff80, v9
	v_sub_u32_e32 v8, v8, v173
	v_add_u32_e32 v57, 0x5e, v8
	v_and_b32_e32 v8, 0xffffff80, v10
	v_sub_u32_e32 v8, v8, v173
	v_add_u32_e32 v56, 0x5d, v8
	v_and_b32_e32 v8, 0xffffff80, v11
	v_sub_u32_e32 v8, v8, v173
	v_add_u32_e32 v58, 0x5c, v8
	ds_read_b128 v[8:11], v174 offset:144
	v_sub_u32_e32 v6, v6, v173
	v_add_u32_e32 v6, 0x5f, v6
	v_max_f32_e32 v57, v57, v57
	v_max_f32_e32 v6, v6, v6
	s_waitcnt lgkmcnt(0)
	v_and_b32_e32 v8, 0xffffff80, v8
	v_sub_u32_e32 v8, v8, v173
	v_add_u32_e32 v71, 0x5b, v8
	v_and_b32_e32 v8, 0xffffff80, v9
	v_sub_u32_e32 v8, v8, v173
	v_add_u32_e32 v74, 0x5a, v8
	v_and_b32_e32 v8, 0xffffff80, v10
	v_sub_u32_e32 v8, v8, v173
	v_add_u32_e32 v73, 0x59, v8
	v_and_b32_e32 v8, 0xffffff80, v11
	v_sub_u32_e32 v8, v8, v173
	v_add_u32_e32 v77, 0x58, v8
	ds_read_b128 v[8:11], v174 offset:160
	v_max_f32_e32 v178, v6, v57
	v_min_f32_e32 v6, v6, v57
	v_max_f32_e32 v56, v56, v56
	v_max_f32_e32 v57, v58, v58
	s_waitcnt lgkmcnt(0)
	v_and_b32_e32 v8, 0xffffff80, v8
	v_sub_u32_e32 v8, v8, v173
	v_add_u32_e32 v88, 0x57, v8
	v_and_b32_e32 v8, 0xffffff80, v9
	v_sub_u32_e32 v8, v8, v173
	v_add_u32_e32 v93, 0x56, v8
	v_and_b32_e32 v8, 0xffffff80, v10
	v_sub_u32_e32 v8, v8, v173
	v_add_u32_e32 v91, 0x55, v8
	v_and_b32_e32 v8, 0xffffff80, v11
	v_sub_u32_e32 v8, v8, v173
	v_add_u32_e32 v94, 0x54, v8
	ds_read_b128 v[8:11], v174 offset:176
	v_max_f32_e32 v58, v57, v56
	v_min_f32_e32 v56, v57, v56
	v_max_f32_e32 v57, v74, v74
	v_max_f32_e32 v71, v71, v71
	s_waitcnt lgkmcnt(0)
	v_and_b32_e32 v8, 0xffffff80, v8
	v_sub_u32_e32 v8, v8, v173
	v_add_u32_e32 v107, 0x53, v8
	v_and_b32_e32 v8, 0xffffff80, v9
	v_sub_u32_e32 v8, v8, v173
	v_add_u32_e32 v109, 0x52, v8
	v_and_b32_e32 v8, 0xffffff80, v10
	v_sub_u32_e32 v8, v8, v173
	v_add_u32_e32 v108, 0x51, v8
	v_and_b32_e32 v8, 0xffffff80, v11
	v_sub_u32_e32 v8, v8, v173
	v_add_u32_e32 v110, 0x50, v8
	ds_read_b128 v[8:11], v174 offset:192
	v_max_f32_e32 v74, v71, v57
	v_min_f32_e32 v57, v71, v57
	v_max_f32_e32 v71, v73, v73
	v_max_f32_e32 v73, v77, v77
	s_waitcnt lgkmcnt(0)
	v_and_b32_e32 v8, 0xffffff80, v8
	v_sub_u32_e32 v8, v8, v173
	v_add_u32_e32 v60, 0x4f, v8
	v_and_b32_e32 v8, 0xffffff80, v9
	v_sub_u32_e32 v8, v8, v173
	v_add_u32_e32 v65, 0x4e, v8
	v_and_b32_e32 v8, 0xffffff80, v10
	v_sub_u32_e32 v8, v8, v173
	v_add_u32_e32 v63, 0x4d, v8
	v_and_b32_e32 v8, 0xffffff80, v11
	v_sub_u32_e32 v8, v8, v173
	v_add_u32_e32 v66, 0x4c, v8
	ds_read_b128 v[8:11], v174 offset:208
	v_max_f32_e32 v65, v65, v65
	v_max_f32_e32 v60, v60, v60
	v_max_f32_e32 v191, v60, v65
	v_min_f32_e32 v60, v60, v65
	s_waitcnt lgkmcnt(0)
	v_and_b32_e32 v8, 0xffffff80, v8
	v_sub_u32_e32 v8, v8, v173
	v_add_u32_e32 v95, 0x4b, v8
	v_and_b32_e32 v8, 0xffffff80, v9
	v_sub_u32_e32 v8, v8, v173
	v_add_u32_e32 v97, 0x4a, v8
	v_and_b32_e32 v8, 0xffffff80, v10
	v_sub_u32_e32 v8, v8, v173
	v_add_u32_e32 v96, 0x49, v8
	v_and_b32_e32 v8, 0xffffff80, v11
	v_sub_u32_e32 v8, v8, v173
	v_add_u32_e32 v98, 0x48, v8
	ds_read_b128 v[8:11], v174 offset:224
	v_max_f32_e32 v63, v63, v63
	v_max_f32_e32 v65, v66, v66
	v_max_f32_e32 v66, v65, v63
	v_min_f32_e32 v63, v65, v63
	s_waitcnt lgkmcnt(0)
	v_and_b32_e32 v8, 0xffffff80, v8
	v_sub_u32_e32 v8, v8, v173
	v_add_u32_e32 v100, 0x47, v8
	v_and_b32_e32 v8, 0xffffff80, v9
	v_sub_u32_e32 v8, v8, v173
	v_add_u32_e32 v105, 0x46, v8
	v_and_b32_e32 v8, 0xffffff80, v10
	v_sub_u32_e32 v8, v8, v173
	v_add_u32_e32 v103, 0x45, v8
	v_and_b32_e32 v8, 0xffffff80, v11
	v_sub_u32_e32 v8, v8, v173
	v_add_u32_e32 v106, 0x44, v8
	ds_read_b128 v[8:11], v174 offset:240
	v_max_f32_e32 v65, v97, v97
	v_max_f32_e32 v95, v95, v95
	v_max_f32_e32 v97, v95, v65
	v_min_f32_e32 v65, v95, v65
	s_waitcnt lgkmcnt(0)
	v_and_b32_e32 v8, 0xffffff80, v8
	v_sub_u32_e32 v8, v8, v173
	v_add_u32_e32 v111, 0x43, v8
	v_and_b32_e32 v8, 0xffffff80, v9
	v_sub_u32_e32 v8, v8, v173
	v_add_u32_e32 v113, 0x42, v8
	v_and_b32_e32 v8, 0xffffff80, v10
	v_sub_u32_e32 v8, v8, v173
	v_add_u32_e32 v112, 0x41, v8
	v_and_b32_e32 v8, 0xffffff80, v11
	v_sub_u32_e32 v8, v8, v173
	v_add_u32_e32 v114, 64, v8
	v_max_f32_e32 v8, v72, v72
	v_max_f32_e32 v9, v75, v75
	v_max_f32_e32 v10, v8, v9
	v_min_f32_e32 v8, v8, v9
	v_max_f32_e32 v9, v76, v76
	v_max_f32_e32 v11, v79, v79
	v_max_f32_e32 v72, v11, v9
	v_min_f32_e32 v9, v11, v9
	v_max_f32_e32 v11, v81, v81
	v_max_f32_e32 v75, v78, v78
	v_max_f32_e32 v76, v75, v11
	v_min_f32_e32 v11, v75, v11
	v_max_f32_e32 v75, v80, v80
	v_max_f32_e32 v78, v83, v83
	v_max_f32_e32 v79, v78, v75
	v_min_f32_e32 v75, v78, v75
	v_max_f32_e32 v78, v85, v85
	v_max_f32_e32 v80, v82, v82
	v_max_f32_e32 v81, v80, v78
	v_min_f32_e32 v78, v80, v78
	v_max_f32_e32 v80, v84, v84
	v_max_f32_e32 v82, v87, v87
	v_max_f32_e32 v83, v82, v80
	v_min_f32_e32 v80, v82, v80
	v_max_f32_e32 v82, v90, v90
	v_max_f32_e32 v84, v86, v86
	v_max_f32_e32 v85, v84, v82
	v_min_f32_e32 v82, v84, v82
	v_max_f32_e32 v84, v89, v89
	v_max_f32_e32 v86, v92, v92
	v_max_f32_e32 v87, v86, v84
	v_min_f32_e32 v84, v86, v84
	v_max_f32_e32 v86, v10, v9
	v_min_f32_e32 v9, v10, v9
	v_max_f32_e32 v10, v8, v72
	v_min_f32_e32 v8, v8, v72
	v_max_f32_e32 v72, v75, v76
; #define CE_DESC(a, b) { const float hi_ = fmaxf(a, b), lo_ = fminf(a, b); a = hi_; b = lo_; }
; __device__ __forceinline__ void phase4c(const Params& p, char* smem) {
;     ...
; #pragma unroll
;       for (int g = 0; g < 4; g++) {
; #pragma unroll
;         for (int lk = 1; lk <= 4; lk++) {
; #pragma unroll
;           for (int lj = lk - 1; lj >= 0; lj--) {
; #pragma unroll
;             for (int i = 0; i < 16; i++) {
;               const int l = i ^ (1 << lj);
;               if (l > i) {
;                 if ((i & (1 << lk)) == 0) { CE_DESC(sv[g * 16 + i], sv[g * 16 + l]) } else { CE_DESC(sv[g * 16 + l], sv[g * 16 + i]) }
;               }
;             }
;           }
;         }
;       }
	v_min_f32_e32 v75, v75, v76
	v_max_f32_e32 v76, v79, v11
	v_min_f32_e32 v11, v79, v11
	v_max_f32_e32 v79, v81, v80
	v_min_f32_e32 v80, v81, v80
	v_max_f32_e32 v81, v78, v83
	v_min_f32_e32 v78, v78, v83
	v_max_f32_e32 v83, v84, v85
	v_min_f32_e32 v84, v84, v85
	v_max_f32_e32 v85, v87, v82
	v_min_f32_e32 v82, v87, v82
	v_max_f32_e32 v87, v86, v10
	v_min_f32_e32 v10, v86, v10
	v_max_f32_e32 v86, v9, v8
	v_min_f32_e32 v8, v9, v8
	v_max_f32_e32 v9, v11, v75
	v_min_f32_e32 v11, v11, v75
	v_max_f32_e32 v75, v76, v72
	v_min_f32_e32 v72, v76, v72
	v_max_f32_e32 v76, v79, v81
	v_min_f32_e32 v79, v79, v81
	v_max_f32_e32 v81, v80, v78
	v_min_f32_e32 v78, v80, v78
	v_max_f32_e32 v80, v82, v84
	v_min_f32_e32 v82, v82, v84
	v_max_f32_e32 v84, v85, v83
	v_min_f32_e32 v83, v85, v83
	v_max_f32_e32 v85, v87, v11
	v_min_f32_e32 v11, v87, v11
	v_max_f32_e32 v87, v10, v9
	v_min_f32_e32 v9, v10, v9
	v_max_f32_e32 v10, v86, v72
	v_min_f32_e32 v72, v86, v72
	v_max_f32_e32 v86, v8, v75
	v_min_f32_e32 v8, v8, v75
	v_max_f32_e32 v75, v82, v76
	v_min_f32_e32 v76, v82, v76
	v_max_f32_e32 v82, v80, v79
	v_min_f32_e32 v79, v80, v79
	v_max_f32_e32 v80, v83, v81
	v_min_f32_e32 v81, v83, v81
	v_max_f32_e32 v83, v84, v78
	v_min_f32_e32 v78, v84, v78
	v_max_f32_e32 v84, v85, v10
	v_min_f32_e32 v10, v85, v10
	v_max_f32_e32 v85, v87, v86
	v_min_f32_e32 v86, v87, v86
	v_max_f32_e32 v87, v11, v72
	v_min_f32_e32 v11, v11, v72
	v_max_f32_e32 v72, v9, v8
	v_min_f32_e32 v8, v9, v8
	v_max_f32_e32 v9, v81, v76
	v_min_f32_e32 v76, v81, v76
	v_max_f32_e32 v81, v78, v79
	v_min_f32_e32 v78, v78, v79
	v_max_f32_e32 v79, v80, v75
	v_min_f32_e32 v75, v80, v75
	v_max_f32_e32 v80, v83, v82
	v_min_f32_e32 v82, v83, v82
	v_max_f32_e32 v83, v84, v85
	v_min_f32_e32 v84, v84, v85
	v_max_f32_e32 v85, v10, v86
	v_min_f32_e32 v10, v10, v86
	v_max_f32_e32 v86, v87, v72
	v_min_f32_e32 v72, v87, v72
	v_max_f32_e32 v87, v11, v8
	v_min_f32_e32 v8, v11, v8
	v_max_f32_e32 v11, v78, v76
	v_min_f32_e32 v76, v78, v76
	v_max_f32_e32 v78, v81, v9
	v_min_f32_e32 v9, v81, v9
	v_max_f32_e32 v81, v82, v75
	v_min_f32_e32 v75, v82, v75
	v_max_f32_e32 v82, v80, v79
	v_min_f32_e32 v79, v80, v79
	v_max_f32_e32 v80, v83, v76
	v_min_f32_e32 v76, v83, v76
	v_max_f32_e32 v83, v84, v11
	v_min_f32_e32 v11, v84, v11
	v_max_f32_e32 v84, v85, v9
	v_min_f32_e32 v9, v85, v9
	v_max_f32_e32 v85, v10, v78
	v_min_f32_e32 v10, v10, v78
	v_max_f32_e32 v78, v86, v75
	v_min_f32_e32 v75, v86, v75
	v_max_f32_e32 v86, v72, v81
	v_min_f32_e32 v72, v72, v81
	v_max_f32_e32 v81, v87, v79
	v_min_f32_e32 v79, v87, v79
	v_max_f32_e32 v87, v8, v82
	v_min_f32_e32 v8, v8, v82
	v_max_f32_e32 v82, v80, v78
	v_min_f32_e32 v78, v80, v78
	v_max_f32_e32 v80, v83, v86
	v_min_f32_e32 v83, v83, v86
	v_max_f32_e32 v86, v84, v81
	v_min_f32_e32 v89, v84, v81
	v_max_f32_e32 v81, v85, v87
	v_min_f32_e32 v85, v85, v87
	v_max_f32_e32 v90, v76, v75
	v_min_f32_e32 v92, v76, v75
	v_max_f32_e32 v115, v11, v72
	v_min_f32_e32 v11, v11, v72
	v_max_f32_e32 v135, v9, v79
	v_min_f32_e32 v9, v9, v79
	v_max_f32_e32 v137, v10, v8
	v_min_f32_e32 v8, v10, v8
	v_max_f32_e32 v72, v82, v86
	v_min_f32_e32 v79, v82, v86
	v_max_f32_e32 v87, v83, v85
	v_min_f32_e32 v85, v83, v85
	v_max_f32_e32 v76, v90, v135
	v_min_f32_e32 v82, v90, v135
	v_max_f32_e32 v86, v92, v9
	v_min_f32_e32 v83, v92, v9
	v_max_f32_e32 v92, v11, v8
	v_min_f32_e32 v90, v11, v8
	v_max_f32_e32 v8, v0, v2
	v_min_f32_e32 v0, v0, v2
	v_max_f32_e32 v2, v3, v3
	v_max_f32_e32 v3, v2, v1
	v_min_f32_e32 v1, v2, v1
	v_max_f32_e32 v2, v62, v62
	v_max_f32_e32 v9, v59, v59
	v_max_f32_e32 v10, v9, v2
	v_min_f32_e32 v2, v9, v2
	v_max_f32_e32 v9, v61, v61
	v_max_f32_e32 v11, v64, v64
	v_max_f32_e32 v95, v96, v96
	v_max_f32_e32 v96, v98, v98
	v_max_f32_e32 v59, v11, v9
	v_min_f32_e32 v9, v11, v9
	v_max_f32_e32 v11, v69, v69
	v_max_f32_e32 v61, v67, v67
	v_max_f32_e32 v77, v73, v71
	v_min_f32_e32 v71, v73, v71
	v_max_f32_e32 v73, v93, v93
	v_max_f32_e32 v88, v88, v88
	v_max_f32_e32 v98, v96, v95
	v_min_f32_e32 v95, v96, v95
	v_max_f32_e32 v96, v105, v105
	v_max_f32_e32 v100, v100, v100
	v_max_f32_e32 v62, v61, v11
	v_min_f32_e32 v11, v61, v11
	v_max_f32_e32 v61, v68, v68
	v_max_f32_e32 v64, v70, v70
	v_max_f32_e32 v93, v88, v73
	v_min_f32_e32 v73, v88, v73
	v_max_f32_e32 v88, v91, v91
	v_max_f32_e32 v91, v94, v94
	v_max_f32_e32 v105, v100, v96
	v_min_f32_e32 v96, v100, v96
	v_max_f32_e32 v100, v103, v103
	v_max_f32_e32 v103, v106, v106
	v_max_f32_e32 v67, v64, v61
	v_min_f32_e32 v61, v64, v61
	v_max_f32_e32 v64, v102, v102
	v_max_f32_e32 v68, v99, v99
	v_max_f32_e32 v94, v91, v88
	v_min_f32_e32 v88, v91, v88
	v_max_f32_e32 v91, v109, v109
	v_max_f32_e32 v107, v107, v107
	v_max_f32_e32 v106, v103, v100
	v_min_f32_e32 v100, v103, v100
	v_max_f32_e32 v103, v113, v113
	v_max_f32_e32 v111, v111, v111
	v_max_f32_e32 v69, v68, v64
	v_min_f32_e32 v64, v68, v64
	v_max_f32_e32 v68, v101, v101
	v_max_f32_e32 v70, v104, v104
	v_max_f32_e32 v109, v107, v91
	v_min_f32_e32 v91, v107, v91
	v_max_f32_e32 v107, v108, v108
	v_max_f32_e32 v108, v110, v110
	v_max_f32_e32 v113, v111, v103
	v_min_f32_e32 v103, v111, v103
	v_max_f32_e32 v111, v112, v112
	v_max_f32_e32 v112, v114, v114
	v_max_f32_e32 v99, v70, v68
	v_min_f32_e32 v68, v70, v68
	v_max_f32_e32 v110, v108, v107
	v_min_f32_e32 v107, v108, v107
	v_max_f32_e32 v114, v112, v111
	v_min_f32_e32 v111, v112, v111
	v_max_f32_e32 v70, v8, v1
	v_min_f32_e32 v1, v8, v1
	v_max_f32_e32 v8, v0, v3
	v_min_f32_e32 v0, v0, v3
	v_max_f32_e32 v3, v9, v10
	v_min_f32_e32 v9, v9, v10
	v_max_f32_e32 v10, v59, v2
	v_min_f32_e32 v2, v59, v2
	v_max_f32_e32 v59, v62, v61
	v_min_f32_e32 v61, v62, v61
	v_max_f32_e32 v62, v11, v67
; #define CE_DESC(a, b) { const float hi_ = fmaxf(a, b), lo_ = fminf(a, b); a = hi_; b = lo_; }
; __device__ __forceinline__ void phase4c(const Params& p, char* smem) {
;     ...
; #pragma unroll
;       for (int g = 0; g < 4; g++) {
; #pragma unroll
;         for (int lk = 1; lk <= 4; lk++) {
; #pragma unroll
;           for (int lj = lk - 1; lj >= 0; lj--) {
; #pragma unroll
;             for (int i = 0; i < 16; i++) {
;               const int l = i ^ (1 << lj);
;               if (l > i) {
;                 if ((i & (1 << lk)) == 0) { CE_DESC(sv[g * 16 + i], sv[g * 16 + l]) } else { CE_DESC(sv[g * 16 + l], sv[g * 16 + i]) }
;               }
;             }
;           }
;         }
;       }
	v_min_f32_e32 v11, v11, v67
	v_max_f32_e32 v67, v68, v69
	v_min_f32_e32 v68, v68, v69
	v_max_f32_e32 v69, v99, v64
	v_min_f32_e32 v64, v99, v64
	v_max_f32_e32 v108, v178, v56
	v_min_f32_e32 v56, v178, v56
	v_max_f32_e32 v178, v6, v58
	v_min_f32_e32 v6, v6, v58
	v_max_f32_e32 v58, v71, v74
	v_min_f32_e32 v71, v71, v74
	v_max_f32_e32 v74, v77, v57
	v_min_f32_e32 v57, v77, v57
	v_max_f32_e32 v77, v93, v88
	v_min_f32_e32 v88, v93, v88
	v_max_f32_e32 v93, v73, v94
	v_min_f32_e32 v73, v73, v94
	v_max_f32_e32 v94, v107, v109
	v_min_f32_e32 v107, v107, v109
	v_max_f32_e32 v109, v110, v91
	v_min_f32_e32 v91, v110, v91
	v_max_f32_e32 v112, v191, v63
	v_min_f32_e32 v63, v191, v63
	v_max_f32_e32 v191, v60, v66
	v_min_f32_e32 v60, v60, v66
	v_max_f32_e32 v66, v95, v97
	v_min_f32_e32 v95, v95, v97
	v_max_f32_e32 v97, v98, v65
	v_min_f32_e32 v65, v98, v65
	v_max_f32_e32 v98, v105, v100
	v_min_f32_e32 v100, v105, v100
	v_max_f32_e32 v105, v96, v106
	v_min_f32_e32 v96, v96, v106
	v_max_f32_e32 v106, v111, v113
	v_min_f32_e32 v111, v111, v113
	v_max_f32_e32 v113, v114, v103
	v_min_f32_e32 v103, v114, v103
	v_max_f32_e32 v99, v70, v8
	v_min_f32_e32 v8, v70, v8
	v_max_f32_e32 v70, v1, v0
	v_min_f32_e32 v0, v1, v0
	v_max_f32_e32 v1, v2, v9
	v_min_f32_e32 v2, v2, v9
	v_max_f32_e32 v9, v10, v3
	v_min_f32_e32 v3, v10, v3
	v_max_f32_e32 v10, v59, v62
	v_min_f32_e32 v59, v59, v62
	v_max_f32_e32 v62, v61, v11
	v_min_f32_e32 v11, v61, v11
	v_max_f32_e32 v61, v64, v68
	v_min_f32_e32 v64, v64, v68
	v_max_f32_e32 v68, v69, v67
	v_min_f32_e32 v67, v69, v67
	v_max_f32_e32 v110, v108, v178
	v_min_f32_e32 v108, v108, v178
	v_max_f32_e32 v178, v56, v6
	v_min_f32_e32 v6, v56, v6
	v_max_f32_e32 v56, v57, v71
	v_min_f32_e32 v57, v57, v71
	v_max_f32_e32 v71, v74, v58
	v_min_f32_e32 v58, v74, v58
	v_max_f32_e32 v74, v77, v93
	v_min_f32_e32 v77, v77, v93
	v_max_f32_e32 v93, v88, v73
	v_min_f32_e32 v73, v88, v73
	v_max_f32_e32 v88, v91, v107
	v_min_f32_e32 v91, v91, v107
	v_max_f32_e32 v107, v109, v94
	v_min_f32_e32 v94, v109, v94
	v_max_f32_e32 v114, v112, v191
	v_min_f32_e32 v112, v112, v191
	v_max_f32_e32 v191, v63, v60
	v_min_f32_e32 v60, v63, v60
	v_max_f32_e32 v63, v65, v95
	v_min_f32_e32 v65, v65, v95
	v_max_f32_e32 v95, v97, v66
	v_min_f32_e32 v66, v97, v66
	v_max_f32_e32 v97, v98, v105
	v_min_f32_e32 v98, v98, v105
	v_max_f32_e32 v105, v100, v96
	v_min_f32_e32 v96, v100, v96
	v_max_f32_e32 v100, v103, v111
	v_min_f32_e32 v103, v103, v111
	v_max_f32_e32 v111, v113, v106
	v_min_f32_e32 v106, v113, v106
	v_max_f32_e32 v69, v99, v2
	v_min_f32_e32 v2, v99, v2
	v_max_f32_e32 v99, v8, v1
	v_min_f32_e32 v1, v8, v1
	v_max_f32_e32 v8, v70, v3
	v_min_f32_e32 v3, v70, v3
	v_max_f32_e32 v70, v0, v9
	v_min_f32_e32 v0, v0, v9
	v_max_f32_e32 v9, v64, v10
	v_min_f32_e32 v10, v64, v10
	v_max_f32_e32 v64, v61, v59
	v_min_f32_e32 v59, v61, v59
	v_max_f32_e32 v61, v67, v62
	v_min_f32_e32 v62, v67, v62
	v_max_f32_e32 v67, v68, v11
	v_min_f32_e32 v11, v68, v11
	v_max_f32_e32 v109, v110, v57
	v_min_f32_e32 v57, v110, v57
	v_max_f32_e32 v110, v108, v56
	v_min_f32_e32 v56, v108, v56
	v_max_f32_e32 v108, v178, v58
	v_min_f32_e32 v58, v178, v58
	v_max_f32_e32 v178, v6, v71
	v_min_f32_e32 v6, v6, v71
	v_max_f32_e32 v71, v91, v74
	v_min_f32_e32 v74, v91, v74
	v_max_f32_e32 v91, v88, v77
	v_min_f32_e32 v77, v88, v77
	v_max_f32_e32 v88, v94, v93
	v_min_f32_e32 v93, v94, v93
	v_max_f32_e32 v94, v107, v73
	v_min_f32_e32 v73, v107, v73
	v_max_f32_e32 v113, v114, v65
	v_min_f32_e32 v65, v114, v65
	v_max_f32_e32 v114, v112, v63
	v_min_f32_e32 v63, v112, v63
	v_max_f32_e32 v112, v191, v66
	v_min_f32_e32 v66, v191, v66
	v_max_f32_e32 v191, v60, v95
	v_min_f32_e32 v60, v60, v95
	v_max_f32_e32 v95, v103, v97
	v_min_f32_e32 v97, v103, v97
	v_max_f32_e32 v103, v100, v98
	v_min_f32_e32 v98, v100, v98
	v_max_f32_e32 v100, v106, v105
	v_min_f32_e32 v105, v106, v105
	v_max_f32_e32 v106, v111, v96
	v_min_f32_e32 v96, v111, v96
	v_max_f32_e32 v68, v69, v8
	v_min_f32_e32 v8, v69, v8
	v_max_f32_e32 v69, v99, v70
	v_min_f32_e32 v70, v99, v70
	v_max_f32_e32 v99, v2, v3
	v_min_f32_e32 v2, v2, v3
	v_max_f32_e32 v3, v1, v0
	v_min_f32_e32 v0, v1, v0
	v_max_f32_e32 v1, v62, v10
	v_min_f32_e32 v10, v62, v10
	v_max_f32_e32 v62, v11, v59
	v_min_f32_e32 v11, v11, v59
	v_max_f32_e32 v59, v61, v9
	v_min_f32_e32 v9, v61, v9
	v_max_f32_e32 v61, v67, v64
	v_min_f32_e32 v64, v67, v64
	v_max_f32_e32 v107, v109, v108
	v_min_f32_e32 v108, v109, v108
	v_max_f32_e32 v109, v110, v178
	v_min_f32_e32 v110, v110, v178
	v_max_f32_e32 v178, v57, v58
	v_min_f32_e32 v57, v57, v58
	v_max_f32_e32 v58, v56, v6
	v_min_f32_e32 v6, v56, v6
	v_max_f32_e32 v56, v93, v74
	v_min_f32_e32 v74, v93, v74
	v_max_f32_e32 v93, v73, v77
	v_min_f32_e32 v73, v73, v77
	v_max_f32_e32 v77, v88, v71
	v_min_f32_e32 v71, v88, v71
	v_max_f32_e32 v88, v94, v91
	v_min_f32_e32 v91, v94, v91
	v_max_f32_e32 v111, v113, v112
	v_min_f32_e32 v112, v113, v112
	v_max_f32_e32 v113, v114, v191
	v_min_f32_e32 v114, v114, v191
	v_max_f32_e32 v191, v65, v66
	v_min_f32_e32 v65, v65, v66
	v_max_f32_e32 v66, v63, v60
	v_min_f32_e32 v60, v63, v60
	v_max_f32_e32 v63, v105, v97
	v_min_f32_e32 v97, v105, v97
	v_max_f32_e32 v105, v96, v98
	v_min_f32_e32 v96, v96, v98
	v_max_f32_e32 v98, v100, v95
	v_min_f32_e32 v95, v100, v95
	v_max_f32_e32 v100, v106, v103
	v_min_f32_e32 v103, v106, v103
	v_max_f32_e32 v67, v68, v69
	v_min_f32_e32 v68, v68, v69
	v_max_f32_e32 v69, v8, v70
	v_min_f32_e32 v8, v8, v70
	v_max_f32_e32 v70, v99, v3
	v_min_f32_e32 v3, v99, v3
	v_max_f32_e32 v99, v2, v0
	v_min_f32_e32 v0, v2, v0
	v_max_f32_e32 v2, v11, v10
	v_min_f32_e32 v10, v11, v10
	v_max_f32_e32 v11, v62, v1
; #define CE_DESC(a, b) { const float hi_ = fmaxf(a, b), lo_ = fminf(a, b); a = hi_; b = lo_; }
; __device__ __forceinline__ void phase4c(const Params& p, char* smem) {
;     ...
; #pragma unroll
;       for (int g = 0; g < 4; g++) {
; #pragma unroll
;         for (int lk = 1; lk <= 4; lk++) {
; #pragma unroll
;           for (int lj = lk - 1; lj >= 0; lj--) {
; #pragma unroll
;             for (int i = 0; i < 16; i++) {
;               const int l = i ^ (1 << lj);
;               if (l > i) {
;                 if ((i & (1 << lk)) == 0) { CE_DESC(sv[g * 16 + i], sv[g * 16 + l]) } else { CE_DESC(sv[g * 16 + l], sv[g * 16 + i]) }
;               }
;             }
;           }
;         }
;       }
	v_min_f32_e32 v1, v62, v1
	v_max_f32_e32 v62, v64, v9
	v_min_f32_e32 v9, v64, v9
	v_max_f32_e32 v64, v61, v59
	v_min_f32_e32 v59, v61, v59
	v_max_f32_e32 v94, v107, v109
	v_min_f32_e32 v107, v107, v109
	v_max_f32_e32 v109, v108, v110
	v_min_f32_e32 v108, v108, v110
	v_max_f32_e32 v110, v178, v58
	v_min_f32_e32 v58, v178, v58
	v_max_f32_e32 v178, v57, v6
	v_min_f32_e32 v6, v57, v6
	v_max_f32_e32 v57, v73, v74
	v_min_f32_e32 v73, v73, v74
	v_max_f32_e32 v74, v93, v56
	v_min_f32_e32 v56, v93, v56
	v_max_f32_e32 v93, v91, v71
	v_min_f32_e32 v71, v91, v71
	v_max_f32_e32 v91, v88, v77
	v_min_f32_e32 v77, v88, v77
	v_max_f32_e32 v106, v111, v113
	v_min_f32_e32 v111, v111, v113
	v_max_f32_e32 v113, v112, v114
	v_min_f32_e32 v112, v112, v114
	v_max_f32_e32 v114, v191, v66
	v_min_f32_e32 v66, v191, v66
	v_max_f32_e32 v191, v65, v60
	v_min_f32_e32 v60, v65, v60
	v_max_f32_e32 v65, v96, v97
	v_min_f32_e32 v96, v96, v97
	v_max_f32_e32 v97, v105, v63
	v_min_f32_e32 v63, v105, v63
	v_max_f32_e32 v105, v103, v95
	v_min_f32_e32 v95, v103, v95
	v_max_f32_e32 v103, v100, v98
	v_min_f32_e32 v98, v100, v98
	v_max_f32_e32 v61, v67, v10
	v_min_f32_e32 v10, v67, v10
	v_max_f32_e32 v67, v68, v2
	v_min_f32_e32 v2, v68, v2
	v_max_f32_e32 v68, v69, v1
	v_min_f32_e32 v1, v69, v1
	v_max_f32_e32 v69, v8, v11
	v_min_f32_e32 v8, v8, v11
	v_max_f32_e32 v11, v70, v9
	v_min_f32_e32 v9, v70, v9
	v_max_f32_e32 v70, v3, v62
	v_min_f32_e32 v3, v3, v62
	v_max_f32_e32 v62, v99, v59
	v_min_f32_e32 v59, v99, v59
	v_max_f32_e32 v99, v0, v64
	v_min_f32_e32 v0, v0, v64
	v_max_f32_e32 v88, v94, v73
	v_min_f32_e32 v73, v94, v73
	v_max_f32_e32 v94, v107, v57
	v_min_f32_e32 v57, v107, v57
	v_max_f32_e32 v107, v109, v56
	v_min_f32_e32 v56, v109, v56
	v_max_f32_e32 v109, v108, v74
	v_min_f32_e32 v74, v108, v74
	v_max_f32_e32 v108, v110, v71
	v_min_f32_e32 v71, v110, v71
	v_max_f32_e32 v110, v58, v93
	v_min_f32_e32 v58, v58, v93
	v_max_f32_e32 v93, v178, v77
	v_min_f32_e32 v77, v178, v77
	v_max_f32_e32 v178, v6, v91
	v_min_f32_e32 v6, v6, v91
	v_max_f32_e32 v100, v106, v96
	v_min_f32_e32 v96, v106, v96
	v_max_f32_e32 v106, v111, v65
	v_min_f32_e32 v65, v111, v65
	v_max_f32_e32 v111, v113, v63
	v_min_f32_e32 v63, v113, v63
	v_max_f32_e32 v113, v112, v97
	v_min_f32_e32 v97, v112, v97
	v_max_f32_e32 v112, v114, v95
	v_min_f32_e32 v95, v114, v95
	v_max_f32_e32 v114, v66, v105
	v_min_f32_e32 v66, v66, v105
	v_max_f32_e32 v105, v191, v98
	v_min_f32_e32 v98, v191, v98
	v_max_f32_e32 v191, v60, v103
	v_min_f32_e32 v60, v60, v103
	v_max_f32_e32 v64, v61, v11
	v_min_f32_e32 v11, v61, v11
	v_max_f32_e32 v61, v67, v70
	v_min_f32_e32 v67, v67, v70
	v_max_f32_e32 v70, v68, v62
	v_min_f32_e32 v62, v68, v62
	v_max_f32_e32 v68, v69, v99
	v_min_f32_e32 v69, v69, v99
	v_max_f32_e32 v99, v10, v9
	v_min_f32_e32 v9, v10, v9
	v_max_f32_e32 v10, v2, v3
	v_min_f32_e32 v2, v2, v3
	v_max_f32_e32 v3, v1, v59
	v_min_f32_e32 v1, v1, v59
	v_max_f32_e32 v59, v8, v0
	v_min_f32_e32 v0, v8, v0
	v_max_f32_e32 v91, v88, v108
	v_min_f32_e32 v88, v88, v108
	v_max_f32_e32 v108, v94, v110
	v_min_f32_e32 v94, v94, v110
	v_max_f32_e32 v110, v107, v93
	v_min_f32_e32 v93, v107, v93
	v_max_f32_e32 v107, v109, v178
	v_min_f32_e32 v109, v109, v178
	v_max_f32_e32 v178, v73, v71
	v_min_f32_e32 v71, v73, v71
	v_max_f32_e32 v73, v57, v58
	v_min_f32_e32 v57, v57, v58
	v_max_f32_e32 v58, v56, v77
	v_min_f32_e32 v56, v56, v77
	v_max_f32_e32 v77, v74, v6
	v_min_f32_e32 v6, v74, v6
	v_max_f32_e32 v103, v100, v112
	v_min_f32_e32 v100, v100, v112
	v_max_f32_e32 v112, v106, v114
	v_min_f32_e32 v106, v106, v114
	v_max_f32_e32 v114, v111, v105
	v_min_f32_e32 v105, v111, v105
	v_max_f32_e32 v111, v113, v191
	v_min_f32_e32 v113, v113, v191
	v_max_f32_e32 v191, v96, v95
	v_min_f32_e32 v95, v96, v95
	v_max_f32_e32 v96, v65, v66
	v_min_f32_e32 v65, v65, v66
	v_max_f32_e32 v66, v63, v98
	v_min_f32_e32 v63, v63, v98
	v_max_f32_e32 v98, v97, v60
	v_min_f32_e32 v60, v97, v60
	v_max_f32_e32 v75, v80, v81
	v_min_f32_e32 v84, v80, v81
	v_max_f32_e32 v81, v78, v89
	v_min_f32_e32 v80, v78, v89
	v_max_f32_e32 v78, v115, v137
	v_min_f32_e32 v89, v115, v137
	v_max_f32_e32 v8, v64, v70
	v_min_f32_e32 v64, v64, v70
	v_max_f32_e32 v70, v61, v68
	v_min_f32_e32 v61, v61, v68
	v_max_f32_e32 v68, v11, v62
	v_min_f32_e32 v11, v11, v62
	v_max_f32_e32 v62, v67, v69
	v_min_f32_e32 v67, v67, v69
	v_max_f32_e32 v69, v99, v3
	v_min_f32_e32 v3, v99, v3
	v_max_f32_e32 v99, v10, v59
	v_min_f32_e32 v10, v10, v59
	v_max_f32_e32 v59, v9, v1
	v_min_f32_e32 v1, v9, v1
	v_max_f32_e32 v9, v2, v0
	v_min_f32_e32 v0, v2, v0
	v_max_f32_e32 v74, v91, v110
	v_min_f32_e32 v91, v91, v110
	v_max_f32_e32 v110, v108, v107
	v_min_f32_e32 v107, v108, v107
	v_max_f32_e32 v108, v88, v93
	v_min_f32_e32 v88, v88, v93
	v_max_f32_e32 v93, v94, v109
	v_min_f32_e32 v94, v94, v109
	v_max_f32_e32 v109, v178, v58
	v_min_f32_e32 v58, v178, v58
	v_max_f32_e32 v178, v73, v77
	v_min_f32_e32 v73, v73, v77
	v_max_f32_e32 v77, v71, v56
	v_min_f32_e32 v56, v71, v56
	v_max_f32_e32 v71, v57, v6
	v_min_f32_e32 v6, v57, v6
	v_max_f32_e32 v97, v103, v114
	v_min_f32_e32 v103, v103, v114
	v_max_f32_e32 v114, v112, v111
	v_min_f32_e32 v111, v112, v111
	v_max_f32_e32 v112, v100, v105
	v_min_f32_e32 v100, v100, v105
	v_max_f32_e32 v105, v106, v113
	v_min_f32_e32 v106, v106, v113
	v_max_f32_e32 v113, v191, v66
	v_min_f32_e32 v66, v191, v66
	v_max_f32_e32 v191, v96, v98
	v_min_f32_e32 v96, v96, v98
	v_max_f32_e32 v98, v95, v63
	v_min_f32_e32 v63, v95, v63
	v_max_f32_e32 v95, v65, v60
	v_min_f32_e32 v60, v65, v60
	v_min_f32_e32 v241, v72, v75
	v_min_f32_e32 v240, v79, v84
	v_min_f32_e32 v237, v81, v87
	v_min_f32_e32 v184, v80, v85
; #define CE_DESC(a, b) { const float hi_ = fmaxf(a, b), lo_ = fminf(a, b); a = hi_; b = lo_; }
; __device__ __forceinline__ void phase4c(const Params& p, char* smem) {
;     ...
; #pragma unroll
;       for (int g = 0; g < 4; g++) {
; #pragma unroll
;         for (int lk = 1; lk <= 4; lk++) {
; #pragma unroll
;           for (int lj = lk - 1; lj >= 0; lj--) {
; #pragma unroll
;             for (int i = 0; i < 16; i++) {
;               const int l = i ^ (1 << lj);
;               if (l > i) {
;                 if ((i & (1 << lk)) == 0) { CE_DESC(sv[g * 16 + i], sv[g * 16 + l]) } else { CE_DESC(sv[g * 16 + l], sv[g * 16 + i]) }
;               }
;             }
;           }
;         }
;       }
;     ...
;       MERGE16(0, 16)
;       MERGE16(32, 48)
;       MERGE16(0, 32)
	v_min_f32_e32 v236, v76, v78
	v_min_f32_e32 v183, v82, v89
	v_min_f32_e32 v182, v86, v92
	v_min_f32_e32 v115, v83, v90
	v_min_f32_e32 v2, v8, v70
	v_min_f32_e32 v101, v64, v61
	v_min_f32_e32 v102, v68, v62
	v_min_f32_e32 v104, v11, v67
	v_min_f32_e32 v135, v69, v99
	v_min_f32_e32 v137, v3, v10
	v_min_f32_e32 v176, v59, v9
	v_min_f32_e32 v177, v1, v0
	v_min_f32_e32 v57, v74, v110
	v_min_f32_e32 v179, v91, v107
	v_min_f32_e32 v185, v108, v93
	v_min_f32_e32 v186, v88, v94
	v_min_f32_e32 v187, v109, v178
	v_min_f32_e32 v188, v58, v73
	v_min_f32_e32 v189, v77, v71
	v_min_f32_e32 v190, v56, v6
	v_min_f32_e32 v65, v97, v114
	v_min_f32_e32 v192, v103, v111
	v_min_f32_e32 v193, v112, v105
	v_min_f32_e32 v194, v100, v106
	v_min_f32_e32 v242, v113, v191
	v_min_f32_e32 v243, v66, v96
	v_min_f32_e32 v244, v98, v95
	v_min_f32_e32 v245, v63, v60
	v_max3_f32 v0, v241, v1, v0
	v_max3_f32 v1, v79, v84, v176
	v_max3_f32 v9, v240, v59, v9
	v_max3_f32 v59, v81, v87, v137
	v_max3_f32 v3, v237, v3, v10
	v_max3_f32 v10, v80, v85, v135
	v_max3_f32 v69, v184, v69, v99
	v_max3_f32 v11, v236, v11, v67
	v_max3_f32 v67, v82, v89, v102
	v_max3_f32 v62, v183, v68, v62
	v_max3_f32 v68, v86, v92, v101
	v_max3_f32 v61, v182, v64, v61
	v_max3_f32 v2, v83, v90, v2
	v_max3_f32 v8, v115, v8, v70
	v_max3_f32 v64, v76, v78, v104
	v_max3_f32 v70, v72, v75, v177
	v_max3_f32 v57, v57, v63, v60
	v_max3_f32 v60, v91, v107, v244
	v_max3_f32 v63, v179, v98, v95
	v_max3_f32 v83, v108, v93, v243
	v_max3_f32 v66, v185, v66, v96
	v_max3_f32 v84, v88, v94, v242
	v_max3_f32 v85, v186, v113, v191
	v_max3_f32 v86, v187, v100, v106
	v_max3_f32 v58, v58, v73, v193
	v_max3_f32 v73, v188, v112, v105
	v_max3_f32 v71, v77, v71, v192
	v_max3_f32 v77, v189, v103, v111
	v_max3_f32 v6, v56, v6, v65
	v_max3_f32 v56, v190, v97, v114
	v_max3_f32 v65, v109, v178, v194
	v_max3_f32 v74, v74, v110, v245
	v_max_f32_e32 v72, v70, v64
	v_min_f32_e32 v64, v70, v64
	v_max_f32_e32 v70, v0, v11
	v_min_f32_e32 v0, v0, v11
	v_max_f32_e32 v11, v1, v67
	v_min_f32_e32 v1, v1, v67
	v_max_f32_e32 v67, v9, v62
	v_min_f32_e32 v9, v9, v62
	v_max_f32_e32 v62, v59, v68
	v_min_f32_e32 v59, v59, v68
	v_max_f32_e32 v68, v3, v61
	v_min_f32_e32 v3, v3, v61
	v_max_f32_e32 v61, v10, v2
	v_min_f32_e32 v2, v10, v2
	v_max_f32_e32 v10, v69, v8
	v_min_f32_e32 v8, v69, v8
	v_max_f32_e32 v87, v74, v65
	v_min_f32_e32 v65, v74, v65
	v_max_f32_e32 v74, v57, v86
	v_min_f32_e32 v57, v57, v86
	v_max_f32_e32 v86, v60, v58
	v_min_f32_e32 v58, v60, v58
	v_max_f32_e32 v60, v63, v73
	v_min_f32_e32 v63, v63, v73
	v_max_f32_e32 v73, v83, v71
	v_min_f32_e32 v71, v83, v71
	v_max_f32_e32 v83, v66, v77
	v_min_f32_e32 v66, v66, v77
	v_max_f32_e32 v77, v84, v6
	v_min_f32_e32 v6, v84, v6
	v_max_f32_e32 v84, v85, v56
	v_min_f32_e32 v56, v85, v56
	v_max_f32_e32 v69, v72, v62
	v_min_f32_e32 v62, v72, v62
	v_max_f32_e32 v72, v70, v68
	v_min_f32_e32 v68, v70, v68
	v_max_f32_e32 v70, v11, v61
	v_min_f32_e32 v11, v11, v61
	v_max_f32_e32 v61, v67, v10
	v_min_f32_e32 v10, v67, v10
	v_max_f32_e32 v67, v64, v59
	v_min_f32_e32 v59, v64, v59
	v_max_f32_e32 v64, v0, v3
	v_min_f32_e32 v0, v0, v3
	v_max_f32_e32 v3, v1, v2
	v_min_f32_e32 v1, v1, v2
	v_max_f32_e32 v2, v9, v8
	v_min_f32_e32 v8, v9, v8
	v_max_f32_e32 v85, v87, v73
	v_min_f32_e32 v73, v87, v73
	v_max_f32_e32 v87, v74, v83
	v_min_f32_e32 v74, v74, v83
	v_max_f32_e32 v83, v86, v77
	v_min_f32_e32 v77, v86, v77
	v_max_f32_e32 v86, v60, v84
	v_min_f32_e32 v60, v60, v84
	v_max_f32_e32 v84, v65, v71
	v_min_f32_e32 v65, v65, v71
	v_max_f32_e32 v71, v57, v66
	v_min_f32_e32 v57, v57, v66
	v_max_f32_e32 v66, v58, v6
	v_min_f32_e32 v6, v58, v6
	v_max_f32_e32 v58, v63, v56
	v_min_f32_e32 v56, v63, v56
	v_max_f32_e32 v9, v69, v70
	v_min_f32_e32 v69, v69, v70
	v_max_f32_e32 v70, v72, v61
	v_min_f32_e32 v61, v72, v61
	v_max_f32_e32 v72, v62, v11
	v_min_f32_e32 v11, v62, v11
	v_max_f32_e32 v62, v68, v10
	v_min_f32_e32 v10, v68, v10
	v_max_f32_e32 v68, v67, v3
	v_min_f32_e32 v3, v67, v3
	v_max_f32_e32 v67, v64, v2
	v_min_f32_e32 v2, v64, v2
	v_max_f32_e32 v64, v59, v1
	v_min_f32_e32 v1, v59, v1
	v_max_f32_e32 v59, v0, v8
	v_min_f32_e32 v0, v0, v8
	v_max_f32_e32 v63, v85, v83
	v_min_f32_e32 v83, v85, v83
	v_max_f32_e32 v85, v87, v86
	v_min_f32_e32 v86, v87, v86
	v_max_f32_e32 v87, v73, v77
	v_min_f32_e32 v73, v73, v77
	v_max_f32_e32 v77, v74, v60
	v_min_f32_e32 v60, v74, v60
	v_max_f32_e32 v74, v84, v66
	v_min_f32_e32 v66, v84, v66
	v_max_f32_e32 v84, v71, v58
	v_min_f32_e32 v58, v71, v58
	v_max_f32_e32 v71, v65, v6
	v_min_f32_e32 v6, v65, v6
	v_max_f32_e32 v65, v57, v56
	v_min_f32_e32 v56, v57, v56
	v_min_f32_e32 v8, v9, v70
	v_min_f32_e32 v75, v69, v61
	v_min_f32_e32 v76, v72, v62
	v_min_f32_e32 v78, v11, v10
	v_min_f32_e32 v79, v68, v67
	v_min_f32_e32 v80, v3, v2
	v_min_f32_e32 v81, v64, v59
	v_min_f32_e32 v82, v1, v0
	v_min_f32_e32 v57, v63, v85
	v_min_f32_e32 v88, v83, v86
	v_min_f32_e32 v89, v87, v77
	v_min_f32_e32 v90, v73, v60
	v_min_f32_e32 v91, v74, v84
	v_min_f32_e32 v92, v66, v58
	v_min_f32_e32 v93, v71, v65
	v_min_f32_e32 v94, v6, v56
	v_max3_f32 v6, v8, v6, v56
	v_max3_f32 v8, v69, v61, v93
	v_max3_f32 v56, v75, v71, v65
	v_max3_f32 v61, v72, v62, v92
	v_max3_f32 v58, v76, v66, v58
	v_max3_f32 v10, v11, v10, v91
	v_max3_f32 v11, v78, v74, v84
	v_max3_f32 v60, v79, v73, v60
	v_max3_f32 v2, v3, v2, v89
	v_max3_f32 v3, v80, v87, v77
	v_max3_f32 v59, v64, v59, v88
	v_max3_f32 v62, v81, v83, v86
	v_max3_f32 v0, v1, v0, v57
	v_max3_f32 v1, v82, v63, v85
	v_max3_f32 v57, v68, v67, v90
	v_max3_f32 v9, v9, v70, v94
	v_max_f32_e32 v63, v9, v57
	v_min_f32_e32 v9, v9, v57
	v_max_f32_e32 v57, v6, v60
	v_min_f32_e32 v6, v6, v60
; #define DPP_F(v, ctrl) __int_as_float(__builtin_amdgcn_update_dpp(0, __float_as_int(v), (ctrl), 0xF, 0xF, true))
; __device__ __forceinline__ void phase4c(const Params& p, char* smem) {
;     ...
;       MERGE16(0, 16)
;       MERGE16(32, 48)
;       MERGE16(0, 32)
; #pragma unroll
;       for (int i = 0; i < 16; i++) sv[16 + i] = DPP_F(sv[i], 0xB1);
;       MERGE16(0, 16)
;       if (part == 0) {
	v_max_f32_e32 v60, v8, v2
	v_min_f32_e32 v2, v8, v2
	v_max_f32_e32 v8, v56, v3
	v_min_f32_e32 v3, v56, v3
	v_max_f32_e32 v56, v61, v59
	v_min_f32_e32 v59, v61, v59
	v_max_f32_e32 v61, v58, v62
	v_min_f32_e32 v58, v58, v62
	v_max_f32_e32 v62, v10, v0
	v_min_f32_e32 v0, v10, v0
	v_max_f32_e32 v10, v11, v1
	v_min_f32_e32 v1, v11, v1
	v_max_f32_e32 v11, v63, v56
	v_min_f32_e32 v56, v63, v56
	v_max_f32_e32 v63, v57, v61
	v_min_f32_e32 v57, v57, v61
	v_max_f32_e32 v61, v60, v62
	v_min_f32_e32 v60, v60, v62
	v_max_f32_e32 v62, v8, v10
	v_min_f32_e32 v8, v8, v10
	v_max_f32_e32 v10, v9, v59
	v_min_f32_e32 v9, v9, v59
	v_max_f32_e32 v59, v6, v58
	v_min_f32_e32 v6, v6, v58
	v_max_f32_e32 v58, v2, v0
	v_min_f32_e32 v0, v2, v0
	v_max_f32_e32 v2, v3, v1
	v_min_f32_e32 v1, v3, v1
	v_max_f32_e32 v3, v11, v61
	v_min_f32_e32 v11, v11, v61
	v_max_f32_e32 v61, v63, v62
	v_min_f32_e32 v62, v63, v62
	v_max_f32_e32 v63, v56, v60
	v_min_f32_e32 v60, v56, v60
	v_max_f32_e32 v56, v57, v8
	v_min_f32_e32 v8, v57, v8
	v_max_f32_e32 v66, v10, v58
	v_min_f32_e32 v10, v10, v58
	v_max_f32_e32 v58, v59, v2
	v_min_f32_e32 v2, v59, v2
	v_max_f32_e32 v59, v9, v0
	v_min_f32_e32 v9, v9, v0
	v_max_f32_e32 v67, v6, v1
	v_min_f32_e32 v68, v6, v1
	v_max_f32_e32 v72, v3, v61
	v_min_f32_e32 v57, v3, v61
	v_max_f32_e32 v65, v11, v62
	v_min_f32_e32 v1, v11, v62
	v_max_f32_e32 v71, v63, v56
	v_min_f32_e32 v56, v63, v56
	v_max_f32_e32 v64, v60, v8
	v_min_f32_e32 v0, v60, v8
	v_max_f32_e32 v77, v66, v58
	v_min_f32_e32 v61, v66, v58
	v_max_f32_e32 v69, v10, v2
	v_min_f32_e32 v6, v10, v2
	v_max_f32_e32 v74, v59, v67
	v_min_f32_e32 v58, v59, v67
	v_max_f32_e32 v66, v9, v68
	v_min_f32_e32 v2, v9, v68
	v_mov_b32_dpp v3, v72 quad_perm:[1,0,3,2] row_mask:0xf bank_mask:0xf bound_ctrl:1
	v_mov_b32_dpp v70, v57 quad_perm:[1,0,3,2] row_mask:0xf bank_mask:0xf bound_ctrl:1
	v_mov_b32_dpp v62, v65 quad_perm:[1,0,3,2] row_mask:0xf bank_mask:0xf bound_ctrl:1
	v_mov_b32_dpp v78, v1 quad_perm:[1,0,3,2] row_mask:0xf bank_mask:0xf bound_ctrl:1
	v_mov_b32_dpp v59, v71 quad_perm:[1,0,3,2] row_mask:0xf bank_mask:0xf bound_ctrl:1
	v_mov_b32_dpp v75, v56 quad_perm:[1,0,3,2] row_mask:0xf bank_mask:0xf bound_ctrl:1
	v_mov_b32_dpp v67, v64 quad_perm:[1,0,3,2] row_mask:0xf bank_mask:0xf bound_ctrl:1
	v_mov_b32_dpp v80, v0 quad_perm:[1,0,3,2] row_mask:0xf bank_mask:0xf bound_ctrl:1
	v_mov_b32_dpp v60, v77 quad_perm:[1,0,3,2] row_mask:0xf bank_mask:0xf bound_ctrl:1
	v_mov_b32_dpp v76, v61 quad_perm:[1,0,3,2] row_mask:0xf bank_mask:0xf bound_ctrl:1
	v_mov_b32_dpp v68, v69 quad_perm:[1,0,3,2] row_mask:0xf bank_mask:0xf bound_ctrl:1
	v_mov_b32_dpp v81, v6 quad_perm:[1,0,3,2] row_mask:0xf bank_mask:0xf bound_ctrl:1
	v_mov_b32_dpp v63, v74 quad_perm:[1,0,3,2] row_mask:0xf bank_mask:0xf bound_ctrl:1
	v_mov_b32_dpp v79, v58 quad_perm:[1,0,3,2] row_mask:0xf bank_mask:0xf bound_ctrl:1
	v_mov_b32_dpp v73, v66 quad_perm:[1,0,3,2] row_mask:0xf bank_mask:0xf bound_ctrl:1
	v_mov_b32_dpp v82, v2 quad_perm:[1,0,3,2] row_mask:0xf bank_mask:0xf bound_ctrl:1
	s_and_saveexec_b64 s[0:1], s[4:5]
	s_cbranch_execz .LBB0_1415
; #define DPP_F(v, ctrl) __int_as_float(__builtin_amdgcn_update_dpp(0, __float_as_int(v), (ctrl), 0xF, 0xF, true))
; __device__ __forceinline__ void phase4c(const Params& p, char* smem) {
;     ...
;       MERGE16(0, 16)
;       MERGE16(32, 48)
;       MERGE16(0, 32)
; #pragma unroll
;       for (int i = 0; i < 16; i++) sv[16 + i] = DPP_F(sv[i], 0xB1);
;       MERGE16(0, 16)
;       if (part == 0) {
;         const size_t ob = ((size_t)(m0 + tokl) * 16 + nt) * 16;
; #pragma unroll
;         for (int q = 0; q < 4; q++) {
;           *(float4*)(TOPS + ob + q * 4) = make_float4(sv[4 * q], sv[4 * q + 1], sv[4 * q + 2], sv[4 * q + 3]);
;           *(int4*)(TOPI + ob + q * 4) = make_int4(127 - (int)(__float_as_uint(sv[4 * q]) & 127u), 127 - (int)(__float_as_uint(sv[4 * q + 1]) & 127u),
;                                                   127 - (int)(__float_as_uint(sv[4 * q + 2]) & 127u), 127 - (int)(__float_as_uint(sv[4 * q + 3]) & 127u));
;         }
;       }
	v_max_f32_e32 v8, v82, v82
	v_max_f32_e32 v9, v72, v72
	v_max_f32_e32 v63, v63, v63
	v_max_f32_e32 v1, v1, v1
	v_max_f32_e32 v72, v9, v8
	v_max_f32_e32 v8, v80, v80
	v_max_f32_e32 v9, v77, v77
	v_max_f32_e32 v63, v1, v63
	v_max_f32_e32 v1, v59, v59
	v_max_f32_e32 v6, v6, v6
	v_max_f32_e32 v77, v9, v8
	v_max_f32_e32 v9, v81, v81
	v_max_f32_e32 v10, v71, v71
	v_max_f32_e32 v11, v79, v79
	v_max_f32_e32 v65, v65, v65
	v_max_f32_e32 v6, v6, v1
	v_max_f32_e32 v1, v60, v60
	v_max_f32_e32 v0, v0, v0
	v_max_f32_e32 v71, v10, v9
	v_max_f32_e32 v9, v78, v78
	v_max_f32_e32 v10, v74, v74
	v_max_f32_e32 v65, v65, v11
	v_max_f32_e32 v11, v75, v75
	v_max_f32_e32 v69, v69, v69
	v_max_f32_e32 v75, v76, v76
	v_max_f32_e32 v64, v64, v64
	v_max_f32_e32 v70, v70, v70
	v_max_f32_e32 v66, v66, v66
	v_max_f32_e32 v73, v73, v73
	v_max_f32_e32 v57, v57, v57
	v_max_f32_e32 v67, v67, v67
	v_max_f32_e32 v61, v61, v61
	v_max_f32_e32 v68, v68, v68
	v_max_f32_e32 v56, v56, v56
	v_max_f32_e32 v62, v62, v62
	v_max_f32_e32 v58, v58, v58
	v_max_f32_e32 v60, v0, v1
	v_max_f32_e32 v0, v3, v3
	v_max_f32_e32 v1, v2, v2
	v_max_f32_e32 v74, v10, v9
	v_max_f32_e32 v69, v69, v11
	v_max_f32_e32 v64, v64, v75
	v_max_f32_e32 v66, v66, v70
	v_max_f32_e32 v57, v57, v73
	v_max_f32_e32 v61, v61, v67
	v_max_f32_e32 v56, v56, v68
	v_max_f32_e32 v58, v58, v62
	v_max_f32_e32 v73, v1, v0
	v_min_f32_e32 v8, v72, v77
	v_min_f32_e32 v9, v71, v74
	v_min_f32_e32 v11, v65, v69
	v_min_f32_e32 v70, v64, v66
	v_min_f32_e32 v67, v57, v61
	v_min_f32_e32 v62, v56, v58
	v_min_f32_e32 v59, v63, v6
	v_min_f32_e32 v78, v60, v73
	v_min_f32_e32 v10, v8, v9
	v_min_f32_e32 v75, v11, v70
	v_min_f32_e32 v68, v67, v62
	v_min_f32_e32 v0, v59, v78
	v_min_f32_e32 v76, v10, v75
	v_min_f32_e32 v1, v68, v0
	v_max_f32_e32 v10, v10, v75
	v_max_f32_e32 v0, v68, v0
	v_max_f32_e32 v8, v8, v9
	v_max_f32_e32 v9, v11, v70
	v_max_f32_e32 v62, v67, v62
	v_max_f32_e32 v59, v59, v78
	v_min_f32_e32 v3, v76, v1
	v_max_f32_e32 v2, v76, v1
	v_min_f32_e32 v1, v10, v0
	v_max_f32_e32 v0, v10, v0
	v_min_f32_e32 v10, v8, v9
	v_min_f32_e32 v67, v62, v59
	v_min_f32_e32 v11, v10, v67
	v_max_f32_e32 v10, v10, v67
	v_max_f32_e32 v59, v62, v59
	v_max_f32_e32 v62, v72, v77
	v_max_f32_e32 v67, v71, v74
	v_max_f32_e32 v65, v65, v69
	v_max_f32_e32 v64, v64, v66
	v_min_f32_e32 v68, v62, v67
	v_min_f32_e32 v66, v65, v64
	v_max_f32_e32 v61, v57, v61
	v_max_f32_e32 v70, v56, v58
	v_max_f32_e32 v6, v63, v6
	v_max_f32_e32 v60, v60, v73
	v_min_f32_e32 v69, v68, v66
	v_min_f32_e32 v56, v61, v70
	v_min_f32_e32 v57, v6, v60
	v_max_f32_e32 v63, v68, v66
	v_max_f32_e32 v66, v62, v67
	v_max_f32_e32 v64, v65, v64
	v_max_f32_e32 v61, v61, v70
	v_max_f32_e32 v6, v6, v60
	v_min_f32_e32 v58, v56, v57
	v_max_f32_e32 v56, v56, v57
	v_min_f32_e32 v62, v66, v64
	v_min_f32_e32 v60, v61, v6
	v_min_f32_e32 v57, v63, v56
	v_max_f32_e32 v56, v63, v56
	v_min_f32_e32 v63, v62, v60
	v_max_f32_e32 v62, v62, v60
	v_max_f32_e32 v60, v66, v64
	v_max_f32_e32 v6, v61, v6
	v_min_f32_e32 v61, v60, v6
	v_max_f32_e32 v60, v60, v6
	v_accvgpr_read_b32 v6, a128
	v_add_u32_e32 v64, s20, v6
	v_ashrrev_i32_e32 v65, 31, v64
	v_lshlrev_b64 v[64:65], 10, v[64:65]
	v_lshl_or_b32 v64, s2, 6, v64
	v_lshl_add_u64 v[66:67], s[48:49], 0, v[64:65]
	v_xor_b32_e32 v6, -1, v61
	v_max_f32_e32 v8, v8, v9
	global_store_dwordx4 v[66:67], v[60:63], off
	v_min_f32_e32 v9, v8, v59
	v_max_f32_e32 v8, v8, v59
	v_xor_b32_e32 v60, -1, v60
	v_and_b32_e32 v61, 0x7f, v6
	v_xor_b32_e32 v6, -1, v63
	v_xor_b32_e32 v62, -1, v62
	v_min_f32_e32 v59, v69, v58
	v_max_f32_e32 v58, v69, v58
	v_lshl_add_u64 v[64:65], s[54:55], 0, v[64:65]
	v_and_b32_e32 v60, 0x7f, v60
	v_and_b32_e32 v63, 0x7f, v6
	v_and_b32_e32 v62, 0x7f, v62
	v_xor_b32_e32 v6, -1, v57
	global_store_dwordx4 v[64:65], v[60:63], off
	global_store_dwordx4 v[66:67], v[56:59], off offset:16
	s_nop 1
	v_xor_b32_e32 v56, -1, v56
	v_and_b32_e32 v57, 0x7f, v6
	v_xor_b32_e32 v6, -1, v59
	v_xor_b32_e32 v58, -1, v58
	v_and_b32_e32 v56, 0x7f, v56
	v_and_b32_e32 v59, 0x7f, v6
	v_and_b32_e32 v58, 0x7f, v58
	v_xor_b32_e32 v6, -1, v9
	global_store_dwordx4 v[64:65], v[56:59], off offset:16
	global_store_dwordx4 v[66:67], v[8:11], off offset:32
	s_nop 1
	v_xor_b32_e32 v8, -1, v8
	v_and_b32_e32 v9, 0x7f, v6
	v_xor_b32_e32 v6, -1, v11
	v_xor_b32_e32 v10, -1, v10
	v_and_b32_e32 v8, 0x7f, v8
	v_and_b32_e32 v11, 0x7f, v6
	v_and_b32_e32 v10, 0x7f, v10
	global_store_dwordx4 v[64:65], v[8:11], off offset:32
	global_store_dwordx4 v[66:67], v[0:3], off offset:48
	s_nop 1
	v_xor_b32_e32 v1, -1, v1
	v_xor_b32_e32 v0, -1, v0
	v_xor_b32_e32 v3, -1, v3
	v_xor_b32_e32 v2, -1, v2
	v_and_b32_e32 v1, 0x7f, v1
	v_and_b32_e32 v0, 0x7f, v0
	v_and_b32_e32 v3, 0x7f, v3
	v_and_b32_e32 v2, 0x7f, v2
	global_store_dwordx4 v[64:65], v[0:3], off offset:48
	s_branch .LBB0_1415

; __device__ __forceinline__ float bflo(unsigned u) { return __uint_as_float(u << 16); }
; __device__ __forceinline__ float bfhi(unsigned u) { return __uint_as_float(u & 0xffff0000u); }
; __device__ __forceinline__ float sum32(float v) { v = dpp_row_sum16(v); v += __shfl_xor(v, 16); return v; }
; __device__ __forceinline__ float sigmoidf_(float x) { return __builtin_amdgcn_rcpf(1.f + __expf(-x)); }
; __device__ __forceinline__ int rowmap(int e, int lane) { return (e & 3) + 8 * (e >> 2) + 4 * (lane >> 5); }
; __device__ __forceinline__ void phase6(const Params& p, char* smem) {
;     ...
; #pragma unroll
;     for (int i = 0; i < 2; i++)
; #pragma unroll
;       for (int e = 0; e < 16; e++) {
;         const int row = m0 + wm * 64 + i * 32 + rowmap(e, lane);
;         float sq = 0.f;
; #pragma unroll
;         for (int j = 0; j < 2; j++) {
;           const int col = n0 + wn * 64 + j * 32 + (lane & 31);
;           float* xp = X + (size_t)row * 1024 + col;
;           float v = *xp + ((e & 1) ? bfhi(pe[i][j][e >> 1]) : bflo(pe[i][j][e >> 1])) * sigmoidf_(acc1[i][j][e]);
;           *xp = v;
;           sq += v * v;
;         }
;         sq = sum32(sq);
;         if ((lane & 31) == 0) atomicAdd(&SSQ3[row], sq);
;       }
.LBB0_1588:
	s_nop 7
	v_accvgpr_read_b32 v112, a0
	v_accvgpr_read_b32 v113, a1
	v_accvgpr_read_b32 v114, a2
	v_accvgpr_read_b32 v115, a3
	v_accvgpr_read_b32 v116, a4
	v_accvgpr_read_b32 v117, a5
	v_accvgpr_read_b32 v118, a6
	v_accvgpr_read_b32 v119, a7
	v_accvgpr_read_b32 v120, a8
	v_accvgpr_read_b32 v121, a9
	v_accvgpr_read_b32 v122, a10
	v_accvgpr_read_b32 v123, a11
	v_accvgpr_read_b32 v124, a12
	v_accvgpr_read_b32 v125, a13
	v_accvgpr_read_b32 v126, a14
	v_accvgpr_read_b32 v127, a15
	v_accvgpr_read_b32 v96, a32
	v_accvgpr_read_b32 v97, a33
	v_accvgpr_read_b32 v98, a34
	v_accvgpr_read_b32 v99, a35
	v_accvgpr_read_b32 v100, a36
	v_accvgpr_read_b32 v101, a37
	v_accvgpr_read_b32 v102, a38
	v_accvgpr_read_b32 v103, a39
	v_accvgpr_read_b32 v104, a40
	v_accvgpr_read_b32 v105, a41
	v_accvgpr_read_b32 v106, a42
	v_accvgpr_read_b32 v107, a43
	v_accvgpr_read_b32 v108, a44
	v_accvgpr_read_b32 v109, a45
	v_accvgpr_read_b32 v110, a46
	v_accvgpr_read_b32 v111, a47
	v_accvgpr_read_b32 v80, a48
	v_accvgpr_read_b32 v81, a49
	v_accvgpr_read_b32 v82, a50
	v_accvgpr_read_b32 v83, a51
	v_accvgpr_read_b32 v84, a52
	v_accvgpr_read_b32 v85, a53
	v_accvgpr_read_b32 v86, a54
	v_accvgpr_read_b32 v87, a55
	v_accvgpr_read_b32 v88, a56
	v_accvgpr_read_b32 v89, a57
	v_accvgpr_read_b32 v90, a58
	v_accvgpr_read_b32 v91, a59
	v_accvgpr_read_b32 v92, a60
	v_accvgpr_read_b32 v93, a61
	v_accvgpr_read_b32 v94, a62
	v_accvgpr_read_b32 v95, a63
	v_accvgpr_read_b32 v64, a16
	v_accvgpr_read_b32 v65, a17
	v_accvgpr_read_b32 v66, a18
	v_accvgpr_read_b32 v67, a19
	v_accvgpr_read_b32 v68, a20
	v_accvgpr_read_b32 v69, a21
	v_accvgpr_read_b32 v70, a22
	v_accvgpr_read_b32 v71, a23
	v_accvgpr_read_b32 v72, a24
	v_accvgpr_read_b32 v73, a25
	v_accvgpr_read_b32 v74, a26
	v_accvgpr_read_b32 v75, a27
	v_accvgpr_read_b32 v76, a28
	v_accvgpr_read_b32 v77, a29
	v_accvgpr_read_b32 v78, a30
	v_accvgpr_read_b32 v79, a31
	v_add_u32_e32 v206, s8, v215
	v_or_b32_e32 v130, s38, v217
	v_or_b32_e32 v206, v206, v236
	v_lshlrev_b32_e32 v130, 2, v130
	s_nop 0
	v_lshl_add_u64 v[132:133], s[78:79], 0, v[130:131]
	v_add_lshl_u32 v130, v206, 0, 12
	v_lshl_add_u64 v[134:135], v[130:131], 0, v[132:133]
	global_load_dword a0, v[134:135], off
	global_load_dword a1, v[134:135], off offset:128
	v_add_lshl_u32 v130, v206, 1, 12
	v_lshl_add_u64 v[134:135], v[130:131], 0, v[132:133]
	global_load_dword a2, v[134:135], off
	global_load_dword a3, v[134:135], off offset:128
	v_add_lshl_u32 v130, v206, 2, 12
	v_lshl_add_u64 v[134:135], v[130:131], 0, v[132:133]
	global_load_dword a4, v[134:135], off
	global_load_dword a5, v[134:135], off offset:128
	v_add_lshl_u32 v130, v206, 3, 12
	v_lshl_add_u64 v[134:135], v[130:131], 0, v[132:133]
	global_load_dword a6, v[134:135], off
	global_load_dword a7, v[134:135], off offset:128
	v_add_lshl_u32 v130, v206, 8, 12
	v_lshl_add_u64 v[134:135], v[130:131], 0, v[132:133]
	global_load_dword a8, v[134:135], off
	global_load_dword a9, v[134:135], off offset:128
	v_add_lshl_u32 v130, v206, 9, 12
	v_lshl_add_u64 v[134:135], v[130:131], 0, v[132:133]
	global_load_dword a10, v[134:135], off
	global_load_dword a11, v[134:135], off offset:128
	v_add_lshl_u32 v130, v206, 10, 12
	v_lshl_add_u64 v[134:135], v[130:131], 0, v[132:133]
	global_load_dword a12, v[134:135], off
	global_load_dword a13, v[134:135], off offset:128
	v_add_lshl_u32 v130, v206, 11, 12
	v_lshl_add_u64 v[134:135], v[130:131], 0, v[132:133]
	global_load_dword a14, v[134:135], off
	global_load_dword a15, v[134:135], off offset:128
	v_add_lshl_u32 v130, v206, 16, 12
	v_lshl_add_u64 v[134:135], v[130:131], 0, v[132:133]
	global_load_dword a16, v[134:135], off
	global_load_dword a17, v[134:135], off offset:128
	v_add_lshl_u32 v130, v206, 17, 12
	v_lshl_add_u64 v[134:135], v[130:131], 0, v[132:133]
	global_load_dword a18, v[134:135], off
	global_load_dword a19, v[134:135], off offset:128
	v_add_lshl_u32 v130, v206, 18, 12
	v_lshl_add_u64 v[134:135], v[130:131], 0, v[132:133]
	global_load_dword a20, v[134:135], off
	global_load_dword a21, v[134:135], off offset:128
	v_add_lshl_u32 v130, v206, 19, 12
	v_lshl_add_u64 v[134:135], v[130:131], 0, v[132:133]
	global_load_dword a22, v[134:135], off
	global_load_dword a23, v[134:135], off offset:128
	v_add_lshl_u32 v130, v206, 24, 12
	v_lshl_add_u64 v[134:135], v[130:131], 0, v[132:133]
	global_load_dword a24, v[134:135], off
	global_load_dword a25, v[134:135], off offset:128
	v_add_lshl_u32 v130, v206, 25, 12
	v_lshl_add_u64 v[134:135], v[130:131], 0, v[132:133]
	global_load_dword a26, v[134:135], off
	global_load_dword a27, v[134:135], off offset:128
	v_add_lshl_u32 v130, v206, 26, 12
	v_lshl_add_u64 v[134:135], v[130:131], 0, v[132:133]
	global_load_dword a28, v[134:135], off
	global_load_dword a29, v[134:135], off offset:128
	v_add_lshl_u32 v130, v206, 27, 12
	v_lshl_add_u64 v[134:135], v[130:131], 0, v[132:133]
	global_load_dword a30, v[134:135], off
	global_load_dword a31, v[134:135], off offset:128
	v_add_lshl_u32 v130, v206, 32, 12
	v_lshl_add_u64 v[134:135], v[130:131], 0, v[132:133]
	global_load_dword a32, v[134:135], off
	global_load_dword a33, v[134:135], off offset:128
	v_add_lshl_u32 v130, v206, 33, 12
	v_lshl_add_u64 v[134:135], v[130:131], 0, v[132:133]
	global_load_dword a34, v[134:135], off
	global_load_dword a35, v[134:135], off offset:128
	v_add_lshl_u32 v130, v206, 34, 12
	v_lshl_add_u64 v[134:135], v[130:131], 0, v[132:133]
	global_load_dword a36, v[134:135], off
	global_load_dword a37, v[134:135], off offset:128
	v_add_lshl_u32 v130, v206, 35, 12
	v_lshl_add_u64 v[134:135], v[130:131], 0, v[132:133]
	global_load_dword a38, v[134:135], off
	global_load_dword a39, v[134:135], off offset:128
; __device__ __forceinline__ float bflo(unsigned u) { return __uint_as_float(u << 16); }
; __device__ __forceinline__ float bfhi(unsigned u) { return __uint_as_float(u & 0xffff0000u); }
; __device__ __forceinline__ float sum32(float v) { v = dpp_row_sum16(v); v += __shfl_xor(v, 16); return v; }
; __device__ __forceinline__ float sigmoidf_(float x) { return __builtin_amdgcn_rcpf(1.f + __expf(-x)); }
; __device__ __forceinline__ int rowmap(int e, int lane) { return (e & 3) + 8 * (e >> 2) + 4 * (lane >> 5); }
; __device__ __forceinline__ void phase6(const Params& p, char* smem) {
;     ...
; #pragma unroll
;     for (int i = 0; i < 2; i++)
; #pragma unroll
;       for (int e = 0; e < 16; e++) {
;         const int row = m0 + wm * 64 + i * 32 + rowmap(e, lane);
;         float sq = 0.f;
; #pragma unroll
;         for (int j = 0; j < 2; j++) {
;           const int col = n0 + wn * 64 + j * 32 + (lane & 31);
;           float* xp = X + (size_t)row * 1024 + col;
;           float v = *xp + ((e & 1) ? bfhi(pe[i][j][e >> 1]) : bflo(pe[i][j][e >> 1])) * sigmoidf_(acc1[i][j][e]);
;           *xp = v;
;           sq += v * v;
;         }
;         sq = sum32(sq);
;         if ((lane & 31) == 0) atomicAdd(&SSQ3[row], sq);
;       }
	v_add_lshl_u32 v130, v206, 40, 12
	v_lshl_add_u64 v[134:135], v[130:131], 0, v[132:133]
	global_load_dword a40, v[134:135], off
	global_load_dword a41, v[134:135], off offset:128
	v_add_lshl_u32 v130, v206, 41, 12
	v_lshl_add_u64 v[134:135], v[130:131], 0, v[132:133]
	global_load_dword a42, v[134:135], off
	global_load_dword a43, v[134:135], off offset:128
	v_add_lshl_u32 v130, v206, 42, 12
	v_lshl_add_u64 v[134:135], v[130:131], 0, v[132:133]
	global_load_dword a44, v[134:135], off
	global_load_dword a45, v[134:135], off offset:128
	v_add_lshl_u32 v130, v206, 43, 12
	v_lshl_add_u64 v[134:135], v[130:131], 0, v[132:133]
	global_load_dword a46, v[134:135], off
	global_load_dword a47, v[134:135], off offset:128
	v_add_lshl_u32 v130, v206, 48, 12
	v_lshl_add_u64 v[134:135], v[130:131], 0, v[132:133]
	global_load_dword a48, v[134:135], off
	global_load_dword a49, v[134:135], off offset:128
	v_add_lshl_u32 v130, v206, 49, 12
	v_lshl_add_u64 v[134:135], v[130:131], 0, v[132:133]
	global_load_dword a50, v[134:135], off
	global_load_dword a51, v[134:135], off offset:128
	v_add_lshl_u32 v130, v206, 50, 12
	v_lshl_add_u64 v[134:135], v[130:131], 0, v[132:133]
	global_load_dword a52, v[134:135], off
	global_load_dword a53, v[134:135], off offset:128
	v_add_lshl_u32 v130, v206, 51, 12
	v_lshl_add_u64 v[134:135], v[130:131], 0, v[132:133]
	global_load_dword a54, v[134:135], off
	global_load_dword a55, v[134:135], off offset:128
	v_add_lshl_u32 v130, v206, 56, 12
	v_lshl_add_u64 v[134:135], v[130:131], 0, v[132:133]
	global_load_dword a56, v[134:135], off
	global_load_dword a57, v[134:135], off offset:128
	v_add_lshl_u32 v130, v206, 57, 12
	v_lshl_add_u64 v[134:135], v[130:131], 0, v[132:133]
	global_load_dword a58, v[134:135], off
	global_load_dword a59, v[134:135], off offset:128
	v_add_lshl_u32 v130, v206, 58, 12
	v_lshl_add_u64 v[134:135], v[130:131], 0, v[132:133]
	global_load_dword a60, v[134:135], off
	global_load_dword a61, v[134:135], off offset:128
	v_add_lshl_u32 v130, v206, 59, 12
	v_lshl_add_u64 v[134:135], v[130:131], 0, v[132:133]
	global_load_dword a62, v[134:135], off
	global_load_dword a63, v[134:135], off offset:128
	s_waitcnt vmcnt(0)
	v_cvt_pk_bf16_f32 v49, v48, v49
	v_add_u32_e32 v48, s8, v215
	v_cvt_pk_bf16_f32 v206, v32, v33
	v_or_b32_e32 v32, v48, v236
	v_ashrrev_i32_e32 v33, 31, v32
	v_or_b32_e32 v130, s38, v217
	v_lshlrev_b64 v[132:133], 12, v[32:33]
	v_lshl_add_u64 v[132:133], s[78:79], 0, v[132:133]
	v_lshlrev_b32_e32 v130, 2, v130
	v_lshl_add_u64 v[132:133], v[132:133], 0, v[130:131]
	v_accvgpr_read_b32 v134, a0
	v_mul_f32_e32 v112, 0xbfb8aa3b, v112
	v_exp_f32_e32 v112, v112
	v_lshlrev_b32_e32 v135, 16, v206
	v_add_f32_e32 v112, 1.0, v112
	v_rcp_f32_e32 v112, v112
	v_mul_f32_e32 v96, 0xbfb8aa3b, v96
	v_exp_f32_e32 v96, v96
	s_nop 0
	v_add_f32_e32 v96, 1.0, v96
	v_rcp_f32_e32 v96, v96
	v_fmac_f32_e32 v134, v112, v135
	v_accvgpr_read_b32 v112, a1
	v_lshlrev_b32_e32 v135, 16, v49
	global_store_dword v[132:133], v134, off
	v_fmac_f32_e32 v112, v96, v135
	v_mul_f32_e32 v96, v112, v112
	v_fmac_f32_e32 v96, v134, v134
	global_store_dword v[132:133], v112, off offset:128
	s_nop 0
	v_add_f32_dpp v96, v96, v96 quad_perm:[1,0,3,2] row_mask:0xf bank_mask:0xf bound_ctrl:1
	s_nop 1
	v_add_f32_dpp v96, v96, v96 quad_perm:[2,3,0,1] row_mask:0xf bank_mask:0xf bound_ctrl:1
	s_nop 1
	v_add_f32_dpp v96, v96, v96 row_half_mirror row_mask:0xf bank_mask:0xf bound_ctrl:1
	s_nop 1
	v_add_f32_dpp v96, v96, v96 row_mirror row_mask:0xf bank_mask:0xf bound_ctrl:1
	ds_bpermute_b32 v112, v237, v96
	s_and_saveexec_b64 s[8:9], s[4:5]
	s_cbranch_execz .LBB0_1590
	s_waitcnt lgkmcnt(0)
	v_add_f32_e32 v96, v96, v112
	v_lshl_add_u64 v[32:33], v[32:33], 2, s[92:93]
	global_atomic_add_f32 v[32:33], v96, off
.LBB0_1590:
	s_or_b64 exec, exec, s[8:9]
	v_accvgpr_read_b32 v135, a84
	v_or_b32_e32 v32, v48, v135
	v_ashrrev_i32_e32 v33, 31, v32
	v_lshlrev_b64 v[132:133], 12, v[32:33]
	v_lshl_add_u64 v[132:133], s[78:79], 0, v[132:133]
	v_lshl_add_u64 v[132:133], v[132:133], 0, v[130:131]
	s_waitcnt lgkmcnt(0)
	v_accvgpr_read_b32 v112, a2
	v_accvgpr_read_b32 v134, a3
	v_mul_f32_e32 v97, 0xbfb8aa3b, v97
	v_mul_f32_e32 v96, 0xbfb8aa3b, v113
	v_exp_f32_e32 v97, v97
	v_exp_f32_e32 v96, v96
	v_and_b32_e32 v49, 0xffff0000, v49
	v_and_b32_e32 v113, 0xffff0000, v206
	v_add_f32_e32 v97, 1.0, v97
	v_add_f32_e32 v96, 1.0, v96
	v_rcp_f32_e32 v97, v97
	v_rcp_f32_e32 v96, v96
	v_fmac_f32_e32 v134, v97, v49
	v_fmac_f32_e32 v112, v96, v113
	v_mul_f32_e32 v49, v134, v134
	v_fmac_f32_e32 v49, v112, v112
	global_store_dword v[132:133], v112, off
	global_store_dword v[132:133], v134, off offset:128
	v_add_f32_dpp v49, v49, v49 quad_perm:[1,0,3,2] row_mask:0xf bank_mask:0xf bound_ctrl:1
	s_nop 1
	v_add_f32_dpp v49, v49, v49 quad_perm:[2,3,0,1] row_mask:0xf bank_mask:0xf bound_ctrl:1
	s_nop 1
	v_add_f32_dpp v49, v49, v49 row_half_mirror row_mask:0xf bank_mask:0xf bound_ctrl:1
	s_nop 1
	v_add_f32_dpp v49, v49, v49 row_mirror row_mask:0xf bank_mask:0xf bound_ctrl:1
	ds_bpermute_b32 v96, v237, v49
	s_mov_b64 s[8:9], exec
	s_and_b64 s[10:11], s[8:9], s[4:5]
	v_accvgpr_read_b32 v132, a85
	v_accvgpr_read_b32 v133, a86
	v_accvgpr_read_b32 v134, a87
	v_accvgpr_read_b32 v148, a88
	v_accvgpr_read_b32 v149, a89
	v_accvgpr_read_b32 v150, a90
	v_accvgpr_read_b32 v151, a91
	v_accvgpr_read_b32 v152, a92
	s_mov_b64 exec, s[10:11]
	s_cbranch_execz .LBB0_1592
	s_waitcnt lgkmcnt(0)
	v_add_f32_e32 v49, v49, v96
	v_lshl_add_u64 v[32:33], v[32:33], 2, s[92:93]
	global_atomic_add_f32 v[32:33], v49, off
; __device__ __forceinline__ float bflo(unsigned u) { return __uint_as_float(u << 16); }
; __device__ __forceinline__ float bfhi(unsigned u) { return __uint_as_float(u & 0xffff0000u); }
; __device__ __forceinline__ float sum32(float v) { v = dpp_row_sum16(v); v += __shfl_xor(v, 16); return v; }
; __device__ __forceinline__ float sigmoidf_(float x) { return __builtin_amdgcn_rcpf(1.f + __expf(-x)); }
; __device__ __forceinline__ int rowmap(int e, int lane) { return (e & 3) + 8 * (e >> 2) + 4 * (lane >> 5); }
; __device__ __forceinline__ void phase6(const Params& p, char* smem) {
;     ...
; #pragma unroll
;     for (int i = 0; i < 2; i++)
; #pragma unroll
;       for (int e = 0; e < 16; e++) {
;         const int row = m0 + wm * 64 + i * 32 + rowmap(e, lane);
;         float sq = 0.f;
; #pragma unroll
;         for (int j = 0; j < 2; j++) {
;           const int col = n0 + wn * 64 + j * 32 + (lane & 31);
;           float* xp = X + (size_t)row * 1024 + col;
;           float v = *xp + ((e & 1) ? bfhi(pe[i][j][e >> 1]) : bflo(pe[i][j][e >> 1])) * sigmoidf_(acc1[i][j][e]);
;           *xp = v;
;           sq += v * v;
;         }
;         sq = sum32(sq);
;         if ((lane & 31) == 0) atomicAdd(&SSQ3[row], sq);
;       }
.LBB0_1592:
	s_or_b64 exec, exec, s[8:9]
	v_or_b32_e32 v32, v48, v132
	v_ashrrev_i32_e32 v33, 31, v32
	s_waitcnt lgkmcnt(0)
	v_lshlrev_b64 v[96:97], 12, v[32:33]
	v_lshl_add_u64 v[96:97], s[78:79], 0, v[96:97]
	v_lshl_add_u64 v[96:97], v[96:97], 0, v[130:131]
	v_accvgpr_read_b32 v112, a4
	v_accvgpr_read_b32 v113, a5
	v_mul_f32_e32 v98, 0xbfb8aa3b, v98
	v_mul_f32_e32 v49, 0xbfb8aa3b, v114
	v_exp_f32_e32 v98, v98
	v_exp_f32_e32 v49, v49
	v_cvt_pk_bf16_f32 v34, v34, v35
	v_cvt_pk_bf16_f32 v35, v50, v51
	v_add_f32_e32 v50, 1.0, v98
	v_add_f32_e32 v49, 1.0, v49
	v_rcp_f32_e32 v50, v50
	v_rcp_f32_e32 v49, v49
	v_lshlrev_b32_e32 v98, 16, v35
	v_lshlrev_b32_e32 v51, 16, v34
	v_fmac_f32_e32 v112, v49, v51
	v_fmac_f32_e32 v113, v50, v98
	v_mul_f32_e32 v49, v113, v113
	v_fmac_f32_e32 v49, v112, v112
	global_store_dword v[96:97], v112, off
	global_store_dword v[96:97], v113, off offset:128
	v_add_f32_dpp v49, v49, v49 quad_perm:[1,0,3,2] row_mask:0xf bank_mask:0xf bound_ctrl:1
	s_nop 1
	v_add_f32_dpp v49, v49, v49 quad_perm:[2,3,0,1] row_mask:0xf bank_mask:0xf bound_ctrl:1
	s_nop 1
	v_add_f32_dpp v49, v49, v49 row_half_mirror row_mask:0xf bank_mask:0xf bound_ctrl:1
	s_nop 1
	v_add_f32_dpp v49, v49, v49 row_mirror row_mask:0xf bank_mask:0xf bound_ctrl:1
	ds_bpermute_b32 v50, v237, v49
	s_and_saveexec_b64 s[8:9], s[4:5]
	s_cbranch_execz .LBB0_1594
	s_waitcnt lgkmcnt(0)
	v_add_f32_e32 v49, v49, v50
	v_lshl_add_u64 v[32:33], v[32:33], 2, s[92:93]
	global_atomic_add_f32 v[32:33], v49, off
.LBB0_1594:
	s_or_b64 exec, exec, s[8:9]
	v_or_b32_e32 v32, v48, v133
	v_ashrrev_i32_e32 v33, 31, v32
	s_waitcnt lgkmcnt(0)
	v_lshlrev_b64 v[50:51], 12, v[32:33]
	v_lshl_add_u64 v[50:51], s[78:79], 0, v[50:51]
	v_lshl_add_u64 v[50:51], v[50:51], 0, v[130:131]
	v_accvgpr_read_b32 v49, a6
	v_accvgpr_read_b32 v96, a7
	v_mul_f32_e32 v98, 0xbfb8aa3b, v99
	v_mul_f32_e32 v97, 0xbfb8aa3b, v115
	v_exp_f32_e32 v98, v98
	v_exp_f32_e32 v97, v97
	v_and_b32_e32 v35, 0xffff0000, v35
	v_and_b32_e32 v34, 0xffff0000, v34
	v_add_f32_e32 v98, 1.0, v98
	v_add_f32_e32 v97, 1.0, v97
	v_rcp_f32_e32 v98, v98
	v_rcp_f32_e32 v97, v97
	v_fmac_f32_e32 v96, v98, v35
	v_fmac_f32_e32 v49, v97, v34
	v_mul_f32_e32 v34, v96, v96
	v_fmac_f32_e32 v34, v49, v49
	global_store_dword v[50:51], v49, off
	global_store_dword v[50:51], v96, off offset:128
	v_add_f32_dpp v34, v34, v34 quad_perm:[1,0,3,2] row_mask:0xf bank_mask:0xf bound_ctrl:1
	s_nop 1
	v_add_f32_dpp v34, v34, v34 quad_perm:[2,3,0,1] row_mask:0xf bank_mask:0xf bound_ctrl:1
	s_nop 1
	v_add_f32_dpp v34, v34, v34 row_half_mirror row_mask:0xf bank_mask:0xf bound_ctrl:1
	s_nop 1
	v_add_f32_dpp v34, v34, v34 row_mirror row_mask:0xf bank_mask:0xf bound_ctrl:1
	ds_bpermute_b32 v35, v237, v34
	s_mov_b64 s[8:9], exec
	s_and_b64 s[10:11], s[8:9], s[4:5]
	v_accvgpr_read_b32 v99, a93
	v_accvgpr_read_b32 v112, a94
	v_accvgpr_read_b32 v113, a95
	v_accvgpr_read_b32 v114, a96
	v_accvgpr_read_b32 v115, a97
	v_accvgpr_read_b32 v153, a98
	s_mov_b64 exec, s[10:11]
	s_cbranch_execz .LBB0_1596
	s_waitcnt lgkmcnt(0)
	v_add_f32_e32 v34, v34, v35
	v_lshl_add_u64 v[32:33], v[32:33], 2, s[92:93]
	global_atomic_add_f32 v[32:33], v34, off
.LBB0_1596:
	s_or_b64 exec, exec, s[8:9]
	v_or_b32_e32 v32, v48, v134
	v_ashrrev_i32_e32 v33, 31, v32
	s_waitcnt lgkmcnt(0)
	v_lshlrev_b64 v[34:35], 12, v[32:33]
	v_lshl_add_u64 v[34:35], s[78:79], 0, v[34:35]
	v_lshl_add_u64 v[50:51], v[34:35], 0, v[130:131]
	v_accvgpr_read_b32 v49, a8
	v_accvgpr_read_b32 v96, a9
	v_mul_f32_e32 v35, 0xbfb8aa3b, v100
	v_mul_f32_e32 v34, 0xbfb8aa3b, v116
	v_exp_f32_e32 v98, v35
	v_exp_f32_e32 v97, v34
	v_cvt_pk_bf16_f32 v34, v36, v37
	v_cvt_pk_bf16_f32 v35, v52, v53
	v_add_f32_e32 v37, 1.0, v98
	v_add_f32_e32 v36, 1.0, v97
	v_rcp_f32_e32 v37, v37
	v_rcp_f32_e32 v36, v36
	v_lshlrev_b32_e32 v53, 16, v35
	v_lshlrev_b32_e32 v52, 16, v34
	v_fmac_f32_e32 v49, v36, v52
	v_fmac_f32_e32 v96, v37, v53
	v_mul_f32_e32 v36, v96, v96
	v_fmac_f32_e32 v36, v49, v49
	global_store_dword v[50:51], v49, off
	global_store_dword v[50:51], v96, off offset:128
	v_add_f32_dpp v36, v36, v36 quad_perm:[1,0,3,2] row_mask:0xf bank_mask:0xf bound_ctrl:1
	s_nop 1
	v_add_f32_dpp v36, v36, v36 quad_perm:[2,3,0,1] row_mask:0xf bank_mask:0xf bound_ctrl:1
	s_nop 1
	v_add_f32_dpp v36, v36, v36 row_half_mirror row_mask:0xf bank_mask:0xf bound_ctrl:1
	s_nop 1
	v_add_f32_dpp v36, v36, v36 row_mirror row_mask:0xf bank_mask:0xf bound_ctrl:1
	ds_bpermute_b32 v37, v237, v36
	s_and_saveexec_b64 s[8:9], s[4:5]
	s_cbranch_execz .LBB0_1598
	s_waitcnt lgkmcnt(0)
	v_add_f32_e32 v36, v36, v37
	v_lshl_add_u64 v[32:33], v[32:33], 2, s[92:93]
	global_atomic_add_f32 v[32:33], v36, off
.LBB0_1598:
	s_or_b64 exec, exec, s[8:9]
	v_or_b32_e32 v32, v48, v148
	v_ashrrev_i32_e32 v33, 31, v32
	s_waitcnt lgkmcnt(0)
	v_lshlrev_b64 v[36:37], 12, v[32:33]
	v_lshl_add_u64 v[36:37], s[78:79], 0, v[36:37]
	v_lshl_add_u64 v[36:37], v[36:37], 0, v[130:131]
	v_accvgpr_read_b32 v49, a10
	v_accvgpr_read_b32 v50, a11
	v_mul_f32_e32 v52, 0xbfb8aa3b, v101
	v_mul_f32_e32 v51, 0xbfb8aa3b, v117
	v_exp_f32_e32 v52, v52
	v_exp_f32_e32 v51, v51
	v_and_b32_e32 v35, 0xffff0000, v35
	v_and_b32_e32 v34, 0xffff0000, v34
	v_add_f32_e32 v52, 1.0, v52
	v_add_f32_e32 v51, 1.0, v51
	v_rcp_f32_e32 v52, v52
	v_rcp_f32_e32 v51, v51
	v_fmac_f32_e32 v50, v52, v35
	v_fmac_f32_e32 v49, v51, v34
	v_mul_f32_e32 v34, v50, v50
	v_fmac_f32_e32 v34, v49, v49
	global_store_dword v[36:37], v49, off
	global_store_dword v[36:37], v50, off offset:128
	v_add_f32_dpp v34, v34, v34 quad_perm:[1,0,3,2] row_mask:0xf bank_mask:0xf bound_ctrl:1
	s_nop 1
	v_add_f32_dpp v34, v34, v34 quad_perm:[2,3,0,1] row_mask:0xf bank_mask:0xf bound_ctrl:1
	s_nop 1
	v_add_f32_dpp v34, v34, v34 row_half_mirror row_mask:0xf bank_mask:0xf bound_ctrl:1
	s_nop 1
	v_add_f32_dpp v34, v34, v34 row_mirror row_mask:0xf bank_mask:0xf bound_ctrl:1
	ds_bpermute_b32 v35, v237, v34
	s_and_saveexec_b64 s[8:9], s[4:5]
	s_cbranch_execz .LBB0_1600
	s_waitcnt lgkmcnt(0)
	v_add_f32_e32 v34, v34, v35
	v_lshl_add_u64 v[32:33], v[32:33], 2, s[92:93]
	global_atomic_add_f32 v[32:33], v34, off
; __device__ __forceinline__ float bflo(unsigned u) { return __uint_as_float(u << 16); }
; __device__ __forceinline__ float bfhi(unsigned u) { return __uint_as_float(u & 0xffff0000u); }
; __device__ __forceinline__ float sum32(float v) { v = dpp_row_sum16(v); v += __shfl_xor(v, 16); return v; }
; __device__ __forceinline__ float sigmoidf_(float x) { return __builtin_amdgcn_rcpf(1.f + __expf(-x)); }
; __device__ __forceinline__ int rowmap(int e, int lane) { return (e & 3) + 8 * (e >> 2) + 4 * (lane >> 5); }
; __device__ __forceinline__ void phase6(const Params& p, char* smem) {
;     ...
; #pragma unroll
;     for (int i = 0; i < 2; i++)
; #pragma unroll
;       for (int e = 0; e < 16; e++) {
;         const int row = m0 + wm * 64 + i * 32 + rowmap(e, lane);
;         float sq = 0.f;
; #pragma unroll
;         for (int j = 0; j < 2; j++) {
;           const int col = n0 + wn * 64 + j * 32 + (lane & 31);
;           float* xp = X + (size_t)row * 1024 + col;
;           float v = *xp + ((e & 1) ? bfhi(pe[i][j][e >> 1]) : bflo(pe[i][j][e >> 1])) * sigmoidf_(acc1[i][j][e]);
;           *xp = v;
;           sq += v * v;
;         }
;         sq = sum32(sq);
;         if ((lane & 31) == 0) atomicAdd(&SSQ3[row], sq);
;       }
.LBB0_1600:
	s_or_b64 exec, exec, s[8:9]
	v_or_b32_e32 v32, v48, v149
	v_ashrrev_i32_e32 v33, 31, v32
	s_waitcnt lgkmcnt(0)
	v_lshlrev_b64 v[34:35], 12, v[32:33]
	v_lshl_add_u64 v[34:35], s[78:79], 0, v[34:35]
	v_lshl_add_u64 v[50:51], v[34:35], 0, v[130:131]
	v_accvgpr_read_b32 v49, a12
	v_accvgpr_read_b32 v52, a13
	v_mul_f32_e32 v35, 0xbfb8aa3b, v102
	v_mul_f32_e32 v34, 0xbfb8aa3b, v118
	v_exp_f32_e32 v37, v35
	v_exp_f32_e32 v36, v34
	v_cvt_pk_bf16_f32 v35, v54, v55
	v_cvt_pk_bf16_f32 v34, v38, v39
	v_add_f32_e32 v37, 1.0, v37
	v_add_f32_e32 v36, 1.0, v36
	v_rcp_f32_e32 v37, v37
	v_rcp_f32_e32 v36, v36
	v_lshlrev_b32_e32 v39, 16, v35
	v_lshlrev_b32_e32 v38, 16, v34
	v_fmac_f32_e32 v49, v36, v38
	v_fmac_f32_e32 v52, v37, v39
	v_mul_f32_e32 v36, v52, v52
	v_fmac_f32_e32 v36, v49, v49
	global_store_dword v[50:51], v49, off
	global_store_dword v[50:51], v52, off offset:128
	v_add_f32_dpp v36, v36, v36 quad_perm:[1,0,3,2] row_mask:0xf bank_mask:0xf bound_ctrl:1
	s_nop 1
	v_add_f32_dpp v36, v36, v36 quad_perm:[2,3,0,1] row_mask:0xf bank_mask:0xf bound_ctrl:1
	s_nop 1
	v_add_f32_dpp v36, v36, v36 row_half_mirror row_mask:0xf bank_mask:0xf bound_ctrl:1
	s_nop 1
	v_add_f32_dpp v36, v36, v36 row_mirror row_mask:0xf bank_mask:0xf bound_ctrl:1
	ds_bpermute_b32 v37, v237, v36
	s_and_saveexec_b64 s[8:9], s[4:5]
	s_cbranch_execz .LBB0_1602
	s_waitcnt lgkmcnt(0)
	v_add_f32_e32 v36, v36, v37
	v_lshl_add_u64 v[32:33], v[32:33], 2, s[92:93]
	global_atomic_add_f32 v[32:33], v36, off
.LBB0_1602:
	s_or_b64 exec, exec, s[8:9]
	v_or_b32_e32 v32, v48, v150
	v_ashrrev_i32_e32 v33, 31, v32
	s_waitcnt lgkmcnt(0)
	v_lshlrev_b64 v[36:37], 12, v[32:33]
	v_lshl_add_u64 v[36:37], s[78:79], 0, v[36:37]
	v_lshl_add_u64 v[36:37], v[36:37], 0, v[130:131]
	v_accvgpr_read_b32 v38, a14
	v_accvgpr_read_b32 v39, a15
	v_mul_f32_e32 v50, 0xbfb8aa3b, v103
	v_mul_f32_e32 v49, 0xbfb8aa3b, v119
	v_exp_f32_e32 v50, v50
	v_exp_f32_e32 v49, v49
	v_and_b32_e32 v35, 0xffff0000, v35
	v_and_b32_e32 v34, 0xffff0000, v34
	v_add_f32_e32 v50, 1.0, v50
	v_add_f32_e32 v49, 1.0, v49
	v_rcp_f32_e32 v50, v50
	v_rcp_f32_e32 v49, v49
	v_fmac_f32_e32 v39, v50, v35
	v_fmac_f32_e32 v38, v49, v34
	v_mul_f32_e32 v34, v39, v39
	v_fmac_f32_e32 v34, v38, v38
	global_store_dword v[36:37], v38, off
	global_store_dword v[36:37], v39, off offset:128
	v_add_f32_dpp v34, v34, v34 quad_perm:[1,0,3,2] row_mask:0xf bank_mask:0xf bound_ctrl:1
	s_nop 1
	v_add_f32_dpp v34, v34, v34 quad_perm:[2,3,0,1] row_mask:0xf bank_mask:0xf bound_ctrl:1
	s_nop 1
	v_add_f32_dpp v34, v34, v34 row_half_mirror row_mask:0xf bank_mask:0xf bound_ctrl:1
	s_nop 1
	v_add_f32_dpp v34, v34, v34 row_mirror row_mask:0xf bank_mask:0xf bound_ctrl:1
	ds_bpermute_b32 v35, v237, v34
	s_and_saveexec_b64 s[8:9], s[4:5]
	s_cbranch_execz .LBB0_1604
	s_waitcnt lgkmcnt(0)
	v_add_f32_e32 v34, v34, v35
	v_lshl_add_u64 v[32:33], v[32:33], 2, s[92:93]
	global_atomic_add_f32 v[32:33], v34, off
.LBB0_1604:
	s_or_b64 exec, exec, s[8:9]
	v_or_b32_e32 v32, v48, v151
	v_ashrrev_i32_e32 v33, 31, v32
	s_waitcnt lgkmcnt(0)
	v_lshlrev_b64 v[34:35], 12, v[32:33]
	v_lshl_add_u64 v[34:35], s[78:79], 0, v[34:35]
	v_lshl_add_u64 v[38:39], v[34:35], 0, v[130:131]
	v_accvgpr_read_b32 v49, a16
	v_accvgpr_read_b32 v50, a17
	v_mul_f32_e32 v35, 0xbfb8aa3b, v104
	v_mul_f32_e32 v34, 0xbfb8aa3b, v120
	v_exp_f32_e32 v37, v35
	v_exp_f32_e32 v36, v34
	v_cvt_pk_bf16_f32 v35, v56, v57
	v_cvt_pk_bf16_f32 v34, v40, v41
	v_add_f32_e32 v37, 1.0, v37
	v_add_f32_e32 v36, 1.0, v36
	v_rcp_f32_e32 v37, v37
	v_rcp_f32_e32 v36, v36
	v_lshlrev_b32_e32 v41, 16, v35
	v_lshlrev_b32_e32 v40, 16, v34
	v_fmac_f32_e32 v49, v36, v40
	v_fmac_f32_e32 v50, v37, v41
	v_mul_f32_e32 v36, v50, v50
	v_fmac_f32_e32 v36, v49, v49
	global_store_dword v[38:39], v49, off
	global_store_dword v[38:39], v50, off offset:128
	v_add_f32_dpp v36, v36, v36 quad_perm:[1,0,3,2] row_mask:0xf bank_mask:0xf bound_ctrl:1
	s_nop 1
	v_add_f32_dpp v36, v36, v36 quad_perm:[2,3,0,1] row_mask:0xf bank_mask:0xf bound_ctrl:1
	s_nop 1
	v_add_f32_dpp v36, v36, v36 row_half_mirror row_mask:0xf bank_mask:0xf bound_ctrl:1
	s_nop 1
	v_add_f32_dpp v36, v36, v36 row_mirror row_mask:0xf bank_mask:0xf bound_ctrl:1
	ds_bpermute_b32 v37, v237, v36
	s_and_saveexec_b64 s[8:9], s[4:5]
	s_cbranch_execz .LBB0_1606
	s_waitcnt lgkmcnt(0)
	v_add_f32_e32 v36, v36, v37
	v_lshl_add_u64 v[32:33], v[32:33], 2, s[92:93]
	global_atomic_add_f32 v[32:33], v36, off
.LBB0_1606:
	s_or_b64 exec, exec, s[8:9]
	v_or_b32_e32 v32, v48, v152
	v_ashrrev_i32_e32 v33, 31, v32
	s_waitcnt lgkmcnt(0)
	v_lshlrev_b64 v[36:37], 12, v[32:33]
	v_lshl_add_u64 v[36:37], s[78:79], 0, v[36:37]
	v_lshl_add_u64 v[36:37], v[36:37], 0, v[130:131]
	v_accvgpr_read_b32 v38, a18
	v_accvgpr_read_b32 v39, a19
	v_mul_f32_e32 v41, 0xbfb8aa3b, v105
	v_mul_f32_e32 v40, 0xbfb8aa3b, v121
	v_exp_f32_e32 v41, v41
	v_exp_f32_e32 v40, v40
	v_and_b32_e32 v35, 0xffff0000, v35
	v_and_b32_e32 v34, 0xffff0000, v34
	v_add_f32_e32 v41, 1.0, v41
	v_add_f32_e32 v40, 1.0, v40
	v_rcp_f32_e32 v41, v41
	v_rcp_f32_e32 v40, v40
	v_fmac_f32_e32 v39, v41, v35
	v_fmac_f32_e32 v38, v40, v34
	v_mul_f32_e32 v34, v39, v39
	v_fmac_f32_e32 v34, v38, v38
	global_store_dword v[36:37], v38, off
	global_store_dword v[36:37], v39, off offset:128
	v_add_f32_dpp v34, v34, v34 quad_perm:[1,0,3,2] row_mask:0xf bank_mask:0xf bound_ctrl:1
	s_nop 1
	v_add_f32_dpp v34, v34, v34 quad_perm:[2,3,0,1] row_mask:0xf bank_mask:0xf bound_ctrl:1
	s_nop 1
	v_add_f32_dpp v34, v34, v34 row_half_mirror row_mask:0xf bank_mask:0xf bound_ctrl:1
	s_nop 1
	v_add_f32_dpp v34, v34, v34 row_mirror row_mask:0xf bank_mask:0xf bound_ctrl:1
	ds_bpermute_b32 v35, v237, v34
	s_and_saveexec_b64 s[8:9], s[4:5]
	s_cbranch_execz .LBB0_1608
	s_waitcnt lgkmcnt(0)
	v_add_f32_e32 v34, v34, v35
	v_lshl_add_u64 v[32:33], v[32:33], 2, s[92:93]
	global_atomic_add_f32 v[32:33], v34, off
; __device__ __forceinline__ float bflo(unsigned u) { return __uint_as_float(u << 16); }
; __device__ __forceinline__ float bfhi(unsigned u) { return __uint_as_float(u & 0xffff0000u); }
; __device__ __forceinline__ float sum32(float v) { v = dpp_row_sum16(v); v += __shfl_xor(v, 16); return v; }
; __device__ __forceinline__ float sigmoidf_(float x) { return __builtin_amdgcn_rcpf(1.f + __expf(-x)); }
; __device__ __forceinline__ int rowmap(int e, int lane) { return (e & 3) + 8 * (e >> 2) + 4 * (lane >> 5); }
; __device__ __forceinline__ void phase6(const Params& p, char* smem) {
;     ...
; #pragma unroll
;     for (int i = 0; i < 2; i++)
; #pragma unroll
;       for (int e = 0; e < 16; e++) {
;         const int row = m0 + wm * 64 + i * 32 + rowmap(e, lane);
;         float sq = 0.f;
; #pragma unroll
;         for (int j = 0; j < 2; j++) {
;           const int col = n0 + wn * 64 + j * 32 + (lane & 31);
;           float* xp = X + (size_t)row * 1024 + col;
;           float v = *xp + ((e & 1) ? bfhi(pe[i][j][e >> 1]) : bflo(pe[i][j][e >> 1])) * sigmoidf_(acc1[i][j][e]);
;           *xp = v;
;           sq += v * v;
;         }
;         sq = sum32(sq);
;         if ((lane & 31) == 0) atomicAdd(&SSQ3[row], sq);
;       }
.LBB0_1608:
	s_or_b64 exec, exec, s[8:9]
	v_or_b32_e32 v32, v48, v99
	v_ashrrev_i32_e32 v33, 31, v32
	s_waitcnt lgkmcnt(0)
	v_lshlrev_b64 v[34:35], 12, v[32:33]
	v_lshl_add_u64 v[34:35], s[78:79], 0, v[34:35]
	v_lshl_add_u64 v[38:39], v[34:35], 0, v[130:131]
	v_accvgpr_read_b32 v40, a20
	v_accvgpr_read_b32 v41, a21
	v_mul_f32_e32 v35, 0xbfb8aa3b, v106
	v_mul_f32_e32 v34, 0xbfb8aa3b, v122
	v_exp_f32_e32 v37, v35
	v_exp_f32_e32 v36, v34
	v_cvt_pk_bf16_f32 v35, v58, v59
	v_cvt_pk_bf16_f32 v34, v42, v43
	v_add_f32_e32 v37, 1.0, v37
	v_add_f32_e32 v36, 1.0, v36
	v_rcp_f32_e32 v37, v37
	v_rcp_f32_e32 v36, v36
	v_lshlrev_b32_e32 v43, 16, v35
	v_lshlrev_b32_e32 v42, 16, v34
	v_fmac_f32_e32 v40, v36, v42
	v_fmac_f32_e32 v41, v37, v43
	v_mul_f32_e32 v36, v41, v41
	v_fmac_f32_e32 v36, v40, v40
	global_store_dword v[38:39], v40, off
	global_store_dword v[38:39], v41, off offset:128
	v_add_f32_dpp v36, v36, v36 quad_perm:[1,0,3,2] row_mask:0xf bank_mask:0xf bound_ctrl:1
	s_nop 1
	v_add_f32_dpp v36, v36, v36 quad_perm:[2,3,0,1] row_mask:0xf bank_mask:0xf bound_ctrl:1
	s_nop 1
	v_add_f32_dpp v36, v36, v36 row_half_mirror row_mask:0xf bank_mask:0xf bound_ctrl:1
	s_nop 1
	v_add_f32_dpp v36, v36, v36 row_mirror row_mask:0xf bank_mask:0xf bound_ctrl:1
	ds_bpermute_b32 v37, v237, v36
	s_and_saveexec_b64 s[8:9], s[4:5]
	s_cbranch_execz .LBB0_1610
	s_waitcnt lgkmcnt(0)
	v_add_f32_e32 v36, v36, v37
	v_lshl_add_u64 v[32:33], v[32:33], 2, s[92:93]
	global_atomic_add_f32 v[32:33], v36, off
.LBB0_1610:
	s_or_b64 exec, exec, s[8:9]
	v_or_b32_e32 v32, v48, v112
	v_ashrrev_i32_e32 v33, 31, v32
	s_waitcnt lgkmcnt(0)
	v_lshlrev_b64 v[36:37], 12, v[32:33]
	v_lshl_add_u64 v[36:37], s[78:79], 0, v[36:37]
	v_lshl_add_u64 v[36:37], v[36:37], 0, v[130:131]
	v_accvgpr_read_b32 v38, a22
	v_accvgpr_read_b32 v39, a23
	v_mul_f32_e32 v41, 0xbfb8aa3b, v107
	v_mul_f32_e32 v40, 0xbfb8aa3b, v123
	v_exp_f32_e32 v41, v41
	v_exp_f32_e32 v40, v40
	v_and_b32_e32 v35, 0xffff0000, v35
	v_and_b32_e32 v34, 0xffff0000, v34
	v_add_f32_e32 v41, 1.0, v41
	v_add_f32_e32 v40, 1.0, v40
	v_rcp_f32_e32 v41, v41
	v_rcp_f32_e32 v40, v40
	v_fmac_f32_e32 v39, v41, v35
	v_fmac_f32_e32 v38, v40, v34
	v_mul_f32_e32 v34, v39, v39
	v_fmac_f32_e32 v34, v38, v38
	global_store_dword v[36:37], v38, off
	global_store_dword v[36:37], v39, off offset:128
	v_add_f32_dpp v34, v34, v34 quad_perm:[1,0,3,2] row_mask:0xf bank_mask:0xf bound_ctrl:1
	s_nop 1
	v_add_f32_dpp v34, v34, v34 quad_perm:[2,3,0,1] row_mask:0xf bank_mask:0xf bound_ctrl:1
	s_nop 1
	v_add_f32_dpp v34, v34, v34 row_half_mirror row_mask:0xf bank_mask:0xf bound_ctrl:1
	s_nop 1
	v_add_f32_dpp v34, v34, v34 row_mirror row_mask:0xf bank_mask:0xf bound_ctrl:1
	ds_bpermute_b32 v35, v237, v34
	s_and_saveexec_b64 s[8:9], s[4:5]
	s_cbranch_execz .LBB0_1612
	s_waitcnt lgkmcnt(0)
	v_add_f32_e32 v34, v34, v35
	v_lshl_add_u64 v[32:33], v[32:33], 2, s[92:93]
	global_atomic_add_f32 v[32:33], v34, off
.LBB0_1612:
	s_or_b64 exec, exec, s[8:9]
	v_or_b32_e32 v32, v48, v113
	v_ashrrev_i32_e32 v33, 31, v32
	s_waitcnt lgkmcnt(0)
	v_lshlrev_b64 v[34:35], 12, v[32:33]
	v_lshl_add_u64 v[34:35], s[78:79], 0, v[34:35]
	v_lshl_add_u64 v[38:39], v[34:35], 0, v[130:131]
	v_accvgpr_read_b32 v40, a24
	v_accvgpr_read_b32 v41, a25
	v_mul_f32_e32 v35, 0xbfb8aa3b, v108
	v_mul_f32_e32 v34, 0xbfb8aa3b, v124
	v_exp_f32_e32 v37, v35
	v_exp_f32_e32 v36, v34
	v_cvt_pk_bf16_f32 v35, v60, v61
	v_cvt_pk_bf16_f32 v34, v44, v45
	v_add_f32_e32 v37, 1.0, v37
	v_add_f32_e32 v36, 1.0, v36
	v_rcp_f32_e32 v37, v37
	v_rcp_f32_e32 v36, v36
	v_lshlrev_b32_e32 v43, 16, v35
	v_lshlrev_b32_e32 v42, 16, v34
	v_fmac_f32_e32 v40, v36, v42
	v_fmac_f32_e32 v41, v37, v43
	v_mul_f32_e32 v36, v41, v41
	v_fmac_f32_e32 v36, v40, v40
	global_store_dword v[38:39], v40, off
	global_store_dword v[38:39], v41, off offset:128
	v_add_f32_dpp v36, v36, v36 quad_perm:[1,0,3,2] row_mask:0xf bank_mask:0xf bound_ctrl:1
	s_nop 1
	v_add_f32_dpp v36, v36, v36 quad_perm:[2,3,0,1] row_mask:0xf bank_mask:0xf bound_ctrl:1
	s_nop 1
	v_add_f32_dpp v36, v36, v36 row_half_mirror row_mask:0xf bank_mask:0xf bound_ctrl:1
	s_nop 1
	v_add_f32_dpp v36, v36, v36 row_mirror row_mask:0xf bank_mask:0xf bound_ctrl:1
	ds_bpermute_b32 v37, v237, v36
	s_and_saveexec_b64 s[8:9], s[4:5]
	s_cbranch_execz .LBB0_1614
	s_waitcnt lgkmcnt(0)
	v_add_f32_e32 v36, v36, v37
	v_lshl_add_u64 v[32:33], v[32:33], 2, s[92:93]
	global_atomic_add_f32 v[32:33], v36, off
.LBB0_1614:
	s_or_b64 exec, exec, s[8:9]
	v_or_b32_e32 v32, v48, v114
	v_ashrrev_i32_e32 v33, 31, v32
	s_waitcnt lgkmcnt(0)
	v_lshlrev_b64 v[36:37], 12, v[32:33]
	v_lshl_add_u64 v[36:37], s[78:79], 0, v[36:37]
	v_lshl_add_u64 v[36:37], v[36:37], 0, v[130:131]
	v_accvgpr_read_b32 v38, a26
	v_accvgpr_read_b32 v39, a27
	v_mul_f32_e32 v41, 0xbfb8aa3b, v109
	v_mul_f32_e32 v40, 0xbfb8aa3b, v125
	v_exp_f32_e32 v41, v41
	v_exp_f32_e32 v40, v40
	v_and_b32_e32 v35, 0xffff0000, v35
	v_and_b32_e32 v34, 0xffff0000, v34
	v_add_f32_e32 v41, 1.0, v41
	v_add_f32_e32 v40, 1.0, v40
	v_rcp_f32_e32 v41, v41
	v_rcp_f32_e32 v40, v40
	v_fmac_f32_e32 v39, v41, v35
	v_fmac_f32_e32 v38, v40, v34
	v_mul_f32_e32 v34, v39, v39
	v_fmac_f32_e32 v34, v38, v38
	global_store_dword v[36:37], v38, off
	global_store_dword v[36:37], v39, off offset:128
	v_add_f32_dpp v34, v34, v34 quad_perm:[1,0,3,2] row_mask:0xf bank_mask:0xf bound_ctrl:1
	s_nop 1
	v_add_f32_dpp v34, v34, v34 quad_perm:[2,3,0,1] row_mask:0xf bank_mask:0xf bound_ctrl:1
	s_nop 1
	v_add_f32_dpp v34, v34, v34 row_half_mirror row_mask:0xf bank_mask:0xf bound_ctrl:1
	s_nop 1
	v_add_f32_dpp v34, v34, v34 row_mirror row_mask:0xf bank_mask:0xf bound_ctrl:1
	ds_bpermute_b32 v35, v237, v34
	s_and_saveexec_b64 s[8:9], s[4:5]
	s_cbranch_execz .LBB0_1616
	s_waitcnt lgkmcnt(0)
	v_add_f32_e32 v34, v34, v35
	v_lshl_add_u64 v[32:33], v[32:33], 2, s[92:93]
	global_atomic_add_f32 v[32:33], v34, off
; __device__ __forceinline__ float bflo(unsigned u) { return __uint_as_float(u << 16); }
; __device__ __forceinline__ float bfhi(unsigned u) { return __uint_as_float(u & 0xffff0000u); }
; __device__ __forceinline__ float sum32(float v) { v = dpp_row_sum16(v); v += __shfl_xor(v, 16); return v; }
; __device__ __forceinline__ float sigmoidf_(float x) { return __builtin_amdgcn_rcpf(1.f + __expf(-x)); }
; __device__ __forceinline__ int rowmap(int e, int lane) { return (e & 3) + 8 * (e >> 2) + 4 * (lane >> 5); }
; __device__ __forceinline__ void phase6(const Params& p, char* smem) {
;     ...
; #pragma unroll
;     for (int i = 0; i < 2; i++)
; #pragma unroll
;       for (int e = 0; e < 16; e++) {
;         const int row = m0 + wm * 64 + i * 32 + rowmap(e, lane);
;         float sq = 0.f;
; #pragma unroll
;         for (int j = 0; j < 2; j++) {
;           const int col = n0 + wn * 64 + j * 32 + (lane & 31);
;           float* xp = X + (size_t)row * 1024 + col;
;           float v = *xp + ((e & 1) ? bfhi(pe[i][j][e >> 1]) : bflo(pe[i][j][e >> 1])) * sigmoidf_(acc1[i][j][e]);
;           *xp = v;
;           sq += v * v;
;         }
;         sq = sum32(sq);
;         if ((lane & 31) == 0) atomicAdd(&SSQ3[row], sq);
;       }
.LBB0_1616:
	s_or_b64 exec, exec, s[8:9]
	v_or_b32_e32 v32, v48, v115
	v_ashrrev_i32_e32 v33, 31, v32
	s_waitcnt lgkmcnt(0)
	v_lshlrev_b64 v[34:35], 12, v[32:33]
	v_lshl_add_u64 v[34:35], s[78:79], 0, v[34:35]
	v_lshl_add_u64 v[38:39], v[34:35], 0, v[130:131]
	v_accvgpr_read_b32 v40, a28
	v_accvgpr_read_b32 v41, a29
	v_mul_f32_e32 v35, 0xbfb8aa3b, v110
	v_mul_f32_e32 v34, 0xbfb8aa3b, v126
	v_exp_f32_e32 v37, v35
	v_exp_f32_e32 v36, v34
	v_cvt_pk_bf16_f32 v35, v62, v63
	v_cvt_pk_bf16_f32 v34, v46, v47
	v_add_f32_e32 v37, 1.0, v37
	v_add_f32_e32 v36, 1.0, v36
	v_rcp_f32_e32 v37, v37
	v_rcp_f32_e32 v36, v36
	v_lshlrev_b32_e32 v43, 16, v35
	v_lshlrev_b32_e32 v42, 16, v34
	v_fmac_f32_e32 v40, v36, v42
	v_fmac_f32_e32 v41, v37, v43
	v_mul_f32_e32 v36, v41, v41
	v_fmac_f32_e32 v36, v40, v40
	global_store_dword v[38:39], v40, off
	global_store_dword v[38:39], v41, off offset:128
	v_add_f32_dpp v36, v36, v36 quad_perm:[1,0,3,2] row_mask:0xf bank_mask:0xf bound_ctrl:1
	s_nop 1
	v_add_f32_dpp v36, v36, v36 quad_perm:[2,3,0,1] row_mask:0xf bank_mask:0xf bound_ctrl:1
	s_nop 1
	v_add_f32_dpp v36, v36, v36 row_half_mirror row_mask:0xf bank_mask:0xf bound_ctrl:1
	s_nop 1
	v_add_f32_dpp v36, v36, v36 row_mirror row_mask:0xf bank_mask:0xf bound_ctrl:1
	ds_bpermute_b32 v37, v237, v36
	s_and_saveexec_b64 s[8:9], s[4:5]
	s_cbranch_execz .LBB0_1618
	s_waitcnt lgkmcnt(0)
	v_add_f32_e32 v36, v36, v37
	v_lshl_add_u64 v[32:33], v[32:33], 2, s[92:93]
	global_atomic_add_f32 v[32:33], v36, off
.LBB0_1618:
	s_or_b64 exec, exec, s[8:9]
	v_or_b32_e32 v32, v48, v153
	v_ashrrev_i32_e32 v33, 31, v32
	s_waitcnt lgkmcnt(0)
	v_lshlrev_b64 v[36:37], 12, v[32:33]
	v_lshl_add_u64 v[36:37], s[78:79], 0, v[36:37]
	v_lshl_add_u64 v[36:37], v[36:37], 0, v[130:131]
	v_accvgpr_read_b32 v38, a30
	v_accvgpr_read_b32 v39, a31
	v_mul_f32_e32 v41, 0xbfb8aa3b, v111
	v_mul_f32_e32 v40, 0xbfb8aa3b, v127
	v_exp_f32_e32 v41, v41
	v_exp_f32_e32 v40, v40
	v_and_b32_e32 v35, 0xffff0000, v35
	v_and_b32_e32 v34, 0xffff0000, v34
	v_add_f32_e32 v41, 1.0, v41
	v_add_f32_e32 v40, 1.0, v40
	v_rcp_f32_e32 v41, v41
	v_rcp_f32_e32 v40, v40
	v_fmac_f32_e32 v39, v41, v35
	v_fmac_f32_e32 v38, v40, v34
	v_mul_f32_e32 v34, v39, v39
	v_fmac_f32_e32 v34, v38, v38
	global_store_dword v[36:37], v38, off
	global_store_dword v[36:37], v39, off offset:128
	v_add_f32_dpp v34, v34, v34 quad_perm:[1,0,3,2] row_mask:0xf bank_mask:0xf bound_ctrl:1
	s_nop 1
	v_add_f32_dpp v34, v34, v34 quad_perm:[2,3,0,1] row_mask:0xf bank_mask:0xf bound_ctrl:1
	s_nop 1
	v_add_f32_dpp v34, v34, v34 row_half_mirror row_mask:0xf bank_mask:0xf bound_ctrl:1
	s_nop 1
	v_add_f32_dpp v34, v34, v34 row_mirror row_mask:0xf bank_mask:0xf bound_ctrl:1
	ds_bpermute_b32 v35, v237, v34
	s_and_saveexec_b64 s[8:9], s[4:5]
	s_cbranch_execz .LBB0_1620
	s_waitcnt lgkmcnt(0)
	v_add_f32_e32 v34, v34, v35
	v_lshl_add_u64 v[32:33], v[32:33], 2, s[92:93]
	global_atomic_add_f32 v[32:33], v34, off
.LBB0_1620:
	s_or_b64 exec, exec, s[8:9]
	v_or_b32_e32 v34, 32, v48
	v_or_b32_e32 v32, v34, v236
	v_ashrrev_i32_e32 v33, 31, v32
	v_lshlrev_b64 v[36:37], 12, v[32:33]
	v_lshl_add_u64 v[36:37], s[78:79], 0, v[36:37]
	v_lshl_add_u64 v[36:37], v[36:37], 0, v[130:131]
	v_accvgpr_read_b32 v38, a32
	v_accvgpr_read_b32 v39, a33
	v_mul_f32_e32 v40, 0xbfb8aa3b, v64
	s_waitcnt lgkmcnt(0)
	v_mul_f32_e32 v35, 0xbfb8aa3b, v80
	v_exp_f32_e32 v40, v40
	v_exp_f32_e32 v41, v35
	v_cvt_pk_bf16_f32 v35, v0, v1
	v_cvt_pk_bf16_f32 v16, v16, v17
	v_add_f32_e32 v1, 1.0, v40
	v_add_f32_e32 v0, 1.0, v41
	v_rcp_f32_e32 v1, v1
	v_rcp_f32_e32 v0, v0
	v_lshlrev_b32_e32 v40, 16, v16
	v_lshlrev_b32_e32 v17, 16, v35
	v_fmac_f32_e32 v38, v0, v17
	v_fmac_f32_e32 v39, v1, v40
	v_mul_f32_e32 v0, v39, v39
	v_fmac_f32_e32 v0, v38, v38
	global_store_dword v[36:37], v38, off
	global_store_dword v[36:37], v39, off offset:128
	v_add_f32_dpp v0, v0, v0 quad_perm:[1,0,3,2] row_mask:0xf bank_mask:0xf bound_ctrl:1
	s_nop 1
	v_add_f32_dpp v0, v0, v0 quad_perm:[2,3,0,1] row_mask:0xf bank_mask:0xf bound_ctrl:1
	s_nop 1
	v_add_f32_dpp v0, v0, v0 row_half_mirror row_mask:0xf bank_mask:0xf bound_ctrl:1
	s_nop 1
	v_add_f32_dpp v0, v0, v0 row_mirror row_mask:0xf bank_mask:0xf bound_ctrl:1
	ds_bpermute_b32 v1, v237, v0
	s_and_saveexec_b64 s[8:9], s[4:5]
	s_cbranch_execz .LBB0_1622
	s_waitcnt lgkmcnt(0)
	v_add_f32_e32 v17, v0, v1
	v_lshl_add_u64 v[0:1], v[32:33], 2, s[92:93]
	global_atomic_add_f32 v[0:1], v17, off
.LBB0_1622:
	s_or_b64 exec, exec, s[8:9]
	v_or_b32_e32 v0, v34, v135
	s_waitcnt lgkmcnt(0)
	v_ashrrev_i32_e32 v1, 31, v0
	v_lshlrev_b64 v[32:33], 12, v[0:1]
	v_lshl_add_u64 v[32:33], s[78:79], 0, v[32:33]
	v_lshl_add_u64 v[32:33], v[32:33], 0, v[130:131]
	v_accvgpr_read_b32 v36, a34
	v_accvgpr_read_b32 v37, a35
	v_mul_f32_e32 v38, 0xbfb8aa3b, v65
	v_mul_f32_e32 v17, 0xbfb8aa3b, v81
	v_exp_f32_e32 v38, v38
	v_exp_f32_e32 v17, v17
	v_and_b32_e32 v16, 0xffff0000, v16
	v_and_b32_e32 v35, 0xffff0000, v35
	v_add_f32_e32 v38, 1.0, v38
	v_add_f32_e32 v17, 1.0, v17
	v_rcp_f32_e32 v38, v38
	v_rcp_f32_e32 v17, v17
	v_fmac_f32_e32 v37, v38, v16
	v_fmac_f32_e32 v36, v17, v35
	v_mul_f32_e32 v16, v37, v37
	v_fmac_f32_e32 v16, v36, v36
	global_store_dword v[32:33], v36, off
	global_store_dword v[32:33], v37, off offset:128
	v_add_f32_dpp v16, v16, v16 quad_perm:[1,0,3,2] row_mask:0xf bank_mask:0xf bound_ctrl:1
	s_nop 1
	v_add_f32_dpp v16, v16, v16 quad_perm:[2,3,0,1] row_mask:0xf bank_mask:0xf bound_ctrl:1
	s_nop 1
	v_add_f32_dpp v16, v16, v16 row_half_mirror row_mask:0xf bank_mask:0xf bound_ctrl:1
	s_nop 1
	v_add_f32_dpp v16, v16, v16 row_mirror row_mask:0xf bank_mask:0xf bound_ctrl:1
	ds_bpermute_b32 v17, v237, v16
	s_and_saveexec_b64 s[8:9], s[4:5]
	s_cbranch_execz .LBB0_1624
	s_waitcnt lgkmcnt(0)
	v_add_f32_e32 v16, v16, v17
	v_lshl_add_u64 v[0:1], v[0:1], 2, s[92:93]
	global_atomic_add_f32 v[0:1], v16, off
; __device__ __forceinline__ float bflo(unsigned u) { return __uint_as_float(u << 16); }
; __device__ __forceinline__ float bfhi(unsigned u) { return __uint_as_float(u & 0xffff0000u); }
; __device__ __forceinline__ float sum32(float v) { v = dpp_row_sum16(v); v += __shfl_xor(v, 16); return v; }
; __device__ __forceinline__ float sigmoidf_(float x) { return __builtin_amdgcn_rcpf(1.f + __expf(-x)); }
; __device__ __forceinline__ int rowmap(int e, int lane) { return (e & 3) + 8 * (e >> 2) + 4 * (lane >> 5); }
; __device__ __forceinline__ void phase6(const Params& p, char* smem) {
;     ...
; #pragma unroll
;     for (int i = 0; i < 2; i++)
; #pragma unroll
;       for (int e = 0; e < 16; e++) {
;         const int row = m0 + wm * 64 + i * 32 + rowmap(e, lane);
;         float sq = 0.f;
; #pragma unroll
;         for (int j = 0; j < 2; j++) {
;           const int col = n0 + wn * 64 + j * 32 + (lane & 31);
;           float* xp = X + (size_t)row * 1024 + col;
;           float v = *xp + ((e & 1) ? bfhi(pe[i][j][e >> 1]) : bflo(pe[i][j][e >> 1])) * sigmoidf_(acc1[i][j][e]);
;           *xp = v;
;           sq += v * v;
;         }
;         sq = sum32(sq);
;         if ((lane & 31) == 0) atomicAdd(&SSQ3[row], sq);
;       }
.LBB0_1624:
	s_or_b64 exec, exec, s[8:9]
	v_or_b32_e32 v0, v34, v132
	v_ashrrev_i32_e32 v1, 31, v0
	s_waitcnt lgkmcnt(0)
	v_lshlrev_b64 v[16:17], 12, v[0:1]
	v_lshl_add_u64 v[16:17], s[78:79], 0, v[16:17]
	v_lshl_add_u64 v[32:33], v[16:17], 0, v[130:131]
	v_accvgpr_read_b32 v35, a36
	v_accvgpr_read_b32 v36, a37
	v_mul_f32_e32 v17, 0xbfb8aa3b, v66
	v_mul_f32_e32 v16, 0xbfb8aa3b, v82
	v_exp_f32_e32 v17, v17
	v_exp_f32_e32 v16, v16
	v_cvt_pk_bf16_f32 v2, v2, v3
	v_cvt_pk_bf16_f32 v3, v18, v19
	v_add_f32_e32 v17, 1.0, v17
	v_add_f32_e32 v16, 1.0, v16
	v_rcp_f32_e32 v17, v17
	v_rcp_f32_e32 v16, v16
	v_lshlrev_b32_e32 v19, 16, v3
	v_lshlrev_b32_e32 v18, 16, v2
	v_fmac_f32_e32 v35, v16, v18
	v_fmac_f32_e32 v36, v17, v19
	v_mul_f32_e32 v16, v36, v36
	v_fmac_f32_e32 v16, v35, v35
	global_store_dword v[32:33], v35, off
	global_store_dword v[32:33], v36, off offset:128
	v_add_f32_dpp v16, v16, v16 quad_perm:[1,0,3,2] row_mask:0xf bank_mask:0xf bound_ctrl:1
	s_nop 1
	v_add_f32_dpp v16, v16, v16 quad_perm:[2,3,0,1] row_mask:0xf bank_mask:0xf bound_ctrl:1
	s_nop 1
	v_add_f32_dpp v16, v16, v16 row_half_mirror row_mask:0xf bank_mask:0xf bound_ctrl:1
	s_nop 1
	v_add_f32_dpp v16, v16, v16 row_mirror row_mask:0xf bank_mask:0xf bound_ctrl:1
	ds_bpermute_b32 v17, v237, v16
	s_and_saveexec_b64 s[8:9], s[4:5]
	s_cbranch_execz .LBB0_1626
	s_waitcnt lgkmcnt(0)
	v_add_f32_e32 v16, v16, v17
	v_lshl_add_u64 v[0:1], v[0:1], 2, s[92:93]
	global_atomic_add_f32 v[0:1], v16, off
.LBB0_1626:
	s_or_b64 exec, exec, s[8:9]
	v_or_b32_e32 v0, v34, v133
	v_ashrrev_i32_e32 v1, 31, v0
	s_waitcnt lgkmcnt(0)
	v_lshlrev_b64 v[16:17], 12, v[0:1]
	v_lshl_add_u64 v[16:17], s[78:79], 0, v[16:17]
	v_lshl_add_u64 v[16:17], v[16:17], 0, v[130:131]
	v_accvgpr_read_b32 v18, a38
	v_accvgpr_read_b32 v19, a39
	v_mul_f32_e32 v33, 0xbfb8aa3b, v67
	v_mul_f32_e32 v32, 0xbfb8aa3b, v83
	v_exp_f32_e32 v33, v33
	v_exp_f32_e32 v32, v32
	v_and_b32_e32 v3, 0xffff0000, v3
	v_and_b32_e32 v2, 0xffff0000, v2
	v_add_f32_e32 v33, 1.0, v33
	v_add_f32_e32 v32, 1.0, v32
	v_rcp_f32_e32 v33, v33
	v_rcp_f32_e32 v32, v32
	v_fmac_f32_e32 v19, v33, v3
	v_fmac_f32_e32 v18, v32, v2
	v_mul_f32_e32 v2, v19, v19
	v_fmac_f32_e32 v2, v18, v18
	global_store_dword v[16:17], v18, off
	global_store_dword v[16:17], v19, off offset:128
	v_add_f32_dpp v2, v2, v2 quad_perm:[1,0,3,2] row_mask:0xf bank_mask:0xf bound_ctrl:1
	s_nop 1
	v_add_f32_dpp v2, v2, v2 quad_perm:[2,3,0,1] row_mask:0xf bank_mask:0xf bound_ctrl:1
	s_nop 1
	v_add_f32_dpp v2, v2, v2 row_half_mirror row_mask:0xf bank_mask:0xf bound_ctrl:1
	s_nop 1
	v_add_f32_dpp v2, v2, v2 row_mirror row_mask:0xf bank_mask:0xf bound_ctrl:1
	ds_bpermute_b32 v3, v237, v2
	s_and_saveexec_b64 s[8:9], s[4:5]
	s_cbranch_execz .LBB0_1628
	s_waitcnt lgkmcnt(0)
	v_add_f32_e32 v2, v2, v3
	v_lshl_add_u64 v[0:1], v[0:1], 2, s[92:93]
	global_atomic_add_f32 v[0:1], v2, off
.LBB0_1628:
	s_or_b64 exec, exec, s[8:9]
	v_or_b32_e32 v0, v34, v134
	v_ashrrev_i32_e32 v1, 31, v0
	s_waitcnt lgkmcnt(0)
	v_lshlrev_b64 v[2:3], 12, v[0:1]
	v_lshl_add_u64 v[2:3], s[78:79], 0, v[2:3]
	v_lshl_add_u64 v[16:17], v[2:3], 0, v[130:131]
	v_accvgpr_read_b32 v18, a40
	v_accvgpr_read_b32 v19, a41
	v_mul_f32_e32 v3, 0xbfb8aa3b, v68
	v_mul_f32_e32 v2, 0xbfb8aa3b, v84
	v_exp_f32_e32 v33, v3
	v_exp_f32_e32 v32, v2
	v_cvt_pk_bf16_f32 v2, v4, v5
	v_cvt_pk_bf16_f32 v3, v20, v21
	v_add_f32_e32 v5, 1.0, v33
	v_add_f32_e32 v4, 1.0, v32
	v_rcp_f32_e32 v5, v5
	v_rcp_f32_e32 v4, v4
	v_lshlrev_b32_e32 v21, 16, v3
	v_lshlrev_b32_e32 v20, 16, v2
	v_fmac_f32_e32 v18, v4, v20
	v_fmac_f32_e32 v19, v5, v21
	v_mul_f32_e32 v4, v19, v19
	v_fmac_f32_e32 v4, v18, v18
	global_store_dword v[16:17], v18, off
	global_store_dword v[16:17], v19, off offset:128
	v_add_f32_dpp v4, v4, v4 quad_perm:[1,0,3,2] row_mask:0xf bank_mask:0xf bound_ctrl:1
	s_nop 1
	v_add_f32_dpp v4, v4, v4 quad_perm:[2,3,0,1] row_mask:0xf bank_mask:0xf bound_ctrl:1
	s_nop 1
	v_add_f32_dpp v4, v4, v4 row_half_mirror row_mask:0xf bank_mask:0xf bound_ctrl:1
	s_nop 1
	v_add_f32_dpp v4, v4, v4 row_mirror row_mask:0xf bank_mask:0xf bound_ctrl:1
	ds_bpermute_b32 v5, v237, v4
	s_and_saveexec_b64 s[8:9], s[4:5]
	s_cbranch_execz .LBB0_1630
	s_waitcnt lgkmcnt(0)
	v_add_f32_e32 v4, v4, v5
	v_lshl_add_u64 v[0:1], v[0:1], 2, s[92:93]
	global_atomic_add_f32 v[0:1], v4, off
.LBB0_1630:
	s_or_b64 exec, exec, s[8:9]
	v_or_b32_e32 v0, v34, v148
	v_ashrrev_i32_e32 v1, 31, v0
	s_waitcnt lgkmcnt(0)
	v_lshlrev_b64 v[4:5], 12, v[0:1]
	v_lshl_add_u64 v[4:5], s[78:79], 0, v[4:5]
	v_lshl_add_u64 v[4:5], v[4:5], 0, v[130:131]
	v_accvgpr_read_b32 v16, a42
	v_accvgpr_read_b32 v17, a43
	v_mul_f32_e32 v19, 0xbfb8aa3b, v69
	v_mul_f32_e32 v18, 0xbfb8aa3b, v85
	v_exp_f32_e32 v19, v19
	v_exp_f32_e32 v18, v18
	v_and_b32_e32 v3, 0xffff0000, v3
	v_and_b32_e32 v2, 0xffff0000, v2
	v_add_f32_e32 v19, 1.0, v19
	v_add_f32_e32 v18, 1.0, v18
	v_rcp_f32_e32 v19, v19
	v_rcp_f32_e32 v18, v18
	v_fmac_f32_e32 v17, v19, v3
	v_fmac_f32_e32 v16, v18, v2
	v_mul_f32_e32 v2, v17, v17
	v_fmac_f32_e32 v2, v16, v16
	global_store_dword v[4:5], v16, off
	global_store_dword v[4:5], v17, off offset:128
	v_add_f32_dpp v2, v2, v2 quad_perm:[1,0,3,2] row_mask:0xf bank_mask:0xf bound_ctrl:1
	s_nop 1
	v_add_f32_dpp v2, v2, v2 quad_perm:[2,3,0,1] row_mask:0xf bank_mask:0xf bound_ctrl:1
	s_nop 1
	v_add_f32_dpp v2, v2, v2 row_half_mirror row_mask:0xf bank_mask:0xf bound_ctrl:1
	s_nop 1
	v_add_f32_dpp v2, v2, v2 row_mirror row_mask:0xf bank_mask:0xf bound_ctrl:1
	ds_bpermute_b32 v3, v237, v2
	s_and_saveexec_b64 s[8:9], s[4:5]
	s_cbranch_execz .LBB0_1632
	s_waitcnt lgkmcnt(0)
	v_add_f32_e32 v2, v2, v3
	v_lshl_add_u64 v[0:1], v[0:1], 2, s[92:93]
	global_atomic_add_f32 v[0:1], v2, off
; __device__ __forceinline__ float bflo(unsigned u) { return __uint_as_float(u << 16); }
; __device__ __forceinline__ float bfhi(unsigned u) { return __uint_as_float(u & 0xffff0000u); }
; __device__ __forceinline__ float sum32(float v) { v = dpp_row_sum16(v); v += __shfl_xor(v, 16); return v; }
; __device__ __forceinline__ float sigmoidf_(float x) { return __builtin_amdgcn_rcpf(1.f + __expf(-x)); }
; __device__ __forceinline__ int rowmap(int e, int lane) { return (e & 3) + 8 * (e >> 2) + 4 * (lane >> 5); }
; __device__ __forceinline__ void phase6(const Params& p, char* smem) {
;     ...
; #pragma unroll
;     for (int i = 0; i < 2; i++)
; #pragma unroll
;       for (int e = 0; e < 16; e++) {
;         const int row = m0 + wm * 64 + i * 32 + rowmap(e, lane);
;         float sq = 0.f;
; #pragma unroll
;         for (int j = 0; j < 2; j++) {
;           const int col = n0 + wn * 64 + j * 32 + (lane & 31);
;           float* xp = X + (size_t)row * 1024 + col;
;           float v = *xp + ((e & 1) ? bfhi(pe[i][j][e >> 1]) : bflo(pe[i][j][e >> 1])) * sigmoidf_(acc1[i][j][e]);
;           *xp = v;
;           sq += v * v;
;         }
;         sq = sum32(sq);
;         if ((lane & 31) == 0) atomicAdd(&SSQ3[row], sq);
;       }
.LBB0_1632:
	s_or_b64 exec, exec, s[8:9]
	v_or_b32_e32 v0, v34, v149
	v_ashrrev_i32_e32 v1, 31, v0
	s_waitcnt lgkmcnt(0)
	v_lshlrev_b64 v[2:3], 12, v[0:1]
	v_lshl_add_u64 v[2:3], s[78:79], 0, v[2:3]
	v_lshl_add_u64 v[16:17], v[2:3], 0, v[130:131]
	v_accvgpr_read_b32 v18, a44
	v_accvgpr_read_b32 v19, a45
	v_mul_f32_e32 v3, 0xbfb8aa3b, v70
	v_mul_f32_e32 v2, 0xbfb8aa3b, v86
	v_exp_f32_e32 v5, v3
	v_exp_f32_e32 v4, v2
	v_cvt_pk_bf16_f32 v3, v22, v23
	v_cvt_pk_bf16_f32 v2, v6, v7
	v_add_f32_e32 v5, 1.0, v5
	v_add_f32_e32 v4, 1.0, v4
	v_rcp_f32_e32 v5, v5
	v_rcp_f32_e32 v4, v4
	v_lshlrev_b32_e32 v7, 16, v3
	v_lshlrev_b32_e32 v6, 16, v2
	v_fmac_f32_e32 v18, v4, v6
	v_fmac_f32_e32 v19, v5, v7
	v_mul_f32_e32 v4, v19, v19
	v_fmac_f32_e32 v4, v18, v18
	global_store_dword v[16:17], v18, off
	global_store_dword v[16:17], v19, off offset:128
	v_add_f32_dpp v4, v4, v4 quad_perm:[1,0,3,2] row_mask:0xf bank_mask:0xf bound_ctrl:1
	s_nop 1
	v_add_f32_dpp v4, v4, v4 quad_perm:[2,3,0,1] row_mask:0xf bank_mask:0xf bound_ctrl:1
	s_nop 1
	v_add_f32_dpp v4, v4, v4 row_half_mirror row_mask:0xf bank_mask:0xf bound_ctrl:1
	s_nop 1
	v_add_f32_dpp v4, v4, v4 row_mirror row_mask:0xf bank_mask:0xf bound_ctrl:1
	ds_bpermute_b32 v5, v237, v4
	s_and_saveexec_b64 s[8:9], s[4:5]
	s_cbranch_execz .LBB0_1634
	s_waitcnt lgkmcnt(0)
	v_add_f32_e32 v4, v4, v5
	v_lshl_add_u64 v[0:1], v[0:1], 2, s[92:93]
	global_atomic_add_f32 v[0:1], v4, off
.LBB0_1634:
	s_or_b64 exec, exec, s[8:9]
	v_or_b32_e32 v0, v34, v150
	v_ashrrev_i32_e32 v1, 31, v0
	s_waitcnt lgkmcnt(0)
	v_lshlrev_b64 v[4:5], 12, v[0:1]
	v_lshl_add_u64 v[4:5], s[78:79], 0, v[4:5]
	v_lshl_add_u64 v[4:5], v[4:5], 0, v[130:131]
	v_accvgpr_read_b32 v6, a46
	v_accvgpr_read_b32 v7, a47
	v_mul_f32_e32 v17, 0xbfb8aa3b, v71
	v_mul_f32_e32 v16, 0xbfb8aa3b, v87
	v_exp_f32_e32 v17, v17
	v_exp_f32_e32 v16, v16
	v_and_b32_e32 v3, 0xffff0000, v3
	v_and_b32_e32 v2, 0xffff0000, v2
	v_add_f32_e32 v17, 1.0, v17
	v_add_f32_e32 v16, 1.0, v16
	v_rcp_f32_e32 v17, v17
	v_rcp_f32_e32 v16, v16
	v_fmac_f32_e32 v7, v17, v3
	v_fmac_f32_e32 v6, v16, v2
	v_mul_f32_e32 v2, v7, v7
	v_fmac_f32_e32 v2, v6, v6
	global_store_dword v[4:5], v6, off
	global_store_dword v[4:5], v7, off offset:128
	v_add_f32_dpp v2, v2, v2 quad_perm:[1,0,3,2] row_mask:0xf bank_mask:0xf bound_ctrl:1
	s_nop 1
	v_add_f32_dpp v2, v2, v2 quad_perm:[2,3,0,1] row_mask:0xf bank_mask:0xf bound_ctrl:1
	s_nop 1
	v_add_f32_dpp v2, v2, v2 row_half_mirror row_mask:0xf bank_mask:0xf bound_ctrl:1
	s_nop 1
	v_add_f32_dpp v2, v2, v2 row_mirror row_mask:0xf bank_mask:0xf bound_ctrl:1
	ds_bpermute_b32 v3, v237, v2
	s_and_saveexec_b64 s[8:9], s[4:5]
	s_cbranch_execz .LBB0_1636
	s_waitcnt lgkmcnt(0)
	v_add_f32_e32 v2, v2, v3
	v_lshl_add_u64 v[0:1], v[0:1], 2, s[92:93]
	global_atomic_add_f32 v[0:1], v2, off
.LBB0_1636:
	s_or_b64 exec, exec, s[8:9]
	v_or_b32_e32 v0, v34, v151
	v_ashrrev_i32_e32 v1, 31, v0
	s_waitcnt lgkmcnt(0)
	v_lshlrev_b64 v[2:3], 12, v[0:1]
	v_lshl_add_u64 v[2:3], s[78:79], 0, v[2:3]
	v_lshl_add_u64 v[6:7], v[2:3], 0, v[130:131]
	v_accvgpr_read_b32 v16, a48
	v_accvgpr_read_b32 v17, a49
	v_mul_f32_e32 v3, 0xbfb8aa3b, v72
	v_mul_f32_e32 v2, 0xbfb8aa3b, v88
	v_exp_f32_e32 v5, v3
	v_exp_f32_e32 v4, v2
	v_cvt_pk_bf16_f32 v3, v24, v25
	v_cvt_pk_bf16_f32 v2, v8, v9
	v_add_f32_e32 v5, 1.0, v5
	v_add_f32_e32 v4, 1.0, v4
	v_rcp_f32_e32 v5, v5
	v_rcp_f32_e32 v4, v4
	v_lshlrev_b32_e32 v9, 16, v3
	v_lshlrev_b32_e32 v8, 16, v2
	v_fmac_f32_e32 v16, v4, v8
	v_fmac_f32_e32 v17, v5, v9
	v_mul_f32_e32 v4, v17, v17
	v_fmac_f32_e32 v4, v16, v16
	global_store_dword v[6:7], v16, off
	global_store_dword v[6:7], v17, off offset:128
	v_add_f32_dpp v4, v4, v4 quad_perm:[1,0,3,2] row_mask:0xf bank_mask:0xf bound_ctrl:1
	s_nop 1
	v_add_f32_dpp v4, v4, v4 quad_perm:[2,3,0,1] row_mask:0xf bank_mask:0xf bound_ctrl:1
	s_nop 1
	v_add_f32_dpp v4, v4, v4 row_half_mirror row_mask:0xf bank_mask:0xf bound_ctrl:1
	s_nop 1
	v_add_f32_dpp v4, v4, v4 row_mirror row_mask:0xf bank_mask:0xf bound_ctrl:1
	ds_bpermute_b32 v5, v237, v4
	s_and_saveexec_b64 s[8:9], s[4:5]
	s_cbranch_execz .LBB0_1638
	s_waitcnt lgkmcnt(0)
	v_add_f32_e32 v4, v4, v5
	v_lshl_add_u64 v[0:1], v[0:1], 2, s[92:93]
	global_atomic_add_f32 v[0:1], v4, off
.LBB0_1638:
	s_or_b64 exec, exec, s[8:9]
	v_or_b32_e32 v0, v34, v152
	v_ashrrev_i32_e32 v1, 31, v0
	s_waitcnt lgkmcnt(0)
	v_lshlrev_b64 v[4:5], 12, v[0:1]
	v_lshl_add_u64 v[4:5], s[78:79], 0, v[4:5]
	v_lshl_add_u64 v[4:5], v[4:5], 0, v[130:131]
	v_accvgpr_read_b32 v6, a50
	v_accvgpr_read_b32 v7, a51
	v_mul_f32_e32 v9, 0xbfb8aa3b, v73
	v_mul_f32_e32 v8, 0xbfb8aa3b, v89
	v_exp_f32_e32 v9, v9
	v_exp_f32_e32 v8, v8
	v_and_b32_e32 v3, 0xffff0000, v3
	v_and_b32_e32 v2, 0xffff0000, v2
	v_add_f32_e32 v9, 1.0, v9
	v_add_f32_e32 v8, 1.0, v8
	v_rcp_f32_e32 v9, v9
	v_rcp_f32_e32 v8, v8
	v_fmac_f32_e32 v7, v9, v3
	v_fmac_f32_e32 v6, v8, v2
	v_mul_f32_e32 v2, v7, v7
	v_fmac_f32_e32 v2, v6, v6
	global_store_dword v[4:5], v6, off
	global_store_dword v[4:5], v7, off offset:128
	v_add_f32_dpp v2, v2, v2 quad_perm:[1,0,3,2] row_mask:0xf bank_mask:0xf bound_ctrl:1
	s_nop 1
	v_add_f32_dpp v2, v2, v2 quad_perm:[2,3,0,1] row_mask:0xf bank_mask:0xf bound_ctrl:1
	s_nop 1
	v_add_f32_dpp v2, v2, v2 row_half_mirror row_mask:0xf bank_mask:0xf bound_ctrl:1
	s_nop 1
	v_add_f32_dpp v2, v2, v2 row_mirror row_mask:0xf bank_mask:0xf bound_ctrl:1
	ds_bpermute_b32 v3, v237, v2
	s_and_saveexec_b64 s[8:9], s[4:5]
	s_cbranch_execz .LBB0_1640
	s_waitcnt lgkmcnt(0)
	v_add_f32_e32 v2, v2, v3
	v_lshl_add_u64 v[0:1], v[0:1], 2, s[92:93]
	global_atomic_add_f32 v[0:1], v2, off
; __device__ __forceinline__ float bflo(unsigned u) { return __uint_as_float(u << 16); }
; __device__ __forceinline__ float bfhi(unsigned u) { return __uint_as_float(u & 0xffff0000u); }
; __device__ __forceinline__ float sum32(float v) { v = dpp_row_sum16(v); v += __shfl_xor(v, 16); return v; }
; __device__ __forceinline__ float sigmoidf_(float x) { return __builtin_amdgcn_rcpf(1.f + __expf(-x)); }
; __device__ __forceinline__ int rowmap(int e, int lane) { return (e & 3) + 8 * (e >> 2) + 4 * (lane >> 5); }
; __device__ __forceinline__ void phase6(const Params& p, char* smem) {
;     ...
; #pragma unroll
;     for (int i = 0; i < 2; i++)
; #pragma unroll
;       for (int e = 0; e < 16; e++) {
;         const int row = m0 + wm * 64 + i * 32 + rowmap(e, lane);
;         float sq = 0.f;
; #pragma unroll
;         for (int j = 0; j < 2; j++) {
;           const int col = n0 + wn * 64 + j * 32 + (lane & 31);
;           float* xp = X + (size_t)row * 1024 + col;
;           float v = *xp + ((e & 1) ? bfhi(pe[i][j][e >> 1]) : bflo(pe[i][j][e >> 1])) * sigmoidf_(acc1[i][j][e]);
;           *xp = v;
;           sq += v * v;
;         }
;         sq = sum32(sq);
;         if ((lane & 31) == 0) atomicAdd(&SSQ3[row], sq);
;       }
.LBB0_1640:
	s_or_b64 exec, exec, s[8:9]
	v_or_b32_e32 v0, v34, v99
	v_ashrrev_i32_e32 v1, 31, v0
	s_waitcnt lgkmcnt(0)
	v_lshlrev_b64 v[2:3], 12, v[0:1]
	v_lshl_add_u64 v[2:3], s[78:79], 0, v[2:3]
	v_lshl_add_u64 v[6:7], v[2:3], 0, v[130:131]
	v_accvgpr_read_b32 v8, a52
	v_accvgpr_read_b32 v9, a53
	v_mul_f32_e32 v3, 0xbfb8aa3b, v74
	v_mul_f32_e32 v2, 0xbfb8aa3b, v90
	v_exp_f32_e32 v5, v3
	v_exp_f32_e32 v4, v2
	v_cvt_pk_bf16_f32 v3, v26, v27
	v_cvt_pk_bf16_f32 v2, v10, v11
	v_add_f32_e32 v5, 1.0, v5
	v_add_f32_e32 v4, 1.0, v4
	v_rcp_f32_e32 v5, v5
	v_rcp_f32_e32 v4, v4
	v_lshlrev_b32_e32 v11, 16, v3
	v_lshlrev_b32_e32 v10, 16, v2
	v_fmac_f32_e32 v8, v4, v10
	v_fmac_f32_e32 v9, v5, v11
	v_mul_f32_e32 v4, v9, v9
	v_fmac_f32_e32 v4, v8, v8
	global_store_dword v[6:7], v8, off
	global_store_dword v[6:7], v9, off offset:128
	v_add_f32_dpp v4, v4, v4 quad_perm:[1,0,3,2] row_mask:0xf bank_mask:0xf bound_ctrl:1
	s_nop 1
	v_add_f32_dpp v4, v4, v4 quad_perm:[2,3,0,1] row_mask:0xf bank_mask:0xf bound_ctrl:1
	s_nop 1
	v_add_f32_dpp v4, v4, v4 row_half_mirror row_mask:0xf bank_mask:0xf bound_ctrl:1
	s_nop 1
	v_add_f32_dpp v4, v4, v4 row_mirror row_mask:0xf bank_mask:0xf bound_ctrl:1
	ds_bpermute_b32 v5, v237, v4
	s_and_saveexec_b64 s[8:9], s[4:5]
	s_cbranch_execz .LBB0_1642
	s_waitcnt lgkmcnt(0)
	v_add_f32_e32 v4, v4, v5
	v_lshl_add_u64 v[0:1], v[0:1], 2, s[92:93]
	global_atomic_add_f32 v[0:1], v4, off
.LBB0_1642:
	s_or_b64 exec, exec, s[8:9]
	v_or_b32_e32 v0, v34, v112
	v_ashrrev_i32_e32 v1, 31, v0
	s_waitcnt lgkmcnt(0)
	v_lshlrev_b64 v[4:5], 12, v[0:1]
	v_lshl_add_u64 v[4:5], s[78:79], 0, v[4:5]
	v_lshl_add_u64 v[4:5], v[4:5], 0, v[130:131]
	v_accvgpr_read_b32 v6, a54
	v_accvgpr_read_b32 v7, a55
	v_mul_f32_e32 v9, 0xbfb8aa3b, v75
	v_mul_f32_e32 v8, 0xbfb8aa3b, v91
	v_exp_f32_e32 v9, v9
	v_exp_f32_e32 v8, v8
	v_and_b32_e32 v3, 0xffff0000, v3
	v_and_b32_e32 v2, 0xffff0000, v2
	v_add_f32_e32 v9, 1.0, v9
	v_add_f32_e32 v8, 1.0, v8
	v_rcp_f32_e32 v9, v9
	v_rcp_f32_e32 v8, v8
	v_fmac_f32_e32 v7, v9, v3
	v_fmac_f32_e32 v6, v8, v2
	v_mul_f32_e32 v2, v7, v7
	v_fmac_f32_e32 v2, v6, v6
	global_store_dword v[4:5], v6, off
	global_store_dword v[4:5], v7, off offset:128
	v_add_f32_dpp v2, v2, v2 quad_perm:[1,0,3,2] row_mask:0xf bank_mask:0xf bound_ctrl:1
	s_nop 1
	v_add_f32_dpp v2, v2, v2 quad_perm:[2,3,0,1] row_mask:0xf bank_mask:0xf bound_ctrl:1
	s_nop 1
	v_add_f32_dpp v2, v2, v2 row_half_mirror row_mask:0xf bank_mask:0xf bound_ctrl:1
	s_nop 1
	v_add_f32_dpp v2, v2, v2 row_mirror row_mask:0xf bank_mask:0xf bound_ctrl:1
	ds_bpermute_b32 v3, v237, v2
	s_and_saveexec_b64 s[8:9], s[4:5]
	s_cbranch_execz .LBB0_1644
	s_waitcnt lgkmcnt(0)
	v_add_f32_e32 v2, v2, v3
	v_lshl_add_u64 v[0:1], v[0:1], 2, s[92:93]
	global_atomic_add_f32 v[0:1], v2, off
.LBB0_1644:
	s_or_b64 exec, exec, s[8:9]
	v_or_b32_e32 v0, v34, v113
	v_ashrrev_i32_e32 v1, 31, v0
	s_waitcnt lgkmcnt(0)
	v_lshlrev_b64 v[2:3], 12, v[0:1]
	v_lshl_add_u64 v[2:3], s[78:79], 0, v[2:3]
	v_lshl_add_u64 v[6:7], v[2:3], 0, v[130:131]
	v_accvgpr_read_b32 v8, a56
	v_accvgpr_read_b32 v9, a57
	v_mul_f32_e32 v3, 0xbfb8aa3b, v76
	v_mul_f32_e32 v2, 0xbfb8aa3b, v92
	v_exp_f32_e32 v5, v3
	v_exp_f32_e32 v4, v2
	v_cvt_pk_bf16_f32 v3, v28, v29
	v_cvt_pk_bf16_f32 v2, v12, v13
	v_add_f32_e32 v5, 1.0, v5
	v_add_f32_e32 v4, 1.0, v4
	v_rcp_f32_e32 v5, v5
	v_rcp_f32_e32 v4, v4
	v_lshlrev_b32_e32 v11, 16, v3
	v_lshlrev_b32_e32 v10, 16, v2
	v_fmac_f32_e32 v8, v4, v10
	v_fmac_f32_e32 v9, v5, v11
	v_mul_f32_e32 v4, v9, v9
	v_fmac_f32_e32 v4, v8, v8
	global_store_dword v[6:7], v8, off
	global_store_dword v[6:7], v9, off offset:128
	v_add_f32_dpp v4, v4, v4 quad_perm:[1,0,3,2] row_mask:0xf bank_mask:0xf bound_ctrl:1
	s_nop 1
	v_add_f32_dpp v4, v4, v4 quad_perm:[2,3,0,1] row_mask:0xf bank_mask:0xf bound_ctrl:1
	s_nop 1
	v_add_f32_dpp v4, v4, v4 row_half_mirror row_mask:0xf bank_mask:0xf bound_ctrl:1
	s_nop 1
	v_add_f32_dpp v4, v4, v4 row_mirror row_mask:0xf bank_mask:0xf bound_ctrl:1
	ds_bpermute_b32 v5, v237, v4
	s_and_saveexec_b64 s[8:9], s[4:5]
	s_cbranch_execz .LBB0_1646
	s_waitcnt lgkmcnt(0)
	v_add_f32_e32 v4, v4, v5
	v_lshl_add_u64 v[0:1], v[0:1], 2, s[92:93]
	global_atomic_add_f32 v[0:1], v4, off
; __device__ __forceinline__ float bflo(unsigned u) { return __uint_as_float(u << 16); }
; __device__ __forceinline__ float bfhi(unsigned u) { return __uint_as_float(u & 0xffff0000u); }
; __device__ __forceinline__ float sum32(float v) { v = dpp_row_sum16(v); v += __shfl_xor(v, 16); return v; }
; __device__ __forceinline__ float sigmoidf_(float x) { return __builtin_amdgcn_rcpf(1.f + __expf(-x)); }
; __device__ __forceinline__ int rowmap(int e, int lane) { return (e & 3) + 8 * (e >> 2) + 4 * (lane >> 5); }
; __device__ __forceinline__ void phase6(const Params& p, char* smem) {
;     ...
; #pragma unroll
;     for (int i = 0; i < 2; i++)
; #pragma unroll
;       for (int e = 0; e < 16; e++) {
;         const int row = m0 + wm * 64 + i * 32 + rowmap(e, lane);
;         float sq = 0.f;
; #pragma unroll
;         for (int j = 0; j < 2; j++) {
;           const int col = n0 + wn * 64 + j * 32 + (lane & 31);
;           float* xp = X + (size_t)row * 1024 + col;
;           float v = *xp + ((e & 1) ? bfhi(pe[i][j][e >> 1]) : bflo(pe[i][j][e >> 1])) * sigmoidf_(acc1[i][j][e]);
;           *xp = v;
;           sq += v * v;
;         }
;         sq = sum32(sq);
;         if ((lane & 31) == 0) atomicAdd(&SSQ3[row], sq);
;       }
.LBB0_1646:
	s_or_b64 exec, exec, s[8:9]
	v_or_b32_e32 v0, v34, v114
	v_ashrrev_i32_e32 v1, 31, v0
	s_waitcnt lgkmcnt(0)
	v_lshlrev_b64 v[4:5], 12, v[0:1]
	v_lshl_add_u64 v[4:5], s[78:79], 0, v[4:5]
	v_lshl_add_u64 v[4:5], v[4:5], 0, v[130:131]
	v_accvgpr_read_b32 v6, a58
	v_accvgpr_read_b32 v7, a59
	v_mul_f32_e32 v9, 0xbfb8aa3b, v77
	v_mul_f32_e32 v8, 0xbfb8aa3b, v93
	v_exp_f32_e32 v9, v9
	v_exp_f32_e32 v8, v8
	v_and_b32_e32 v3, 0xffff0000, v3
	v_and_b32_e32 v2, 0xffff0000, v2
	v_add_f32_e32 v9, 1.0, v9
	v_add_f32_e32 v8, 1.0, v8
	v_rcp_f32_e32 v9, v9
	v_rcp_f32_e32 v8, v8
	v_fmac_f32_e32 v7, v9, v3
	v_fmac_f32_e32 v6, v8, v2
	v_mul_f32_e32 v2, v7, v7
	v_fmac_f32_e32 v2, v6, v6
	global_store_dword v[4:5], v6, off
	global_store_dword v[4:5], v7, off offset:128
	v_add_f32_dpp v2, v2, v2 quad_perm:[1,0,3,2] row_mask:0xf bank_mask:0xf bound_ctrl:1
	s_nop 1
	v_add_f32_dpp v2, v2, v2 quad_perm:[2,3,0,1] row_mask:0xf bank_mask:0xf bound_ctrl:1
	s_nop 1
	v_add_f32_dpp v2, v2, v2 row_half_mirror row_mask:0xf bank_mask:0xf bound_ctrl:1
	s_nop 1
	v_add_f32_dpp v2, v2, v2 row_mirror row_mask:0xf bank_mask:0xf bound_ctrl:1
	ds_bpermute_b32 v3, v237, v2
	s_and_saveexec_b64 s[8:9], s[4:5]
	s_cbranch_execz .LBB0_1648
	s_waitcnt lgkmcnt(0)
	v_add_f32_e32 v2, v2, v3
	v_lshl_add_u64 v[0:1], v[0:1], 2, s[92:93]
	global_atomic_add_f32 v[0:1], v2, off
.LBB0_1648:
	s_or_b64 exec, exec, s[8:9]
	v_or_b32_e32 v0, v34, v115
	v_ashrrev_i32_e32 v1, 31, v0
	s_waitcnt lgkmcnt(0)
	v_lshlrev_b64 v[2:3], 12, v[0:1]
	v_lshl_add_u64 v[2:3], s[78:79], 0, v[2:3]
	v_lshl_add_u64 v[6:7], v[2:3], 0, v[130:131]
	v_accvgpr_read_b32 v8, a60
	v_accvgpr_read_b32 v9, a61
	v_mul_f32_e32 v3, 0xbfb8aa3b, v78
	v_mul_f32_e32 v2, 0xbfb8aa3b, v94
	v_exp_f32_e32 v5, v3
	v_exp_f32_e32 v4, v2
	v_cvt_pk_bf16_f32 v3, v30, v31
	v_cvt_pk_bf16_f32 v2, v14, v15
	v_add_f32_e32 v5, 1.0, v5
	v_add_f32_e32 v4, 1.0, v4
	v_rcp_f32_e32 v5, v5
	v_rcp_f32_e32 v4, v4
	v_lshlrev_b32_e32 v11, 16, v3
	v_lshlrev_b32_e32 v10, 16, v2
	v_fmac_f32_e32 v8, v4, v10
	v_fmac_f32_e32 v9, v5, v11
	v_mul_f32_e32 v4, v9, v9
	v_fmac_f32_e32 v4, v8, v8
	global_store_dword v[6:7], v8, off
	global_store_dword v[6:7], v9, off offset:128
	v_add_f32_dpp v4, v4, v4 quad_perm:[1,0,3,2] row_mask:0xf bank_mask:0xf bound_ctrl:1
	s_nop 1
	v_add_f32_dpp v4, v4, v4 quad_perm:[2,3,0,1] row_mask:0xf bank_mask:0xf bound_ctrl:1
	s_nop 1
	v_add_f32_dpp v4, v4, v4 row_half_mirror row_mask:0xf bank_mask:0xf bound_ctrl:1
	s_nop 1
	v_add_f32_dpp v4, v4, v4 row_mirror row_mask:0xf bank_mask:0xf bound_ctrl:1
	ds_bpermute_b32 v5, v237, v4
	s_and_saveexec_b64 s[8:9], s[4:5]
	s_cbranch_execz .LBB0_1650
	s_waitcnt lgkmcnt(0)
	v_add_f32_e32 v4, v4, v5
	v_lshl_add_u64 v[0:1], v[0:1], 2, s[92:93]
	global_atomic_add_f32 v[0:1], v4, off
.LBB0_1650:
	s_or_b64 exec, exec, s[8:9]
	v_or_b32_e32 v0, v34, v153
	v_ashrrev_i32_e32 v1, 31, v0
	s_waitcnt lgkmcnt(0)
	v_lshlrev_b64 v[4:5], 12, v[0:1]
	v_lshl_add_u64 v[4:5], s[78:79], 0, v[4:5]
	v_lshl_add_u64 v[4:5], v[4:5], 0, v[130:131]
	v_accvgpr_read_b32 v6, a62
	v_accvgpr_read_b32 v7, a63
	v_mul_f32_e32 v9, 0xbfb8aa3b, v79
	v_mul_f32_e32 v8, 0xbfb8aa3b, v95
	v_exp_f32_e32 v9, v9
	v_exp_f32_e32 v8, v8
	v_and_b32_e32 v3, 0xffff0000, v3
	v_and_b32_e32 v2, 0xffff0000, v2
	v_add_f32_e32 v9, 1.0, v9
	v_add_f32_e32 v8, 1.0, v8
	v_rcp_f32_e32 v9, v9
	v_rcp_f32_e32 v8, v8
	v_fmac_f32_e32 v7, v9, v3
	v_fmac_f32_e32 v6, v8, v2
	v_mul_f32_e32 v2, v7, v7
	v_fmac_f32_e32 v2, v6, v6
	global_store_dword v[4:5], v6, off
	global_store_dword v[4:5], v7, off offset:128
	v_add_f32_dpp v2, v2, v2 quad_perm:[1,0,3,2] row_mask:0xf bank_mask:0xf bound_ctrl:1
	s_nop 1
	v_add_f32_dpp v2, v2, v2 quad_perm:[2,3,0,1] row_mask:0xf bank_mask:0xf bound_ctrl:1
	s_nop 1
	v_add_f32_dpp v2, v2, v2 row_half_mirror row_mask:0xf bank_mask:0xf bound_ctrl:1
	s_nop 1
	v_add_f32_dpp v2, v2, v2 row_mirror row_mask:0xf bank_mask:0xf bound_ctrl:1
	ds_bpermute_b32 v3, v237, v2
	s_and_saveexec_b64 s[8:9], s[4:5]
	s_cbranch_execz .LBB0_1577
	s_waitcnt lgkmcnt(0)
	v_add_f32_e32 v2, v2, v3
	v_lshl_add_u64 v[0:1], v[0:1], 2, s[92:93]
	global_atomic_add_f32 v[0:1], v2, off
	s_branch .LBB0_1577

; #define LAS __attribute__((address_space(3)))
; __global__ void __launch_bounds__(256) mega_kernel(Params p) {
;   __shared__ __attribute__((aligned(16))) char smem[SMEM_BYTES];
;   cg::grid_group grid = cg::this_grid();
;   __shared__ uint4 xb_words;
;   if (threadIdx.x == 0) xb_words = make_uint4(0u, 0u, 0u, 0u);
;   __syncthreads();
;   XcdBarrier xb = xcd_barrier_post((unsigned*)(p.ws + OFF_BAR), (volatile LAS unsigned*)&xb_words);
;   phase0(p, smem);
	.amdhsa_kernel _Z11mega_kernel6Params
		.amdhsa_group_segment_fixed_size 145424
		.amdhsa_private_segment_fixed_size 0
		.amdhsa_kernarg_size 488
		.amdhsa_user_sgpr_count 2
		.amdhsa_user_sgpr_dispatch_ptr 0
		.amdhsa_user_sgpr_queue_ptr 0
		.amdhsa_user_sgpr_kernarg_segment_ptr 1
		.amdhsa_user_sgpr_dispatch_id 0
		.amdhsa_user_sgpr_kernarg_preload_length 0
		.amdhsa_user_sgpr_kernarg_preload_offset 0
		.amdhsa_user_sgpr_private_segment_size 0
		.amdhsa_uses_dynamic_stack 0
		.amdhsa_enable_private_segment 0
		.amdhsa_system_sgpr_workgroup_id_x 1
		.amdhsa_system_sgpr_workgroup_id_y 0
		.amdhsa_system_sgpr_workgroup_id_z 0
		.amdhsa_system_sgpr_workgroup_info 0
		.amdhsa_system_vgpr_workitem_id 2
		.amdhsa_next_free_vgpr 512
		.amdhsa_next_free_sgpr 100
		.amdhsa_accum_offset 256
		.amdhsa_reserve_vcc 1
		.amdhsa_float_round_mode_32 0
		.amdhsa_float_round_mode_16_64 0
		.amdhsa_float_denorm_mode_32 3
		.amdhsa_float_denorm_mode_16_64 3
		.amdhsa_dx10_clamp 1
		.amdhsa_ieee_mode 1
		.amdhsa_fp16_overflow 0
		.amdhsa_tg_split 0
		.amdhsa_exception_fp_ieee_invalid_op 0
		.amdhsa_exception_fp_denorm_src 0
		.amdhsa_exception_fp_ieee_div_zero 0
		.amdhsa_exception_fp_ieee_overflow 0
		.amdhsa_exception_fp_ieee_underflow 0
		.amdhsa_exception_fp_ieee_inexact 0
		.amdhsa_exception_int_div_zero 0
	.end_amdhsa_kernel

; #define LAS __attribute__((address_space(3)))
; __global__ void __launch_bounds__(256) mega_kernel(Params p) {
;   __shared__ __attribute__((aligned(16))) char smem[SMEM_BYTES];
;   cg::grid_group grid = cg::this_grid();
;   __shared__ uint4 xb_words;
;   if (threadIdx.x == 0) xb_words = make_uint4(0u, 0u, 0u, 0u);
;   __syncthreads();
;   XcdBarrier xb = xcd_barrier_post((unsigned*)(p.ws + OFF_BAR), (volatile LAS unsigned*)&xb_words);
;   phase0(p, smem);
amdhsa.kernels:
  - .agpr_count:     256
    .args:
      - .offset:         0
        .size:           232
        .value_kind:     by_value
      - .offset:         232
        .size:           4
        .value_kind:     hidden_block_count_x
      - .offset:         236
        .size:           4
        .value_kind:     hidden_block_count_y
      - .offset:         240
        .size:           4
        .value_kind:     hidden_block_count_z
      - .offset:         244
        .size:           2
        .value_kind:     hidden_group_size_x
      - .offset:         246
        .size:           2
        .value_kind:     hidden_group_size_y
      - .offset:         248
        .size:           2
        .value_kind:     hidden_group_size_z
      - .offset:         250
        .size:           2
        .value_kind:     hidden_remainder_x
      - .offset:         252
        .size:           2
        .value_kind:     hidden_remainder_y
      - .offset:         254
        .size:           2
        .value_kind:     hidden_remainder_z
      - .offset:         272
        .size:           8
        .value_kind:     hidden_global_offset_x
      - .offset:         280
        .size:           8
        .value_kind:     hidden_global_offset_y
      - .offset:         288
        .size:           8
        .value_kind:     hidden_global_offset_z
      - .offset:         296
        .size:           2
        .value_kind:     hidden_grid_dims
      - .offset:         320
        .size:           8
        .value_kind:     hidden_multigrid_sync_arg
    .group_segment_fixed_size: 145424
    .kernarg_segment_align: 8
    .kernarg_segment_size: 488
    .language:       OpenCL C
    .language_version:
      - 2
      - 0
    .max_flat_workgroup_size: 256
    .name:           _Z11mega_kernel6Params
    .private_segment_fixed_size: 0
    .sgpr_count:     106
    .sgpr_spill_count: 110
    .symbol:         _Z11mega_kernel6Params.kd
    .uniform_work_group_size: 1
    .uses_dynamic_stack: false
    .vgpr_count:     512
    .vgpr_spill_count: 0
    .wavefront_size: 64
